# outproj0/1: K-tiles 0..30 through the hand-written pipelined loop (DMA spread, LDS reads pipelined), compiled peeled last tile + epilogue kept
# speedup vs baseline: 1.0082x; 1.0082x over previous
.LBB0_315:
	s_ashr_i32 s34, s52, 31
	s_lshr_b32 s34, s34, 23
	s_add_i32 s34, s52, s34
	s_ashr_i32 s34, s34, 9
	s_lshl_b32 s55, s34, 6
	s_lshl_b32 s34, s52, 3
	s_and_b32 s34, s34, 56
	s_or_b32 s54, s55, s34
	s_bfe_u32 s56, s52, 0x30003
	s_or_b32 s34, s54, s56
	s_ashr_i32 s35, s34, 31
	s_lshl_b64 s[38:39], s[34:35], 19
	v_lshl_add_u64 v[0:1], v[86:87], 0, s[38:39]
	v_readfirstlane_b32 s38, v129
	s_mov_b32 m0, s38
	v_readfirstlane_b32 s38, v119
	s_barrier
	s_bfe_u32 s53, s52, 0x30006
	s_lshl_b64 s[98:99], s[34:35], 19
	s_add_u32 s98, s98, s50
	s_addc_u32 s99, s99, s51
	s_add_u32 s98, s98, 0x5a00000
	s_addc_u32 s99, s99, 0
	s_lshl_b32 s100, s53, 19
	s_add_u32 s100, s100, s50
	s_addc_u32 s101, s51, 0
	s_add_u32 s100, s100, 0x2800000
	s_addc_u32 s101, s101, 0
	v_readfirstlane_b32 s38, v129
	v_and_b32_e32 v80, 15, v131
	v_bfe_u32 v81, v131, 4, 2
	v_bfe_u32 v82, v131, 1, 3
	v_xor_b32_e32 v82, v81, v82
	v_lshlrev_b32_e32 v82, 4, v82
	v_lshl_or_b32 v210, v80, 7, v82
	v_xor_b32_e32 v211, 64, v210
	v_lshrrev_b32_e32 v82, 6, v131
	v_lshl_add_u32 v208, v82, 12, v210
	v_lshl_add_u32 v209, v82, 12, v211
	v_bfe_u32 v80, v131, 4, 3
	v_and_b32_e32 v81, 7, v131
	v_xor_b32_e32 v80, v80, v81
	v_lshlrev_b32_e32 v80, 4, v80
	v_lshrrev_b32_e32 v81, 3, v131
	v_lshl_or_b32 v212, v81, 12, v80
	v_add_u32_e32 v213, 131072, v212
	v_add_u32_e32 v214, 262144, v212
	v_add_u32_e32 v215, 393216, v212
	s_add_u32 m0, s38, 0
	v_mov_b32_e32 v40, 0
	v_mov_b32_e32 v41, 0
	global_load_lds_dwordx4 v212, s[98:99]
	s_add_u32 m0, s38, 4096
	v_mov_b32_e32 v42, 0
	v_mov_b32_e32 v43, 0
	global_load_lds_dwordx4 v213, s[98:99]
	s_add_u32 m0, s38, 8192
	v_mov_b32_e32 v28, 0
	v_mov_b32_e32 v29, 0
	global_load_lds_dwordx4 v214, s[98:99]
	s_add_u32 m0, s38, 12288
	v_mov_b32_e32 v30, 0
	v_mov_b32_e32 v31, 0
	global_load_lds_dwordx4 v215, s[98:99]
	s_add_u32 s98, s98, 128
	s_addc_u32 s99, s99, 0
	s_add_u32 m0, s38, 16384
	v_mov_b32_e32 v60, 0
	v_mov_b32_e32 v61, 0
	global_load_lds_dwordx4 v212, s[100:101]
	s_add_u32 m0, s38, 20480
	v_mov_b32_e32 v62, 0
	v_mov_b32_e32 v63, 0
	global_load_lds_dwordx4 v213, s[100:101]
	s_add_u32 m0, s38, 24576
	v_mov_b32_e32 v20, 0
	v_mov_b32_e32 v21, 0
	global_load_lds_dwordx4 v214, s[100:101]
	s_add_u32 m0, s38, 28672
	v_mov_b32_e32 v22, 0
	v_mov_b32_e32 v23, 0
	global_load_lds_dwordx4 v215, s[100:101]
	s_add_u32 s100, s100, 128
	s_addc_u32 s101, s101, 0
	s_add_u32 m0, s38, 32768
	v_mov_b32_e32 v44, 0
	v_mov_b32_e32 v45, 0
	global_load_lds_dwordx4 v212, s[98:99]
	s_add_u32 m0, s38, 36864
	v_mov_b32_e32 v46, 0
	v_mov_b32_e32 v47, 0
	global_load_lds_dwordx4 v213, s[98:99]
	s_add_u32 m0, s38, 40960
	v_mov_b32_e32 v24, 0
	v_mov_b32_e32 v25, 0
	global_load_lds_dwordx4 v214, s[98:99]
	s_add_u32 m0, s38, 45056
	v_mov_b32_e32 v26, 0
	v_mov_b32_e32 v27, 0
	global_load_lds_dwordx4 v215, s[98:99]
	s_add_u32 s98, s98, 128
	s_addc_u32 s99, s99, 0
	s_add_u32 m0, s38, 49152
	v_mov_b32_e32 v56, 0
	v_mov_b32_e32 v57, 0
	global_load_lds_dwordx4 v212, s[100:101]
	s_add_u32 m0, s38, 53248
	v_mov_b32_e32 v58, 0
	v_mov_b32_e32 v59, 0
	global_load_lds_dwordx4 v213, s[100:101]
	s_add_u32 m0, s38, 57344
	v_mov_b32_e32 v12, 0
	v_mov_b32_e32 v13, 0
	global_load_lds_dwordx4 v214, s[100:101]
	s_add_u32 m0, s38, 61440
	v_mov_b32_e32 v14, 0
	v_mov_b32_e32 v15, 0
	global_load_lds_dwordx4 v215, s[100:101]
	s_add_u32 s100, s100, 128
	s_addc_u32 s101, s101, 0
	v_mov_b32_e32 v52, 0
	v_mov_b32_e32 v53, 0
	v_mov_b32_e32 v54, 0
	v_mov_b32_e32 v55, 0
	v_mov_b32_e32 v16, 0
	v_mov_b32_e32 v17, 0
	v_mov_b32_e32 v18, 0
	v_mov_b32_e32 v19, 0
	v_mov_b32_e32 v48, 0
	v_mov_b32_e32 v49, 0
	v_mov_b32_e32 v50, 0
	v_mov_b32_e32 v51, 0
	v_mov_b32_e32 v0, 0
	v_mov_b32_e32 v1, 0
	v_mov_b32_e32 v2, 0
	v_mov_b32_e32 v3, 0
	v_mov_b32_e32 v36, 0
	v_mov_b32_e32 v37, 0
	v_mov_b32_e32 v38, 0
	v_mov_b32_e32 v39, 0
	v_mov_b32_e32 v8, 0
	v_mov_b32_e32 v9, 0
	v_mov_b32_e32 v10, 0
	v_mov_b32_e32 v11, 0
	v_mov_b32_e32 v32, 0
	v_mov_b32_e32 v33, 0
	v_mov_b32_e32 v34, 0
	v_mov_b32_e32 v35, 0
	v_mov_b32_e32 v4, 0
	v_mov_b32_e32 v5, 0
	v_mov_b32_e32 v6, 0
	v_mov_b32_e32 v7, 0
	s_waitcnt vmcnt(8)
	s_barrier
	ds_read_b128 v[64:67], v208 offset:0
	ds_read_b128 v[68:71], v208 offset:2048
	ds_read_b128 v[160:163], v210 offset:16384
	ds_read_b128 v[164:167], v210 offset:18432
	ds_read_b128 v[168:171], v210 offset:20480
	ds_read_b128 v[172:175], v210 offset:22528
	ds_read_b128 v[176:179], v210 offset:24576
	ds_read_b128 v[180:183], v210 offset:26624
	ds_read_b128 v[184:187], v210 offset:28672
	s_waitcnt lgkmcnt(6)
	v_mfma_f32_16x16x32_bf16 v[40:43], v[64:67], v[160:163], v[40:43]
	v_mfma_f32_16x16x32_bf16 v[52:55], v[68:71], v[160:163], v[52:55]
	ds_read_b128 v[188:191], v210 offset:30720
	s_waitcnt lgkmcnt(6)
	v_mfma_f32_16x16x32_bf16 v[28:31], v[64:67], v[164:167], v[28:31]
	v_mfma_f32_16x16x32_bf16 v[16:19], v[68:71], v[164:167], v[16:19]
	ds_read_b128 v[72:75], v209 offset:0
	ds_read_b128 v[76:79], v209 offset:2048
	ds_read_b128 v[192:195], v211 offset:16384
	s_waitcnt lgkmcnt(8)
	v_mfma_f32_16x16x32_bf16 v[60:63], v[64:67], v[168:171], v[60:63]
	v_mfma_f32_16x16x32_bf16 v[48:51], v[68:71], v[168:171], v[48:51]
	ds_read_b128 v[196:199], v211 offset:18432
	s_waitcnt lgkmcnt(8)
	v_mfma_f32_16x16x32_bf16 v[20:23], v[64:67], v[172:175], v[20:23]
	v_mfma_f32_16x16x32_bf16 v[0:3], v[68:71], v[172:175], v[0:3]
	ds_read_b128 v[200:203], v211 offset:20480
	s_waitcnt lgkmcnt(8)
	v_mfma_f32_16x16x32_bf16 v[44:47], v[64:67], v[176:179], v[44:47]
	v_mfma_f32_16x16x32_bf16 v[36:39], v[68:71], v[176:179], v[36:39]
	ds_read_b128 v[204:207], v211 offset:22528
	s_waitcnt lgkmcnt(8)
	v_mfma_f32_16x16x32_bf16 v[24:27], v[64:67], v[180:183], v[24:27]
	v_mfma_f32_16x16x32_bf16 v[8:11], v[68:71], v[180:183], v[8:11]
	ds_read_b128 v[160:163], v211 offset:24576
	s_waitcnt lgkmcnt(8)
	v_mfma_f32_16x16x32_bf16 v[56:59], v[64:67], v[184:187], v[56:59]
	v_mfma_f32_16x16x32_bf16 v[32:35], v[68:71], v[184:187], v[32:35]
	ds_read_b128 v[164:167], v211 offset:26624
	s_waitcnt lgkmcnt(8)
	v_mfma_f32_16x16x32_bf16 v[12:15], v[64:67], v[188:191], v[12:15]
	v_mfma_f32_16x16x32_bf16 v[4:7], v[68:71], v[188:191], v[4:7]
	ds_read_b128 v[168:171], v211 offset:28672
	s_waitcnt lgkmcnt(6)
	v_mfma_f32_16x16x32_bf16 v[40:43], v[72:75], v[192:195], v[40:43]
	v_mfma_f32_16x16x32_bf16 v[52:55], v[76:79], v[192:195], v[52:55]
	ds_read_b128 v[172:175], v211 offset:30720
	s_waitcnt vmcnt(0) lgkmcnt(0)
	s_barrier
	s_add_u32 m0, s38, 0
	s_nop 0
	global_load_lds_dwordx4 v212, s[98:99]
	s_waitcnt lgkmcnt(6)
	v_mfma_f32_16x16x32_bf16 v[28:31], v[72:75], v[196:199], v[28:31]
	v_mfma_f32_16x16x32_bf16 v[16:19], v[76:79], v[196:199], v[16:19]
	ds_read_b128 v[64:67], v208 offset:32768
	ds_read_b128 v[68:71], v208 offset:34816
	ds_read_b128 v[176:179], v210 offset:49152
	s_add_u32 m0, s38, 4096
	s_nop 0
	global_load_lds_dwordx4 v213, s[98:99]
	s_waitcnt lgkmcnt(8)
	v_mfma_f32_16x16x32_bf16 v[60:63], v[72:75], v[200:203], v[60:63]
	v_mfma_f32_16x16x32_bf16 v[48:51], v[76:79], v[200:203], v[48:51]
	ds_read_b128 v[180:183], v210 offset:51200
	s_add_u32 m0, s38, 8192
	s_nop 0
	global_load_lds_dwordx4 v214, s[98:99]
	s_waitcnt lgkmcnt(8)
	v_mfma_f32_16x16x32_bf16 v[20:23], v[72:75], v[204:207], v[20:23]
	v_mfma_f32_16x16x32_bf16 v[0:3], v[76:79], v[204:207], v[0:3]
	ds_read_b128 v[184:187], v210 offset:53248
	s_add_u32 m0, s38, 12288
	s_nop 0
	global_load_lds_dwordx4 v215, s[98:99]
	s_add_u32 s98, s98, 128
	s_addc_u32 s99, s99, 0
	s_waitcnt lgkmcnt(8)
	v_mfma_f32_16x16x32_bf16 v[44:47], v[72:75], v[160:163], v[44:47]
	v_mfma_f32_16x16x32_bf16 v[36:39], v[76:79], v[160:163], v[36:39]
	ds_read_b128 v[188:191], v210 offset:55296
	s_add_u32 m0, s38, 16384
	s_nop 0
	global_load_lds_dwordx4 v212, s[100:101]
	s_waitcnt lgkmcnt(8)
	v_mfma_f32_16x16x32_bf16 v[24:27], v[72:75], v[164:167], v[24:27]
	v_mfma_f32_16x16x32_bf16 v[8:11], v[76:79], v[164:167], v[8:11]
	ds_read_b128 v[192:195], v210 offset:57344
	s_add_u32 m0, s38, 20480
	s_nop 0
	global_load_lds_dwordx4 v213, s[100:101]
	s_waitcnt lgkmcnt(8)
	v_mfma_f32_16x16x32_bf16 v[56:59], v[72:75], v[168:171], v[56:59]
	v_mfma_f32_16x16x32_bf16 v[32:35], v[76:79], v[168:171], v[32:35]
	ds_read_b128 v[196:199], v210 offset:59392
	s_add_u32 m0, s38, 24576
	s_nop 0
	global_load_lds_dwordx4 v214, s[100:101]
	s_waitcnt lgkmcnt(8)
	v_mfma_f32_16x16x32_bf16 v[12:15], v[72:75], v[172:175], v[12:15]
	v_mfma_f32_16x16x32_bf16 v[4:7], v[76:79], v[172:175], v[4:7]
	ds_read_b128 v[200:203], v210 offset:61440
	s_add_u32 m0, s38, 28672
	s_nop 0
	global_load_lds_dwordx4 v215, s[100:101]
	s_add_u32 s100, s100, 128
	s_addc_u32 s101, s101, 0
	s_waitcnt lgkmcnt(6)
	v_mfma_f32_16x16x32_bf16 v[40:43], v[64:67], v[176:179], v[40:43]
	v_mfma_f32_16x16x32_bf16 v[52:55], v[68:71], v[176:179], v[52:55]
	ds_read_b128 v[204:207], v210 offset:63488
	s_waitcnt lgkmcnt(6)
	v_mfma_f32_16x16x32_bf16 v[28:31], v[64:67], v[180:183], v[28:31]
	v_mfma_f32_16x16x32_bf16 v[16:19], v[68:71], v[180:183], v[16:19]
	ds_read_b128 v[72:75], v209 offset:32768
	ds_read_b128 v[76:79], v209 offset:34816
	ds_read_b128 v[160:163], v211 offset:49152
	s_waitcnt lgkmcnt(8)
	v_mfma_f32_16x16x32_bf16 v[60:63], v[64:67], v[184:187], v[60:63]
	v_mfma_f32_16x16x32_bf16 v[48:51], v[68:71], v[184:187], v[48:51]
	ds_read_b128 v[164:167], v211 offset:51200
	s_waitcnt lgkmcnt(8)
	v_mfma_f32_16x16x32_bf16 v[20:23], v[64:67], v[188:191], v[20:23]
	v_mfma_f32_16x16x32_bf16 v[0:3], v[68:71], v[188:191], v[0:3]
	ds_read_b128 v[168:171], v211 offset:53248
	s_waitcnt lgkmcnt(8)
	v_mfma_f32_16x16x32_bf16 v[44:47], v[64:67], v[192:195], v[44:47]
	v_mfma_f32_16x16x32_bf16 v[36:39], v[68:71], v[192:195], v[36:39]
	ds_read_b128 v[172:175], v211 offset:55296
	s_waitcnt lgkmcnt(8)
	v_mfma_f32_16x16x32_bf16 v[24:27], v[64:67], v[196:199], v[24:27]
	v_mfma_f32_16x16x32_bf16 v[8:11], v[68:71], v[196:199], v[8:11]
	ds_read_b128 v[176:179], v211 offset:57344
	s_waitcnt lgkmcnt(8)
	v_mfma_f32_16x16x32_bf16 v[56:59], v[64:67], v[200:203], v[56:59]
	v_mfma_f32_16x16x32_bf16 v[32:35], v[68:71], v[200:203], v[32:35]
	ds_read_b128 v[180:183], v211 offset:59392
	s_waitcnt lgkmcnt(8)
	v_mfma_f32_16x16x32_bf16 v[12:15], v[64:67], v[204:207], v[12:15]
	v_mfma_f32_16x16x32_bf16 v[4:7], v[68:71], v[204:207], v[4:7]
	ds_read_b128 v[184:187], v211 offset:61440
	s_waitcnt lgkmcnt(6)
	v_mfma_f32_16x16x32_bf16 v[40:43], v[72:75], v[160:163], v[40:43]
	v_mfma_f32_16x16x32_bf16 v[52:55], v[76:79], v[160:163], v[52:55]
	ds_read_b128 v[188:191], v211 offset:63488
	s_waitcnt vmcnt(0) lgkmcnt(0)
	s_barrier
	s_add_u32 m0, s38, 32768
	s_nop 0
	global_load_lds_dwordx4 v212, s[98:99]
	s_waitcnt lgkmcnt(6)
	v_mfma_f32_16x16x32_bf16 v[28:31], v[72:75], v[164:167], v[28:31]
	v_mfma_f32_16x16x32_bf16 v[16:19], v[76:79], v[164:167], v[16:19]
	ds_read_b128 v[64:67], v208 offset:0
	ds_read_b128 v[68:71], v208 offset:2048
	ds_read_b128 v[192:195], v210 offset:16384
	s_add_u32 m0, s38, 36864
	s_nop 0
	global_load_lds_dwordx4 v213, s[98:99]
	s_waitcnt lgkmcnt(8)
	v_mfma_f32_16x16x32_bf16 v[60:63], v[72:75], v[168:171], v[60:63]
	v_mfma_f32_16x16x32_bf16 v[48:51], v[76:79], v[168:171], v[48:51]
	ds_read_b128 v[196:199], v210 offset:18432
	s_add_u32 m0, s38, 40960
	s_nop 0
	global_load_lds_dwordx4 v214, s[98:99]
	s_waitcnt lgkmcnt(8)
	v_mfma_f32_16x16x32_bf16 v[20:23], v[72:75], v[172:175], v[20:23]
	v_mfma_f32_16x16x32_bf16 v[0:3], v[76:79], v[172:175], v[0:3]
	ds_read_b128 v[200:203], v210 offset:20480
	s_add_u32 m0, s38, 45056
	s_nop 0
	global_load_lds_dwordx4 v215, s[98:99]
	s_add_u32 s98, s98, 128
	s_addc_u32 s99, s99, 0
	s_waitcnt lgkmcnt(8)
	v_mfma_f32_16x16x32_bf16 v[44:47], v[72:75], v[176:179], v[44:47]
	v_mfma_f32_16x16x32_bf16 v[36:39], v[76:79], v[176:179], v[36:39]
	ds_read_b128 v[204:207], v210 offset:22528
	s_add_u32 m0, s38, 49152
	s_nop 0
	global_load_lds_dwordx4 v212, s[100:101]
	s_waitcnt lgkmcnt(8)
	v_mfma_f32_16x16x32_bf16 v[24:27], v[72:75], v[180:183], v[24:27]
	v_mfma_f32_16x16x32_bf16 v[8:11], v[76:79], v[180:183], v[8:11]
	ds_read_b128 v[160:163], v210 offset:24576
	s_add_u32 m0, s38, 53248
	s_nop 0
	global_load_lds_dwordx4 v213, s[100:101]
	s_waitcnt lgkmcnt(8)
	v_mfma_f32_16x16x32_bf16 v[56:59], v[72:75], v[184:187], v[56:59]
	v_mfma_f32_16x16x32_bf16 v[32:35], v[76:79], v[184:187], v[32:35]
	ds_read_b128 v[164:167], v210 offset:26624
	s_add_u32 m0, s38, 57344
	s_nop 0
	global_load_lds_dwordx4 v214, s[100:101]
	s_waitcnt lgkmcnt(8)
	v_mfma_f32_16x16x32_bf16 v[12:15], v[72:75], v[188:191], v[12:15]
	v_mfma_f32_16x16x32_bf16 v[4:7], v[76:79], v[188:191], v[4:7]
	ds_read_b128 v[168:171], v210 offset:28672
	s_add_u32 m0, s38, 61440
	s_nop 0
	global_load_lds_dwordx4 v215, s[100:101]
	s_add_u32 s100, s100, 128
	s_addc_u32 s101, s101, 0
	s_waitcnt lgkmcnt(6)
	v_mfma_f32_16x16x32_bf16 v[40:43], v[64:67], v[192:195], v[40:43]
	v_mfma_f32_16x16x32_bf16 v[52:55], v[68:71], v[192:195], v[52:55]
	ds_read_b128 v[172:175], v210 offset:30720
	s_waitcnt lgkmcnt(6)
	v_mfma_f32_16x16x32_bf16 v[28:31], v[64:67], v[196:199], v[28:31]
	v_mfma_f32_16x16x32_bf16 v[16:19], v[68:71], v[196:199], v[16:19]
	ds_read_b128 v[72:75], v209 offset:0
	ds_read_b128 v[76:79], v209 offset:2048
	ds_read_b128 v[176:179], v211 offset:16384
	s_waitcnt lgkmcnt(8)
	v_mfma_f32_16x16x32_bf16 v[60:63], v[64:67], v[200:203], v[60:63]
	v_mfma_f32_16x16x32_bf16 v[48:51], v[68:71], v[200:203], v[48:51]
	ds_read_b128 v[180:183], v211 offset:18432
	s_waitcnt lgkmcnt(8)
	v_mfma_f32_16x16x32_bf16 v[20:23], v[64:67], v[204:207], v[20:23]
	v_mfma_f32_16x16x32_bf16 v[0:3], v[68:71], v[204:207], v[0:3]
	ds_read_b128 v[184:187], v211 offset:20480
	s_waitcnt lgkmcnt(8)
	v_mfma_f32_16x16x32_bf16 v[44:47], v[64:67], v[160:163], v[44:47]
	v_mfma_f32_16x16x32_bf16 v[36:39], v[68:71], v[160:163], v[36:39]
	ds_read_b128 v[188:191], v211 offset:22528
	s_waitcnt lgkmcnt(8)
	v_mfma_f32_16x16x32_bf16 v[24:27], v[64:67], v[164:167], v[24:27]
	v_mfma_f32_16x16x32_bf16 v[8:11], v[68:71], v[164:167], v[8:11]
	ds_read_b128 v[192:195], v211 offset:24576
	s_waitcnt lgkmcnt(8)
	v_mfma_f32_16x16x32_bf16 v[56:59], v[64:67], v[168:171], v[56:59]
	v_mfma_f32_16x16x32_bf16 v[32:35], v[68:71], v[168:171], v[32:35]
	ds_read_b128 v[196:199], v211 offset:26624
	s_waitcnt lgkmcnt(8)
	v_mfma_f32_16x16x32_bf16 v[12:15], v[64:67], v[172:175], v[12:15]
	v_mfma_f32_16x16x32_bf16 v[4:7], v[68:71], v[172:175], v[4:7]
	ds_read_b128 v[200:203], v211 offset:28672
	s_waitcnt lgkmcnt(6)
	v_mfma_f32_16x16x32_bf16 v[40:43], v[72:75], v[176:179], v[40:43]
	v_mfma_f32_16x16x32_bf16 v[52:55], v[76:79], v[176:179], v[52:55]
	ds_read_b128 v[204:207], v211 offset:30720
	s_waitcnt vmcnt(0) lgkmcnt(0)
	s_barrier
	s_add_u32 m0, s38, 0
	s_nop 0
	global_load_lds_dwordx4 v212, s[98:99]
	s_waitcnt lgkmcnt(6)
	v_mfma_f32_16x16x32_bf16 v[28:31], v[72:75], v[180:183], v[28:31]
	v_mfma_f32_16x16x32_bf16 v[16:19], v[76:79], v[180:183], v[16:19]
	ds_read_b128 v[64:67], v208 offset:32768
	ds_read_b128 v[68:71], v208 offset:34816
	ds_read_b128 v[160:163], v210 offset:49152
	s_add_u32 m0, s38, 4096
	s_nop 0
	global_load_lds_dwordx4 v213, s[98:99]
	s_waitcnt lgkmcnt(8)
	v_mfma_f32_16x16x32_bf16 v[60:63], v[72:75], v[184:187], v[60:63]
	v_mfma_f32_16x16x32_bf16 v[48:51], v[76:79], v[184:187], v[48:51]
	ds_read_b128 v[164:167], v210 offset:51200
	s_add_u32 m0, s38, 8192
	s_nop 0
	global_load_lds_dwordx4 v214, s[98:99]
	s_waitcnt lgkmcnt(8)
	v_mfma_f32_16x16x32_bf16 v[20:23], v[72:75], v[188:191], v[20:23]
	v_mfma_f32_16x16x32_bf16 v[0:3], v[76:79], v[188:191], v[0:3]
	ds_read_b128 v[168:171], v210 offset:53248
	s_add_u32 m0, s38, 12288
	s_nop 0
	global_load_lds_dwordx4 v215, s[98:99]
	s_add_u32 s98, s98, 128
	s_addc_u32 s99, s99, 0
	s_waitcnt lgkmcnt(8)
	v_mfma_f32_16x16x32_bf16 v[44:47], v[72:75], v[192:195], v[44:47]
	v_mfma_f32_16x16x32_bf16 v[36:39], v[76:79], v[192:195], v[36:39]
	ds_read_b128 v[172:175], v210 offset:55296
	s_add_u32 m0, s38, 16384
	s_nop 0
	global_load_lds_dwordx4 v212, s[100:101]
	s_waitcnt lgkmcnt(8)
	v_mfma_f32_16x16x32_bf16 v[24:27], v[72:75], v[196:199], v[24:27]
	v_mfma_f32_16x16x32_bf16 v[8:11], v[76:79], v[196:199], v[8:11]
	ds_read_b128 v[176:179], v210 offset:57344
	s_add_u32 m0, s38, 20480
	s_nop 0
	global_load_lds_dwordx4 v213, s[100:101]
	s_waitcnt lgkmcnt(8)
	v_mfma_f32_16x16x32_bf16 v[56:59], v[72:75], v[200:203], v[56:59]
	v_mfma_f32_16x16x32_bf16 v[32:35], v[76:79], v[200:203], v[32:35]
	ds_read_b128 v[180:183], v210 offset:59392
	s_add_u32 m0, s38, 24576
	s_nop 0
	global_load_lds_dwordx4 v214, s[100:101]
	s_waitcnt lgkmcnt(8)
	v_mfma_f32_16x16x32_bf16 v[12:15], v[72:75], v[204:207], v[12:15]
	v_mfma_f32_16x16x32_bf16 v[4:7], v[76:79], v[204:207], v[4:7]
	ds_read_b128 v[184:187], v210 offset:61440
	s_add_u32 m0, s38, 28672
	s_nop 0
	global_load_lds_dwordx4 v215, s[100:101]
	s_add_u32 s100, s100, 128
	s_addc_u32 s101, s101, 0
	s_waitcnt lgkmcnt(6)
	v_mfma_f32_16x16x32_bf16 v[40:43], v[64:67], v[160:163], v[40:43]
	v_mfma_f32_16x16x32_bf16 v[52:55], v[68:71], v[160:163], v[52:55]
	ds_read_b128 v[188:191], v210 offset:63488
	s_waitcnt lgkmcnt(6)
	v_mfma_f32_16x16x32_bf16 v[28:31], v[64:67], v[164:167], v[28:31]
	v_mfma_f32_16x16x32_bf16 v[16:19], v[68:71], v[164:167], v[16:19]
	ds_read_b128 v[72:75], v209 offset:32768
	ds_read_b128 v[76:79], v209 offset:34816
	ds_read_b128 v[192:195], v211 offset:49152
	s_waitcnt lgkmcnt(8)
	v_mfma_f32_16x16x32_bf16 v[60:63], v[64:67], v[168:171], v[60:63]
	v_mfma_f32_16x16x32_bf16 v[48:51], v[68:71], v[168:171], v[48:51]
	ds_read_b128 v[196:199], v211 offset:51200
	s_waitcnt lgkmcnt(8)
	v_mfma_f32_16x16x32_bf16 v[20:23], v[64:67], v[172:175], v[20:23]
	v_mfma_f32_16x16x32_bf16 v[0:3], v[68:71], v[172:175], v[0:3]
	ds_read_b128 v[200:203], v211 offset:53248
	s_waitcnt lgkmcnt(8)
	v_mfma_f32_16x16x32_bf16 v[44:47], v[64:67], v[176:179], v[44:47]
	v_mfma_f32_16x16x32_bf16 v[36:39], v[68:71], v[176:179], v[36:39]
	ds_read_b128 v[204:207], v211 offset:55296
	s_waitcnt lgkmcnt(8)
	v_mfma_f32_16x16x32_bf16 v[24:27], v[64:67], v[180:183], v[24:27]
	v_mfma_f32_16x16x32_bf16 v[8:11], v[68:71], v[180:183], v[8:11]
	ds_read_b128 v[160:163], v211 offset:57344
	s_waitcnt lgkmcnt(8)
	v_mfma_f32_16x16x32_bf16 v[56:59], v[64:67], v[184:187], v[56:59]
	v_mfma_f32_16x16x32_bf16 v[32:35], v[68:71], v[184:187], v[32:35]
	ds_read_b128 v[164:167], v211 offset:59392
	s_waitcnt lgkmcnt(8)
	v_mfma_f32_16x16x32_bf16 v[12:15], v[64:67], v[188:191], v[12:15]
	v_mfma_f32_16x16x32_bf16 v[4:7], v[68:71], v[188:191], v[4:7]
	ds_read_b128 v[168:171], v211 offset:61440
	s_waitcnt lgkmcnt(6)
	v_mfma_f32_16x16x32_bf16 v[40:43], v[72:75], v[192:195], v[40:43]
	v_mfma_f32_16x16x32_bf16 v[52:55], v[76:79], v[192:195], v[52:55]
	ds_read_b128 v[172:175], v211 offset:63488
	s_waitcnt vmcnt(0) lgkmcnt(0)
	s_barrier
	s_add_u32 m0, s38, 32768
	s_nop 0
	global_load_lds_dwordx4 v212, s[98:99]
	s_waitcnt lgkmcnt(6)
	v_mfma_f32_16x16x32_bf16 v[28:31], v[72:75], v[196:199], v[28:31]
	v_mfma_f32_16x16x32_bf16 v[16:19], v[76:79], v[196:199], v[16:19]
	ds_read_b128 v[64:67], v208 offset:0
	ds_read_b128 v[68:71], v208 offset:2048
	ds_read_b128 v[176:179], v210 offset:16384
	s_add_u32 m0, s38, 36864
	s_nop 0
	global_load_lds_dwordx4 v213, s[98:99]
	s_waitcnt lgkmcnt(8)
	v_mfma_f32_16x16x32_bf16 v[60:63], v[72:75], v[200:203], v[60:63]
	v_mfma_f32_16x16x32_bf16 v[48:51], v[76:79], v[200:203], v[48:51]
	ds_read_b128 v[180:183], v210 offset:18432
	s_add_u32 m0, s38, 40960
	s_nop 0
	global_load_lds_dwordx4 v214, s[98:99]
	s_waitcnt lgkmcnt(8)
	v_mfma_f32_16x16x32_bf16 v[20:23], v[72:75], v[204:207], v[20:23]
	v_mfma_f32_16x16x32_bf16 v[0:3], v[76:79], v[204:207], v[0:3]
	ds_read_b128 v[184:187], v210 offset:20480
	s_add_u32 m0, s38, 45056
	s_nop 0
	global_load_lds_dwordx4 v215, s[98:99]
	s_add_u32 s98, s98, 128
	s_addc_u32 s99, s99, 0
	s_waitcnt lgkmcnt(8)
	v_mfma_f32_16x16x32_bf16 v[44:47], v[72:75], v[160:163], v[44:47]
	v_mfma_f32_16x16x32_bf16 v[36:39], v[76:79], v[160:163], v[36:39]
	ds_read_b128 v[188:191], v210 offset:22528
	s_add_u32 m0, s38, 49152
	s_nop 0
	global_load_lds_dwordx4 v212, s[100:101]
	s_waitcnt lgkmcnt(8)
	v_mfma_f32_16x16x32_bf16 v[24:27], v[72:75], v[164:167], v[24:27]
	v_mfma_f32_16x16x32_bf16 v[8:11], v[76:79], v[164:167], v[8:11]
	ds_read_b128 v[192:195], v210 offset:24576
	s_add_u32 m0, s38, 53248
	s_nop 0
	global_load_lds_dwordx4 v213, s[100:101]
	s_waitcnt lgkmcnt(8)
	v_mfma_f32_16x16x32_bf16 v[56:59], v[72:75], v[168:171], v[56:59]
	v_mfma_f32_16x16x32_bf16 v[32:35], v[76:79], v[168:171], v[32:35]
	ds_read_b128 v[196:199], v210 offset:26624
	s_add_u32 m0, s38, 57344
	s_nop 0
	global_load_lds_dwordx4 v214, s[100:101]
	s_waitcnt lgkmcnt(8)
	v_mfma_f32_16x16x32_bf16 v[12:15], v[72:75], v[172:175], v[12:15]
	v_mfma_f32_16x16x32_bf16 v[4:7], v[76:79], v[172:175], v[4:7]
	ds_read_b128 v[200:203], v210 offset:28672
	s_add_u32 m0, s38, 61440
	s_nop 0
	global_load_lds_dwordx4 v215, s[100:101]
	s_add_u32 s100, s100, 128
	s_addc_u32 s101, s101, 0
	s_waitcnt lgkmcnt(6)
	v_mfma_f32_16x16x32_bf16 v[40:43], v[64:67], v[176:179], v[40:43]
	v_mfma_f32_16x16x32_bf16 v[52:55], v[68:71], v[176:179], v[52:55]
	ds_read_b128 v[204:207], v210 offset:30720
	s_waitcnt lgkmcnt(6)
	v_mfma_f32_16x16x32_bf16 v[28:31], v[64:67], v[180:183], v[28:31]
	v_mfma_f32_16x16x32_bf16 v[16:19], v[68:71], v[180:183], v[16:19]
	ds_read_b128 v[72:75], v209 offset:0
	ds_read_b128 v[76:79], v209 offset:2048
	ds_read_b128 v[160:163], v211 offset:16384
	s_waitcnt lgkmcnt(8)
	v_mfma_f32_16x16x32_bf16 v[60:63], v[64:67], v[184:187], v[60:63]
	v_mfma_f32_16x16x32_bf16 v[48:51], v[68:71], v[184:187], v[48:51]
	ds_read_b128 v[164:167], v211 offset:18432
	s_waitcnt lgkmcnt(8)
	v_mfma_f32_16x16x32_bf16 v[20:23], v[64:67], v[188:191], v[20:23]
	v_mfma_f32_16x16x32_bf16 v[0:3], v[68:71], v[188:191], v[0:3]
	ds_read_b128 v[168:171], v211 offset:20480
	s_waitcnt lgkmcnt(8)
	v_mfma_f32_16x16x32_bf16 v[44:47], v[64:67], v[192:195], v[44:47]
	v_mfma_f32_16x16x32_bf16 v[36:39], v[68:71], v[192:195], v[36:39]
	ds_read_b128 v[172:175], v211 offset:22528
	s_waitcnt lgkmcnt(8)
	v_mfma_f32_16x16x32_bf16 v[24:27], v[64:67], v[196:199], v[24:27]
	v_mfma_f32_16x16x32_bf16 v[8:11], v[68:71], v[196:199], v[8:11]
	ds_read_b128 v[176:179], v211 offset:24576
	s_waitcnt lgkmcnt(8)
	v_mfma_f32_16x16x32_bf16 v[56:59], v[64:67], v[200:203], v[56:59]
	v_mfma_f32_16x16x32_bf16 v[32:35], v[68:71], v[200:203], v[32:35]
	ds_read_b128 v[180:183], v211 offset:26624
	s_waitcnt lgkmcnt(8)
	v_mfma_f32_16x16x32_bf16 v[12:15], v[64:67], v[204:207], v[12:15]
	v_mfma_f32_16x16x32_bf16 v[4:7], v[68:71], v[204:207], v[4:7]
	ds_read_b128 v[184:187], v211 offset:28672
	s_waitcnt lgkmcnt(6)
	v_mfma_f32_16x16x32_bf16 v[40:43], v[72:75], v[160:163], v[40:43]
	v_mfma_f32_16x16x32_bf16 v[52:55], v[76:79], v[160:163], v[52:55]
	ds_read_b128 v[188:191], v211 offset:30720
	s_waitcnt vmcnt(0) lgkmcnt(0)
	s_barrier
	s_add_u32 m0, s38, 0
	s_nop 0
	global_load_lds_dwordx4 v212, s[98:99]
	s_waitcnt lgkmcnt(6)
	v_mfma_f32_16x16x32_bf16 v[28:31], v[72:75], v[164:167], v[28:31]
	v_mfma_f32_16x16x32_bf16 v[16:19], v[76:79], v[164:167], v[16:19]
	ds_read_b128 v[64:67], v208 offset:32768
	ds_read_b128 v[68:71], v208 offset:34816
	ds_read_b128 v[192:195], v210 offset:49152
	s_add_u32 m0, s38, 4096
	s_nop 0
	global_load_lds_dwordx4 v213, s[98:99]
	s_waitcnt lgkmcnt(8)
	v_mfma_f32_16x16x32_bf16 v[60:63], v[72:75], v[168:171], v[60:63]
	v_mfma_f32_16x16x32_bf16 v[48:51], v[76:79], v[168:171], v[48:51]
	ds_read_b128 v[196:199], v210 offset:51200
	s_add_u32 m0, s38, 8192
	s_nop 0
	global_load_lds_dwordx4 v214, s[98:99]
	s_waitcnt lgkmcnt(8)
	v_mfma_f32_16x16x32_bf16 v[20:23], v[72:75], v[172:175], v[20:23]
	v_mfma_f32_16x16x32_bf16 v[0:3], v[76:79], v[172:175], v[0:3]
	ds_read_b128 v[200:203], v210 offset:53248
	s_add_u32 m0, s38, 12288
	s_nop 0
	global_load_lds_dwordx4 v215, s[98:99]
	s_add_u32 s98, s98, 128
	s_addc_u32 s99, s99, 0
	s_waitcnt lgkmcnt(8)
	v_mfma_f32_16x16x32_bf16 v[44:47], v[72:75], v[176:179], v[44:47]
	v_mfma_f32_16x16x32_bf16 v[36:39], v[76:79], v[176:179], v[36:39]
	ds_read_b128 v[204:207], v210 offset:55296
	s_add_u32 m0, s38, 16384
	s_nop 0
	global_load_lds_dwordx4 v212, s[100:101]
	s_waitcnt lgkmcnt(8)
	v_mfma_f32_16x16x32_bf16 v[24:27], v[72:75], v[180:183], v[24:27]
	v_mfma_f32_16x16x32_bf16 v[8:11], v[76:79], v[180:183], v[8:11]
	ds_read_b128 v[160:163], v210 offset:57344
	s_add_u32 m0, s38, 20480
	s_nop 0
	global_load_lds_dwordx4 v213, s[100:101]
	s_waitcnt lgkmcnt(8)
	v_mfma_f32_16x16x32_bf16 v[56:59], v[72:75], v[184:187], v[56:59]
	v_mfma_f32_16x16x32_bf16 v[32:35], v[76:79], v[184:187], v[32:35]
	ds_read_b128 v[164:167], v210 offset:59392
	s_add_u32 m0, s38, 24576
	s_nop 0
	global_load_lds_dwordx4 v214, s[100:101]
	s_waitcnt lgkmcnt(8)
	v_mfma_f32_16x16x32_bf16 v[12:15], v[72:75], v[188:191], v[12:15]
	v_mfma_f32_16x16x32_bf16 v[4:7], v[76:79], v[188:191], v[4:7]
	ds_read_b128 v[168:171], v210 offset:61440
	s_add_u32 m0, s38, 28672
	s_nop 0
	global_load_lds_dwordx4 v215, s[100:101]
	s_add_u32 s100, s100, 128
	s_addc_u32 s101, s101, 0
	s_waitcnt lgkmcnt(6)
	v_mfma_f32_16x16x32_bf16 v[40:43], v[64:67], v[192:195], v[40:43]
	v_mfma_f32_16x16x32_bf16 v[52:55], v[68:71], v[192:195], v[52:55]
	ds_read_b128 v[172:175], v210 offset:63488
	s_waitcnt lgkmcnt(6)
	v_mfma_f32_16x16x32_bf16 v[28:31], v[64:67], v[196:199], v[28:31]
	v_mfma_f32_16x16x32_bf16 v[16:19], v[68:71], v[196:199], v[16:19]
	ds_read_b128 v[72:75], v209 offset:32768
	ds_read_b128 v[76:79], v209 offset:34816
	ds_read_b128 v[176:179], v211 offset:49152
	s_waitcnt lgkmcnt(8)
	v_mfma_f32_16x16x32_bf16 v[60:63], v[64:67], v[200:203], v[60:63]
	v_mfma_f32_16x16x32_bf16 v[48:51], v[68:71], v[200:203], v[48:51]
	ds_read_b128 v[180:183], v211 offset:51200
	s_waitcnt lgkmcnt(8)
	v_mfma_f32_16x16x32_bf16 v[20:23], v[64:67], v[204:207], v[20:23]
	v_mfma_f32_16x16x32_bf16 v[0:3], v[68:71], v[204:207], v[0:3]
	ds_read_b128 v[184:187], v211 offset:53248
	s_waitcnt lgkmcnt(8)
	v_mfma_f32_16x16x32_bf16 v[44:47], v[64:67], v[160:163], v[44:47]
	v_mfma_f32_16x16x32_bf16 v[36:39], v[68:71], v[160:163], v[36:39]
	ds_read_b128 v[188:191], v211 offset:55296
	s_waitcnt lgkmcnt(8)
	v_mfma_f32_16x16x32_bf16 v[24:27], v[64:67], v[164:167], v[24:27]
	v_mfma_f32_16x16x32_bf16 v[8:11], v[68:71], v[164:167], v[8:11]
	ds_read_b128 v[192:195], v211 offset:57344
	s_waitcnt lgkmcnt(8)
	v_mfma_f32_16x16x32_bf16 v[56:59], v[64:67], v[168:171], v[56:59]
	v_mfma_f32_16x16x32_bf16 v[32:35], v[68:71], v[168:171], v[32:35]
	ds_read_b128 v[196:199], v211 offset:59392
	s_waitcnt lgkmcnt(8)
	v_mfma_f32_16x16x32_bf16 v[12:15], v[64:67], v[172:175], v[12:15]
	v_mfma_f32_16x16x32_bf16 v[4:7], v[68:71], v[172:175], v[4:7]
	ds_read_b128 v[200:203], v211 offset:61440
	s_waitcnt lgkmcnt(6)
	v_mfma_f32_16x16x32_bf16 v[40:43], v[72:75], v[176:179], v[40:43]
	v_mfma_f32_16x16x32_bf16 v[52:55], v[76:79], v[176:179], v[52:55]
	ds_read_b128 v[204:207], v211 offset:63488
	s_waitcnt vmcnt(0) lgkmcnt(0)
	s_barrier
	s_add_u32 m0, s38, 32768
	s_nop 0
	global_load_lds_dwordx4 v212, s[98:99]
	s_waitcnt lgkmcnt(6)
	v_mfma_f32_16x16x32_bf16 v[28:31], v[72:75], v[180:183], v[28:31]
	v_mfma_f32_16x16x32_bf16 v[16:19], v[76:79], v[180:183], v[16:19]
	ds_read_b128 v[64:67], v208 offset:0
	ds_read_b128 v[68:71], v208 offset:2048
	ds_read_b128 v[160:163], v210 offset:16384
	s_add_u32 m0, s38, 36864
	s_nop 0
	global_load_lds_dwordx4 v213, s[98:99]
	s_waitcnt lgkmcnt(8)
	v_mfma_f32_16x16x32_bf16 v[60:63], v[72:75], v[184:187], v[60:63]
	v_mfma_f32_16x16x32_bf16 v[48:51], v[76:79], v[184:187], v[48:51]
	ds_read_b128 v[164:167], v210 offset:18432
	s_add_u32 m0, s38, 40960
	s_nop 0
	global_load_lds_dwordx4 v214, s[98:99]
	s_waitcnt lgkmcnt(8)
	v_mfma_f32_16x16x32_bf16 v[20:23], v[72:75], v[188:191], v[20:23]
	v_mfma_f32_16x16x32_bf16 v[0:3], v[76:79], v[188:191], v[0:3]
	ds_read_b128 v[168:171], v210 offset:20480
	s_add_u32 m0, s38, 45056
	s_nop 0
	global_load_lds_dwordx4 v215, s[98:99]
	s_add_u32 s98, s98, 128
	s_addc_u32 s99, s99, 0
	s_waitcnt lgkmcnt(8)
	v_mfma_f32_16x16x32_bf16 v[44:47], v[72:75], v[192:195], v[44:47]
	v_mfma_f32_16x16x32_bf16 v[36:39], v[76:79], v[192:195], v[36:39]
	ds_read_b128 v[172:175], v210 offset:22528
	s_add_u32 m0, s38, 49152
	s_nop 0
	global_load_lds_dwordx4 v212, s[100:101]
	s_waitcnt lgkmcnt(8)
	v_mfma_f32_16x16x32_bf16 v[24:27], v[72:75], v[196:199], v[24:27]
	v_mfma_f32_16x16x32_bf16 v[8:11], v[76:79], v[196:199], v[8:11]
	ds_read_b128 v[176:179], v210 offset:24576
	s_add_u32 m0, s38, 53248
	s_nop 0
	global_load_lds_dwordx4 v213, s[100:101]
	s_waitcnt lgkmcnt(8)
	v_mfma_f32_16x16x32_bf16 v[56:59], v[72:75], v[200:203], v[56:59]
	v_mfma_f32_16x16x32_bf16 v[32:35], v[76:79], v[200:203], v[32:35]
	ds_read_b128 v[180:183], v210 offset:26624
	s_add_u32 m0, s38, 57344
	s_nop 0
	global_load_lds_dwordx4 v214, s[100:101]
	s_waitcnt lgkmcnt(8)
	v_mfma_f32_16x16x32_bf16 v[12:15], v[72:75], v[204:207], v[12:15]
	v_mfma_f32_16x16x32_bf16 v[4:7], v[76:79], v[204:207], v[4:7]
	ds_read_b128 v[184:187], v210 offset:28672
	s_add_u32 m0, s38, 61440
	s_nop 0
	global_load_lds_dwordx4 v215, s[100:101]
	s_add_u32 s100, s100, 128
	s_addc_u32 s101, s101, 0
	s_waitcnt lgkmcnt(6)
	v_mfma_f32_16x16x32_bf16 v[40:43], v[64:67], v[160:163], v[40:43]
	v_mfma_f32_16x16x32_bf16 v[52:55], v[68:71], v[160:163], v[52:55]
	ds_read_b128 v[188:191], v210 offset:30720
	s_waitcnt lgkmcnt(6)
	v_mfma_f32_16x16x32_bf16 v[28:31], v[64:67], v[164:167], v[28:31]
	v_mfma_f32_16x16x32_bf16 v[16:19], v[68:71], v[164:167], v[16:19]
	ds_read_b128 v[72:75], v209 offset:0
	ds_read_b128 v[76:79], v209 offset:2048
	ds_read_b128 v[192:195], v211 offset:16384
	s_waitcnt lgkmcnt(8)
	v_mfma_f32_16x16x32_bf16 v[60:63], v[64:67], v[168:171], v[60:63]
	v_mfma_f32_16x16x32_bf16 v[48:51], v[68:71], v[168:171], v[48:51]
	ds_read_b128 v[196:199], v211 offset:18432
	s_waitcnt lgkmcnt(8)
	v_mfma_f32_16x16x32_bf16 v[20:23], v[64:67], v[172:175], v[20:23]
	v_mfma_f32_16x16x32_bf16 v[0:3], v[68:71], v[172:175], v[0:3]
	ds_read_b128 v[200:203], v211 offset:20480
	s_waitcnt lgkmcnt(8)
	v_mfma_f32_16x16x32_bf16 v[44:47], v[64:67], v[176:179], v[44:47]
	v_mfma_f32_16x16x32_bf16 v[36:39], v[68:71], v[176:179], v[36:39]
	ds_read_b128 v[204:207], v211 offset:22528
	s_waitcnt lgkmcnt(8)
	v_mfma_f32_16x16x32_bf16 v[24:27], v[64:67], v[180:183], v[24:27]
	v_mfma_f32_16x16x32_bf16 v[8:11], v[68:71], v[180:183], v[8:11]
	ds_read_b128 v[160:163], v211 offset:24576
	s_waitcnt lgkmcnt(8)
	v_mfma_f32_16x16x32_bf16 v[56:59], v[64:67], v[184:187], v[56:59]
	v_mfma_f32_16x16x32_bf16 v[32:35], v[68:71], v[184:187], v[32:35]
	ds_read_b128 v[164:167], v211 offset:26624
	s_waitcnt lgkmcnt(8)
	v_mfma_f32_16x16x32_bf16 v[12:15], v[64:67], v[188:191], v[12:15]
	v_mfma_f32_16x16x32_bf16 v[4:7], v[68:71], v[188:191], v[4:7]
	ds_read_b128 v[168:171], v211 offset:28672
	s_waitcnt lgkmcnt(6)
	v_mfma_f32_16x16x32_bf16 v[40:43], v[72:75], v[192:195], v[40:43]
	v_mfma_f32_16x16x32_bf16 v[52:55], v[76:79], v[192:195], v[52:55]
	ds_read_b128 v[172:175], v211 offset:30720
	s_waitcnt vmcnt(0) lgkmcnt(0)
	s_barrier
	s_add_u32 m0, s38, 0
	s_nop 0
	global_load_lds_dwordx4 v212, s[98:99]
	s_waitcnt lgkmcnt(6)
	v_mfma_f32_16x16x32_bf16 v[28:31], v[72:75], v[196:199], v[28:31]
	v_mfma_f32_16x16x32_bf16 v[16:19], v[76:79], v[196:199], v[16:19]
	ds_read_b128 v[64:67], v208 offset:32768
	ds_read_b128 v[68:71], v208 offset:34816
	ds_read_b128 v[176:179], v210 offset:49152
	s_add_u32 m0, s38, 4096
	s_nop 0
	global_load_lds_dwordx4 v213, s[98:99]
	s_waitcnt lgkmcnt(8)
	v_mfma_f32_16x16x32_bf16 v[60:63], v[72:75], v[200:203], v[60:63]
	v_mfma_f32_16x16x32_bf16 v[48:51], v[76:79], v[200:203], v[48:51]
	ds_read_b128 v[180:183], v210 offset:51200
	s_add_u32 m0, s38, 8192
	s_nop 0
	global_load_lds_dwordx4 v214, s[98:99]
	s_waitcnt lgkmcnt(8)
	v_mfma_f32_16x16x32_bf16 v[20:23], v[72:75], v[204:207], v[20:23]
	v_mfma_f32_16x16x32_bf16 v[0:3], v[76:79], v[204:207], v[0:3]
	ds_read_b128 v[184:187], v210 offset:53248
	s_add_u32 m0, s38, 12288
	s_nop 0
	global_load_lds_dwordx4 v215, s[98:99]
	s_add_u32 s98, s98, 128
	s_addc_u32 s99, s99, 0
	s_waitcnt lgkmcnt(8)
	v_mfma_f32_16x16x32_bf16 v[44:47], v[72:75], v[160:163], v[44:47]
	v_mfma_f32_16x16x32_bf16 v[36:39], v[76:79], v[160:163], v[36:39]
	ds_read_b128 v[188:191], v210 offset:55296
	s_add_u32 m0, s38, 16384
	s_nop 0
	global_load_lds_dwordx4 v212, s[100:101]
	s_waitcnt lgkmcnt(8)
	v_mfma_f32_16x16x32_bf16 v[24:27], v[72:75], v[164:167], v[24:27]
	v_mfma_f32_16x16x32_bf16 v[8:11], v[76:79], v[164:167], v[8:11]
	ds_read_b128 v[192:195], v210 offset:57344
	s_add_u32 m0, s38, 20480
	s_nop 0
	global_load_lds_dwordx4 v213, s[100:101]
	s_waitcnt lgkmcnt(8)
	v_mfma_f32_16x16x32_bf16 v[56:59], v[72:75], v[168:171], v[56:59]
	v_mfma_f32_16x16x32_bf16 v[32:35], v[76:79], v[168:171], v[32:35]
	ds_read_b128 v[196:199], v210 offset:59392
	s_add_u32 m0, s38, 24576
	s_nop 0
	global_load_lds_dwordx4 v214, s[100:101]
	s_waitcnt lgkmcnt(8)
	v_mfma_f32_16x16x32_bf16 v[12:15], v[72:75], v[172:175], v[12:15]
	v_mfma_f32_16x16x32_bf16 v[4:7], v[76:79], v[172:175], v[4:7]
	ds_read_b128 v[200:203], v210 offset:61440
	s_add_u32 m0, s38, 28672
	s_nop 0
	global_load_lds_dwordx4 v215, s[100:101]
	s_add_u32 s100, s100, 128
	s_addc_u32 s101, s101, 0
	s_waitcnt lgkmcnt(6)
	v_mfma_f32_16x16x32_bf16 v[40:43], v[64:67], v[176:179], v[40:43]
	v_mfma_f32_16x16x32_bf16 v[52:55], v[68:71], v[176:179], v[52:55]
	ds_read_b128 v[204:207], v210 offset:63488
	s_waitcnt lgkmcnt(6)
	v_mfma_f32_16x16x32_bf16 v[28:31], v[64:67], v[180:183], v[28:31]
	v_mfma_f32_16x16x32_bf16 v[16:19], v[68:71], v[180:183], v[16:19]
	ds_read_b128 v[72:75], v209 offset:32768
	ds_read_b128 v[76:79], v209 offset:34816
	ds_read_b128 v[160:163], v211 offset:49152
	s_waitcnt lgkmcnt(8)
	v_mfma_f32_16x16x32_bf16 v[60:63], v[64:67], v[184:187], v[60:63]
	v_mfma_f32_16x16x32_bf16 v[48:51], v[68:71], v[184:187], v[48:51]
	ds_read_b128 v[164:167], v211 offset:51200
	s_waitcnt lgkmcnt(8)
	v_mfma_f32_16x16x32_bf16 v[20:23], v[64:67], v[188:191], v[20:23]
	v_mfma_f32_16x16x32_bf16 v[0:3], v[68:71], v[188:191], v[0:3]
	ds_read_b128 v[168:171], v211 offset:53248
	s_waitcnt lgkmcnt(8)
	v_mfma_f32_16x16x32_bf16 v[44:47], v[64:67], v[192:195], v[44:47]
	v_mfma_f32_16x16x32_bf16 v[36:39], v[68:71], v[192:195], v[36:39]
	ds_read_b128 v[172:175], v211 offset:55296
	s_waitcnt lgkmcnt(8)
	v_mfma_f32_16x16x32_bf16 v[24:27], v[64:67], v[196:199], v[24:27]
	v_mfma_f32_16x16x32_bf16 v[8:11], v[68:71], v[196:199], v[8:11]
	ds_read_b128 v[176:179], v211 offset:57344
	s_waitcnt lgkmcnt(8)
	v_mfma_f32_16x16x32_bf16 v[56:59], v[64:67], v[200:203], v[56:59]
	v_mfma_f32_16x16x32_bf16 v[32:35], v[68:71], v[200:203], v[32:35]
	ds_read_b128 v[180:183], v211 offset:59392
	s_waitcnt lgkmcnt(8)
	v_mfma_f32_16x16x32_bf16 v[12:15], v[64:67], v[204:207], v[12:15]
	v_mfma_f32_16x16x32_bf16 v[4:7], v[68:71], v[204:207], v[4:7]
	ds_read_b128 v[184:187], v211 offset:61440
	s_waitcnt lgkmcnt(6)
	v_mfma_f32_16x16x32_bf16 v[40:43], v[72:75], v[160:163], v[40:43]
	v_mfma_f32_16x16x32_bf16 v[52:55], v[76:79], v[160:163], v[52:55]
	ds_read_b128 v[188:191], v211 offset:63488
	s_waitcnt vmcnt(0) lgkmcnt(0)
	s_barrier
	s_add_u32 m0, s38, 32768
	s_nop 0
	global_load_lds_dwordx4 v212, s[98:99]
	s_waitcnt lgkmcnt(6)
	v_mfma_f32_16x16x32_bf16 v[28:31], v[72:75], v[164:167], v[28:31]
	v_mfma_f32_16x16x32_bf16 v[16:19], v[76:79], v[164:167], v[16:19]
	ds_read_b128 v[64:67], v208 offset:0
	ds_read_b128 v[68:71], v208 offset:2048
	ds_read_b128 v[192:195], v210 offset:16384
	s_add_u32 m0, s38, 36864
	s_nop 0
	global_load_lds_dwordx4 v213, s[98:99]
	s_waitcnt lgkmcnt(8)
	v_mfma_f32_16x16x32_bf16 v[60:63], v[72:75], v[168:171], v[60:63]
	v_mfma_f32_16x16x32_bf16 v[48:51], v[76:79], v[168:171], v[48:51]
	ds_read_b128 v[196:199], v210 offset:18432
	s_add_u32 m0, s38, 40960
	s_nop 0
	global_load_lds_dwordx4 v214, s[98:99]
	s_waitcnt lgkmcnt(8)
	v_mfma_f32_16x16x32_bf16 v[20:23], v[72:75], v[172:175], v[20:23]
	v_mfma_f32_16x16x32_bf16 v[0:3], v[76:79], v[172:175], v[0:3]
	ds_read_b128 v[200:203], v210 offset:20480
	s_add_u32 m0, s38, 45056
	s_nop 0
	global_load_lds_dwordx4 v215, s[98:99]
	s_add_u32 s98, s98, 128
	s_addc_u32 s99, s99, 0
	s_waitcnt lgkmcnt(8)
	v_mfma_f32_16x16x32_bf16 v[44:47], v[72:75], v[176:179], v[44:47]
	v_mfma_f32_16x16x32_bf16 v[36:39], v[76:79], v[176:179], v[36:39]
	ds_read_b128 v[204:207], v210 offset:22528
	s_add_u32 m0, s38, 49152
	s_nop 0
	global_load_lds_dwordx4 v212, s[100:101]
	s_waitcnt lgkmcnt(8)
	v_mfma_f32_16x16x32_bf16 v[24:27], v[72:75], v[180:183], v[24:27]
	v_mfma_f32_16x16x32_bf16 v[8:11], v[76:79], v[180:183], v[8:11]
	ds_read_b128 v[160:163], v210 offset:24576
	s_add_u32 m0, s38, 53248
	s_nop 0
	global_load_lds_dwordx4 v213, s[100:101]
	s_waitcnt lgkmcnt(8)
	v_mfma_f32_16x16x32_bf16 v[56:59], v[72:75], v[184:187], v[56:59]
	v_mfma_f32_16x16x32_bf16 v[32:35], v[76:79], v[184:187], v[32:35]
	ds_read_b128 v[164:167], v210 offset:26624
	s_add_u32 m0, s38, 57344
	s_nop 0
	global_load_lds_dwordx4 v214, s[100:101]
	s_waitcnt lgkmcnt(8)
	v_mfma_f32_16x16x32_bf16 v[12:15], v[72:75], v[188:191], v[12:15]
	v_mfma_f32_16x16x32_bf16 v[4:7], v[76:79], v[188:191], v[4:7]
	ds_read_b128 v[168:171], v210 offset:28672
	s_add_u32 m0, s38, 61440
	s_nop 0
	global_load_lds_dwordx4 v215, s[100:101]
	s_add_u32 s100, s100, 128
	s_addc_u32 s101, s101, 0
	s_waitcnt lgkmcnt(6)
	v_mfma_f32_16x16x32_bf16 v[40:43], v[64:67], v[192:195], v[40:43]
	v_mfma_f32_16x16x32_bf16 v[52:55], v[68:71], v[192:195], v[52:55]
	ds_read_b128 v[172:175], v210 offset:30720
	s_waitcnt lgkmcnt(6)
	v_mfma_f32_16x16x32_bf16 v[28:31], v[64:67], v[196:199], v[28:31]
	v_mfma_f32_16x16x32_bf16 v[16:19], v[68:71], v[196:199], v[16:19]
	ds_read_b128 v[72:75], v209 offset:0
	ds_read_b128 v[76:79], v209 offset:2048
	ds_read_b128 v[176:179], v211 offset:16384
	s_waitcnt lgkmcnt(8)
	v_mfma_f32_16x16x32_bf16 v[60:63], v[64:67], v[200:203], v[60:63]
	v_mfma_f32_16x16x32_bf16 v[48:51], v[68:71], v[200:203], v[48:51]
	ds_read_b128 v[180:183], v211 offset:18432
	s_waitcnt lgkmcnt(8)
	v_mfma_f32_16x16x32_bf16 v[20:23], v[64:67], v[204:207], v[20:23]
	v_mfma_f32_16x16x32_bf16 v[0:3], v[68:71], v[204:207], v[0:3]
	ds_read_b128 v[184:187], v211 offset:20480
	s_waitcnt lgkmcnt(8)
	v_mfma_f32_16x16x32_bf16 v[44:47], v[64:67], v[160:163], v[44:47]
	v_mfma_f32_16x16x32_bf16 v[36:39], v[68:71], v[160:163], v[36:39]
	ds_read_b128 v[188:191], v211 offset:22528
	s_waitcnt lgkmcnt(8)
	v_mfma_f32_16x16x32_bf16 v[24:27], v[64:67], v[164:167], v[24:27]
	v_mfma_f32_16x16x32_bf16 v[8:11], v[68:71], v[164:167], v[8:11]
	ds_read_b128 v[192:195], v211 offset:24576
	s_waitcnt lgkmcnt(8)
	v_mfma_f32_16x16x32_bf16 v[56:59], v[64:67], v[168:171], v[56:59]
	v_mfma_f32_16x16x32_bf16 v[32:35], v[68:71], v[168:171], v[32:35]
	ds_read_b128 v[196:199], v211 offset:26624
	s_waitcnt lgkmcnt(8)
	v_mfma_f32_16x16x32_bf16 v[12:15], v[64:67], v[172:175], v[12:15]
	v_mfma_f32_16x16x32_bf16 v[4:7], v[68:71], v[172:175], v[4:7]
	ds_read_b128 v[200:203], v211 offset:28672
	s_waitcnt lgkmcnt(6)
	v_mfma_f32_16x16x32_bf16 v[40:43], v[72:75], v[176:179], v[40:43]
	v_mfma_f32_16x16x32_bf16 v[52:55], v[76:79], v[176:179], v[52:55]
	ds_read_b128 v[204:207], v211 offset:30720
	s_waitcnt vmcnt(0) lgkmcnt(0)
	s_barrier
	s_add_u32 m0, s38, 0
	s_nop 0
	global_load_lds_dwordx4 v212, s[98:99]
	s_waitcnt lgkmcnt(6)
	v_mfma_f32_16x16x32_bf16 v[28:31], v[72:75], v[180:183], v[28:31]
	v_mfma_f32_16x16x32_bf16 v[16:19], v[76:79], v[180:183], v[16:19]
	ds_read_b128 v[64:67], v208 offset:32768
	ds_read_b128 v[68:71], v208 offset:34816
	ds_read_b128 v[160:163], v210 offset:49152
	s_add_u32 m0, s38, 4096
	s_nop 0
	global_load_lds_dwordx4 v213, s[98:99]
	s_waitcnt lgkmcnt(8)
	v_mfma_f32_16x16x32_bf16 v[60:63], v[72:75], v[184:187], v[60:63]
	v_mfma_f32_16x16x32_bf16 v[48:51], v[76:79], v[184:187], v[48:51]
	ds_read_b128 v[164:167], v210 offset:51200
	s_add_u32 m0, s38, 8192
	s_nop 0
	global_load_lds_dwordx4 v214, s[98:99]
	s_waitcnt lgkmcnt(8)
	v_mfma_f32_16x16x32_bf16 v[20:23], v[72:75], v[188:191], v[20:23]
	v_mfma_f32_16x16x32_bf16 v[0:3], v[76:79], v[188:191], v[0:3]
	ds_read_b128 v[168:171], v210 offset:53248
	s_add_u32 m0, s38, 12288
	s_nop 0
	global_load_lds_dwordx4 v215, s[98:99]
	s_add_u32 s98, s98, 128
	s_addc_u32 s99, s99, 0
	s_waitcnt lgkmcnt(8)
	v_mfma_f32_16x16x32_bf16 v[44:47], v[72:75], v[192:195], v[44:47]
	v_mfma_f32_16x16x32_bf16 v[36:39], v[76:79], v[192:195], v[36:39]
	ds_read_b128 v[172:175], v210 offset:55296
	s_add_u32 m0, s38, 16384
	s_nop 0
	global_load_lds_dwordx4 v212, s[100:101]
	s_waitcnt lgkmcnt(8)
	v_mfma_f32_16x16x32_bf16 v[24:27], v[72:75], v[196:199], v[24:27]
	v_mfma_f32_16x16x32_bf16 v[8:11], v[76:79], v[196:199], v[8:11]
	ds_read_b128 v[176:179], v210 offset:57344
	s_add_u32 m0, s38, 20480
	s_nop 0
	global_load_lds_dwordx4 v213, s[100:101]
	s_waitcnt lgkmcnt(8)
	v_mfma_f32_16x16x32_bf16 v[56:59], v[72:75], v[200:203], v[56:59]
	v_mfma_f32_16x16x32_bf16 v[32:35], v[76:79], v[200:203], v[32:35]
	ds_read_b128 v[180:183], v210 offset:59392
	s_add_u32 m0, s38, 24576
	s_nop 0
	global_load_lds_dwordx4 v214, s[100:101]
	s_waitcnt lgkmcnt(8)
	v_mfma_f32_16x16x32_bf16 v[12:15], v[72:75], v[204:207], v[12:15]
	v_mfma_f32_16x16x32_bf16 v[4:7], v[76:79], v[204:207], v[4:7]
	ds_read_b128 v[184:187], v210 offset:61440
	s_add_u32 m0, s38, 28672
	s_nop 0
	global_load_lds_dwordx4 v215, s[100:101]
	s_add_u32 s100, s100, 128
	s_addc_u32 s101, s101, 0
	s_waitcnt lgkmcnt(6)
	v_mfma_f32_16x16x32_bf16 v[40:43], v[64:67], v[160:163], v[40:43]
	v_mfma_f32_16x16x32_bf16 v[52:55], v[68:71], v[160:163], v[52:55]
	ds_read_b128 v[188:191], v210 offset:63488
	s_waitcnt lgkmcnt(6)
	v_mfma_f32_16x16x32_bf16 v[28:31], v[64:67], v[164:167], v[28:31]
	v_mfma_f32_16x16x32_bf16 v[16:19], v[68:71], v[164:167], v[16:19]
	ds_read_b128 v[72:75], v209 offset:32768
	ds_read_b128 v[76:79], v209 offset:34816
	ds_read_b128 v[192:195], v211 offset:49152
	s_waitcnt lgkmcnt(8)
	v_mfma_f32_16x16x32_bf16 v[60:63], v[64:67], v[168:171], v[60:63]
	v_mfma_f32_16x16x32_bf16 v[48:51], v[68:71], v[168:171], v[48:51]
	ds_read_b128 v[196:199], v211 offset:51200
	s_waitcnt lgkmcnt(8)
	v_mfma_f32_16x16x32_bf16 v[20:23], v[64:67], v[172:175], v[20:23]
	v_mfma_f32_16x16x32_bf16 v[0:3], v[68:71], v[172:175], v[0:3]
	ds_read_b128 v[200:203], v211 offset:53248
	s_waitcnt lgkmcnt(8)
	v_mfma_f32_16x16x32_bf16 v[44:47], v[64:67], v[176:179], v[44:47]
	v_mfma_f32_16x16x32_bf16 v[36:39], v[68:71], v[176:179], v[36:39]
	ds_read_b128 v[204:207], v211 offset:55296
	s_waitcnt lgkmcnt(8)
	v_mfma_f32_16x16x32_bf16 v[24:27], v[64:67], v[180:183], v[24:27]
	v_mfma_f32_16x16x32_bf16 v[8:11], v[68:71], v[180:183], v[8:11]
	ds_read_b128 v[160:163], v211 offset:57344
	s_waitcnt lgkmcnt(8)
	v_mfma_f32_16x16x32_bf16 v[56:59], v[64:67], v[184:187], v[56:59]
	v_mfma_f32_16x16x32_bf16 v[32:35], v[68:71], v[184:187], v[32:35]
	ds_read_b128 v[164:167], v211 offset:59392
	s_waitcnt lgkmcnt(8)
	v_mfma_f32_16x16x32_bf16 v[12:15], v[64:67], v[188:191], v[12:15]
	v_mfma_f32_16x16x32_bf16 v[4:7], v[68:71], v[188:191], v[4:7]
	ds_read_b128 v[168:171], v211 offset:61440
	s_waitcnt lgkmcnt(6)
	v_mfma_f32_16x16x32_bf16 v[40:43], v[72:75], v[192:195], v[40:43]
	v_mfma_f32_16x16x32_bf16 v[52:55], v[76:79], v[192:195], v[52:55]
	ds_read_b128 v[172:175], v211 offset:63488
	s_waitcnt vmcnt(0) lgkmcnt(0)
	s_barrier
	s_add_u32 m0, s38, 32768
	s_nop 0
	global_load_lds_dwordx4 v212, s[98:99]
	s_waitcnt lgkmcnt(6)
	v_mfma_f32_16x16x32_bf16 v[28:31], v[72:75], v[196:199], v[28:31]
	v_mfma_f32_16x16x32_bf16 v[16:19], v[76:79], v[196:199], v[16:19]
	ds_read_b128 v[64:67], v208 offset:0
	ds_read_b128 v[68:71], v208 offset:2048
	ds_read_b128 v[176:179], v210 offset:16384
	s_add_u32 m0, s38, 36864
	s_nop 0
	global_load_lds_dwordx4 v213, s[98:99]
	s_waitcnt lgkmcnt(8)
	v_mfma_f32_16x16x32_bf16 v[60:63], v[72:75], v[200:203], v[60:63]
	v_mfma_f32_16x16x32_bf16 v[48:51], v[76:79], v[200:203], v[48:51]
	ds_read_b128 v[180:183], v210 offset:18432
	s_add_u32 m0, s38, 40960
	s_nop 0
	global_load_lds_dwordx4 v214, s[98:99]
	s_waitcnt lgkmcnt(8)
	v_mfma_f32_16x16x32_bf16 v[20:23], v[72:75], v[204:207], v[20:23]
	v_mfma_f32_16x16x32_bf16 v[0:3], v[76:79], v[204:207], v[0:3]
	ds_read_b128 v[184:187], v210 offset:20480
	s_add_u32 m0, s38, 45056
	s_nop 0
	global_load_lds_dwordx4 v215, s[98:99]
	s_add_u32 s98, s98, 128
	s_addc_u32 s99, s99, 0
	s_waitcnt lgkmcnt(8)
	v_mfma_f32_16x16x32_bf16 v[44:47], v[72:75], v[160:163], v[44:47]
	v_mfma_f32_16x16x32_bf16 v[36:39], v[76:79], v[160:163], v[36:39]
	ds_read_b128 v[188:191], v210 offset:22528
	s_add_u32 m0, s38, 49152
	s_nop 0
	global_load_lds_dwordx4 v212, s[100:101]
	s_waitcnt lgkmcnt(8)
	v_mfma_f32_16x16x32_bf16 v[24:27], v[72:75], v[164:167], v[24:27]
	v_mfma_f32_16x16x32_bf16 v[8:11], v[76:79], v[164:167], v[8:11]
	ds_read_b128 v[192:195], v210 offset:24576
	s_add_u32 m0, s38, 53248
	s_nop 0
	global_load_lds_dwordx4 v213, s[100:101]
	s_waitcnt lgkmcnt(8)
	v_mfma_f32_16x16x32_bf16 v[56:59], v[72:75], v[168:171], v[56:59]
	v_mfma_f32_16x16x32_bf16 v[32:35], v[76:79], v[168:171], v[32:35]
	ds_read_b128 v[196:199], v210 offset:26624
	s_add_u32 m0, s38, 57344
	s_nop 0
	global_load_lds_dwordx4 v214, s[100:101]
	s_waitcnt lgkmcnt(8)
	v_mfma_f32_16x16x32_bf16 v[12:15], v[72:75], v[172:175], v[12:15]
	v_mfma_f32_16x16x32_bf16 v[4:7], v[76:79], v[172:175], v[4:7]
	ds_read_b128 v[200:203], v210 offset:28672
	s_add_u32 m0, s38, 61440
	s_nop 0
	global_load_lds_dwordx4 v215, s[100:101]
	s_add_u32 s100, s100, 128
	s_addc_u32 s101, s101, 0
	s_waitcnt lgkmcnt(6)
	v_mfma_f32_16x16x32_bf16 v[40:43], v[64:67], v[176:179], v[40:43]
	v_mfma_f32_16x16x32_bf16 v[52:55], v[68:71], v[176:179], v[52:55]
	ds_read_b128 v[204:207], v210 offset:30720
	s_waitcnt lgkmcnt(6)
	v_mfma_f32_16x16x32_bf16 v[28:31], v[64:67], v[180:183], v[28:31]
	v_mfma_f32_16x16x32_bf16 v[16:19], v[68:71], v[180:183], v[16:19]
	ds_read_b128 v[72:75], v209 offset:0
	ds_read_b128 v[76:79], v209 offset:2048
	ds_read_b128 v[160:163], v211 offset:16384
	s_waitcnt lgkmcnt(8)
	v_mfma_f32_16x16x32_bf16 v[60:63], v[64:67], v[184:187], v[60:63]
	v_mfma_f32_16x16x32_bf16 v[48:51], v[68:71], v[184:187], v[48:51]
	ds_read_b128 v[164:167], v211 offset:18432
	s_waitcnt lgkmcnt(8)
	v_mfma_f32_16x16x32_bf16 v[20:23], v[64:67], v[188:191], v[20:23]
	v_mfma_f32_16x16x32_bf16 v[0:3], v[68:71], v[188:191], v[0:3]
	ds_read_b128 v[168:171], v211 offset:20480
	s_waitcnt lgkmcnt(8)
	v_mfma_f32_16x16x32_bf16 v[44:47], v[64:67], v[192:195], v[44:47]
	v_mfma_f32_16x16x32_bf16 v[36:39], v[68:71], v[192:195], v[36:39]
	ds_read_b128 v[172:175], v211 offset:22528
	s_waitcnt lgkmcnt(8)
	v_mfma_f32_16x16x32_bf16 v[24:27], v[64:67], v[196:199], v[24:27]
	v_mfma_f32_16x16x32_bf16 v[8:11], v[68:71], v[196:199], v[8:11]
	ds_read_b128 v[176:179], v211 offset:24576
	s_waitcnt lgkmcnt(8)
	v_mfma_f32_16x16x32_bf16 v[56:59], v[64:67], v[200:203], v[56:59]
	v_mfma_f32_16x16x32_bf16 v[32:35], v[68:71], v[200:203], v[32:35]
	ds_read_b128 v[180:183], v211 offset:26624
	s_waitcnt lgkmcnt(8)
	v_mfma_f32_16x16x32_bf16 v[12:15], v[64:67], v[204:207], v[12:15]
	v_mfma_f32_16x16x32_bf16 v[4:7], v[68:71], v[204:207], v[4:7]
	ds_read_b128 v[184:187], v211 offset:28672
	s_waitcnt lgkmcnt(6)
	v_mfma_f32_16x16x32_bf16 v[40:43], v[72:75], v[160:163], v[40:43]
	v_mfma_f32_16x16x32_bf16 v[52:55], v[76:79], v[160:163], v[52:55]
	ds_read_b128 v[188:191], v211 offset:30720
	s_waitcnt vmcnt(0) lgkmcnt(0)
	s_barrier
	s_add_u32 m0, s38, 0
	s_nop 0
	global_load_lds_dwordx4 v212, s[98:99]
	s_waitcnt lgkmcnt(6)
	v_mfma_f32_16x16x32_bf16 v[28:31], v[72:75], v[164:167], v[28:31]
	v_mfma_f32_16x16x32_bf16 v[16:19], v[76:79], v[164:167], v[16:19]
	ds_read_b128 v[64:67], v208 offset:32768
	ds_read_b128 v[68:71], v208 offset:34816
	ds_read_b128 v[192:195], v210 offset:49152
	s_add_u32 m0, s38, 4096
	s_nop 0
	global_load_lds_dwordx4 v213, s[98:99]
	s_waitcnt lgkmcnt(8)
	v_mfma_f32_16x16x32_bf16 v[60:63], v[72:75], v[168:171], v[60:63]
	v_mfma_f32_16x16x32_bf16 v[48:51], v[76:79], v[168:171], v[48:51]
	ds_read_b128 v[196:199], v210 offset:51200
	s_add_u32 m0, s38, 8192
	s_nop 0
	global_load_lds_dwordx4 v214, s[98:99]
	s_waitcnt lgkmcnt(8)
	v_mfma_f32_16x16x32_bf16 v[20:23], v[72:75], v[172:175], v[20:23]
	v_mfma_f32_16x16x32_bf16 v[0:3], v[76:79], v[172:175], v[0:3]
	ds_read_b128 v[200:203], v210 offset:53248
	s_add_u32 m0, s38, 12288
	s_nop 0
	global_load_lds_dwordx4 v215, s[98:99]
	s_add_u32 s98, s98, 128
	s_addc_u32 s99, s99, 0
	s_waitcnt lgkmcnt(8)
	v_mfma_f32_16x16x32_bf16 v[44:47], v[72:75], v[176:179], v[44:47]
	v_mfma_f32_16x16x32_bf16 v[36:39], v[76:79], v[176:179], v[36:39]
	ds_read_b128 v[204:207], v210 offset:55296
	s_add_u32 m0, s38, 16384
	s_nop 0
	global_load_lds_dwordx4 v212, s[100:101]
	s_waitcnt lgkmcnt(8)
	v_mfma_f32_16x16x32_bf16 v[24:27], v[72:75], v[180:183], v[24:27]
	v_mfma_f32_16x16x32_bf16 v[8:11], v[76:79], v[180:183], v[8:11]
	ds_read_b128 v[160:163], v210 offset:57344
	s_add_u32 m0, s38, 20480
	s_nop 0
	global_load_lds_dwordx4 v213, s[100:101]
	s_waitcnt lgkmcnt(8)
	v_mfma_f32_16x16x32_bf16 v[56:59], v[72:75], v[184:187], v[56:59]
	v_mfma_f32_16x16x32_bf16 v[32:35], v[76:79], v[184:187], v[32:35]
	ds_read_b128 v[164:167], v210 offset:59392
	s_add_u32 m0, s38, 24576
	s_nop 0
	global_load_lds_dwordx4 v214, s[100:101]
	s_waitcnt lgkmcnt(8)
	v_mfma_f32_16x16x32_bf16 v[12:15], v[72:75], v[188:191], v[12:15]
	v_mfma_f32_16x16x32_bf16 v[4:7], v[76:79], v[188:191], v[4:7]
	ds_read_b128 v[168:171], v210 offset:61440
	s_add_u32 m0, s38, 28672
	s_nop 0
	global_load_lds_dwordx4 v215, s[100:101]
	s_add_u32 s100, s100, 128
	s_addc_u32 s101, s101, 0
	s_waitcnt lgkmcnt(6)
	v_mfma_f32_16x16x32_bf16 v[40:43], v[64:67], v[192:195], v[40:43]
	v_mfma_f32_16x16x32_bf16 v[52:55], v[68:71], v[192:195], v[52:55]
	ds_read_b128 v[172:175], v210 offset:63488
	s_waitcnt lgkmcnt(6)
	v_mfma_f32_16x16x32_bf16 v[28:31], v[64:67], v[196:199], v[28:31]
	v_mfma_f32_16x16x32_bf16 v[16:19], v[68:71], v[196:199], v[16:19]
	ds_read_b128 v[72:75], v209 offset:32768
	ds_read_b128 v[76:79], v209 offset:34816
	ds_read_b128 v[176:179], v211 offset:49152
	s_waitcnt lgkmcnt(8)
	v_mfma_f32_16x16x32_bf16 v[60:63], v[64:67], v[200:203], v[60:63]
	v_mfma_f32_16x16x32_bf16 v[48:51], v[68:71], v[200:203], v[48:51]
	ds_read_b128 v[180:183], v211 offset:51200
	s_waitcnt lgkmcnt(8)
	v_mfma_f32_16x16x32_bf16 v[20:23], v[64:67], v[204:207], v[20:23]
	v_mfma_f32_16x16x32_bf16 v[0:3], v[68:71], v[204:207], v[0:3]
	ds_read_b128 v[184:187], v211 offset:53248
	s_waitcnt lgkmcnt(8)
	v_mfma_f32_16x16x32_bf16 v[44:47], v[64:67], v[160:163], v[44:47]
	v_mfma_f32_16x16x32_bf16 v[36:39], v[68:71], v[160:163], v[36:39]
	ds_read_b128 v[188:191], v211 offset:55296
	s_waitcnt lgkmcnt(8)
	v_mfma_f32_16x16x32_bf16 v[24:27], v[64:67], v[164:167], v[24:27]
	v_mfma_f32_16x16x32_bf16 v[8:11], v[68:71], v[164:167], v[8:11]
	ds_read_b128 v[192:195], v211 offset:57344
	s_waitcnt lgkmcnt(8)
	v_mfma_f32_16x16x32_bf16 v[56:59], v[64:67], v[168:171], v[56:59]
	v_mfma_f32_16x16x32_bf16 v[32:35], v[68:71], v[168:171], v[32:35]
	ds_read_b128 v[196:199], v211 offset:59392
	s_waitcnt lgkmcnt(8)
	v_mfma_f32_16x16x32_bf16 v[12:15], v[64:67], v[172:175], v[12:15]
	v_mfma_f32_16x16x32_bf16 v[4:7], v[68:71], v[172:175], v[4:7]
	ds_read_b128 v[200:203], v211 offset:61440
	s_waitcnt lgkmcnt(6)
	v_mfma_f32_16x16x32_bf16 v[40:43], v[72:75], v[176:179], v[40:43]
	v_mfma_f32_16x16x32_bf16 v[52:55], v[76:79], v[176:179], v[52:55]
	ds_read_b128 v[204:207], v211 offset:63488
	s_waitcnt vmcnt(0) lgkmcnt(0)
	s_barrier
	s_add_u32 m0, s38, 32768
	s_nop 0
	global_load_lds_dwordx4 v212, s[98:99]
	s_waitcnt lgkmcnt(6)
	v_mfma_f32_16x16x32_bf16 v[28:31], v[72:75], v[180:183], v[28:31]
	v_mfma_f32_16x16x32_bf16 v[16:19], v[76:79], v[180:183], v[16:19]
	ds_read_b128 v[64:67], v208 offset:0
	ds_read_b128 v[68:71], v208 offset:2048
	ds_read_b128 v[160:163], v210 offset:16384
	s_add_u32 m0, s38, 36864
	s_nop 0
	global_load_lds_dwordx4 v213, s[98:99]
	s_waitcnt lgkmcnt(8)
	v_mfma_f32_16x16x32_bf16 v[60:63], v[72:75], v[184:187], v[60:63]
	v_mfma_f32_16x16x32_bf16 v[48:51], v[76:79], v[184:187], v[48:51]
	ds_read_b128 v[164:167], v210 offset:18432
	s_add_u32 m0, s38, 40960
	s_nop 0
	global_load_lds_dwordx4 v214, s[98:99]
	s_waitcnt lgkmcnt(8)
	v_mfma_f32_16x16x32_bf16 v[20:23], v[72:75], v[188:191], v[20:23]
	v_mfma_f32_16x16x32_bf16 v[0:3], v[76:79], v[188:191], v[0:3]
	ds_read_b128 v[168:171], v210 offset:20480
	s_add_u32 m0, s38, 45056
	s_nop 0
	global_load_lds_dwordx4 v215, s[98:99]
	s_add_u32 s98, s98, 128
	s_addc_u32 s99, s99, 0
	s_waitcnt lgkmcnt(8)
	v_mfma_f32_16x16x32_bf16 v[44:47], v[72:75], v[192:195], v[44:47]
	v_mfma_f32_16x16x32_bf16 v[36:39], v[76:79], v[192:195], v[36:39]
	ds_read_b128 v[172:175], v210 offset:22528
	s_add_u32 m0, s38, 49152
	s_nop 0
	global_load_lds_dwordx4 v212, s[100:101]
	s_waitcnt lgkmcnt(8)
	v_mfma_f32_16x16x32_bf16 v[24:27], v[72:75], v[196:199], v[24:27]
	v_mfma_f32_16x16x32_bf16 v[8:11], v[76:79], v[196:199], v[8:11]
	ds_read_b128 v[176:179], v210 offset:24576
	s_add_u32 m0, s38, 53248
	s_nop 0
	global_load_lds_dwordx4 v213, s[100:101]
	s_waitcnt lgkmcnt(8)
	v_mfma_f32_16x16x32_bf16 v[56:59], v[72:75], v[200:203], v[56:59]
	v_mfma_f32_16x16x32_bf16 v[32:35], v[76:79], v[200:203], v[32:35]
	ds_read_b128 v[180:183], v210 offset:26624
	s_add_u32 m0, s38, 57344
	s_nop 0
	global_load_lds_dwordx4 v214, s[100:101]
	s_waitcnt lgkmcnt(8)
	v_mfma_f32_16x16x32_bf16 v[12:15], v[72:75], v[204:207], v[12:15]
	v_mfma_f32_16x16x32_bf16 v[4:7], v[76:79], v[204:207], v[4:7]
	ds_read_b128 v[184:187], v210 offset:28672
	s_add_u32 m0, s38, 61440
	s_nop 0
	global_load_lds_dwordx4 v215, s[100:101]
	s_add_u32 s100, s100, 128
	s_addc_u32 s101, s101, 0
	s_waitcnt lgkmcnt(6)
	v_mfma_f32_16x16x32_bf16 v[40:43], v[64:67], v[160:163], v[40:43]
	v_mfma_f32_16x16x32_bf16 v[52:55], v[68:71], v[160:163], v[52:55]
	ds_read_b128 v[188:191], v210 offset:30720
	s_waitcnt lgkmcnt(6)
	v_mfma_f32_16x16x32_bf16 v[28:31], v[64:67], v[164:167], v[28:31]
	v_mfma_f32_16x16x32_bf16 v[16:19], v[68:71], v[164:167], v[16:19]
	ds_read_b128 v[72:75], v209 offset:0
	ds_read_b128 v[76:79], v209 offset:2048
	ds_read_b128 v[192:195], v211 offset:16384
	s_waitcnt lgkmcnt(8)
	v_mfma_f32_16x16x32_bf16 v[60:63], v[64:67], v[168:171], v[60:63]
	v_mfma_f32_16x16x32_bf16 v[48:51], v[68:71], v[168:171], v[48:51]
	ds_read_b128 v[196:199], v211 offset:18432
	s_waitcnt lgkmcnt(8)
	v_mfma_f32_16x16x32_bf16 v[20:23], v[64:67], v[172:175], v[20:23]
	v_mfma_f32_16x16x32_bf16 v[0:3], v[68:71], v[172:175], v[0:3]
	ds_read_b128 v[200:203], v211 offset:20480
	s_waitcnt lgkmcnt(8)
	v_mfma_f32_16x16x32_bf16 v[44:47], v[64:67], v[176:179], v[44:47]
	v_mfma_f32_16x16x32_bf16 v[36:39], v[68:71], v[176:179], v[36:39]
	ds_read_b128 v[204:207], v211 offset:22528
	s_waitcnt lgkmcnt(8)
	v_mfma_f32_16x16x32_bf16 v[24:27], v[64:67], v[180:183], v[24:27]
	v_mfma_f32_16x16x32_bf16 v[8:11], v[68:71], v[180:183], v[8:11]
	ds_read_b128 v[160:163], v211 offset:24576
	s_waitcnt lgkmcnt(8)
	v_mfma_f32_16x16x32_bf16 v[56:59], v[64:67], v[184:187], v[56:59]
	v_mfma_f32_16x16x32_bf16 v[32:35], v[68:71], v[184:187], v[32:35]
	ds_read_b128 v[164:167], v211 offset:26624
	s_waitcnt lgkmcnt(8)
	v_mfma_f32_16x16x32_bf16 v[12:15], v[64:67], v[188:191], v[12:15]
	v_mfma_f32_16x16x32_bf16 v[4:7], v[68:71], v[188:191], v[4:7]
	ds_read_b128 v[168:171], v211 offset:28672
	s_waitcnt lgkmcnt(6)
	v_mfma_f32_16x16x32_bf16 v[40:43], v[72:75], v[192:195], v[40:43]
	v_mfma_f32_16x16x32_bf16 v[52:55], v[76:79], v[192:195], v[52:55]
	ds_read_b128 v[172:175], v211 offset:30720
	s_waitcnt vmcnt(0) lgkmcnt(0)
	s_barrier
	s_add_u32 m0, s38, 0
	s_nop 0
	global_load_lds_dwordx4 v212, s[98:99]
	s_waitcnt lgkmcnt(6)
	v_mfma_f32_16x16x32_bf16 v[28:31], v[72:75], v[196:199], v[28:31]
	v_mfma_f32_16x16x32_bf16 v[16:19], v[76:79], v[196:199], v[16:19]
	ds_read_b128 v[64:67], v208 offset:32768
	ds_read_b128 v[68:71], v208 offset:34816
	ds_read_b128 v[176:179], v210 offset:49152
	s_add_u32 m0, s38, 4096
	s_nop 0
	global_load_lds_dwordx4 v213, s[98:99]
	s_waitcnt lgkmcnt(8)
	v_mfma_f32_16x16x32_bf16 v[60:63], v[72:75], v[200:203], v[60:63]
	v_mfma_f32_16x16x32_bf16 v[48:51], v[76:79], v[200:203], v[48:51]
	ds_read_b128 v[180:183], v210 offset:51200
	s_add_u32 m0, s38, 8192
	s_nop 0
	global_load_lds_dwordx4 v214, s[98:99]
	s_waitcnt lgkmcnt(8)
	v_mfma_f32_16x16x32_bf16 v[20:23], v[72:75], v[204:207], v[20:23]
	v_mfma_f32_16x16x32_bf16 v[0:3], v[76:79], v[204:207], v[0:3]
	ds_read_b128 v[184:187], v210 offset:53248
	s_add_u32 m0, s38, 12288
	s_nop 0
	global_load_lds_dwordx4 v215, s[98:99]
	s_add_u32 s98, s98, 128
	s_addc_u32 s99, s99, 0
	s_waitcnt lgkmcnt(8)
	v_mfma_f32_16x16x32_bf16 v[44:47], v[72:75], v[160:163], v[44:47]
	v_mfma_f32_16x16x32_bf16 v[36:39], v[76:79], v[160:163], v[36:39]
	ds_read_b128 v[188:191], v210 offset:55296
	s_add_u32 m0, s38, 16384
	s_nop 0
	global_load_lds_dwordx4 v212, s[100:101]
	s_waitcnt lgkmcnt(8)
	v_mfma_f32_16x16x32_bf16 v[24:27], v[72:75], v[164:167], v[24:27]
	v_mfma_f32_16x16x32_bf16 v[8:11], v[76:79], v[164:167], v[8:11]
	ds_read_b128 v[192:195], v210 offset:57344
	s_add_u32 m0, s38, 20480
	s_nop 0
	global_load_lds_dwordx4 v213, s[100:101]
	s_waitcnt lgkmcnt(8)
	v_mfma_f32_16x16x32_bf16 v[56:59], v[72:75], v[168:171], v[56:59]
	v_mfma_f32_16x16x32_bf16 v[32:35], v[76:79], v[168:171], v[32:35]
	ds_read_b128 v[196:199], v210 offset:59392
	s_add_u32 m0, s38, 24576
	s_nop 0
	global_load_lds_dwordx4 v214, s[100:101]
	s_waitcnt lgkmcnt(8)
	v_mfma_f32_16x16x32_bf16 v[12:15], v[72:75], v[172:175], v[12:15]
	v_mfma_f32_16x16x32_bf16 v[4:7], v[76:79], v[172:175], v[4:7]
	ds_read_b128 v[200:203], v210 offset:61440
	s_add_u32 m0, s38, 28672
	s_nop 0
	global_load_lds_dwordx4 v215, s[100:101]
	s_add_u32 s100, s100, 128
	s_addc_u32 s101, s101, 0
	s_waitcnt lgkmcnt(6)
	v_mfma_f32_16x16x32_bf16 v[40:43], v[64:67], v[176:179], v[40:43]
	v_mfma_f32_16x16x32_bf16 v[52:55], v[68:71], v[176:179], v[52:55]
	ds_read_b128 v[204:207], v210 offset:63488
	s_waitcnt lgkmcnt(6)
	v_mfma_f32_16x16x32_bf16 v[28:31], v[64:67], v[180:183], v[28:31]
	v_mfma_f32_16x16x32_bf16 v[16:19], v[68:71], v[180:183], v[16:19]
	ds_read_b128 v[72:75], v209 offset:32768
	ds_read_b128 v[76:79], v209 offset:34816
	ds_read_b128 v[160:163], v211 offset:49152
	s_waitcnt lgkmcnt(8)
	v_mfma_f32_16x16x32_bf16 v[60:63], v[64:67], v[184:187], v[60:63]
	v_mfma_f32_16x16x32_bf16 v[48:51], v[68:71], v[184:187], v[48:51]
	ds_read_b128 v[164:167], v211 offset:51200
	s_waitcnt lgkmcnt(8)
	v_mfma_f32_16x16x32_bf16 v[20:23], v[64:67], v[188:191], v[20:23]
	v_mfma_f32_16x16x32_bf16 v[0:3], v[68:71], v[188:191], v[0:3]
	ds_read_b128 v[168:171], v211 offset:53248
	s_waitcnt lgkmcnt(8)
	v_mfma_f32_16x16x32_bf16 v[44:47], v[64:67], v[192:195], v[44:47]
	v_mfma_f32_16x16x32_bf16 v[36:39], v[68:71], v[192:195], v[36:39]
	ds_read_b128 v[172:175], v211 offset:55296
	s_waitcnt lgkmcnt(8)
	v_mfma_f32_16x16x32_bf16 v[24:27], v[64:67], v[196:199], v[24:27]
	v_mfma_f32_16x16x32_bf16 v[8:11], v[68:71], v[196:199], v[8:11]
	ds_read_b128 v[176:179], v211 offset:57344
	s_waitcnt lgkmcnt(8)
	v_mfma_f32_16x16x32_bf16 v[56:59], v[64:67], v[200:203], v[56:59]
	v_mfma_f32_16x16x32_bf16 v[32:35], v[68:71], v[200:203], v[32:35]
	ds_read_b128 v[180:183], v211 offset:59392
	s_waitcnt lgkmcnt(8)
	v_mfma_f32_16x16x32_bf16 v[12:15], v[64:67], v[204:207], v[12:15]
	v_mfma_f32_16x16x32_bf16 v[4:7], v[68:71], v[204:207], v[4:7]
	ds_read_b128 v[184:187], v211 offset:61440
	s_waitcnt lgkmcnt(6)
	v_mfma_f32_16x16x32_bf16 v[40:43], v[72:75], v[160:163], v[40:43]
	v_mfma_f32_16x16x32_bf16 v[52:55], v[76:79], v[160:163], v[52:55]
	ds_read_b128 v[188:191], v211 offset:63488
	s_waitcnt vmcnt(0) lgkmcnt(0)
	s_barrier
	s_add_u32 m0, s38, 32768
	s_nop 0
	global_load_lds_dwordx4 v212, s[98:99]
	s_waitcnt lgkmcnt(6)
	v_mfma_f32_16x16x32_bf16 v[28:31], v[72:75], v[164:167], v[28:31]
	v_mfma_f32_16x16x32_bf16 v[16:19], v[76:79], v[164:167], v[16:19]
	ds_read_b128 v[64:67], v208 offset:0
	ds_read_b128 v[68:71], v208 offset:2048
	ds_read_b128 v[192:195], v210 offset:16384
	s_add_u32 m0, s38, 36864
	s_nop 0
	global_load_lds_dwordx4 v213, s[98:99]
	s_waitcnt lgkmcnt(8)
	v_mfma_f32_16x16x32_bf16 v[60:63], v[72:75], v[168:171], v[60:63]
	v_mfma_f32_16x16x32_bf16 v[48:51], v[76:79], v[168:171], v[48:51]
	ds_read_b128 v[196:199], v210 offset:18432
	s_add_u32 m0, s38, 40960
	s_nop 0
	global_load_lds_dwordx4 v214, s[98:99]
	s_waitcnt lgkmcnt(8)
	v_mfma_f32_16x16x32_bf16 v[20:23], v[72:75], v[172:175], v[20:23]
	v_mfma_f32_16x16x32_bf16 v[0:3], v[76:79], v[172:175], v[0:3]
	ds_read_b128 v[200:203], v210 offset:20480
	s_add_u32 m0, s38, 45056
	s_nop 0
	global_load_lds_dwordx4 v215, s[98:99]
	s_add_u32 s98, s98, 128
	s_addc_u32 s99, s99, 0
	s_waitcnt lgkmcnt(8)
	v_mfma_f32_16x16x32_bf16 v[44:47], v[72:75], v[176:179], v[44:47]
	v_mfma_f32_16x16x32_bf16 v[36:39], v[76:79], v[176:179], v[36:39]
	ds_read_b128 v[204:207], v210 offset:22528
	s_add_u32 m0, s38, 49152
	s_nop 0
	global_load_lds_dwordx4 v212, s[100:101]
	s_waitcnt lgkmcnt(8)
	v_mfma_f32_16x16x32_bf16 v[24:27], v[72:75], v[180:183], v[24:27]
	v_mfma_f32_16x16x32_bf16 v[8:11], v[76:79], v[180:183], v[8:11]
	ds_read_b128 v[160:163], v210 offset:24576
	s_add_u32 m0, s38, 53248
	s_nop 0
	global_load_lds_dwordx4 v213, s[100:101]
	s_waitcnt lgkmcnt(8)
	v_mfma_f32_16x16x32_bf16 v[56:59], v[72:75], v[184:187], v[56:59]
	v_mfma_f32_16x16x32_bf16 v[32:35], v[76:79], v[184:187], v[32:35]
	ds_read_b128 v[164:167], v210 offset:26624
	s_add_u32 m0, s38, 57344
	s_nop 0
	global_load_lds_dwordx4 v214, s[100:101]
	s_waitcnt lgkmcnt(8)
	v_mfma_f32_16x16x32_bf16 v[12:15], v[72:75], v[188:191], v[12:15]
	v_mfma_f32_16x16x32_bf16 v[4:7], v[76:79], v[188:191], v[4:7]
	ds_read_b128 v[168:171], v210 offset:28672
	s_add_u32 m0, s38, 61440
	s_nop 0
	global_load_lds_dwordx4 v215, s[100:101]
	s_add_u32 s100, s100, 128
	s_addc_u32 s101, s101, 0
	s_waitcnt lgkmcnt(6)
	v_mfma_f32_16x16x32_bf16 v[40:43], v[64:67], v[192:195], v[40:43]
	v_mfma_f32_16x16x32_bf16 v[52:55], v[68:71], v[192:195], v[52:55]
	ds_read_b128 v[172:175], v210 offset:30720
	s_waitcnt lgkmcnt(6)
	v_mfma_f32_16x16x32_bf16 v[28:31], v[64:67], v[196:199], v[28:31]
	v_mfma_f32_16x16x32_bf16 v[16:19], v[68:71], v[196:199], v[16:19]
	ds_read_b128 v[72:75], v209 offset:0
	ds_read_b128 v[76:79], v209 offset:2048
	ds_read_b128 v[176:179], v211 offset:16384
	s_waitcnt lgkmcnt(8)
	v_mfma_f32_16x16x32_bf16 v[60:63], v[64:67], v[200:203], v[60:63]
	v_mfma_f32_16x16x32_bf16 v[48:51], v[68:71], v[200:203], v[48:51]
	ds_read_b128 v[180:183], v211 offset:18432
	s_waitcnt lgkmcnt(8)
	v_mfma_f32_16x16x32_bf16 v[20:23], v[64:67], v[204:207], v[20:23]
	v_mfma_f32_16x16x32_bf16 v[0:3], v[68:71], v[204:207], v[0:3]
	ds_read_b128 v[184:187], v211 offset:20480
	s_waitcnt lgkmcnt(8)
	v_mfma_f32_16x16x32_bf16 v[44:47], v[64:67], v[160:163], v[44:47]
	v_mfma_f32_16x16x32_bf16 v[36:39], v[68:71], v[160:163], v[36:39]
	ds_read_b128 v[188:191], v211 offset:22528
	s_waitcnt lgkmcnt(8)
	v_mfma_f32_16x16x32_bf16 v[24:27], v[64:67], v[164:167], v[24:27]
	v_mfma_f32_16x16x32_bf16 v[8:11], v[68:71], v[164:167], v[8:11]
	ds_read_b128 v[192:195], v211 offset:24576
	s_waitcnt lgkmcnt(8)
	v_mfma_f32_16x16x32_bf16 v[56:59], v[64:67], v[168:171], v[56:59]
	v_mfma_f32_16x16x32_bf16 v[32:35], v[68:71], v[168:171], v[32:35]
	ds_read_b128 v[196:199], v211 offset:26624
	s_waitcnt lgkmcnt(8)
	v_mfma_f32_16x16x32_bf16 v[12:15], v[64:67], v[172:175], v[12:15]
	v_mfma_f32_16x16x32_bf16 v[4:7], v[68:71], v[172:175], v[4:7]
	ds_read_b128 v[200:203], v211 offset:28672
	s_waitcnt lgkmcnt(6)
	v_mfma_f32_16x16x32_bf16 v[40:43], v[72:75], v[176:179], v[40:43]
	v_mfma_f32_16x16x32_bf16 v[52:55], v[76:79], v[176:179], v[52:55]
	ds_read_b128 v[204:207], v211 offset:30720
	s_waitcnt vmcnt(0) lgkmcnt(0)
	s_barrier
	s_add_u32 m0, s38, 0
	s_nop 0
	global_load_lds_dwordx4 v212, s[98:99]
	s_waitcnt lgkmcnt(6)
	v_mfma_f32_16x16x32_bf16 v[28:31], v[72:75], v[180:183], v[28:31]
	v_mfma_f32_16x16x32_bf16 v[16:19], v[76:79], v[180:183], v[16:19]
	ds_read_b128 v[64:67], v208 offset:32768
	ds_read_b128 v[68:71], v208 offset:34816
	ds_read_b128 v[160:163], v210 offset:49152
	s_add_u32 m0, s38, 4096
	s_nop 0
	global_load_lds_dwordx4 v213, s[98:99]
	s_waitcnt lgkmcnt(8)
	v_mfma_f32_16x16x32_bf16 v[60:63], v[72:75], v[184:187], v[60:63]
	v_mfma_f32_16x16x32_bf16 v[48:51], v[76:79], v[184:187], v[48:51]
	ds_read_b128 v[164:167], v210 offset:51200
	s_add_u32 m0, s38, 8192
	s_nop 0
	global_load_lds_dwordx4 v214, s[98:99]
	s_waitcnt lgkmcnt(8)
	v_mfma_f32_16x16x32_bf16 v[20:23], v[72:75], v[188:191], v[20:23]
	v_mfma_f32_16x16x32_bf16 v[0:3], v[76:79], v[188:191], v[0:3]
	ds_read_b128 v[168:171], v210 offset:53248
	s_add_u32 m0, s38, 12288
	s_nop 0
	global_load_lds_dwordx4 v215, s[98:99]
	s_add_u32 s98, s98, 128
	s_addc_u32 s99, s99, 0
	s_waitcnt lgkmcnt(8)
	v_mfma_f32_16x16x32_bf16 v[44:47], v[72:75], v[192:195], v[44:47]
	v_mfma_f32_16x16x32_bf16 v[36:39], v[76:79], v[192:195], v[36:39]
	ds_read_b128 v[172:175], v210 offset:55296
	s_add_u32 m0, s38, 16384
	s_nop 0
	global_load_lds_dwordx4 v212, s[100:101]
	s_waitcnt lgkmcnt(8)
	v_mfma_f32_16x16x32_bf16 v[24:27], v[72:75], v[196:199], v[24:27]
	v_mfma_f32_16x16x32_bf16 v[8:11], v[76:79], v[196:199], v[8:11]
	ds_read_b128 v[176:179], v210 offset:57344
	s_add_u32 m0, s38, 20480
	s_nop 0
	global_load_lds_dwordx4 v213, s[100:101]
	s_waitcnt lgkmcnt(8)
	v_mfma_f32_16x16x32_bf16 v[56:59], v[72:75], v[200:203], v[56:59]
	v_mfma_f32_16x16x32_bf16 v[32:35], v[76:79], v[200:203], v[32:35]
	ds_read_b128 v[180:183], v210 offset:59392
	s_add_u32 m0, s38, 24576
	s_nop 0
	global_load_lds_dwordx4 v214, s[100:101]
	s_waitcnt lgkmcnt(8)
	v_mfma_f32_16x16x32_bf16 v[12:15], v[72:75], v[204:207], v[12:15]
	v_mfma_f32_16x16x32_bf16 v[4:7], v[76:79], v[204:207], v[4:7]
	ds_read_b128 v[184:187], v210 offset:61440
	s_add_u32 m0, s38, 28672
	s_nop 0
	global_load_lds_dwordx4 v215, s[100:101]
	s_add_u32 s100, s100, 128
	s_addc_u32 s101, s101, 0
	s_waitcnt lgkmcnt(6)
	v_mfma_f32_16x16x32_bf16 v[40:43], v[64:67], v[160:163], v[40:43]
	v_mfma_f32_16x16x32_bf16 v[52:55], v[68:71], v[160:163], v[52:55]
	ds_read_b128 v[188:191], v210 offset:63488
	s_waitcnt lgkmcnt(6)
	v_mfma_f32_16x16x32_bf16 v[28:31], v[64:67], v[164:167], v[28:31]
	v_mfma_f32_16x16x32_bf16 v[16:19], v[68:71], v[164:167], v[16:19]
	ds_read_b128 v[72:75], v209 offset:32768
	ds_read_b128 v[76:79], v209 offset:34816
	ds_read_b128 v[192:195], v211 offset:49152
	s_waitcnt lgkmcnt(8)
	v_mfma_f32_16x16x32_bf16 v[60:63], v[64:67], v[168:171], v[60:63]
	v_mfma_f32_16x16x32_bf16 v[48:51], v[68:71], v[168:171], v[48:51]
	ds_read_b128 v[196:199], v211 offset:51200
	s_waitcnt lgkmcnt(8)
	v_mfma_f32_16x16x32_bf16 v[20:23], v[64:67], v[172:175], v[20:23]
	v_mfma_f32_16x16x32_bf16 v[0:3], v[68:71], v[172:175], v[0:3]
	ds_read_b128 v[200:203], v211 offset:53248
	s_waitcnt lgkmcnt(8)
	v_mfma_f32_16x16x32_bf16 v[44:47], v[64:67], v[176:179], v[44:47]
	v_mfma_f32_16x16x32_bf16 v[36:39], v[68:71], v[176:179], v[36:39]
	ds_read_b128 v[204:207], v211 offset:55296
	s_waitcnt lgkmcnt(8)
	v_mfma_f32_16x16x32_bf16 v[24:27], v[64:67], v[180:183], v[24:27]
	v_mfma_f32_16x16x32_bf16 v[8:11], v[68:71], v[180:183], v[8:11]
	ds_read_b128 v[160:163], v211 offset:57344
	s_waitcnt lgkmcnt(8)
	v_mfma_f32_16x16x32_bf16 v[56:59], v[64:67], v[184:187], v[56:59]
	v_mfma_f32_16x16x32_bf16 v[32:35], v[68:71], v[184:187], v[32:35]
	ds_read_b128 v[164:167], v211 offset:59392
	s_waitcnt lgkmcnt(8)
	v_mfma_f32_16x16x32_bf16 v[12:15], v[64:67], v[188:191], v[12:15]
	v_mfma_f32_16x16x32_bf16 v[4:7], v[68:71], v[188:191], v[4:7]
	ds_read_b128 v[168:171], v211 offset:61440
	s_waitcnt lgkmcnt(6)
	v_mfma_f32_16x16x32_bf16 v[40:43], v[72:75], v[192:195], v[40:43]
	v_mfma_f32_16x16x32_bf16 v[52:55], v[76:79], v[192:195], v[52:55]
	ds_read_b128 v[172:175], v211 offset:63488
	s_waitcnt vmcnt(0) lgkmcnt(0)
	s_barrier
	s_add_u32 m0, s38, 32768
	s_nop 0
	global_load_lds_dwordx4 v212, s[98:99]
	s_waitcnt lgkmcnt(6)
	v_mfma_f32_16x16x32_bf16 v[28:31], v[72:75], v[196:199], v[28:31]
	v_mfma_f32_16x16x32_bf16 v[16:19], v[76:79], v[196:199], v[16:19]
	ds_read_b128 v[64:67], v208 offset:0
	ds_read_b128 v[68:71], v208 offset:2048
	ds_read_b128 v[176:179], v210 offset:16384
	s_add_u32 m0, s38, 36864
	s_nop 0
	global_load_lds_dwordx4 v213, s[98:99]
	s_waitcnt lgkmcnt(8)
	v_mfma_f32_16x16x32_bf16 v[60:63], v[72:75], v[200:203], v[60:63]
	v_mfma_f32_16x16x32_bf16 v[48:51], v[76:79], v[200:203], v[48:51]
	ds_read_b128 v[180:183], v210 offset:18432
	s_add_u32 m0, s38, 40960
	s_nop 0
	global_load_lds_dwordx4 v214, s[98:99]
	s_waitcnt lgkmcnt(8)
	v_mfma_f32_16x16x32_bf16 v[20:23], v[72:75], v[204:207], v[20:23]
	v_mfma_f32_16x16x32_bf16 v[0:3], v[76:79], v[204:207], v[0:3]
	ds_read_b128 v[184:187], v210 offset:20480
	s_add_u32 m0, s38, 45056
	s_nop 0
	global_load_lds_dwordx4 v215, s[98:99]
	s_add_u32 s98, s98, 128
	s_addc_u32 s99, s99, 0
	s_waitcnt lgkmcnt(8)
	v_mfma_f32_16x16x32_bf16 v[44:47], v[72:75], v[160:163], v[44:47]
	v_mfma_f32_16x16x32_bf16 v[36:39], v[76:79], v[160:163], v[36:39]
	ds_read_b128 v[188:191], v210 offset:22528
	s_add_u32 m0, s38, 49152
	s_nop 0
	global_load_lds_dwordx4 v212, s[100:101]
	s_waitcnt lgkmcnt(8)
	v_mfma_f32_16x16x32_bf16 v[24:27], v[72:75], v[164:167], v[24:27]
	v_mfma_f32_16x16x32_bf16 v[8:11], v[76:79], v[164:167], v[8:11]
	ds_read_b128 v[192:195], v210 offset:24576
	s_add_u32 m0, s38, 53248
	s_nop 0
	global_load_lds_dwordx4 v213, s[100:101]
	s_waitcnt lgkmcnt(8)
	v_mfma_f32_16x16x32_bf16 v[56:59], v[72:75], v[168:171], v[56:59]
	v_mfma_f32_16x16x32_bf16 v[32:35], v[76:79], v[168:171], v[32:35]
	ds_read_b128 v[196:199], v210 offset:26624
	s_add_u32 m0, s38, 57344
	s_nop 0
	global_load_lds_dwordx4 v214, s[100:101]
	s_waitcnt lgkmcnt(8)
	v_mfma_f32_16x16x32_bf16 v[12:15], v[72:75], v[172:175], v[12:15]
	v_mfma_f32_16x16x32_bf16 v[4:7], v[76:79], v[172:175], v[4:7]
	ds_read_b128 v[200:203], v210 offset:28672
	s_add_u32 m0, s38, 61440
	s_nop 0
	global_load_lds_dwordx4 v215, s[100:101]
	s_add_u32 s100, s100, 128
	s_addc_u32 s101, s101, 0
	s_waitcnt lgkmcnt(6)
	v_mfma_f32_16x16x32_bf16 v[40:43], v[64:67], v[176:179], v[40:43]
	v_mfma_f32_16x16x32_bf16 v[52:55], v[68:71], v[176:179], v[52:55]
	ds_read_b128 v[204:207], v210 offset:30720
	s_waitcnt lgkmcnt(6)
	v_mfma_f32_16x16x32_bf16 v[28:31], v[64:67], v[180:183], v[28:31]
	v_mfma_f32_16x16x32_bf16 v[16:19], v[68:71], v[180:183], v[16:19]
	ds_read_b128 v[72:75], v209 offset:0
	ds_read_b128 v[76:79], v209 offset:2048
	ds_read_b128 v[160:163], v211 offset:16384
	s_waitcnt lgkmcnt(8)
	v_mfma_f32_16x16x32_bf16 v[60:63], v[64:67], v[184:187], v[60:63]
	v_mfma_f32_16x16x32_bf16 v[48:51], v[68:71], v[184:187], v[48:51]
	ds_read_b128 v[164:167], v211 offset:18432
	s_waitcnt lgkmcnt(8)
	v_mfma_f32_16x16x32_bf16 v[20:23], v[64:67], v[188:191], v[20:23]
	v_mfma_f32_16x16x32_bf16 v[0:3], v[68:71], v[188:191], v[0:3]
	ds_read_b128 v[168:171], v211 offset:20480
	s_waitcnt lgkmcnt(8)
	v_mfma_f32_16x16x32_bf16 v[44:47], v[64:67], v[192:195], v[44:47]
	v_mfma_f32_16x16x32_bf16 v[36:39], v[68:71], v[192:195], v[36:39]
	ds_read_b128 v[172:175], v211 offset:22528
	s_waitcnt lgkmcnt(8)
	v_mfma_f32_16x16x32_bf16 v[24:27], v[64:67], v[196:199], v[24:27]
	v_mfma_f32_16x16x32_bf16 v[8:11], v[68:71], v[196:199], v[8:11]
	ds_read_b128 v[176:179], v211 offset:24576
	s_waitcnt lgkmcnt(8)
	v_mfma_f32_16x16x32_bf16 v[56:59], v[64:67], v[200:203], v[56:59]
	v_mfma_f32_16x16x32_bf16 v[32:35], v[68:71], v[200:203], v[32:35]
	ds_read_b128 v[180:183], v211 offset:26624
	s_waitcnt lgkmcnt(8)
	v_mfma_f32_16x16x32_bf16 v[12:15], v[64:67], v[204:207], v[12:15]
	v_mfma_f32_16x16x32_bf16 v[4:7], v[68:71], v[204:207], v[4:7]
	ds_read_b128 v[184:187], v211 offset:28672
	s_waitcnt lgkmcnt(6)
	v_mfma_f32_16x16x32_bf16 v[40:43], v[72:75], v[160:163], v[40:43]
	v_mfma_f32_16x16x32_bf16 v[52:55], v[76:79], v[160:163], v[52:55]
	ds_read_b128 v[188:191], v211 offset:30720
	s_waitcnt vmcnt(0) lgkmcnt(0)
	s_barrier
	s_add_u32 m0, s38, 0
	s_nop 0
	global_load_lds_dwordx4 v212, s[98:99]
	s_waitcnt lgkmcnt(6)
	v_mfma_f32_16x16x32_bf16 v[28:31], v[72:75], v[164:167], v[28:31]
	v_mfma_f32_16x16x32_bf16 v[16:19], v[76:79], v[164:167], v[16:19]
	ds_read_b128 v[64:67], v208 offset:32768
	ds_read_b128 v[68:71], v208 offset:34816
	ds_read_b128 v[192:195], v210 offset:49152
	s_add_u32 m0, s38, 4096
	s_nop 0
	global_load_lds_dwordx4 v213, s[98:99]
	s_waitcnt lgkmcnt(8)
	v_mfma_f32_16x16x32_bf16 v[60:63], v[72:75], v[168:171], v[60:63]
	v_mfma_f32_16x16x32_bf16 v[48:51], v[76:79], v[168:171], v[48:51]
	ds_read_b128 v[196:199], v210 offset:51200
	s_add_u32 m0, s38, 8192
	s_nop 0
	global_load_lds_dwordx4 v214, s[98:99]
	s_waitcnt lgkmcnt(8)
	v_mfma_f32_16x16x32_bf16 v[20:23], v[72:75], v[172:175], v[20:23]
	v_mfma_f32_16x16x32_bf16 v[0:3], v[76:79], v[172:175], v[0:3]
	ds_read_b128 v[200:203], v210 offset:53248
	s_add_u32 m0, s38, 12288
	s_nop 0
	global_load_lds_dwordx4 v215, s[98:99]
	s_add_u32 s98, s98, 128
	s_addc_u32 s99, s99, 0
	s_waitcnt lgkmcnt(8)
	v_mfma_f32_16x16x32_bf16 v[44:47], v[72:75], v[176:179], v[44:47]
	v_mfma_f32_16x16x32_bf16 v[36:39], v[76:79], v[176:179], v[36:39]
	ds_read_b128 v[204:207], v210 offset:55296
	s_add_u32 m0, s38, 16384
	s_nop 0
	global_load_lds_dwordx4 v212, s[100:101]
	s_waitcnt lgkmcnt(8)
	v_mfma_f32_16x16x32_bf16 v[24:27], v[72:75], v[180:183], v[24:27]
	v_mfma_f32_16x16x32_bf16 v[8:11], v[76:79], v[180:183], v[8:11]
	ds_read_b128 v[160:163], v210 offset:57344
	s_add_u32 m0, s38, 20480
	s_nop 0
	global_load_lds_dwordx4 v213, s[100:101]
	s_waitcnt lgkmcnt(8)
	v_mfma_f32_16x16x32_bf16 v[56:59], v[72:75], v[184:187], v[56:59]
	v_mfma_f32_16x16x32_bf16 v[32:35], v[76:79], v[184:187], v[32:35]
	ds_read_b128 v[164:167], v210 offset:59392
	s_add_u32 m0, s38, 24576
	s_nop 0
	global_load_lds_dwordx4 v214, s[100:101]
	s_waitcnt lgkmcnt(8)
	v_mfma_f32_16x16x32_bf16 v[12:15], v[72:75], v[188:191], v[12:15]
	v_mfma_f32_16x16x32_bf16 v[4:7], v[76:79], v[188:191], v[4:7]
	ds_read_b128 v[168:171], v210 offset:61440
	s_add_u32 m0, s38, 28672
	s_nop 0
	global_load_lds_dwordx4 v215, s[100:101]
	s_add_u32 s100, s100, 128
	s_addc_u32 s101, s101, 0
	s_waitcnt lgkmcnt(6)
	v_mfma_f32_16x16x32_bf16 v[40:43], v[64:67], v[192:195], v[40:43]
	v_mfma_f32_16x16x32_bf16 v[52:55], v[68:71], v[192:195], v[52:55]
	ds_read_b128 v[172:175], v210 offset:63488
	s_waitcnt lgkmcnt(6)
	v_mfma_f32_16x16x32_bf16 v[28:31], v[64:67], v[196:199], v[28:31]
	v_mfma_f32_16x16x32_bf16 v[16:19], v[68:71], v[196:199], v[16:19]
	ds_read_b128 v[72:75], v209 offset:32768
	ds_read_b128 v[76:79], v209 offset:34816
	ds_read_b128 v[176:179], v211 offset:49152
	s_waitcnt lgkmcnt(8)
	v_mfma_f32_16x16x32_bf16 v[60:63], v[64:67], v[200:203], v[60:63]
	v_mfma_f32_16x16x32_bf16 v[48:51], v[68:71], v[200:203], v[48:51]
	ds_read_b128 v[180:183], v211 offset:51200
	s_waitcnt lgkmcnt(8)
	v_mfma_f32_16x16x32_bf16 v[20:23], v[64:67], v[204:207], v[20:23]
	v_mfma_f32_16x16x32_bf16 v[0:3], v[68:71], v[204:207], v[0:3]
	ds_read_b128 v[184:187], v211 offset:53248
	s_waitcnt lgkmcnt(8)
	v_mfma_f32_16x16x32_bf16 v[44:47], v[64:67], v[160:163], v[44:47]
	v_mfma_f32_16x16x32_bf16 v[36:39], v[68:71], v[160:163], v[36:39]
	ds_read_b128 v[188:191], v211 offset:55296
	s_waitcnt lgkmcnt(8)
	v_mfma_f32_16x16x32_bf16 v[24:27], v[64:67], v[164:167], v[24:27]
	v_mfma_f32_16x16x32_bf16 v[8:11], v[68:71], v[164:167], v[8:11]
	ds_read_b128 v[192:195], v211 offset:57344
	s_waitcnt lgkmcnt(8)
	v_mfma_f32_16x16x32_bf16 v[56:59], v[64:67], v[168:171], v[56:59]
	v_mfma_f32_16x16x32_bf16 v[32:35], v[68:71], v[168:171], v[32:35]
	ds_read_b128 v[196:199], v211 offset:59392
	s_waitcnt lgkmcnt(8)
	v_mfma_f32_16x16x32_bf16 v[12:15], v[64:67], v[172:175], v[12:15]
	v_mfma_f32_16x16x32_bf16 v[4:7], v[68:71], v[172:175], v[4:7]
	ds_read_b128 v[200:203], v211 offset:61440
	s_waitcnt lgkmcnt(6)
	v_mfma_f32_16x16x32_bf16 v[40:43], v[72:75], v[176:179], v[40:43]
	v_mfma_f32_16x16x32_bf16 v[52:55], v[76:79], v[176:179], v[52:55]
	ds_read_b128 v[204:207], v211 offset:63488
	s_waitcnt vmcnt(0) lgkmcnt(0)
	s_barrier
	s_add_u32 m0, s38, 32768
	s_nop 0
	global_load_lds_dwordx4 v212, s[98:99]
	s_waitcnt lgkmcnt(6)
	v_mfma_f32_16x16x32_bf16 v[28:31], v[72:75], v[180:183], v[28:31]
	v_mfma_f32_16x16x32_bf16 v[16:19], v[76:79], v[180:183], v[16:19]
	ds_read_b128 v[64:67], v208 offset:0
	ds_read_b128 v[68:71], v208 offset:2048
	ds_read_b128 v[160:163], v210 offset:16384
	s_add_u32 m0, s38, 36864
	s_nop 0
	global_load_lds_dwordx4 v213, s[98:99]
	s_waitcnt lgkmcnt(8)
	v_mfma_f32_16x16x32_bf16 v[60:63], v[72:75], v[184:187], v[60:63]
	v_mfma_f32_16x16x32_bf16 v[48:51], v[76:79], v[184:187], v[48:51]
	ds_read_b128 v[164:167], v210 offset:18432
	s_add_u32 m0, s38, 40960
	s_nop 0
	global_load_lds_dwordx4 v214, s[98:99]
	s_waitcnt lgkmcnt(8)
	v_mfma_f32_16x16x32_bf16 v[20:23], v[72:75], v[188:191], v[20:23]
	v_mfma_f32_16x16x32_bf16 v[0:3], v[76:79], v[188:191], v[0:3]
	ds_read_b128 v[168:171], v210 offset:20480
	s_add_u32 m0, s38, 45056
	s_nop 0
	global_load_lds_dwordx4 v215, s[98:99]
	s_add_u32 s98, s98, 128
	s_addc_u32 s99, s99, 0
	s_waitcnt lgkmcnt(8)
	v_mfma_f32_16x16x32_bf16 v[44:47], v[72:75], v[192:195], v[44:47]
	v_mfma_f32_16x16x32_bf16 v[36:39], v[76:79], v[192:195], v[36:39]
	ds_read_b128 v[172:175], v210 offset:22528
	s_add_u32 m0, s38, 49152
	s_nop 0
	global_load_lds_dwordx4 v212, s[100:101]
	s_waitcnt lgkmcnt(8)
	v_mfma_f32_16x16x32_bf16 v[24:27], v[72:75], v[196:199], v[24:27]
	v_mfma_f32_16x16x32_bf16 v[8:11], v[76:79], v[196:199], v[8:11]
	ds_read_b128 v[176:179], v210 offset:24576
	s_add_u32 m0, s38, 53248
	s_nop 0
	global_load_lds_dwordx4 v213, s[100:101]
	s_waitcnt lgkmcnt(8)
	v_mfma_f32_16x16x32_bf16 v[56:59], v[72:75], v[200:203], v[56:59]
	v_mfma_f32_16x16x32_bf16 v[32:35], v[76:79], v[200:203], v[32:35]
	ds_read_b128 v[180:183], v210 offset:26624
	s_add_u32 m0, s38, 57344
	s_nop 0
	global_load_lds_dwordx4 v214, s[100:101]
	s_waitcnt lgkmcnt(8)
	v_mfma_f32_16x16x32_bf16 v[12:15], v[72:75], v[204:207], v[12:15]
	v_mfma_f32_16x16x32_bf16 v[4:7], v[76:79], v[204:207], v[4:7]
	ds_read_b128 v[184:187], v210 offset:28672
	s_add_u32 m0, s38, 61440
	s_nop 0
	global_load_lds_dwordx4 v215, s[100:101]
	s_add_u32 s100, s100, 128
	s_addc_u32 s101, s101, 0
	s_waitcnt lgkmcnt(6)
	v_mfma_f32_16x16x32_bf16 v[40:43], v[64:67], v[160:163], v[40:43]
	v_mfma_f32_16x16x32_bf16 v[52:55], v[68:71], v[160:163], v[52:55]
	ds_read_b128 v[188:191], v210 offset:30720
	s_waitcnt lgkmcnt(6)
	v_mfma_f32_16x16x32_bf16 v[28:31], v[64:67], v[164:167], v[28:31]
	v_mfma_f32_16x16x32_bf16 v[16:19], v[68:71], v[164:167], v[16:19]
	ds_read_b128 v[72:75], v209 offset:0
	ds_read_b128 v[76:79], v209 offset:2048
	ds_read_b128 v[192:195], v211 offset:16384
	s_waitcnt lgkmcnt(8)
	v_mfma_f32_16x16x32_bf16 v[60:63], v[64:67], v[168:171], v[60:63]
	v_mfma_f32_16x16x32_bf16 v[48:51], v[68:71], v[168:171], v[48:51]
	ds_read_b128 v[196:199], v211 offset:18432
	s_waitcnt lgkmcnt(8)
	v_mfma_f32_16x16x32_bf16 v[20:23], v[64:67], v[172:175], v[20:23]
	v_mfma_f32_16x16x32_bf16 v[0:3], v[68:71], v[172:175], v[0:3]
	ds_read_b128 v[200:203], v211 offset:20480
	s_waitcnt lgkmcnt(8)
	v_mfma_f32_16x16x32_bf16 v[44:47], v[64:67], v[176:179], v[44:47]
	v_mfma_f32_16x16x32_bf16 v[36:39], v[68:71], v[176:179], v[36:39]
	ds_read_b128 v[204:207], v211 offset:22528
	s_waitcnt lgkmcnt(8)
	v_mfma_f32_16x16x32_bf16 v[24:27], v[64:67], v[180:183], v[24:27]
	v_mfma_f32_16x16x32_bf16 v[8:11], v[68:71], v[180:183], v[8:11]
	ds_read_b128 v[160:163], v211 offset:24576
	s_waitcnt lgkmcnt(8)
	v_mfma_f32_16x16x32_bf16 v[56:59], v[64:67], v[184:187], v[56:59]
	v_mfma_f32_16x16x32_bf16 v[32:35], v[68:71], v[184:187], v[32:35]
	ds_read_b128 v[164:167], v211 offset:26624
	s_waitcnt lgkmcnt(8)
	v_mfma_f32_16x16x32_bf16 v[12:15], v[64:67], v[188:191], v[12:15]
	v_mfma_f32_16x16x32_bf16 v[4:7], v[68:71], v[188:191], v[4:7]
	ds_read_b128 v[168:171], v211 offset:28672
	s_waitcnt lgkmcnt(6)
	v_mfma_f32_16x16x32_bf16 v[40:43], v[72:75], v[192:195], v[40:43]
	v_mfma_f32_16x16x32_bf16 v[52:55], v[76:79], v[192:195], v[52:55]
	ds_read_b128 v[172:175], v211 offset:30720
	s_waitcnt vmcnt(0) lgkmcnt(0)
	s_barrier
	s_add_u32 m0, s38, 0
	s_nop 0
	global_load_lds_dwordx4 v212, s[98:99]
	s_waitcnt lgkmcnt(6)
	v_mfma_f32_16x16x32_bf16 v[28:31], v[72:75], v[196:199], v[28:31]
	v_mfma_f32_16x16x32_bf16 v[16:19], v[76:79], v[196:199], v[16:19]
	ds_read_b128 v[64:67], v208 offset:32768
	ds_read_b128 v[68:71], v208 offset:34816
	ds_read_b128 v[176:179], v210 offset:49152
	s_add_u32 m0, s38, 4096
	s_nop 0
	global_load_lds_dwordx4 v213, s[98:99]
	s_waitcnt lgkmcnt(8)
	v_mfma_f32_16x16x32_bf16 v[60:63], v[72:75], v[200:203], v[60:63]
	v_mfma_f32_16x16x32_bf16 v[48:51], v[76:79], v[200:203], v[48:51]
	ds_read_b128 v[180:183], v210 offset:51200
	s_add_u32 m0, s38, 8192
	s_nop 0
	global_load_lds_dwordx4 v214, s[98:99]
	s_waitcnt lgkmcnt(8)
	v_mfma_f32_16x16x32_bf16 v[20:23], v[72:75], v[204:207], v[20:23]
	v_mfma_f32_16x16x32_bf16 v[0:3], v[76:79], v[204:207], v[0:3]
	ds_read_b128 v[184:187], v210 offset:53248
	s_add_u32 m0, s38, 12288
	s_nop 0
	global_load_lds_dwordx4 v215, s[98:99]
	s_add_u32 s98, s98, 128
	s_addc_u32 s99, s99, 0
	s_waitcnt lgkmcnt(8)
	v_mfma_f32_16x16x32_bf16 v[44:47], v[72:75], v[160:163], v[44:47]
	v_mfma_f32_16x16x32_bf16 v[36:39], v[76:79], v[160:163], v[36:39]
	ds_read_b128 v[188:191], v210 offset:55296
	s_add_u32 m0, s38, 16384
	s_nop 0
	global_load_lds_dwordx4 v212, s[100:101]
	s_waitcnt lgkmcnt(8)
	v_mfma_f32_16x16x32_bf16 v[24:27], v[72:75], v[164:167], v[24:27]
	v_mfma_f32_16x16x32_bf16 v[8:11], v[76:79], v[164:167], v[8:11]
	ds_read_b128 v[192:195], v210 offset:57344
	s_add_u32 m0, s38, 20480
	s_nop 0
	global_load_lds_dwordx4 v213, s[100:101]
	s_waitcnt lgkmcnt(8)
	v_mfma_f32_16x16x32_bf16 v[56:59], v[72:75], v[168:171], v[56:59]
	v_mfma_f32_16x16x32_bf16 v[32:35], v[76:79], v[168:171], v[32:35]
	ds_read_b128 v[196:199], v210 offset:59392
	s_add_u32 m0, s38, 24576
	s_nop 0
	global_load_lds_dwordx4 v214, s[100:101]
	s_waitcnt lgkmcnt(8)
	v_mfma_f32_16x16x32_bf16 v[12:15], v[72:75], v[172:175], v[12:15]
	v_mfma_f32_16x16x32_bf16 v[4:7], v[76:79], v[172:175], v[4:7]
	ds_read_b128 v[200:203], v210 offset:61440
	s_add_u32 m0, s38, 28672
	s_nop 0
	global_load_lds_dwordx4 v215, s[100:101]
	s_add_u32 s100, s100, 128
	s_addc_u32 s101, s101, 0
	s_waitcnt lgkmcnt(6)
	v_mfma_f32_16x16x32_bf16 v[40:43], v[64:67], v[176:179], v[40:43]
	v_mfma_f32_16x16x32_bf16 v[52:55], v[68:71], v[176:179], v[52:55]
	ds_read_b128 v[204:207], v210 offset:63488
	s_waitcnt lgkmcnt(6)
	v_mfma_f32_16x16x32_bf16 v[28:31], v[64:67], v[180:183], v[28:31]
	v_mfma_f32_16x16x32_bf16 v[16:19], v[68:71], v[180:183], v[16:19]
	ds_read_b128 v[72:75], v209 offset:32768
	ds_read_b128 v[76:79], v209 offset:34816
	ds_read_b128 v[160:163], v211 offset:49152
	s_waitcnt lgkmcnt(8)
	v_mfma_f32_16x16x32_bf16 v[60:63], v[64:67], v[184:187], v[60:63]
	v_mfma_f32_16x16x32_bf16 v[48:51], v[68:71], v[184:187], v[48:51]
	ds_read_b128 v[164:167], v211 offset:51200
	s_waitcnt lgkmcnt(8)
	v_mfma_f32_16x16x32_bf16 v[20:23], v[64:67], v[188:191], v[20:23]
	v_mfma_f32_16x16x32_bf16 v[0:3], v[68:71], v[188:191], v[0:3]
	ds_read_b128 v[168:171], v211 offset:53248
	s_waitcnt lgkmcnt(8)
	v_mfma_f32_16x16x32_bf16 v[44:47], v[64:67], v[192:195], v[44:47]
	v_mfma_f32_16x16x32_bf16 v[36:39], v[68:71], v[192:195], v[36:39]
	ds_read_b128 v[172:175], v211 offset:55296
	s_waitcnt lgkmcnt(8)
	v_mfma_f32_16x16x32_bf16 v[24:27], v[64:67], v[196:199], v[24:27]
	v_mfma_f32_16x16x32_bf16 v[8:11], v[68:71], v[196:199], v[8:11]
	ds_read_b128 v[176:179], v211 offset:57344
	s_waitcnt lgkmcnt(8)
	v_mfma_f32_16x16x32_bf16 v[56:59], v[64:67], v[200:203], v[56:59]
	v_mfma_f32_16x16x32_bf16 v[32:35], v[68:71], v[200:203], v[32:35]
	ds_read_b128 v[180:183], v211 offset:59392
	s_waitcnt lgkmcnt(8)
	v_mfma_f32_16x16x32_bf16 v[12:15], v[64:67], v[204:207], v[12:15]
	v_mfma_f32_16x16x32_bf16 v[4:7], v[68:71], v[204:207], v[4:7]
	ds_read_b128 v[184:187], v211 offset:61440
	s_waitcnt lgkmcnt(6)
	v_mfma_f32_16x16x32_bf16 v[40:43], v[72:75], v[160:163], v[40:43]
	v_mfma_f32_16x16x32_bf16 v[52:55], v[76:79], v[160:163], v[52:55]
	ds_read_b128 v[188:191], v211 offset:63488
	s_waitcnt vmcnt(0) lgkmcnt(0)
	s_barrier
	s_add_u32 m0, s38, 32768
	s_nop 0
	global_load_lds_dwordx4 v212, s[98:99]
	s_waitcnt lgkmcnt(6)
	v_mfma_f32_16x16x32_bf16 v[28:31], v[72:75], v[164:167], v[28:31]
	v_mfma_f32_16x16x32_bf16 v[16:19], v[76:79], v[164:167], v[16:19]
	ds_read_b128 v[64:67], v208 offset:0
	ds_read_b128 v[68:71], v208 offset:2048
	ds_read_b128 v[192:195], v210 offset:16384
	s_add_u32 m0, s38, 36864
	s_nop 0
	global_load_lds_dwordx4 v213, s[98:99]
	s_waitcnt lgkmcnt(8)
	v_mfma_f32_16x16x32_bf16 v[60:63], v[72:75], v[168:171], v[60:63]
	v_mfma_f32_16x16x32_bf16 v[48:51], v[76:79], v[168:171], v[48:51]
	ds_read_b128 v[196:199], v210 offset:18432
	s_add_u32 m0, s38, 40960
	s_nop 0
	global_load_lds_dwordx4 v214, s[98:99]
	s_waitcnt lgkmcnt(8)
	v_mfma_f32_16x16x32_bf16 v[20:23], v[72:75], v[172:175], v[20:23]
	v_mfma_f32_16x16x32_bf16 v[0:3], v[76:79], v[172:175], v[0:3]
	ds_read_b128 v[200:203], v210 offset:20480
	s_add_u32 m0, s38, 45056
	s_nop 0
	global_load_lds_dwordx4 v215, s[98:99]
	s_add_u32 s98, s98, 128
	s_addc_u32 s99, s99, 0
	s_waitcnt lgkmcnt(8)
	v_mfma_f32_16x16x32_bf16 v[44:47], v[72:75], v[176:179], v[44:47]
	v_mfma_f32_16x16x32_bf16 v[36:39], v[76:79], v[176:179], v[36:39]
	ds_read_b128 v[204:207], v210 offset:22528
	s_add_u32 m0, s38, 49152
	s_nop 0
	global_load_lds_dwordx4 v212, s[100:101]
	s_waitcnt lgkmcnt(8)
	v_mfma_f32_16x16x32_bf16 v[24:27], v[72:75], v[180:183], v[24:27]
	v_mfma_f32_16x16x32_bf16 v[8:11], v[76:79], v[180:183], v[8:11]
	ds_read_b128 v[160:163], v210 offset:24576
	s_add_u32 m0, s38, 53248
	s_nop 0
	global_load_lds_dwordx4 v213, s[100:101]
	s_waitcnt lgkmcnt(8)
	v_mfma_f32_16x16x32_bf16 v[56:59], v[72:75], v[184:187], v[56:59]
	v_mfma_f32_16x16x32_bf16 v[32:35], v[76:79], v[184:187], v[32:35]
	ds_read_b128 v[164:167], v210 offset:26624
	s_add_u32 m0, s38, 57344
	s_nop 0
	global_load_lds_dwordx4 v214, s[100:101]
	s_waitcnt lgkmcnt(8)
	v_mfma_f32_16x16x32_bf16 v[12:15], v[72:75], v[188:191], v[12:15]
	v_mfma_f32_16x16x32_bf16 v[4:7], v[76:79], v[188:191], v[4:7]
	ds_read_b128 v[168:171], v210 offset:28672
	s_add_u32 m0, s38, 61440
	s_nop 0
	global_load_lds_dwordx4 v215, s[100:101]
	s_add_u32 s100, s100, 128
	s_addc_u32 s101, s101, 0
	s_waitcnt lgkmcnt(6)
	v_mfma_f32_16x16x32_bf16 v[40:43], v[64:67], v[192:195], v[40:43]
	v_mfma_f32_16x16x32_bf16 v[52:55], v[68:71], v[192:195], v[52:55]
	ds_read_b128 v[172:175], v210 offset:30720
	s_waitcnt lgkmcnt(6)
	v_mfma_f32_16x16x32_bf16 v[28:31], v[64:67], v[196:199], v[28:31]
	v_mfma_f32_16x16x32_bf16 v[16:19], v[68:71], v[196:199], v[16:19]
	ds_read_b128 v[72:75], v209 offset:0
	ds_read_b128 v[76:79], v209 offset:2048
	ds_read_b128 v[176:179], v211 offset:16384
	s_waitcnt lgkmcnt(8)
	v_mfma_f32_16x16x32_bf16 v[60:63], v[64:67], v[200:203], v[60:63]
	v_mfma_f32_16x16x32_bf16 v[48:51], v[68:71], v[200:203], v[48:51]
	ds_read_b128 v[180:183], v211 offset:18432
	s_waitcnt lgkmcnt(8)
	v_mfma_f32_16x16x32_bf16 v[20:23], v[64:67], v[204:207], v[20:23]
	v_mfma_f32_16x16x32_bf16 v[0:3], v[68:71], v[204:207], v[0:3]
	ds_read_b128 v[184:187], v211 offset:20480
	s_waitcnt lgkmcnt(8)
	v_mfma_f32_16x16x32_bf16 v[44:47], v[64:67], v[160:163], v[44:47]
	v_mfma_f32_16x16x32_bf16 v[36:39], v[68:71], v[160:163], v[36:39]
	ds_read_b128 v[188:191], v211 offset:22528
	s_waitcnt lgkmcnt(8)
	v_mfma_f32_16x16x32_bf16 v[24:27], v[64:67], v[164:167], v[24:27]
	v_mfma_f32_16x16x32_bf16 v[8:11], v[68:71], v[164:167], v[8:11]
	ds_read_b128 v[192:195], v211 offset:24576
	s_waitcnt lgkmcnt(8)
	v_mfma_f32_16x16x32_bf16 v[56:59], v[64:67], v[168:171], v[56:59]
	v_mfma_f32_16x16x32_bf16 v[32:35], v[68:71], v[168:171], v[32:35]
	ds_read_b128 v[196:199], v211 offset:26624
	s_waitcnt lgkmcnt(8)
	v_mfma_f32_16x16x32_bf16 v[12:15], v[64:67], v[172:175], v[12:15]
	v_mfma_f32_16x16x32_bf16 v[4:7], v[68:71], v[172:175], v[4:7]
	ds_read_b128 v[200:203], v211 offset:28672
	s_waitcnt lgkmcnt(6)
	v_mfma_f32_16x16x32_bf16 v[40:43], v[72:75], v[176:179], v[40:43]
	v_mfma_f32_16x16x32_bf16 v[52:55], v[76:79], v[176:179], v[52:55]
	ds_read_b128 v[204:207], v211 offset:30720
	s_waitcnt vmcnt(0) lgkmcnt(0)
	s_barrier
	s_add_u32 m0, s38, 0
	s_nop 0
	global_load_lds_dwordx4 v212, s[98:99]
	s_waitcnt lgkmcnt(6)
	v_mfma_f32_16x16x32_bf16 v[28:31], v[72:75], v[180:183], v[28:31]
	v_mfma_f32_16x16x32_bf16 v[16:19], v[76:79], v[180:183], v[16:19]
	ds_read_b128 v[64:67], v208 offset:32768
	ds_read_b128 v[68:71], v208 offset:34816
	ds_read_b128 v[160:163], v210 offset:49152
	s_add_u32 m0, s38, 4096
	s_nop 0
	global_load_lds_dwordx4 v213, s[98:99]
	s_waitcnt lgkmcnt(8)
	v_mfma_f32_16x16x32_bf16 v[60:63], v[72:75], v[184:187], v[60:63]
	v_mfma_f32_16x16x32_bf16 v[48:51], v[76:79], v[184:187], v[48:51]
	ds_read_b128 v[164:167], v210 offset:51200
	s_add_u32 m0, s38, 8192
	s_nop 0
	global_load_lds_dwordx4 v214, s[98:99]
	s_waitcnt lgkmcnt(8)
	v_mfma_f32_16x16x32_bf16 v[20:23], v[72:75], v[188:191], v[20:23]
	v_mfma_f32_16x16x32_bf16 v[0:3], v[76:79], v[188:191], v[0:3]
	ds_read_b128 v[168:171], v210 offset:53248
	s_add_u32 m0, s38, 12288
	s_nop 0
	global_load_lds_dwordx4 v215, s[98:99]
	s_add_u32 s98, s98, 128
	s_addc_u32 s99, s99, 0
	s_waitcnt lgkmcnt(8)
	v_mfma_f32_16x16x32_bf16 v[44:47], v[72:75], v[192:195], v[44:47]
	v_mfma_f32_16x16x32_bf16 v[36:39], v[76:79], v[192:195], v[36:39]
	ds_read_b128 v[172:175], v210 offset:55296
	s_add_u32 m0, s38, 16384
	s_nop 0
	global_load_lds_dwordx4 v212, s[100:101]
	s_waitcnt lgkmcnt(8)
	v_mfma_f32_16x16x32_bf16 v[24:27], v[72:75], v[196:199], v[24:27]
	v_mfma_f32_16x16x32_bf16 v[8:11], v[76:79], v[196:199], v[8:11]
	ds_read_b128 v[176:179], v210 offset:57344
	s_add_u32 m0, s38, 20480
	s_nop 0
	global_load_lds_dwordx4 v213, s[100:101]
	s_waitcnt lgkmcnt(8)
	v_mfma_f32_16x16x32_bf16 v[56:59], v[72:75], v[200:203], v[56:59]
	v_mfma_f32_16x16x32_bf16 v[32:35], v[76:79], v[200:203], v[32:35]
	ds_read_b128 v[180:183], v210 offset:59392
	s_add_u32 m0, s38, 24576
	s_nop 0
	global_load_lds_dwordx4 v214, s[100:101]
	s_waitcnt lgkmcnt(8)
	v_mfma_f32_16x16x32_bf16 v[12:15], v[72:75], v[204:207], v[12:15]
	v_mfma_f32_16x16x32_bf16 v[4:7], v[76:79], v[204:207], v[4:7]
	ds_read_b128 v[184:187], v210 offset:61440
	s_add_u32 m0, s38, 28672
	s_nop 0
	global_load_lds_dwordx4 v215, s[100:101]
	s_add_u32 s100, s100, 128
	s_addc_u32 s101, s101, 0
	s_waitcnt lgkmcnt(6)
	v_mfma_f32_16x16x32_bf16 v[40:43], v[64:67], v[160:163], v[40:43]
	v_mfma_f32_16x16x32_bf16 v[52:55], v[68:71], v[160:163], v[52:55]
	ds_read_b128 v[188:191], v210 offset:63488
	s_waitcnt lgkmcnt(6)
	v_mfma_f32_16x16x32_bf16 v[28:31], v[64:67], v[164:167], v[28:31]
	v_mfma_f32_16x16x32_bf16 v[16:19], v[68:71], v[164:167], v[16:19]
	ds_read_b128 v[72:75], v209 offset:32768
	ds_read_b128 v[76:79], v209 offset:34816
	ds_read_b128 v[192:195], v211 offset:49152
	s_waitcnt lgkmcnt(8)
	v_mfma_f32_16x16x32_bf16 v[60:63], v[64:67], v[168:171], v[60:63]
	v_mfma_f32_16x16x32_bf16 v[48:51], v[68:71], v[168:171], v[48:51]
	ds_read_b128 v[196:199], v211 offset:51200
	s_waitcnt lgkmcnt(8)
	v_mfma_f32_16x16x32_bf16 v[20:23], v[64:67], v[172:175], v[20:23]
	v_mfma_f32_16x16x32_bf16 v[0:3], v[68:71], v[172:175], v[0:3]
	ds_read_b128 v[200:203], v211 offset:53248
	s_waitcnt lgkmcnt(8)
	v_mfma_f32_16x16x32_bf16 v[44:47], v[64:67], v[176:179], v[44:47]
	v_mfma_f32_16x16x32_bf16 v[36:39], v[68:71], v[176:179], v[36:39]
	ds_read_b128 v[204:207], v211 offset:55296
	s_waitcnt lgkmcnt(8)
	v_mfma_f32_16x16x32_bf16 v[24:27], v[64:67], v[180:183], v[24:27]
	v_mfma_f32_16x16x32_bf16 v[8:11], v[68:71], v[180:183], v[8:11]
	ds_read_b128 v[160:163], v211 offset:57344
	s_waitcnt lgkmcnt(8)
	v_mfma_f32_16x16x32_bf16 v[56:59], v[64:67], v[184:187], v[56:59]
	v_mfma_f32_16x16x32_bf16 v[32:35], v[68:71], v[184:187], v[32:35]
	ds_read_b128 v[164:167], v211 offset:59392
	s_waitcnt lgkmcnt(8)
	v_mfma_f32_16x16x32_bf16 v[12:15], v[64:67], v[188:191], v[12:15]
	v_mfma_f32_16x16x32_bf16 v[4:7], v[68:71], v[188:191], v[4:7]
	ds_read_b128 v[168:171], v211 offset:61440
	s_waitcnt lgkmcnt(6)
	v_mfma_f32_16x16x32_bf16 v[40:43], v[72:75], v[192:195], v[40:43]
	v_mfma_f32_16x16x32_bf16 v[52:55], v[76:79], v[192:195], v[52:55]
	ds_read_b128 v[172:175], v211 offset:63488
	s_waitcnt vmcnt(0) lgkmcnt(0)
	s_barrier
	s_add_u32 m0, s38, 32768
	s_nop 0
	global_load_lds_dwordx4 v212, s[98:99]
	s_waitcnt lgkmcnt(6)
	v_mfma_f32_16x16x32_bf16 v[28:31], v[72:75], v[196:199], v[28:31]
	v_mfma_f32_16x16x32_bf16 v[16:19], v[76:79], v[196:199], v[16:19]
	ds_read_b128 v[64:67], v208 offset:0
	ds_read_b128 v[68:71], v208 offset:2048
	ds_read_b128 v[176:179], v210 offset:16384
	s_add_u32 m0, s38, 36864
	s_nop 0
	global_load_lds_dwordx4 v213, s[98:99]
	s_waitcnt lgkmcnt(8)
	v_mfma_f32_16x16x32_bf16 v[60:63], v[72:75], v[200:203], v[60:63]
	v_mfma_f32_16x16x32_bf16 v[48:51], v[76:79], v[200:203], v[48:51]
	ds_read_b128 v[180:183], v210 offset:18432
	s_add_u32 m0, s38, 40960
	s_nop 0
	global_load_lds_dwordx4 v214, s[98:99]
	s_waitcnt lgkmcnt(8)
	v_mfma_f32_16x16x32_bf16 v[20:23], v[72:75], v[204:207], v[20:23]
	v_mfma_f32_16x16x32_bf16 v[0:3], v[76:79], v[204:207], v[0:3]
	ds_read_b128 v[184:187], v210 offset:20480
	s_add_u32 m0, s38, 45056
	s_nop 0
	global_load_lds_dwordx4 v215, s[98:99]
	s_add_u32 s98, s98, 128
	s_addc_u32 s99, s99, 0
	s_waitcnt lgkmcnt(8)
	v_mfma_f32_16x16x32_bf16 v[44:47], v[72:75], v[160:163], v[44:47]
	v_mfma_f32_16x16x32_bf16 v[36:39], v[76:79], v[160:163], v[36:39]
	ds_read_b128 v[188:191], v210 offset:22528
	s_add_u32 m0, s38, 49152
	s_nop 0
	global_load_lds_dwordx4 v212, s[100:101]
	s_waitcnt lgkmcnt(8)
	v_mfma_f32_16x16x32_bf16 v[24:27], v[72:75], v[164:167], v[24:27]
	v_mfma_f32_16x16x32_bf16 v[8:11], v[76:79], v[164:167], v[8:11]
	ds_read_b128 v[192:195], v210 offset:24576
	s_add_u32 m0, s38, 53248
	s_nop 0
	global_load_lds_dwordx4 v213, s[100:101]
	s_waitcnt lgkmcnt(8)
	v_mfma_f32_16x16x32_bf16 v[56:59], v[72:75], v[168:171], v[56:59]
	v_mfma_f32_16x16x32_bf16 v[32:35], v[76:79], v[168:171], v[32:35]
	ds_read_b128 v[196:199], v210 offset:26624
	s_add_u32 m0, s38, 57344
	s_nop 0
	global_load_lds_dwordx4 v214, s[100:101]
	s_waitcnt lgkmcnt(8)
	v_mfma_f32_16x16x32_bf16 v[12:15], v[72:75], v[172:175], v[12:15]
	v_mfma_f32_16x16x32_bf16 v[4:7], v[76:79], v[172:175], v[4:7]
	ds_read_b128 v[200:203], v210 offset:28672
	s_add_u32 m0, s38, 61440
	s_nop 0
	global_load_lds_dwordx4 v215, s[100:101]
	s_add_u32 s100, s100, 128
	s_addc_u32 s101, s101, 0
	s_waitcnt lgkmcnt(6)
	v_mfma_f32_16x16x32_bf16 v[40:43], v[64:67], v[176:179], v[40:43]
	v_mfma_f32_16x16x32_bf16 v[52:55], v[68:71], v[176:179], v[52:55]
	ds_read_b128 v[204:207], v210 offset:30720
	s_waitcnt lgkmcnt(6)
	v_mfma_f32_16x16x32_bf16 v[28:31], v[64:67], v[180:183], v[28:31]
	v_mfma_f32_16x16x32_bf16 v[16:19], v[68:71], v[180:183], v[16:19]
	ds_read_b128 v[72:75], v209 offset:0
	ds_read_b128 v[76:79], v209 offset:2048
	ds_read_b128 v[160:163], v211 offset:16384
	s_waitcnt lgkmcnt(8)
	v_mfma_f32_16x16x32_bf16 v[60:63], v[64:67], v[184:187], v[60:63]
	v_mfma_f32_16x16x32_bf16 v[48:51], v[68:71], v[184:187], v[48:51]
	ds_read_b128 v[164:167], v211 offset:18432
	s_waitcnt lgkmcnt(8)
	v_mfma_f32_16x16x32_bf16 v[20:23], v[64:67], v[188:191], v[20:23]
	v_mfma_f32_16x16x32_bf16 v[0:3], v[68:71], v[188:191], v[0:3]
	ds_read_b128 v[168:171], v211 offset:20480
	s_waitcnt lgkmcnt(8)
	v_mfma_f32_16x16x32_bf16 v[44:47], v[64:67], v[192:195], v[44:47]
	v_mfma_f32_16x16x32_bf16 v[36:39], v[68:71], v[192:195], v[36:39]
	ds_read_b128 v[172:175], v211 offset:22528
	s_waitcnt lgkmcnt(8)
	v_mfma_f32_16x16x32_bf16 v[24:27], v[64:67], v[196:199], v[24:27]
	v_mfma_f32_16x16x32_bf16 v[8:11], v[68:71], v[196:199], v[8:11]
	ds_read_b128 v[176:179], v211 offset:24576
	s_waitcnt lgkmcnt(8)
	v_mfma_f32_16x16x32_bf16 v[56:59], v[64:67], v[200:203], v[56:59]
	v_mfma_f32_16x16x32_bf16 v[32:35], v[68:71], v[200:203], v[32:35]
	ds_read_b128 v[180:183], v211 offset:26624
	s_waitcnt lgkmcnt(8)
	v_mfma_f32_16x16x32_bf16 v[12:15], v[64:67], v[204:207], v[12:15]
	v_mfma_f32_16x16x32_bf16 v[4:7], v[68:71], v[204:207], v[4:7]
	ds_read_b128 v[184:187], v211 offset:28672
	s_waitcnt lgkmcnt(6)
	v_mfma_f32_16x16x32_bf16 v[40:43], v[72:75], v[160:163], v[40:43]
	v_mfma_f32_16x16x32_bf16 v[52:55], v[76:79], v[160:163], v[52:55]
	ds_read_b128 v[188:191], v211 offset:30720
	s_waitcnt vmcnt(0) lgkmcnt(0)
	s_barrier
	s_add_u32 m0, s38, 0
	s_nop 0
	global_load_lds_dwordx4 v212, s[98:99]
	s_waitcnt lgkmcnt(6)
	v_mfma_f32_16x16x32_bf16 v[28:31], v[72:75], v[164:167], v[28:31]
	v_mfma_f32_16x16x32_bf16 v[16:19], v[76:79], v[164:167], v[16:19]
	ds_read_b128 v[64:67], v208 offset:32768
	ds_read_b128 v[68:71], v208 offset:34816
	ds_read_b128 v[192:195], v210 offset:49152
	s_add_u32 m0, s38, 4096
	s_nop 0
	global_load_lds_dwordx4 v213, s[98:99]
	s_waitcnt lgkmcnt(8)
	v_mfma_f32_16x16x32_bf16 v[60:63], v[72:75], v[168:171], v[60:63]
	v_mfma_f32_16x16x32_bf16 v[48:51], v[76:79], v[168:171], v[48:51]
	ds_read_b128 v[196:199], v210 offset:51200
	s_add_u32 m0, s38, 8192
	s_nop 0
	global_load_lds_dwordx4 v214, s[98:99]
	s_waitcnt lgkmcnt(8)
	v_mfma_f32_16x16x32_bf16 v[20:23], v[72:75], v[172:175], v[20:23]
	v_mfma_f32_16x16x32_bf16 v[0:3], v[76:79], v[172:175], v[0:3]
	ds_read_b128 v[200:203], v210 offset:53248
	s_add_u32 m0, s38, 12288
	s_nop 0
	global_load_lds_dwordx4 v215, s[98:99]
	s_add_u32 s98, s98, 128
	s_addc_u32 s99, s99, 0
	s_waitcnt lgkmcnt(8)
	v_mfma_f32_16x16x32_bf16 v[44:47], v[72:75], v[176:179], v[44:47]
	v_mfma_f32_16x16x32_bf16 v[36:39], v[76:79], v[176:179], v[36:39]
	ds_read_b128 v[204:207], v210 offset:55296
	s_add_u32 m0, s38, 16384
	s_nop 0
	global_load_lds_dwordx4 v212, s[100:101]
	s_waitcnt lgkmcnt(8)
	v_mfma_f32_16x16x32_bf16 v[24:27], v[72:75], v[180:183], v[24:27]
	v_mfma_f32_16x16x32_bf16 v[8:11], v[76:79], v[180:183], v[8:11]
	ds_read_b128 v[160:163], v210 offset:57344
	s_add_u32 m0, s38, 20480
	s_nop 0
	global_load_lds_dwordx4 v213, s[100:101]
	s_waitcnt lgkmcnt(8)
	v_mfma_f32_16x16x32_bf16 v[56:59], v[72:75], v[184:187], v[56:59]
	v_mfma_f32_16x16x32_bf16 v[32:35], v[76:79], v[184:187], v[32:35]
	ds_read_b128 v[164:167], v210 offset:59392
	s_add_u32 m0, s38, 24576
	s_nop 0
	global_load_lds_dwordx4 v214, s[100:101]
	s_waitcnt lgkmcnt(8)
	v_mfma_f32_16x16x32_bf16 v[12:15], v[72:75], v[188:191], v[12:15]
	v_mfma_f32_16x16x32_bf16 v[4:7], v[76:79], v[188:191], v[4:7]
	ds_read_b128 v[168:171], v210 offset:61440
	s_add_u32 m0, s38, 28672
	s_nop 0
	global_load_lds_dwordx4 v215, s[100:101]
	s_add_u32 s100, s100, 128
	s_addc_u32 s101, s101, 0
	s_waitcnt lgkmcnt(6)
	v_mfma_f32_16x16x32_bf16 v[40:43], v[64:67], v[192:195], v[40:43]
	v_mfma_f32_16x16x32_bf16 v[52:55], v[68:71], v[192:195], v[52:55]
	ds_read_b128 v[172:175], v210 offset:63488
	s_waitcnt lgkmcnt(6)
	v_mfma_f32_16x16x32_bf16 v[28:31], v[64:67], v[196:199], v[28:31]
	v_mfma_f32_16x16x32_bf16 v[16:19], v[68:71], v[196:199], v[16:19]
	ds_read_b128 v[72:75], v209 offset:32768
	ds_read_b128 v[76:79], v209 offset:34816
	ds_read_b128 v[176:179], v211 offset:49152
	s_waitcnt lgkmcnt(8)
	v_mfma_f32_16x16x32_bf16 v[60:63], v[64:67], v[200:203], v[60:63]
	v_mfma_f32_16x16x32_bf16 v[48:51], v[68:71], v[200:203], v[48:51]
	ds_read_b128 v[180:183], v211 offset:51200
	s_waitcnt lgkmcnt(8)
	v_mfma_f32_16x16x32_bf16 v[20:23], v[64:67], v[204:207], v[20:23]
	v_mfma_f32_16x16x32_bf16 v[0:3], v[68:71], v[204:207], v[0:3]
	ds_read_b128 v[184:187], v211 offset:53248
	s_waitcnt lgkmcnt(8)
	v_mfma_f32_16x16x32_bf16 v[44:47], v[64:67], v[160:163], v[44:47]
	v_mfma_f32_16x16x32_bf16 v[36:39], v[68:71], v[160:163], v[36:39]
	ds_read_b128 v[188:191], v211 offset:55296
	s_waitcnt lgkmcnt(8)
	v_mfma_f32_16x16x32_bf16 v[24:27], v[64:67], v[164:167], v[24:27]
	v_mfma_f32_16x16x32_bf16 v[8:11], v[68:71], v[164:167], v[8:11]
	ds_read_b128 v[192:195], v211 offset:57344
	s_waitcnt lgkmcnt(8)
	v_mfma_f32_16x16x32_bf16 v[56:59], v[64:67], v[168:171], v[56:59]
	v_mfma_f32_16x16x32_bf16 v[32:35], v[68:71], v[168:171], v[32:35]
	ds_read_b128 v[196:199], v211 offset:59392
	s_waitcnt lgkmcnt(8)
	v_mfma_f32_16x16x32_bf16 v[12:15], v[64:67], v[172:175], v[12:15]
	v_mfma_f32_16x16x32_bf16 v[4:7], v[68:71], v[172:175], v[4:7]
	ds_read_b128 v[200:203], v211 offset:61440
	s_waitcnt lgkmcnt(6)
	v_mfma_f32_16x16x32_bf16 v[40:43], v[72:75], v[176:179], v[40:43]
	v_mfma_f32_16x16x32_bf16 v[52:55], v[76:79], v[176:179], v[52:55]
	ds_read_b128 v[204:207], v211 offset:63488
	s_waitcnt vmcnt(0) lgkmcnt(0)
	s_barrier
	s_add_u32 m0, s38, 32768
	s_nop 0
	global_load_lds_dwordx4 v212, s[98:99]
	s_waitcnt lgkmcnt(6)
	v_mfma_f32_16x16x32_bf16 v[28:31], v[72:75], v[180:183], v[28:31]
	v_mfma_f32_16x16x32_bf16 v[16:19], v[76:79], v[180:183], v[16:19]
	ds_read_b128 v[64:67], v208 offset:0
	ds_read_b128 v[68:71], v208 offset:2048
	ds_read_b128 v[160:163], v210 offset:16384
	s_add_u32 m0, s38, 36864
	s_nop 0
	global_load_lds_dwordx4 v213, s[98:99]
	s_waitcnt lgkmcnt(8)
	v_mfma_f32_16x16x32_bf16 v[60:63], v[72:75], v[184:187], v[60:63]
	v_mfma_f32_16x16x32_bf16 v[48:51], v[76:79], v[184:187], v[48:51]
	ds_read_b128 v[164:167], v210 offset:18432
	s_add_u32 m0, s38, 40960
	s_nop 0
	global_load_lds_dwordx4 v214, s[98:99]
	s_waitcnt lgkmcnt(8)
	v_mfma_f32_16x16x32_bf16 v[20:23], v[72:75], v[188:191], v[20:23]
	v_mfma_f32_16x16x32_bf16 v[0:3], v[76:79], v[188:191], v[0:3]
	ds_read_b128 v[168:171], v210 offset:20480
	s_add_u32 m0, s38, 45056
	s_nop 0
	global_load_lds_dwordx4 v215, s[98:99]
	s_add_u32 s98, s98, 128
	s_addc_u32 s99, s99, 0
	s_waitcnt lgkmcnt(8)
	v_mfma_f32_16x16x32_bf16 v[44:47], v[72:75], v[192:195], v[44:47]
	v_mfma_f32_16x16x32_bf16 v[36:39], v[76:79], v[192:195], v[36:39]
	ds_read_b128 v[172:175], v210 offset:22528
	s_add_u32 m0, s38, 49152
	s_nop 0
	global_load_lds_dwordx4 v212, s[100:101]
	s_waitcnt lgkmcnt(8)
	v_mfma_f32_16x16x32_bf16 v[24:27], v[72:75], v[196:199], v[24:27]
	v_mfma_f32_16x16x32_bf16 v[8:11], v[76:79], v[196:199], v[8:11]
	ds_read_b128 v[176:179], v210 offset:24576
	s_add_u32 m0, s38, 53248
	s_nop 0
	global_load_lds_dwordx4 v213, s[100:101]
	s_waitcnt lgkmcnt(8)
	v_mfma_f32_16x16x32_bf16 v[56:59], v[72:75], v[200:203], v[56:59]
	v_mfma_f32_16x16x32_bf16 v[32:35], v[76:79], v[200:203], v[32:35]
	ds_read_b128 v[180:183], v210 offset:26624
	s_add_u32 m0, s38, 57344
	s_nop 0
	global_load_lds_dwordx4 v214, s[100:101]
	s_waitcnt lgkmcnt(8)
	v_mfma_f32_16x16x32_bf16 v[12:15], v[72:75], v[204:207], v[12:15]
	v_mfma_f32_16x16x32_bf16 v[4:7], v[76:79], v[204:207], v[4:7]
	ds_read_b128 v[184:187], v210 offset:28672
	s_add_u32 m0, s38, 61440
	s_nop 0
	global_load_lds_dwordx4 v215, s[100:101]
	s_add_u32 s100, s100, 128
	s_addc_u32 s101, s101, 0
	s_waitcnt lgkmcnt(6)
	v_mfma_f32_16x16x32_bf16 v[40:43], v[64:67], v[160:163], v[40:43]
	v_mfma_f32_16x16x32_bf16 v[52:55], v[68:71], v[160:163], v[52:55]
	ds_read_b128 v[188:191], v210 offset:30720
	s_waitcnt lgkmcnt(6)
	v_mfma_f32_16x16x32_bf16 v[28:31], v[64:67], v[164:167], v[28:31]
	v_mfma_f32_16x16x32_bf16 v[16:19], v[68:71], v[164:167], v[16:19]
	ds_read_b128 v[72:75], v209 offset:0
	ds_read_b128 v[76:79], v209 offset:2048
	ds_read_b128 v[192:195], v211 offset:16384
	s_waitcnt lgkmcnt(8)
	v_mfma_f32_16x16x32_bf16 v[60:63], v[64:67], v[168:171], v[60:63]
	v_mfma_f32_16x16x32_bf16 v[48:51], v[68:71], v[168:171], v[48:51]
	ds_read_b128 v[196:199], v211 offset:18432
	s_waitcnt lgkmcnt(8)
	v_mfma_f32_16x16x32_bf16 v[20:23], v[64:67], v[172:175], v[20:23]
	v_mfma_f32_16x16x32_bf16 v[0:3], v[68:71], v[172:175], v[0:3]
	ds_read_b128 v[200:203], v211 offset:20480
	s_waitcnt lgkmcnt(8)
	v_mfma_f32_16x16x32_bf16 v[44:47], v[64:67], v[176:179], v[44:47]
	v_mfma_f32_16x16x32_bf16 v[36:39], v[68:71], v[176:179], v[36:39]
	ds_read_b128 v[204:207], v211 offset:22528
	s_waitcnt lgkmcnt(8)
	v_mfma_f32_16x16x32_bf16 v[24:27], v[64:67], v[180:183], v[24:27]
	v_mfma_f32_16x16x32_bf16 v[8:11], v[68:71], v[180:183], v[8:11]
	ds_read_b128 v[160:163], v211 offset:24576
	s_waitcnt lgkmcnt(8)
	v_mfma_f32_16x16x32_bf16 v[56:59], v[64:67], v[184:187], v[56:59]
	v_mfma_f32_16x16x32_bf16 v[32:35], v[68:71], v[184:187], v[32:35]
	ds_read_b128 v[164:167], v211 offset:26624
	s_waitcnt lgkmcnt(8)
	v_mfma_f32_16x16x32_bf16 v[12:15], v[64:67], v[188:191], v[12:15]
	v_mfma_f32_16x16x32_bf16 v[4:7], v[68:71], v[188:191], v[4:7]
	ds_read_b128 v[168:171], v211 offset:28672
	s_waitcnt lgkmcnt(6)
	v_mfma_f32_16x16x32_bf16 v[40:43], v[72:75], v[192:195], v[40:43]
	v_mfma_f32_16x16x32_bf16 v[52:55], v[76:79], v[192:195], v[52:55]
	ds_read_b128 v[172:175], v211 offset:30720
	s_waitcnt vmcnt(0) lgkmcnt(0)
	s_barrier
	s_add_u32 m0, s38, 0
	s_nop 0
	global_load_lds_dwordx4 v212, s[98:99]
	s_waitcnt lgkmcnt(6)
	v_mfma_f32_16x16x32_bf16 v[28:31], v[72:75], v[196:199], v[28:31]
	v_mfma_f32_16x16x32_bf16 v[16:19], v[76:79], v[196:199], v[16:19]
	ds_read_b128 v[64:67], v208 offset:32768
	ds_read_b128 v[68:71], v208 offset:34816
	ds_read_b128 v[176:179], v210 offset:49152
	s_add_u32 m0, s38, 4096
	s_nop 0
	global_load_lds_dwordx4 v213, s[98:99]
	s_waitcnt lgkmcnt(8)
	v_mfma_f32_16x16x32_bf16 v[60:63], v[72:75], v[200:203], v[60:63]
	v_mfma_f32_16x16x32_bf16 v[48:51], v[76:79], v[200:203], v[48:51]
	ds_read_b128 v[180:183], v210 offset:51200
	s_add_u32 m0, s38, 8192
	s_nop 0
	global_load_lds_dwordx4 v214, s[98:99]
	s_waitcnt lgkmcnt(8)
	v_mfma_f32_16x16x32_bf16 v[20:23], v[72:75], v[204:207], v[20:23]
	v_mfma_f32_16x16x32_bf16 v[0:3], v[76:79], v[204:207], v[0:3]
	ds_read_b128 v[184:187], v210 offset:53248
	s_add_u32 m0, s38, 12288
	s_nop 0
	global_load_lds_dwordx4 v215, s[98:99]
	s_add_u32 s98, s98, 128
	s_addc_u32 s99, s99, 0
	s_waitcnt lgkmcnt(8)
	v_mfma_f32_16x16x32_bf16 v[44:47], v[72:75], v[160:163], v[44:47]
	v_mfma_f32_16x16x32_bf16 v[36:39], v[76:79], v[160:163], v[36:39]
	ds_read_b128 v[188:191], v210 offset:55296
	s_add_u32 m0, s38, 16384
	s_nop 0
	global_load_lds_dwordx4 v212, s[100:101]
	s_waitcnt lgkmcnt(8)
	v_mfma_f32_16x16x32_bf16 v[24:27], v[72:75], v[164:167], v[24:27]
	v_mfma_f32_16x16x32_bf16 v[8:11], v[76:79], v[164:167], v[8:11]
	ds_read_b128 v[192:195], v210 offset:57344
	s_add_u32 m0, s38, 20480
	s_nop 0
	global_load_lds_dwordx4 v213, s[100:101]
	s_waitcnt lgkmcnt(8)
	v_mfma_f32_16x16x32_bf16 v[56:59], v[72:75], v[168:171], v[56:59]
	v_mfma_f32_16x16x32_bf16 v[32:35], v[76:79], v[168:171], v[32:35]
	ds_read_b128 v[196:199], v210 offset:59392
	s_add_u32 m0, s38, 24576
	s_nop 0
	global_load_lds_dwordx4 v214, s[100:101]
	s_waitcnt lgkmcnt(8)
	v_mfma_f32_16x16x32_bf16 v[12:15], v[72:75], v[172:175], v[12:15]
	v_mfma_f32_16x16x32_bf16 v[4:7], v[76:79], v[172:175], v[4:7]
	ds_read_b128 v[200:203], v210 offset:61440
	s_add_u32 m0, s38, 28672
	s_nop 0
	global_load_lds_dwordx4 v215, s[100:101]
	s_add_u32 s100, s100, 128
	s_addc_u32 s101, s101, 0
	s_waitcnt lgkmcnt(6)
	v_mfma_f32_16x16x32_bf16 v[40:43], v[64:67], v[176:179], v[40:43]
	v_mfma_f32_16x16x32_bf16 v[52:55], v[68:71], v[176:179], v[52:55]
	ds_read_b128 v[204:207], v210 offset:63488
	s_waitcnt lgkmcnt(6)
	v_mfma_f32_16x16x32_bf16 v[28:31], v[64:67], v[180:183], v[28:31]
	v_mfma_f32_16x16x32_bf16 v[16:19], v[68:71], v[180:183], v[16:19]
	ds_read_b128 v[72:75], v209 offset:32768
	ds_read_b128 v[76:79], v209 offset:34816
	ds_read_b128 v[160:163], v211 offset:49152
	s_waitcnt lgkmcnt(8)
	v_mfma_f32_16x16x32_bf16 v[60:63], v[64:67], v[184:187], v[60:63]
	v_mfma_f32_16x16x32_bf16 v[48:51], v[68:71], v[184:187], v[48:51]
	ds_read_b128 v[164:167], v211 offset:51200
	s_waitcnt lgkmcnt(8)
	v_mfma_f32_16x16x32_bf16 v[20:23], v[64:67], v[188:191], v[20:23]
	v_mfma_f32_16x16x32_bf16 v[0:3], v[68:71], v[188:191], v[0:3]
	ds_read_b128 v[168:171], v211 offset:53248
	s_waitcnt lgkmcnt(8)
	v_mfma_f32_16x16x32_bf16 v[44:47], v[64:67], v[192:195], v[44:47]
	v_mfma_f32_16x16x32_bf16 v[36:39], v[68:71], v[192:195], v[36:39]
	ds_read_b128 v[172:175], v211 offset:55296
	s_waitcnt lgkmcnt(8)
	v_mfma_f32_16x16x32_bf16 v[24:27], v[64:67], v[196:199], v[24:27]
	v_mfma_f32_16x16x32_bf16 v[8:11], v[68:71], v[196:199], v[8:11]
	ds_read_b128 v[176:179], v211 offset:57344
	s_waitcnt lgkmcnt(8)
	v_mfma_f32_16x16x32_bf16 v[56:59], v[64:67], v[200:203], v[56:59]
	v_mfma_f32_16x16x32_bf16 v[32:35], v[68:71], v[200:203], v[32:35]
	ds_read_b128 v[180:183], v211 offset:59392
	s_waitcnt lgkmcnt(8)
	v_mfma_f32_16x16x32_bf16 v[12:15], v[64:67], v[204:207], v[12:15]
	v_mfma_f32_16x16x32_bf16 v[4:7], v[68:71], v[204:207], v[4:7]
	ds_read_b128 v[184:187], v211 offset:61440
	s_waitcnt lgkmcnt(6)
	v_mfma_f32_16x16x32_bf16 v[40:43], v[72:75], v[160:163], v[40:43]
	v_mfma_f32_16x16x32_bf16 v[52:55], v[76:79], v[160:163], v[52:55]
	ds_read_b128 v[188:191], v211 offset:63488
	s_waitcnt vmcnt(0) lgkmcnt(0)
	s_barrier
	s_add_u32 m0, s38, 32768
	s_nop 0
	global_load_lds_dwordx4 v212, s[98:99]
	s_waitcnt lgkmcnt(6)
	v_mfma_f32_16x16x32_bf16 v[28:31], v[72:75], v[164:167], v[28:31]
	v_mfma_f32_16x16x32_bf16 v[16:19], v[76:79], v[164:167], v[16:19]
	ds_read_b128 v[64:67], v208 offset:0
	ds_read_b128 v[68:71], v208 offset:2048
	ds_read_b128 v[192:195], v210 offset:16384
	s_add_u32 m0, s38, 36864
	s_nop 0
	global_load_lds_dwordx4 v213, s[98:99]
	s_waitcnt lgkmcnt(8)
	v_mfma_f32_16x16x32_bf16 v[60:63], v[72:75], v[168:171], v[60:63]
	v_mfma_f32_16x16x32_bf16 v[48:51], v[76:79], v[168:171], v[48:51]
	ds_read_b128 v[196:199], v210 offset:18432
	s_add_u32 m0, s38, 40960
	s_nop 0
	global_load_lds_dwordx4 v214, s[98:99]
	s_waitcnt lgkmcnt(8)
	v_mfma_f32_16x16x32_bf16 v[20:23], v[72:75], v[172:175], v[20:23]
	v_mfma_f32_16x16x32_bf16 v[0:3], v[76:79], v[172:175], v[0:3]
	ds_read_b128 v[200:203], v210 offset:20480
	s_add_u32 m0, s38, 45056
	s_nop 0
	global_load_lds_dwordx4 v215, s[98:99]
	s_add_u32 s98, s98, 128
	s_addc_u32 s99, s99, 0
	s_waitcnt lgkmcnt(8)
	v_mfma_f32_16x16x32_bf16 v[44:47], v[72:75], v[176:179], v[44:47]
	v_mfma_f32_16x16x32_bf16 v[36:39], v[76:79], v[176:179], v[36:39]
	ds_read_b128 v[204:207], v210 offset:22528
	s_add_u32 m0, s38, 49152
	s_nop 0
	global_load_lds_dwordx4 v212, s[100:101]
	s_waitcnt lgkmcnt(8)
	v_mfma_f32_16x16x32_bf16 v[24:27], v[72:75], v[180:183], v[24:27]
	v_mfma_f32_16x16x32_bf16 v[8:11], v[76:79], v[180:183], v[8:11]
	ds_read_b128 v[160:163], v210 offset:24576
	s_add_u32 m0, s38, 53248
	s_nop 0
	global_load_lds_dwordx4 v213, s[100:101]
	s_waitcnt lgkmcnt(8)
	v_mfma_f32_16x16x32_bf16 v[56:59], v[72:75], v[184:187], v[56:59]
	v_mfma_f32_16x16x32_bf16 v[32:35], v[76:79], v[184:187], v[32:35]
	ds_read_b128 v[164:167], v210 offset:26624
	s_add_u32 m0, s38, 57344
	s_nop 0
	global_load_lds_dwordx4 v214, s[100:101]
	s_waitcnt lgkmcnt(8)
	v_mfma_f32_16x16x32_bf16 v[12:15], v[72:75], v[188:191], v[12:15]
	v_mfma_f32_16x16x32_bf16 v[4:7], v[76:79], v[188:191], v[4:7]
	ds_read_b128 v[168:171], v210 offset:28672
	s_add_u32 m0, s38, 61440
	s_nop 0
	global_load_lds_dwordx4 v215, s[100:101]
	s_add_u32 s100, s100, 128
	s_addc_u32 s101, s101, 0
	s_waitcnt lgkmcnt(6)
	v_mfma_f32_16x16x32_bf16 v[40:43], v[64:67], v[192:195], v[40:43]
	v_mfma_f32_16x16x32_bf16 v[52:55], v[68:71], v[192:195], v[52:55]
	ds_read_b128 v[172:175], v210 offset:30720
	s_waitcnt lgkmcnt(6)
	v_mfma_f32_16x16x32_bf16 v[28:31], v[64:67], v[196:199], v[28:31]
	v_mfma_f32_16x16x32_bf16 v[16:19], v[68:71], v[196:199], v[16:19]
	ds_read_b128 v[72:75], v209 offset:0
	ds_read_b128 v[76:79], v209 offset:2048
	ds_read_b128 v[176:179], v211 offset:16384
	s_waitcnt lgkmcnt(8)
	v_mfma_f32_16x16x32_bf16 v[60:63], v[64:67], v[200:203], v[60:63]
	v_mfma_f32_16x16x32_bf16 v[48:51], v[68:71], v[200:203], v[48:51]
	ds_read_b128 v[180:183], v211 offset:18432
	s_waitcnt lgkmcnt(8)
	v_mfma_f32_16x16x32_bf16 v[20:23], v[64:67], v[204:207], v[20:23]
	v_mfma_f32_16x16x32_bf16 v[0:3], v[68:71], v[204:207], v[0:3]
	ds_read_b128 v[184:187], v211 offset:20480
	s_waitcnt lgkmcnt(8)
	v_mfma_f32_16x16x32_bf16 v[44:47], v[64:67], v[160:163], v[44:47]
	v_mfma_f32_16x16x32_bf16 v[36:39], v[68:71], v[160:163], v[36:39]
	ds_read_b128 v[188:191], v211 offset:22528
	s_waitcnt lgkmcnt(8)
	v_mfma_f32_16x16x32_bf16 v[24:27], v[64:67], v[164:167], v[24:27]
	v_mfma_f32_16x16x32_bf16 v[8:11], v[68:71], v[164:167], v[8:11]
	ds_read_b128 v[192:195], v211 offset:24576
	s_waitcnt lgkmcnt(8)
	v_mfma_f32_16x16x32_bf16 v[56:59], v[64:67], v[168:171], v[56:59]
	v_mfma_f32_16x16x32_bf16 v[32:35], v[68:71], v[168:171], v[32:35]
	ds_read_b128 v[196:199], v211 offset:26624
	s_waitcnt lgkmcnt(8)
	v_mfma_f32_16x16x32_bf16 v[12:15], v[64:67], v[172:175], v[12:15]
	v_mfma_f32_16x16x32_bf16 v[4:7], v[68:71], v[172:175], v[4:7]
	ds_read_b128 v[200:203], v211 offset:28672
	s_waitcnt lgkmcnt(6)
	v_mfma_f32_16x16x32_bf16 v[40:43], v[72:75], v[176:179], v[40:43]
	v_mfma_f32_16x16x32_bf16 v[52:55], v[76:79], v[176:179], v[52:55]
	ds_read_b128 v[204:207], v211 offset:30720
	s_waitcnt vmcnt(0) lgkmcnt(0)
	s_barrier
	s_add_u32 m0, s38, 0
	s_nop 0
	global_load_lds_dwordx4 v212, s[98:99]
	s_waitcnt lgkmcnt(6)
	v_mfma_f32_16x16x32_bf16 v[28:31], v[72:75], v[180:183], v[28:31]
	v_mfma_f32_16x16x32_bf16 v[16:19], v[76:79], v[180:183], v[16:19]
	ds_read_b128 v[64:67], v208 offset:32768
	ds_read_b128 v[68:71], v208 offset:34816
	ds_read_b128 v[160:163], v210 offset:49152
	s_add_u32 m0, s38, 4096
	s_nop 0
	global_load_lds_dwordx4 v213, s[98:99]
	s_waitcnt lgkmcnt(8)
	v_mfma_f32_16x16x32_bf16 v[60:63], v[72:75], v[184:187], v[60:63]
	v_mfma_f32_16x16x32_bf16 v[48:51], v[76:79], v[184:187], v[48:51]
	ds_read_b128 v[164:167], v210 offset:51200
	s_add_u32 m0, s38, 8192
	s_nop 0
	global_load_lds_dwordx4 v214, s[98:99]
	s_waitcnt lgkmcnt(8)
	v_mfma_f32_16x16x32_bf16 v[20:23], v[72:75], v[188:191], v[20:23]
	v_mfma_f32_16x16x32_bf16 v[0:3], v[76:79], v[188:191], v[0:3]
	ds_read_b128 v[168:171], v210 offset:53248
	s_add_u32 m0, s38, 12288
	s_nop 0
	global_load_lds_dwordx4 v215, s[98:99]
	s_add_u32 s98, s98, 128
	s_addc_u32 s99, s99, 0
	s_waitcnt lgkmcnt(8)
	v_mfma_f32_16x16x32_bf16 v[44:47], v[72:75], v[192:195], v[44:47]
	v_mfma_f32_16x16x32_bf16 v[36:39], v[76:79], v[192:195], v[36:39]
	ds_read_b128 v[172:175], v210 offset:55296
	s_add_u32 m0, s38, 16384
	s_nop 0
	global_load_lds_dwordx4 v212, s[100:101]
	s_waitcnt lgkmcnt(8)
	v_mfma_f32_16x16x32_bf16 v[24:27], v[72:75], v[196:199], v[24:27]
	v_mfma_f32_16x16x32_bf16 v[8:11], v[76:79], v[196:199], v[8:11]
	ds_read_b128 v[176:179], v210 offset:57344
	s_add_u32 m0, s38, 20480
	s_nop 0
	global_load_lds_dwordx4 v213, s[100:101]
	s_waitcnt lgkmcnt(8)
	v_mfma_f32_16x16x32_bf16 v[56:59], v[72:75], v[200:203], v[56:59]
	v_mfma_f32_16x16x32_bf16 v[32:35], v[76:79], v[200:203], v[32:35]
	ds_read_b128 v[180:183], v210 offset:59392
	s_add_u32 m0, s38, 24576
	s_nop 0
	global_load_lds_dwordx4 v214, s[100:101]
	s_waitcnt lgkmcnt(8)
	v_mfma_f32_16x16x32_bf16 v[12:15], v[72:75], v[204:207], v[12:15]
	v_mfma_f32_16x16x32_bf16 v[4:7], v[76:79], v[204:207], v[4:7]
	ds_read_b128 v[184:187], v210 offset:61440
	s_add_u32 m0, s38, 28672
	s_nop 0
	global_load_lds_dwordx4 v215, s[100:101]
	s_add_u32 s100, s100, 128
	s_addc_u32 s101, s101, 0
	s_waitcnt lgkmcnt(6)
	v_mfma_f32_16x16x32_bf16 v[40:43], v[64:67], v[160:163], v[40:43]
	v_mfma_f32_16x16x32_bf16 v[52:55], v[68:71], v[160:163], v[52:55]
	ds_read_b128 v[188:191], v210 offset:63488
	s_waitcnt lgkmcnt(6)
	v_mfma_f32_16x16x32_bf16 v[28:31], v[64:67], v[164:167], v[28:31]
	v_mfma_f32_16x16x32_bf16 v[16:19], v[68:71], v[164:167], v[16:19]
	ds_read_b128 v[72:75], v209 offset:32768
	ds_read_b128 v[76:79], v209 offset:34816
	ds_read_b128 v[192:195], v211 offset:49152
	s_waitcnt lgkmcnt(8)
	v_mfma_f32_16x16x32_bf16 v[60:63], v[64:67], v[168:171], v[60:63]
	v_mfma_f32_16x16x32_bf16 v[48:51], v[68:71], v[168:171], v[48:51]
	ds_read_b128 v[196:199], v211 offset:51200
	s_waitcnt lgkmcnt(8)
	v_mfma_f32_16x16x32_bf16 v[20:23], v[64:67], v[172:175], v[20:23]
	v_mfma_f32_16x16x32_bf16 v[0:3], v[68:71], v[172:175], v[0:3]
	ds_read_b128 v[200:203], v211 offset:53248
	s_waitcnt lgkmcnt(8)
	v_mfma_f32_16x16x32_bf16 v[44:47], v[64:67], v[176:179], v[44:47]
	v_mfma_f32_16x16x32_bf16 v[36:39], v[68:71], v[176:179], v[36:39]
	ds_read_b128 v[204:207], v211 offset:55296
	s_waitcnt lgkmcnt(8)
	v_mfma_f32_16x16x32_bf16 v[24:27], v[64:67], v[180:183], v[24:27]
	v_mfma_f32_16x16x32_bf16 v[8:11], v[68:71], v[180:183], v[8:11]
	ds_read_b128 v[160:163], v211 offset:57344
	s_waitcnt lgkmcnt(8)
	v_mfma_f32_16x16x32_bf16 v[56:59], v[64:67], v[184:187], v[56:59]
	v_mfma_f32_16x16x32_bf16 v[32:35], v[68:71], v[184:187], v[32:35]
	ds_read_b128 v[164:167], v211 offset:59392
	s_waitcnt lgkmcnt(8)
	v_mfma_f32_16x16x32_bf16 v[12:15], v[64:67], v[188:191], v[12:15]
	v_mfma_f32_16x16x32_bf16 v[4:7], v[68:71], v[188:191], v[4:7]
	ds_read_b128 v[168:171], v211 offset:61440
	s_waitcnt lgkmcnt(6)
	v_mfma_f32_16x16x32_bf16 v[40:43], v[72:75], v[192:195], v[40:43]
	v_mfma_f32_16x16x32_bf16 v[52:55], v[76:79], v[192:195], v[52:55]
	ds_read_b128 v[172:175], v211 offset:63488
	s_waitcnt vmcnt(0) lgkmcnt(0)
	s_barrier
	s_add_u32 m0, s38, 32768
	s_nop 0
	global_load_lds_dwordx4 v212, s[98:99]
	s_waitcnt lgkmcnt(6)
	v_mfma_f32_16x16x32_bf16 v[28:31], v[72:75], v[196:199], v[28:31]
	v_mfma_f32_16x16x32_bf16 v[16:19], v[76:79], v[196:199], v[16:19]
	ds_read_b128 v[64:67], v208 offset:0
	ds_read_b128 v[68:71], v208 offset:2048
	ds_read_b128 v[176:179], v210 offset:16384
	s_add_u32 m0, s38, 36864
	s_nop 0
	global_load_lds_dwordx4 v213, s[98:99]
	s_waitcnt lgkmcnt(8)
	v_mfma_f32_16x16x32_bf16 v[60:63], v[72:75], v[200:203], v[60:63]
	v_mfma_f32_16x16x32_bf16 v[48:51], v[76:79], v[200:203], v[48:51]
	ds_read_b128 v[180:183], v210 offset:18432
	s_add_u32 m0, s38, 40960
	s_nop 0
	global_load_lds_dwordx4 v214, s[98:99]
	s_waitcnt lgkmcnt(8)
	v_mfma_f32_16x16x32_bf16 v[20:23], v[72:75], v[204:207], v[20:23]
	v_mfma_f32_16x16x32_bf16 v[0:3], v[76:79], v[204:207], v[0:3]
	ds_read_b128 v[184:187], v210 offset:20480
	s_add_u32 m0, s38, 45056
	s_nop 0
	global_load_lds_dwordx4 v215, s[98:99]
	s_add_u32 s98, s98, 128
	s_addc_u32 s99, s99, 0
	s_waitcnt lgkmcnt(8)
	v_mfma_f32_16x16x32_bf16 v[44:47], v[72:75], v[160:163], v[44:47]
	v_mfma_f32_16x16x32_bf16 v[36:39], v[76:79], v[160:163], v[36:39]
	ds_read_b128 v[188:191], v210 offset:22528
	s_add_u32 m0, s38, 49152
	s_nop 0
	global_load_lds_dwordx4 v212, s[100:101]
	s_waitcnt lgkmcnt(8)
	v_mfma_f32_16x16x32_bf16 v[24:27], v[72:75], v[164:167], v[24:27]
	v_mfma_f32_16x16x32_bf16 v[8:11], v[76:79], v[164:167], v[8:11]
	ds_read_b128 v[192:195], v210 offset:24576
	s_add_u32 m0, s38, 53248
	s_nop 0
	global_load_lds_dwordx4 v213, s[100:101]
	s_waitcnt lgkmcnt(8)
	v_mfma_f32_16x16x32_bf16 v[56:59], v[72:75], v[168:171], v[56:59]
	v_mfma_f32_16x16x32_bf16 v[32:35], v[76:79], v[168:171], v[32:35]
	ds_read_b128 v[196:199], v210 offset:26624
	s_add_u32 m0, s38, 57344
	s_nop 0
	global_load_lds_dwordx4 v214, s[100:101]
	s_waitcnt lgkmcnt(8)
	v_mfma_f32_16x16x32_bf16 v[12:15], v[72:75], v[172:175], v[12:15]
	v_mfma_f32_16x16x32_bf16 v[4:7], v[76:79], v[172:175], v[4:7]
	ds_read_b128 v[200:203], v210 offset:28672
	s_add_u32 m0, s38, 61440
	s_nop 0
	global_load_lds_dwordx4 v215, s[100:101]
	s_add_u32 s100, s100, 128
	s_addc_u32 s101, s101, 0
	s_waitcnt lgkmcnt(6)
	v_mfma_f32_16x16x32_bf16 v[40:43], v[64:67], v[176:179], v[40:43]
	v_mfma_f32_16x16x32_bf16 v[52:55], v[68:71], v[176:179], v[52:55]
	ds_read_b128 v[204:207], v210 offset:30720
	s_waitcnt lgkmcnt(6)
	v_mfma_f32_16x16x32_bf16 v[28:31], v[64:67], v[180:183], v[28:31]
	v_mfma_f32_16x16x32_bf16 v[16:19], v[68:71], v[180:183], v[16:19]
	ds_read_b128 v[72:75], v209 offset:0
	ds_read_b128 v[76:79], v209 offset:2048
	ds_read_b128 v[160:163], v211 offset:16384
	s_waitcnt lgkmcnt(8)
	v_mfma_f32_16x16x32_bf16 v[60:63], v[64:67], v[184:187], v[60:63]
	v_mfma_f32_16x16x32_bf16 v[48:51], v[68:71], v[184:187], v[48:51]
	ds_read_b128 v[164:167], v211 offset:18432
	s_waitcnt lgkmcnt(8)
	v_mfma_f32_16x16x32_bf16 v[20:23], v[64:67], v[188:191], v[20:23]
	v_mfma_f32_16x16x32_bf16 v[0:3], v[68:71], v[188:191], v[0:3]
	ds_read_b128 v[168:171], v211 offset:20480
	s_waitcnt lgkmcnt(8)
	v_mfma_f32_16x16x32_bf16 v[44:47], v[64:67], v[192:195], v[44:47]
	v_mfma_f32_16x16x32_bf16 v[36:39], v[68:71], v[192:195], v[36:39]
	ds_read_b128 v[172:175], v211 offset:22528
	s_waitcnt lgkmcnt(8)
	v_mfma_f32_16x16x32_bf16 v[24:27], v[64:67], v[196:199], v[24:27]
	v_mfma_f32_16x16x32_bf16 v[8:11], v[68:71], v[196:199], v[8:11]
	ds_read_b128 v[176:179], v211 offset:24576
	s_waitcnt lgkmcnt(8)
	v_mfma_f32_16x16x32_bf16 v[56:59], v[64:67], v[200:203], v[56:59]
	v_mfma_f32_16x16x32_bf16 v[32:35], v[68:71], v[200:203], v[32:35]
	ds_read_b128 v[180:183], v211 offset:26624
	s_waitcnt lgkmcnt(8)
	v_mfma_f32_16x16x32_bf16 v[12:15], v[64:67], v[204:207], v[12:15]
	v_mfma_f32_16x16x32_bf16 v[4:7], v[68:71], v[204:207], v[4:7]
	ds_read_b128 v[184:187], v211 offset:28672
	s_waitcnt lgkmcnt(6)
	v_mfma_f32_16x16x32_bf16 v[40:43], v[72:75], v[160:163], v[40:43]
	v_mfma_f32_16x16x32_bf16 v[52:55], v[76:79], v[160:163], v[52:55]
	ds_read_b128 v[188:191], v211 offset:30720
	s_waitcnt vmcnt(0) lgkmcnt(0)
	s_barrier
	s_add_u32 m0, s38, 0
	s_nop 0
	global_load_lds_dwordx4 v212, s[98:99]
	s_waitcnt lgkmcnt(6)
	v_mfma_f32_16x16x32_bf16 v[28:31], v[72:75], v[164:167], v[28:31]
	v_mfma_f32_16x16x32_bf16 v[16:19], v[76:79], v[164:167], v[16:19]
	ds_read_b128 v[64:67], v208 offset:32768
	ds_read_b128 v[68:71], v208 offset:34816
	ds_read_b128 v[192:195], v210 offset:49152
	s_add_u32 m0, s38, 4096
	s_nop 0
	global_load_lds_dwordx4 v213, s[98:99]
	s_waitcnt lgkmcnt(8)
	v_mfma_f32_16x16x32_bf16 v[60:63], v[72:75], v[168:171], v[60:63]
	v_mfma_f32_16x16x32_bf16 v[48:51], v[76:79], v[168:171], v[48:51]
	ds_read_b128 v[196:199], v210 offset:51200
	s_add_u32 m0, s38, 8192
	s_nop 0
	global_load_lds_dwordx4 v214, s[98:99]
	s_waitcnt lgkmcnt(8)
	v_mfma_f32_16x16x32_bf16 v[20:23], v[72:75], v[172:175], v[20:23]
	v_mfma_f32_16x16x32_bf16 v[0:3], v[76:79], v[172:175], v[0:3]
	ds_read_b128 v[200:203], v210 offset:53248
	s_add_u32 m0, s38, 12288
	s_nop 0
	global_load_lds_dwordx4 v215, s[98:99]
	s_add_u32 s98, s98, 128
	s_addc_u32 s99, s99, 0
	s_waitcnt lgkmcnt(8)
	v_mfma_f32_16x16x32_bf16 v[44:47], v[72:75], v[176:179], v[44:47]
	v_mfma_f32_16x16x32_bf16 v[36:39], v[76:79], v[176:179], v[36:39]
	ds_read_b128 v[204:207], v210 offset:55296
	s_add_u32 m0, s38, 16384
	s_nop 0
	global_load_lds_dwordx4 v212, s[100:101]
	s_waitcnt lgkmcnt(8)
	v_mfma_f32_16x16x32_bf16 v[24:27], v[72:75], v[180:183], v[24:27]
	v_mfma_f32_16x16x32_bf16 v[8:11], v[76:79], v[180:183], v[8:11]
	ds_read_b128 v[160:163], v210 offset:57344
	s_add_u32 m0, s38, 20480
	s_nop 0
	global_load_lds_dwordx4 v213, s[100:101]
	s_waitcnt lgkmcnt(8)
	v_mfma_f32_16x16x32_bf16 v[56:59], v[72:75], v[184:187], v[56:59]
	v_mfma_f32_16x16x32_bf16 v[32:35], v[76:79], v[184:187], v[32:35]
	ds_read_b128 v[164:167], v210 offset:59392
	s_add_u32 m0, s38, 24576
	s_nop 0
	global_load_lds_dwordx4 v214, s[100:101]
	s_waitcnt lgkmcnt(8)
	v_mfma_f32_16x16x32_bf16 v[12:15], v[72:75], v[188:191], v[12:15]
	v_mfma_f32_16x16x32_bf16 v[4:7], v[76:79], v[188:191], v[4:7]
	ds_read_b128 v[168:171], v210 offset:61440
	s_add_u32 m0, s38, 28672
	s_nop 0
	global_load_lds_dwordx4 v215, s[100:101]
	s_add_u32 s100, s100, 128
	s_addc_u32 s101, s101, 0
	s_waitcnt lgkmcnt(6)
	v_mfma_f32_16x16x32_bf16 v[40:43], v[64:67], v[192:195], v[40:43]
	v_mfma_f32_16x16x32_bf16 v[52:55], v[68:71], v[192:195], v[52:55]
	ds_read_b128 v[172:175], v210 offset:63488
	s_waitcnt lgkmcnt(6)
	v_mfma_f32_16x16x32_bf16 v[28:31], v[64:67], v[196:199], v[28:31]
	v_mfma_f32_16x16x32_bf16 v[16:19], v[68:71], v[196:199], v[16:19]
	ds_read_b128 v[72:75], v209 offset:32768
	ds_read_b128 v[76:79], v209 offset:34816
	ds_read_b128 v[176:179], v211 offset:49152
	s_waitcnt lgkmcnt(8)
	v_mfma_f32_16x16x32_bf16 v[60:63], v[64:67], v[200:203], v[60:63]
	v_mfma_f32_16x16x32_bf16 v[48:51], v[68:71], v[200:203], v[48:51]
	ds_read_b128 v[180:183], v211 offset:51200
	s_waitcnt lgkmcnt(8)
	v_mfma_f32_16x16x32_bf16 v[20:23], v[64:67], v[204:207], v[20:23]
	v_mfma_f32_16x16x32_bf16 v[0:3], v[68:71], v[204:207], v[0:3]
	ds_read_b128 v[184:187], v211 offset:53248
	s_waitcnt lgkmcnt(8)
	v_mfma_f32_16x16x32_bf16 v[44:47], v[64:67], v[160:163], v[44:47]
	v_mfma_f32_16x16x32_bf16 v[36:39], v[68:71], v[160:163], v[36:39]
	ds_read_b128 v[188:191], v211 offset:55296
	s_waitcnt lgkmcnt(8)
	v_mfma_f32_16x16x32_bf16 v[24:27], v[64:67], v[164:167], v[24:27]
	v_mfma_f32_16x16x32_bf16 v[8:11], v[68:71], v[164:167], v[8:11]
	ds_read_b128 v[192:195], v211 offset:57344
	s_waitcnt lgkmcnt(8)
	v_mfma_f32_16x16x32_bf16 v[56:59], v[64:67], v[168:171], v[56:59]
	v_mfma_f32_16x16x32_bf16 v[32:35], v[68:71], v[168:171], v[32:35]
	ds_read_b128 v[196:199], v211 offset:59392
	s_waitcnt lgkmcnt(8)
	v_mfma_f32_16x16x32_bf16 v[12:15], v[64:67], v[172:175], v[12:15]
	v_mfma_f32_16x16x32_bf16 v[4:7], v[68:71], v[172:175], v[4:7]
	ds_read_b128 v[200:203], v211 offset:61440
	s_waitcnt lgkmcnt(6)
	v_mfma_f32_16x16x32_bf16 v[40:43], v[72:75], v[176:179], v[40:43]
	v_mfma_f32_16x16x32_bf16 v[52:55], v[76:79], v[176:179], v[52:55]
	ds_read_b128 v[204:207], v211 offset:63488
	s_waitcnt vmcnt(0) lgkmcnt(0)
	s_barrier
	s_add_u32 m0, s38, 32768
	s_nop 0
	global_load_lds_dwordx4 v212, s[98:99]
	s_waitcnt lgkmcnt(6)
	v_mfma_f32_16x16x32_bf16 v[28:31], v[72:75], v[180:183], v[28:31]
	v_mfma_f32_16x16x32_bf16 v[16:19], v[76:79], v[180:183], v[16:19]
	ds_read_b128 v[64:67], v208 offset:0
	ds_read_b128 v[68:71], v208 offset:2048
	ds_read_b128 v[160:163], v210 offset:16384
	s_add_u32 m0, s38, 36864
	s_nop 0
	global_load_lds_dwordx4 v213, s[98:99]
	s_waitcnt lgkmcnt(8)
	v_mfma_f32_16x16x32_bf16 v[60:63], v[72:75], v[184:187], v[60:63]
	v_mfma_f32_16x16x32_bf16 v[48:51], v[76:79], v[184:187], v[48:51]
	ds_read_b128 v[164:167], v210 offset:18432
	s_add_u32 m0, s38, 40960
	s_nop 0
	global_load_lds_dwordx4 v214, s[98:99]
	s_waitcnt lgkmcnt(8)
	v_mfma_f32_16x16x32_bf16 v[20:23], v[72:75], v[188:191], v[20:23]
	v_mfma_f32_16x16x32_bf16 v[0:3], v[76:79], v[188:191], v[0:3]
	ds_read_b128 v[168:171], v210 offset:20480
	s_add_u32 m0, s38, 45056
	s_nop 0
	global_load_lds_dwordx4 v215, s[98:99]
	s_add_u32 s98, s98, 128
	s_addc_u32 s99, s99, 0
	s_waitcnt lgkmcnt(8)
	v_mfma_f32_16x16x32_bf16 v[44:47], v[72:75], v[192:195], v[44:47]
	v_mfma_f32_16x16x32_bf16 v[36:39], v[76:79], v[192:195], v[36:39]
	ds_read_b128 v[172:175], v210 offset:22528
	s_add_u32 m0, s38, 49152
	s_nop 0
	global_load_lds_dwordx4 v212, s[100:101]
	s_waitcnt lgkmcnt(8)
	v_mfma_f32_16x16x32_bf16 v[24:27], v[72:75], v[196:199], v[24:27]
	v_mfma_f32_16x16x32_bf16 v[8:11], v[76:79], v[196:199], v[8:11]
	ds_read_b128 v[176:179], v210 offset:24576
	s_add_u32 m0, s38, 53248
	s_nop 0
	global_load_lds_dwordx4 v213, s[100:101]
	s_waitcnt lgkmcnt(8)
	v_mfma_f32_16x16x32_bf16 v[56:59], v[72:75], v[200:203], v[56:59]
	v_mfma_f32_16x16x32_bf16 v[32:35], v[76:79], v[200:203], v[32:35]
	ds_read_b128 v[180:183], v210 offset:26624
	s_add_u32 m0, s38, 57344
	s_nop 0
	global_load_lds_dwordx4 v214, s[100:101]
	s_waitcnt lgkmcnt(8)
	v_mfma_f32_16x16x32_bf16 v[12:15], v[72:75], v[204:207], v[12:15]
	v_mfma_f32_16x16x32_bf16 v[4:7], v[76:79], v[204:207], v[4:7]
	ds_read_b128 v[184:187], v210 offset:28672
	s_add_u32 m0, s38, 61440
	s_nop 0
	global_load_lds_dwordx4 v215, s[100:101]
	s_add_u32 s100, s100, 128
	s_addc_u32 s101, s101, 0
	s_waitcnt lgkmcnt(6)
	v_mfma_f32_16x16x32_bf16 v[40:43], v[64:67], v[160:163], v[40:43]
	v_mfma_f32_16x16x32_bf16 v[52:55], v[68:71], v[160:163], v[52:55]
	ds_read_b128 v[188:191], v210 offset:30720
	s_waitcnt lgkmcnt(6)
	v_mfma_f32_16x16x32_bf16 v[28:31], v[64:67], v[164:167], v[28:31]
	v_mfma_f32_16x16x32_bf16 v[16:19], v[68:71], v[164:167], v[16:19]
	ds_read_b128 v[72:75], v209 offset:0
	ds_read_b128 v[76:79], v209 offset:2048
	ds_read_b128 v[192:195], v211 offset:16384
	s_waitcnt lgkmcnt(8)
	v_mfma_f32_16x16x32_bf16 v[60:63], v[64:67], v[168:171], v[60:63]
	v_mfma_f32_16x16x32_bf16 v[48:51], v[68:71], v[168:171], v[48:51]
	ds_read_b128 v[196:199], v211 offset:18432
	s_waitcnt lgkmcnt(8)
	v_mfma_f32_16x16x32_bf16 v[20:23], v[64:67], v[172:175], v[20:23]
	v_mfma_f32_16x16x32_bf16 v[0:3], v[68:71], v[172:175], v[0:3]
	ds_read_b128 v[200:203], v211 offset:20480
	s_waitcnt lgkmcnt(8)
	v_mfma_f32_16x16x32_bf16 v[44:47], v[64:67], v[176:179], v[44:47]
	v_mfma_f32_16x16x32_bf16 v[36:39], v[68:71], v[176:179], v[36:39]
	ds_read_b128 v[204:207], v211 offset:22528
	s_waitcnt lgkmcnt(8)
	v_mfma_f32_16x16x32_bf16 v[24:27], v[64:67], v[180:183], v[24:27]
	v_mfma_f32_16x16x32_bf16 v[8:11], v[68:71], v[180:183], v[8:11]
	ds_read_b128 v[160:163], v211 offset:24576
	s_waitcnt lgkmcnt(8)
	v_mfma_f32_16x16x32_bf16 v[56:59], v[64:67], v[184:187], v[56:59]
	v_mfma_f32_16x16x32_bf16 v[32:35], v[68:71], v[184:187], v[32:35]
	ds_read_b128 v[164:167], v211 offset:26624
	s_waitcnt lgkmcnt(8)
	v_mfma_f32_16x16x32_bf16 v[12:15], v[64:67], v[188:191], v[12:15]
	v_mfma_f32_16x16x32_bf16 v[4:7], v[68:71], v[188:191], v[4:7]
	ds_read_b128 v[168:171], v211 offset:28672
	s_waitcnt lgkmcnt(6)
	v_mfma_f32_16x16x32_bf16 v[40:43], v[72:75], v[192:195], v[40:43]
	v_mfma_f32_16x16x32_bf16 v[52:55], v[76:79], v[192:195], v[52:55]
	ds_read_b128 v[172:175], v211 offset:30720
	s_waitcnt lgkmcnt(6)
	v_mfma_f32_16x16x32_bf16 v[28:31], v[72:75], v[196:199], v[28:31]
	v_mfma_f32_16x16x32_bf16 v[16:19], v[76:79], v[196:199], v[16:19]
	s_waitcnt lgkmcnt(5)
	v_mfma_f32_16x16x32_bf16 v[60:63], v[72:75], v[200:203], v[60:63]
	v_mfma_f32_16x16x32_bf16 v[48:51], v[76:79], v[200:203], v[48:51]
	s_waitcnt lgkmcnt(4)
	v_mfma_f32_16x16x32_bf16 v[20:23], v[72:75], v[204:207], v[20:23]
	v_mfma_f32_16x16x32_bf16 v[0:3], v[76:79], v[204:207], v[0:3]
	s_waitcnt lgkmcnt(3)
	v_mfma_f32_16x16x32_bf16 v[44:47], v[72:75], v[160:163], v[44:47]
	v_mfma_f32_16x16x32_bf16 v[36:39], v[76:79], v[160:163], v[36:39]
	s_waitcnt lgkmcnt(2)
	v_mfma_f32_16x16x32_bf16 v[24:27], v[72:75], v[164:167], v[24:27]
	v_mfma_f32_16x16x32_bf16 v[8:11], v[76:79], v[164:167], v[8:11]
	s_waitcnt lgkmcnt(1)
	v_mfma_f32_16x16x32_bf16 v[56:59], v[72:75], v[168:171], v[56:59]
	v_mfma_f32_16x16x32_bf16 v[32:35], v[76:79], v[168:171], v[32:35]
	s_waitcnt lgkmcnt(0)
	v_mfma_f32_16x16x32_bf16 v[12:15], v[72:75], v[172:175], v[12:15]
	v_mfma_f32_16x16x32_bf16 v[4:7], v[76:79], v[172:175], v[4:7]
	s_mov_b32 s55, 0x8000
	v_add_u32_e32 v68, s55, v109
	v_add_u32_e32 v72, v68, v110
	s_waitcnt vmcnt(0)
	s_barrier
	ds_read_b128 v[64:67], v72
	v_add_u32_e32 v126, v68, v108
	ds_read_b128 v[68:71], v126 offset:16384
	ds_read_b128 v[80:83], v126 offset:20480
	ds_read_b128 v[142:145], v126 offset:24576
	s_ashr_i32 s54, s54, 5
	s_lshl_b32 s0, s53, 7
	s_waitcnt lgkmcnt(0)
	v_mfma_f32_16x16x32_bf16 v[160:163], v[64:67], v[68:71], v[40:43]
	s_mul_hi_i32 s38, s54, 0x3000
	s_nop 1
	ds_read_b128 v[40:43], v72 offset:2048
	v_add_u32_e32 v141, 0x400, v113
	v_mfma_f32_16x16x32_bf16 v[164:167], v[64:67], v[80:83], v[60:63]
	ds_read_b128 v[72:75], v126 offset:18432
	v_mfma_f32_16x16x32_bf16 v[168:171], v[64:67], v[142:145], v[44:47]
	s_nop 2
	ds_read_b128 v[44:47], v126 offset:22528
	s_waitcnt lgkmcnt(0)
	v_mfma_f32_16x16x32_bf16 v[52:55], v[40:43], v[68:71], v[52:55]
	ds_read_b128 v[76:79], v126 offset:26624
	v_mfma_f32_16x16x32_bf16 v[80:83], v[40:43], v[80:83], v[48:51]
	ds_read_b128 v[68:71], v126 offset:28672
	s_waitcnt lgkmcnt(0)
	v_mfma_f32_16x16x32_bf16 v[56:59], v[64:67], v[68:71], v[56:59]
	ds_read_b128 v[48:51], v126 offset:30720
	v_mfma_f32_16x16x32_bf16 v[142:145], v[40:43], v[142:145], v[36:39]
	s_nop 2
	v_add_u32_e32 v36, s55, v111
	v_add_u32_e32 v37, v36, v110
	ds_read_b128 v[60:63], v37
	v_mfma_f32_16x16x32_bf16 v[172:175], v[40:43], v[68:71], v[32:35]
	v_add_u32_e32 v126, v36, v108
	s_mul_i32 s55, s54, 0x3000
	s_add_u32 s39, s50, s55
	ds_read_b128 v[32:35], v37 offset:2048
	v_mfma_f32_16x16x32_bf16 v[176:179], v[64:67], v[72:75], v[28:31]
	s_addc_u32 s56, s51, s38
	s_lshl_b32 s53, s53, 9
	s_add_u32 s38, s39, s53
	ds_read_b128 v[28:31], v126 offset:16384
	s_waitcnt lgkmcnt(0)
	v_mfma_f32_16x16x32_bf16 v[160:163], v[60:63], v[28:31], v[160:163]
	ds_read_b128 v[180:183], v126 offset:18432
	s_addc_u32 s39, s56, 0
	v_mfma_f32_16x16x32_bf16 v[28:31], v[32:35], v[28:31], v[52:55]
	ds_read_b128 v[36:39], v126 offset:20480
	s_waitcnt lgkmcnt(0)
	v_mfma_f32_16x16x32_bf16 v[164:167], v[60:63], v[36:39], v[164:167]
	ds_read_b128 v[68:71], v126 offset:22528
	v_mfma_f32_16x16x32_bf16 v[36:39], v[32:35], v[36:39], v[80:83]
	ds_read_b128 v[52:55], v126 offset:24576
	s_waitcnt lgkmcnt(0)
	v_mfma_f32_16x16x32_bf16 v[168:171], v[60:63], v[52:55], v[168:171]
	ds_read_b128 v[184:187], v126 offset:26624
	v_mfma_f32_16x16x32_bf16 v[52:55], v[32:35], v[52:55], v[142:145]
	s_nop 2
	ds_read_b128 v[142:145], v126 offset:28672
	s_waitcnt lgkmcnt(0)
	v_mfma_f32_16x16x32_bf16 v[188:191], v[60:63], v[142:145], v[56:59]
	ds_read_b128 v[80:83], v126 offset:30720
	s_barrier
	v_mfma_f32_16x16x32_bf16 v[56:59], v[32:35], v[142:145], v[172:175]
	v_mfma_f32_16x16x32_bf16 v[24:27], v[64:67], v[76:79], v[24:27]
	v_mfma_f32_16x16x32_bf16 v[16:19], v[40:43], v[72:75], v[16:19]
	v_mfma_f32_16x16x32_bf16 v[8:11], v[40:43], v[76:79], v[8:11]
	v_mfma_f32_16x16x32_bf16 v[72:75], v[60:63], v[180:183], v[176:179]
	v_mfma_f32_16x16x32_bf16 v[24:27], v[60:63], v[184:187], v[24:27]
	v_mfma_f32_16x16x32_bf16 v[16:19], v[32:35], v[180:183], v[16:19]
	v_mfma_f32_16x16x32_bf16 v[8:11], v[32:35], v[184:187], v[8:11]
	v_mfma_f32_16x16x32_bf16 v[20:23], v[64:67], v[44:47], v[20:23]
	v_mfma_f32_16x16x32_bf16 v[12:15], v[64:67], v[48:51], v[12:15]
	v_lshl_add_u64 v[64:65], s[38:39], 0, v[84:85]
	s_add_i32 s38, s54, 4
	s_add_i32 s39, s55, 0xc000
	s_mul_hi_i32 s38, s38, 0x3000
	s_add_u32 s39, s50, s39
	s_addc_u32 s56, s51, s38
	v_lshl_add_u64 v[66:67], v[64:65], 0, s[30:31]
	v_add_co_u32_e32 v64, vcc, s47, v64
	s_add_u32 s38, s39, s53
	s_nop 0
	v_addc_co_u32_e32 v65, vcc, 0, v65, vcc
	s_addc_u32 s39, s56, 0
	v_mfma_f32_16x16x32_bf16 v[20:23], v[60:63], v[68:71], v[20:23]
	s_waitcnt lgkmcnt(0)
	v_mfma_f32_16x16x32_bf16 v[12:15], v[60:63], v[80:83], v[12:15]
	ds_write2_b32 v113, v160, v72 offset1:16
	global_load_dwordx4 v[60:63], v[64:65], off
	ds_write2_b32 v113, v161, v73 offset0:128 offset1:144
	v_lshl_add_u64 v[72:73], s[38:39], 0, v[84:85]
	s_add_i32 s38, s54, 8
	s_add_i32 s39, s55, 0x18000
	s_mul_hi_i32 s38, s38, 0x3000
	s_add_u32 s39, s50, s39
	s_addc_u32 s56, s51, s38
	v_lshl_add_u64 v[126:127], v[72:73], 0, s[30:31]
	v_add_co_u32_e32 v72, vcc, s47, v72
	s_add_u32 s38, s39, s53
	s_nop 0
	v_addc_co_u32_e32 v73, vcc, 0, v73, vcc
	s_addc_u32 s39, s56, 0
	global_load_dwordx4 v[64:67], v[66:67], off offset:16
	ds_write2_b32 v141, v162, v74 offset1:16
	global_load_dwordx4 v[76:79], v[72:73], off
	ds_write2_b32 v141, v163, v75 offset0:128 offset1:144
	global_load_dwordx4 v[72:75], v[126:127], off offset:16
	v_lshl_add_u64 v[126:127], s[38:39], 0, v[84:85]
	s_add_i32 s38, s54, 12
	s_add_i32 s39, s55, 0x24000
	s_mul_hi_i32 s38, s38, 0x3000
	s_add_u32 s39, s50, s39
	s_addc_u32 s56, s51, s38
	v_lshl_add_u64 v[146:147], v[126:127], 0, s[30:31]
	v_add_co_u32_e32 v126, vcc, s47, v126
	s_add_u32 s38, s39, s53
	s_nop 0
	v_addc_co_u32_e32 v127, vcc, 0, v127, vcc
	s_addc_u32 s39, s56, 0
	ds_write2_b32 v113, v164, v20 offset0:32 offset1:48
	global_load_dwordx4 v[142:145], v[126:127], off
	ds_write2_b32 v113, v165, v21 offset0:160 offset1:176
	v_lshl_add_u64 v[20:21], s[38:39], 0, v[84:85]
	s_add_i32 s38, s54, 16
	s_add_i32 s39, s55, 0x30000
	s_mul_hi_i32 s38, s38, 0x3000
	s_add_u32 s39, s50, s39
	s_addc_u32 s56, s51, s38
	v_lshl_add_u64 v[126:127], v[20:21], 0, s[30:31]
	v_add_co_u32_e32 v20, vcc, s47, v20
	s_add_u32 s38, s39, s53
	s_nop 0
	v_addc_co_u32_e32 v21, vcc, 0, v21, vcc
	s_addc_u32 s39, s56, 0
	global_load_dwordx4 v[160:163], v[146:147], off offset:16
	ds_write2_b32 v141, v166, v22 offset0:32 offset1:48
	global_load_dwordx4 v[172:175], v[20:21], off
	ds_write2_b32 v141, v167, v23 offset0:160 offset1:176
	global_load_dwordx4 v[20:23], v[126:127], off offset:16
	v_lshl_add_u64 v[126:127], s[38:39], 0, v[84:85]
	s_add_i32 s38, s54, 20
	s_add_i32 s39, s55, 0x3c000
	s_mul_hi_i32 s38, s38, 0x3000
	s_add_u32 s39, s50, s39
	s_addc_u32 s56, s51, s38
	v_lshl_add_u64 v[146:147], v[126:127], 0, s[30:31]
	v_add_co_u32_e32 v126, vcc, s47, v126
	s_add_u32 s38, s39, s53
	s_nop 0
	v_addc_co_u32_e32 v127, vcc, 0, v127, vcc
	s_addc_u32 s39, s56, 0
	ds_write2_b32 v113, v168, v24 offset0:64 offset1:80
	global_load_dwordx4 v[164:167], v[126:127], off
	ds_write2_b32 v113, v169, v25 offset0:192 offset1:208
	v_lshl_add_u64 v[24:25], s[38:39], 0, v[84:85]
	s_add_i32 s38, s54, 24
	s_add_i32 s39, s55, 0x48000
	s_mul_hi_i32 s38, s38, 0x3000
	s_add_u32 s39, s50, s39
	s_addc_u32 s56, s51, s38
	v_lshl_add_u64 v[126:127], v[24:25], 0, s[30:31]
	v_add_co_u32_e32 v24, vcc, s47, v24
	s_add_u32 s38, s39, s53
	s_nop 0
	v_addc_co_u32_e32 v25, vcc, 0, v25, vcc
	s_addc_u32 s39, s56, 0
	s_add_i32 s54, s54, 28
	s_add_i32 s55, s55, 0x54000
	global_load_dwordx4 v[176:179], v[146:147], off offset:16
	ds_write2_b32 v141, v170, v26 offset0:64 offset1:80
	global_load_dwordx4 v[180:183], v[24:25], off
	ds_write2_b32 v141, v171, v27 offset0:192 offset1:208
	global_load_dwordx4 v[24:27], v[126:127], off offset:16
	v_lshl_add_u64 v[126:127], s[38:39], 0, v[84:85]
	s_mul_hi_i32 s38, s54, 0x3000
	s_add_u32 s39, s50, s55
	s_addc_u32 s54, s51, s38
	v_lshl_add_u64 v[146:147], v[126:127], 0, s[30:31]
	v_add_co_u32_e32 v126, vcc, s47, v126
	s_add_u32 s38, s39, s53
	s_nop 0
	v_addc_co_u32_e32 v127, vcc, 0, v127, vcc
	s_addc_u32 s39, s54, 0
	ds_write2st64_b32 v114, v188, v189 offset1:2
	global_load_dwordx4 v[168:171], v[126:127], off
	v_lshl_add_u64 v[126:127], s[38:39], 0, v[84:85]
	ds_write2st64_b32 v114, v190, v191 offset0:4 offset1:6
	global_load_dwordx4 v[184:187], v[146:147], off offset:16
	v_lshl_add_u64 v[146:147], v[126:127], 0, s[30:31]
	v_add_co_u32_e32 v126, vcc, s47, v126
	ds_write2st64_b32 v115, v12, v13 offset1:2
	s_nop 0
	v_addc_co_u32_e32 v127, vcc, 0, v127, vcc
	global_load_dwordx4 v[188:191], v[126:127], off
	ds_write2st64_b32 v115, v14, v15 offset0:4 offset1:6
	global_load_dwordx4 v[12:15], v[146:147], off offset:16
	v_mfma_f32_16x16x32_bf16 v[0:3], v[40:43], v[44:47], v[0:3]
	s_lshl_b64 s[34:35], s[34:35], 17
	s_add_i32 s52, s52, s3
	v_mfma_f32_16x16x32_bf16 v[4:7], v[40:43], v[48:51], v[4:7]
	s_add_i32 s33, s33, s46
	s_cmpk_gt_i32 s52, 0x3ff
	v_mfma_f32_16x16x32_bf16 v[68:71], v[32:35], v[68:71], v[0:3]
	s_nop 2
	v_lshl_add_u64 v[0:1], s[34:35], 0, v[90:91]
	v_or_b32_e32 v0, s0, v0
	v_lshlrev_b64 v[126:127], 2, v[0:1]
	v_lshl_add_u64 v[0:1], s[68:69], 0, v[126:127]
	v_mfma_f32_16x16x32_bf16 v[32:35], v[32:35], v[80:83], v[4:7]
	ds_read_b128 v[80:83], v112
	ds_read_b128 v[204:207], v112 offset:16
	ds_read_b128 v[200:203], v116
	ds_read_b128 v[192:195], v118 offset:16
	ds_read_b128 v[196:199], v118
	ds_read_b128 v[44:47], v117 offset:16
	ds_read_b128 v[40:43], v117
	ds_read_b128 v[48:51], v116 offset:16
	global_load_dwordx4 v[208:211], v[0:1], off offset:16 nt
	global_load_dwordx4 v[212:215], v[0:1], off nt
	s_waitcnt vmcnt(0)
	v_pk_add_f32 v[0:1], v[62:63], 0 op_sel_hi:[1,0]
	v_pk_add_f32 v[2:3], v[60:61], 0 op_sel_hi:[1,0]
	v_pk_add_f32 v[4:5], v[66:67], 0 op_sel_hi:[1,0]
	v_pk_add_f32 v[6:7], v[64:65], 0 op_sel_hi:[1,0]
	v_pk_add_f32 v[0:1], v[0:1], v[78:79]
	v_pk_add_f32 v[2:3], v[2:3], v[76:77]
	v_pk_add_f32 v[4:5], v[4:5], v[74:75]
	v_pk_add_f32 v[6:7], v[6:7], v[72:73]
	v_pk_add_f32 v[0:1], v[0:1], v[144:145]
	v_pk_add_f32 v[2:3], v[2:3], v[142:143]
	v_pk_add_f32 v[4:5], v[4:5], v[162:163]
	v_pk_add_f32 v[6:7], v[6:7], v[160:161]
	v_pk_add_f32 v[0:1], v[0:1], v[174:175]
	v_pk_add_f32 v[2:3], v[2:3], v[172:173]
	v_pk_add_f32 v[4:5], v[4:5], v[22:23]
	v_pk_add_f32 v[6:7], v[6:7], v[20:21]
	v_pk_add_f32 v[0:1], v[0:1], v[166:167]
	v_pk_add_f32 v[2:3], v[2:3], v[164:165]
	v_pk_add_f32 v[4:5], v[4:5], v[178:179]
	v_pk_add_f32 v[6:7], v[6:7], v[176:177]
	v_pk_add_f32 v[0:1], v[0:1], v[182:183]
	v_pk_add_f32 v[2:3], v[2:3], v[180:181]
	v_pk_add_f32 v[4:5], v[4:5], v[26:27]
	v_pk_add_f32 v[6:7], v[6:7], v[24:25]
	v_lshl_add_u64 v[24:25], s[48:49], 0, v[126:127]
	v_lshl_add_u64 v[26:27], s[34:35], 0, v[96:97]
	v_or_b32_e32 v26, s0, v26
	v_lshlrev_b64 v[26:27], 2, v[26:27]
	v_pk_add_f32 v[0:1], v[0:1], v[170:171]
	v_pk_add_f32 v[2:3], v[2:3], v[168:169]
	v_pk_add_f32 v[4:5], v[4:5], v[186:187]
	v_pk_add_f32 v[6:7], v[6:7], v[184:185]
	v_pk_add_f32 v[0:1], v[0:1], v[190:191]
	v_pk_add_f32 v[2:3], v[2:3], v[188:189]
	v_pk_add_f32 v[4:5], v[4:5], v[14:15]
	v_pk_add_f32 v[6:7], v[6:7], v[12:13]
	s_waitcnt lgkmcnt(6)
	v_pk_fma_f32 v[22:23], v[4:5], v[206:207], v[210:211]
	v_pk_fma_f32 v[14:15], v[0:1], v[82:83], v[214:215]
	v_pk_fma_f32 v[12:13], v[2:3], v[80:81], v[212:213]
	global_store_dwordx4 v[24:25], v[12:15], off
	v_pk_fma_f32 v[20:21], v[6:7], v[204:205], v[208:209]
	global_store_dwordx4 v[24:25], v[20:23], off offset:16
	v_lshl_add_u64 v[12:13], s[34:35], 0, v[92:93]
	v_or_b32_e32 v12, s0, v12
	v_lshlrev_b64 v[24:25], 2, v[12:13]
	v_lshl_add_u64 v[20:21], s[68:69], 0, v[24:25]
	global_load_dwordx4 v[12:15], v[20:21], off offset:16 nt
	v_lshl_add_u64 v[24:25], s[48:49], 0, v[24:25]
	global_load_dwordx4 v[20:23], v[20:21], off nt
	s_waitcnt vmcnt(1) lgkmcnt(0)
	v_pk_fma_f32 v[14:15], v[4:5], v[50:51], v[14:15]
	v_pk_fma_f32 v[12:13], v[6:7], v[48:49], v[12:13]
	global_store_dwordx4 v[24:25], v[12:15], off offset:16
	s_waitcnt vmcnt(1)
	v_pk_fma_f32 v[22:23], v[0:1], v[202:203], v[22:23]
	v_pk_fma_f32 v[20:21], v[2:3], v[200:201], v[20:21]
	v_lshl_add_u64 v[12:13], s[34:35], 0, v[94:95]
	v_or_b32_e32 v12, s0, v12
	global_store_dwordx4 v[24:25], v[20:23], off
	v_lshlrev_b64 v[24:25], 2, v[12:13]
	v_lshl_add_u64 v[48:49], s[68:69], 0, v[26:27]
	v_lshl_add_u64 v[20:21], s[68:69], 0, v[24:25]
	global_load_dwordx4 v[12:15], v[20:21], off offset:16 nt
	v_lshl_add_u64 v[24:25], s[48:49], 0, v[24:25]
	global_load_dwordx4 v[20:23], v[20:21], off nt
	v_lshl_add_u64 v[50:51], s[34:35], 0, v[100:101]
	v_or_b32_e32 v50, s0, v50
	v_lshlrev_b64 v[50:51], 2, v[50:51]
	s_waitcnt vmcnt(1)
	v_pk_fma_f32 v[14:15], v[4:5], v[46:47], v[14:15]
	v_pk_fma_f32 v[12:13], v[6:7], v[44:45], v[12:13]
	s_waitcnt vmcnt(0)
	v_pk_fma_f32 v[22:23], v[0:1], v[42:43], v[22:23]
	v_pk_fma_f32 v[20:21], v[2:3], v[40:41], v[20:21]
	global_store_dwordx4 v[24:25], v[20:23], off
	global_store_dwordx4 v[24:25], v[12:15], off offset:16
	global_load_dwordx4 v[12:15], v[48:49], off offset:16 nt
	v_lshl_add_u64 v[24:25], s[34:35], 0, v[98:99]
	global_load_dwordx4 v[20:23], v[48:49], off nt
	v_or_b32_e32 v24, s0, v24
	v_lshlrev_b64 v[48:49], 2, v[24:25]
	v_lshl_add_u64 v[24:25], s[48:49], 0, v[26:27]
	v_lshl_add_u64 v[44:45], s[68:69], 0, v[48:49]
	v_lshl_add_u64 v[48:49], s[48:49], 0, v[48:49]
	s_waitcnt vmcnt(1)
	v_pk_fma_f32 v[14:15], v[4:5], v[194:195], v[14:15]
	v_pk_fma_f32 v[12:13], v[6:7], v[192:193], v[12:13]
	s_waitcnt vmcnt(0)
	v_pk_fma_f32 v[22:23], v[0:1], v[198:199], v[22:23]
	v_pk_fma_f32 v[20:21], v[2:3], v[196:197], v[20:21]
	global_store_dwordx4 v[24:25], v[20:23], off
	global_store_dwordx4 v[24:25], v[12:15], off offset:16
	ds_write2_b32 v113, v28, v16 offset1:16
	ds_write2_b32 v113, v29, v17 offset0:128 offset1:144
	ds_write2_b32 v141, v30, v18 offset1:16
	ds_write2_b32 v141, v31, v19 offset0:128 offset1:144
	ds_write2_b32 v113, v36, v68 offset0:32 offset1:48
	ds_write2_b32 v113, v37, v69 offset0:160 offset1:176
	ds_write2_b32 v141, v38, v70 offset0:32 offset1:48
	ds_write2_b32 v141, v39, v71 offset0:160 offset1:176
	ds_write2_b32 v113, v52, v8 offset0:64 offset1:80
	ds_write2_b32 v113, v53, v9 offset0:192 offset1:208
	ds_write2_b32 v141, v54, v10 offset0:64 offset1:80
	ds_write2_b32 v141, v55, v11 offset0:192 offset1:208
	ds_write2st64_b32 v114, v56, v57 offset1:2
	ds_write2st64_b32 v114, v58, v59 offset0:4 offset1:6
	ds_write2st64_b32 v115, v32, v33 offset1:2
	ds_write2st64_b32 v115, v34, v35 offset0:4 offset1:6
	ds_read_b128 v[36:39], v112
	ds_read_b128 v[32:35], v112 offset:16
	ds_read_b128 v[28:31], v116
	ds_read_b128 v[24:27], v116 offset:16
	ds_read_b128 v[20:23], v117
	ds_read_b128 v[16:19], v117 offset:16
	ds_read_b128 v[12:15], v118
	ds_read_b128 v[8:11], v118 offset:16
	global_load_dwordx4 v[40:43], v[44:45], off offset:16 nt
	v_lshl_add_u64 v[52:53], s[68:69], 0, v[50:51]
	global_load_dwordx4 v[44:47], v[44:45], off nt
	s_waitcnt vmcnt(1) lgkmcnt(6)
	v_pk_fma_f32 v[34:35], v[4:5], v[34:35], v[42:43]
	v_pk_fma_f32 v[32:33], v[6:7], v[32:33], v[40:41]
	s_waitcnt vmcnt(0)
	v_pk_fma_f32 v[38:39], v[0:1], v[38:39], v[46:47]
	v_pk_fma_f32 v[36:37], v[2:3], v[36:37], v[44:45]
	global_store_dwordx4 v[48:49], v[36:39], off
	global_store_dwordx4 v[48:49], v[32:35], off offset:16
	global_load_dwordx4 v[32:35], v[52:53], off offset:16 nt
	v_lshl_add_u64 v[40:41], s[34:35], 0, v[102:103]
	global_load_dwordx4 v[36:39], v[52:53], off nt
	v_or_b32_e32 v40, s0, v40
	v_lshlrev_b64 v[40:41], 2, v[40:41]
	v_lshl_add_u64 v[42:43], s[48:49], 0, v[50:51]
	v_lshl_add_u64 v[44:45], s[68:69], 0, v[40:41]
	s_waitcnt vmcnt(1) lgkmcnt(4)
	v_pk_fma_f32 v[26:27], v[4:5], v[26:27], v[34:35]
	v_pk_fma_f32 v[24:25], v[6:7], v[24:25], v[32:33]
	s_waitcnt vmcnt(0)
	v_pk_fma_f32 v[30:31], v[0:1], v[30:31], v[38:39]
	v_pk_fma_f32 v[28:29], v[2:3], v[28:29], v[36:37]
	global_store_dwordx4 v[42:43], v[28:31], off
	global_store_dwordx4 v[42:43], v[24:27], off offset:16
	global_load_dwordx4 v[24:27], v[44:45], off offset:16 nt
	v_lshl_add_u64 v[32:33], s[34:35], 0, v[104:105]
	global_load_dwordx4 v[28:31], v[44:45], off nt
	v_or_b32_e32 v32, s0, v32
	v_lshlrev_b64 v[32:33], 2, v[32:33]
	v_lshl_add_u64 v[34:35], s[48:49], 0, v[40:41]
	v_lshl_add_u64 v[36:37], s[68:69], 0, v[32:33]
	s_waitcnt vmcnt(1) lgkmcnt(2)
	v_pk_fma_f32 v[18:19], v[4:5], v[18:19], v[26:27]
	v_pk_fma_f32 v[16:17], v[6:7], v[16:17], v[24:25]
	s_waitcnt vmcnt(0)
	v_pk_fma_f32 v[22:23], v[0:1], v[22:23], v[30:31]
	v_pk_fma_f32 v[20:21], v[2:3], v[20:21], v[28:29]
	global_store_dwordx4 v[34:35], v[20:23], off
	global_store_dwordx4 v[34:35], v[16:19], off offset:16
	global_load_dwordx4 v[16:19], v[36:37], off offset:16 nt
	v_lshl_add_u64 v[24:25], s[48:49], 0, v[32:33]
	global_load_dwordx4 v[20:23], v[36:37], off nt
	s_waitcnt vmcnt(0) lgkmcnt(1)
	v_pk_fma_f32 v[14:15], v[0:1], v[14:15], v[22:23]
	v_pk_fma_f32 v[12:13], v[2:3], v[12:13], v[20:21]
	s_waitcnt lgkmcnt(0)
	v_pk_fma_f32 v[2:3], v[4:5], v[10:11], v[18:19]
	v_pk_fma_f32 v[0:1], v[6:7], v[8:9], v[16:17]
	global_store_dwordx4 v[24:25], v[12:15], off
	global_store_dwordx4 v[24:25], v[0:3], off offset:16
	s_cbranch_scc0 .LBB0_315

.LBB0_686:
	s_ashr_i32 s28, s2, 31
	s_lshr_b32 s28, s28, 23
	s_add_i32 s28, s2, s28
	s_ashr_i32 s28, s28, 9
	s_lshl_b32 s30, s28, 6
	s_lshl_b32 s28, s2, 3
	s_and_b32 s28, s28, 56
	s_or_b32 s39, s30, s28
	s_bfe_u32 s31, s2, 0x30003
	s_or_b32 s28, s39, s31
	s_ashr_i32 s29, s28, 31
	s_lshl_b64 s[28:29], s[28:29], 19
	v_readfirstlane_b32 s40, v129
	v_lshl_add_u64 v[0:1], v[78:79], 0, s[28:29]
	s_mov_b32 m0, s40
	v_readfirstlane_b32 s40, v111
	s_barrier
	s_bfe_u32 s38, s2, 0x30006
	s_add_u32 s98, s28, s50
	s_addc_u32 s99, s29, s51
	s_add_u32 s98, s98, 0x5a00000
	s_addc_u32 s99, s99, 0
	s_lshl_b32 s100, s38, 19
	s_add_u32 s100, s100, s50
	s_addc_u32 s101, s51, 0
	s_add_u32 s100, s100, 0xc00000
	s_addc_u32 s101, s101, 0
	v_readfirstlane_b32 s41, v129
	v_lshrrev_b32_e32 v124, 4, v129
	v_and_b32_e32 v120, 15, v124
	v_bfe_u32 v121, v124, 4, 2
	v_bfe_u32 v122, v124, 1, 3
	v_xor_b32_e32 v122, v121, v122
	v_lshlrev_b32_e32 v122, 4, v122
	v_lshl_or_b32 v210, v120, 7, v122
	v_xor_b32_e32 v211, 64, v210
	v_lshrrev_b32_e32 v122, 6, v124
	v_lshl_add_u32 v208, v122, 12, v210
	v_lshl_add_u32 v209, v122, 12, v211
	v_bfe_u32 v120, v124, 4, 3
	v_and_b32_e32 v121, 7, v124
	v_xor_b32_e32 v120, v120, v121
	v_lshlrev_b32_e32 v120, 4, v120
	v_lshrrev_b32_e32 v121, 3, v124
	v_lshl_or_b32 v212, v121, 12, v120
	v_add_u32_e32 v213, 131072, v212
	v_add_u32_e32 v214, 262144, v212
	v_add_u32_e32 v215, 393216, v212
	s_add_u32 m0, s41, 0
	v_mov_b32_e32 v44, 0
	v_mov_b32_e32 v45, 0
	global_load_lds_dwordx4 v212, s[98:99]
	s_add_u32 m0, s41, 4096
	v_mov_b32_e32 v46, 0
	v_mov_b32_e32 v47, 0
	global_load_lds_dwordx4 v213, s[98:99]
	s_add_u32 m0, s41, 8192
	v_mov_b32_e32 v28, 0
	v_mov_b32_e32 v29, 0
	global_load_lds_dwordx4 v214, s[98:99]
	s_add_u32 m0, s41, 12288
	v_mov_b32_e32 v30, 0
	v_mov_b32_e32 v31, 0
	global_load_lds_dwordx4 v215, s[98:99]
	s_add_u32 s98, s98, 128
	s_addc_u32 s99, s99, 0
	s_add_u32 m0, s41, 16384
	v_mov_b32_e32 v60, 0
	v_mov_b32_e32 v61, 0
	global_load_lds_dwordx4 v212, s[100:101]
	s_add_u32 m0, s41, 20480
	v_mov_b32_e32 v62, 0
	v_mov_b32_e32 v63, 0
	global_load_lds_dwordx4 v213, s[100:101]
	s_add_u32 m0, s41, 24576
	v_mov_b32_e32 v20, 0
	v_mov_b32_e32 v21, 0
	global_load_lds_dwordx4 v214, s[100:101]
	s_add_u32 m0, s41, 28672
	v_mov_b32_e32 v22, 0
	v_mov_b32_e32 v23, 0
	global_load_lds_dwordx4 v215, s[100:101]
	s_add_u32 s100, s100, 128
	s_addc_u32 s101, s101, 0
	s_add_u32 m0, s41, 32768
	v_mov_b32_e32 v52, 0
	v_mov_b32_e32 v53, 0
	global_load_lds_dwordx4 v212, s[98:99]
	s_add_u32 m0, s41, 36864
	v_mov_b32_e32 v54, 0
	v_mov_b32_e32 v55, 0
	global_load_lds_dwordx4 v213, s[98:99]
	s_add_u32 m0, s41, 40960
	v_mov_b32_e32 v24, 0
	v_mov_b32_e32 v25, 0
	global_load_lds_dwordx4 v214, s[98:99]
	s_add_u32 m0, s41, 45056
	v_mov_b32_e32 v26, 0
	v_mov_b32_e32 v27, 0
	global_load_lds_dwordx4 v215, s[98:99]
	s_add_u32 s98, s98, 128
	s_addc_u32 s99, s99, 0
	s_add_u32 m0, s41, 49152
	v_mov_b32_e32 v56, 0
	v_mov_b32_e32 v57, 0
	global_load_lds_dwordx4 v212, s[100:101]
	s_add_u32 m0, s41, 53248
	v_mov_b32_e32 v58, 0
	v_mov_b32_e32 v59, 0
	global_load_lds_dwordx4 v213, s[100:101]
	s_add_u32 m0, s41, 57344
	v_mov_b32_e32 v12, 0
	v_mov_b32_e32 v13, 0
	global_load_lds_dwordx4 v214, s[100:101]
	s_add_u32 m0, s41, 61440
	v_mov_b32_e32 v14, 0
	v_mov_b32_e32 v15, 0
	global_load_lds_dwordx4 v215, s[100:101]
	s_add_u32 s100, s100, 128
	s_addc_u32 s101, s101, 0
	v_mov_b32_e32 v48, 0
	v_mov_b32_e32 v49, 0
	v_mov_b32_e32 v50, 0
	v_mov_b32_e32 v51, 0
	v_mov_b32_e32 v16, 0
	v_mov_b32_e32 v17, 0
	v_mov_b32_e32 v18, 0
	v_mov_b32_e32 v19, 0
	v_mov_b32_e32 v40, 0
	v_mov_b32_e32 v41, 0
	v_mov_b32_e32 v42, 0
	v_mov_b32_e32 v43, 0
	v_mov_b32_e32 v0, 0
	v_mov_b32_e32 v1, 0
	v_mov_b32_e32 v2, 0
	v_mov_b32_e32 v3, 0
	v_mov_b32_e32 v36, 0
	v_mov_b32_e32 v37, 0
	v_mov_b32_e32 v38, 0
	v_mov_b32_e32 v39, 0
	v_mov_b32_e32 v8, 0
	v_mov_b32_e32 v9, 0
	v_mov_b32_e32 v10, 0
	v_mov_b32_e32 v11, 0
	v_mov_b32_e32 v32, 0
	v_mov_b32_e32 v33, 0
	v_mov_b32_e32 v34, 0
	v_mov_b32_e32 v35, 0
	v_mov_b32_e32 v4, 0
	v_mov_b32_e32 v5, 0
	v_mov_b32_e32 v6, 0
	v_mov_b32_e32 v7, 0
	s_waitcnt vmcnt(8)
	s_barrier
	ds_read_b128 v[64:67], v208 offset:0
	ds_read_b128 v[68:71], v208 offset:2048
	ds_read_b128 v[160:163], v210 offset:16384
	ds_read_b128 v[164:167], v210 offset:18432
	ds_read_b128 v[168:171], v210 offset:20480
	ds_read_b128 v[172:175], v210 offset:22528
	ds_read_b128 v[176:179], v210 offset:24576
	ds_read_b128 v[180:183], v210 offset:26624
	ds_read_b128 v[184:187], v210 offset:28672
	s_waitcnt lgkmcnt(6)
	v_mfma_f32_16x16x32_bf16 v[44:47], v[64:67], v[160:163], v[44:47]
	v_mfma_f32_16x16x32_bf16 v[48:51], v[68:71], v[160:163], v[48:51]
	ds_read_b128 v[188:191], v210 offset:30720
	s_waitcnt lgkmcnt(6)
	v_mfma_f32_16x16x32_bf16 v[28:31], v[64:67], v[164:167], v[28:31]
	v_mfma_f32_16x16x32_bf16 v[16:19], v[68:71], v[164:167], v[16:19]
	ds_read_b128 v[72:75], v209 offset:0
	ds_read_b128 v[216:219], v209 offset:2048
	ds_read_b128 v[192:195], v211 offset:16384
	s_waitcnt lgkmcnt(8)
	v_mfma_f32_16x16x32_bf16 v[60:63], v[64:67], v[168:171], v[60:63]
	v_mfma_f32_16x16x32_bf16 v[40:43], v[68:71], v[168:171], v[40:43]
	ds_read_b128 v[196:199], v211 offset:18432
	s_waitcnt lgkmcnt(8)
	v_mfma_f32_16x16x32_bf16 v[20:23], v[64:67], v[172:175], v[20:23]
	v_mfma_f32_16x16x32_bf16 v[0:3], v[68:71], v[172:175], v[0:3]
	ds_read_b128 v[200:203], v211 offset:20480
	s_waitcnt lgkmcnt(8)
	v_mfma_f32_16x16x32_bf16 v[52:55], v[64:67], v[176:179], v[52:55]
	v_mfma_f32_16x16x32_bf16 v[36:39], v[68:71], v[176:179], v[36:39]
	ds_read_b128 v[204:207], v211 offset:22528
	s_waitcnt lgkmcnt(8)
	v_mfma_f32_16x16x32_bf16 v[24:27], v[64:67], v[180:183], v[24:27]
	v_mfma_f32_16x16x32_bf16 v[8:11], v[68:71], v[180:183], v[8:11]
	ds_read_b128 v[160:163], v211 offset:24576
	s_waitcnt lgkmcnt(8)
	v_mfma_f32_16x16x32_bf16 v[56:59], v[64:67], v[184:187], v[56:59]
	v_mfma_f32_16x16x32_bf16 v[32:35], v[68:71], v[184:187], v[32:35]
	ds_read_b128 v[164:167], v211 offset:26624
	s_waitcnt lgkmcnt(8)
	v_mfma_f32_16x16x32_bf16 v[12:15], v[64:67], v[188:191], v[12:15]
	v_mfma_f32_16x16x32_bf16 v[4:7], v[68:71], v[188:191], v[4:7]
	ds_read_b128 v[168:171], v211 offset:28672
	s_waitcnt lgkmcnt(6)
	v_mfma_f32_16x16x32_bf16 v[44:47], v[72:75], v[192:195], v[44:47]
	v_mfma_f32_16x16x32_bf16 v[48:51], v[216:219], v[192:195], v[48:51]
	ds_read_b128 v[172:175], v211 offset:30720
	s_waitcnt vmcnt(0) lgkmcnt(0)
	s_barrier
	s_add_u32 m0, s41, 0
	s_nop 0
	global_load_lds_dwordx4 v212, s[98:99]
	s_waitcnt lgkmcnt(6)
	v_mfma_f32_16x16x32_bf16 v[28:31], v[72:75], v[196:199], v[28:31]
	v_mfma_f32_16x16x32_bf16 v[16:19], v[216:219], v[196:199], v[16:19]
	ds_read_b128 v[64:67], v208 offset:32768
	ds_read_b128 v[68:71], v208 offset:34816
	ds_read_b128 v[176:179], v210 offset:49152
	s_add_u32 m0, s41, 4096
	s_nop 0
	global_load_lds_dwordx4 v213, s[98:99]
	s_waitcnt lgkmcnt(8)
	v_mfma_f32_16x16x32_bf16 v[60:63], v[72:75], v[200:203], v[60:63]
	v_mfma_f32_16x16x32_bf16 v[40:43], v[216:219], v[200:203], v[40:43]
	ds_read_b128 v[180:183], v210 offset:51200
	s_add_u32 m0, s41, 8192
	s_nop 0
	global_load_lds_dwordx4 v214, s[98:99]
	s_waitcnt lgkmcnt(8)
	v_mfma_f32_16x16x32_bf16 v[20:23], v[72:75], v[204:207], v[20:23]
	v_mfma_f32_16x16x32_bf16 v[0:3], v[216:219], v[204:207], v[0:3]
	ds_read_b128 v[184:187], v210 offset:53248
	s_add_u32 m0, s41, 12288
	s_nop 0
	global_load_lds_dwordx4 v215, s[98:99]
	s_add_u32 s98, s98, 128
	s_addc_u32 s99, s99, 0
	s_waitcnt lgkmcnt(8)
	v_mfma_f32_16x16x32_bf16 v[52:55], v[72:75], v[160:163], v[52:55]
	v_mfma_f32_16x16x32_bf16 v[36:39], v[216:219], v[160:163], v[36:39]
	ds_read_b128 v[188:191], v210 offset:55296
	s_add_u32 m0, s41, 16384
	s_nop 0
	global_load_lds_dwordx4 v212, s[100:101]
	s_waitcnt lgkmcnt(8)
	v_mfma_f32_16x16x32_bf16 v[24:27], v[72:75], v[164:167], v[24:27]
	v_mfma_f32_16x16x32_bf16 v[8:11], v[216:219], v[164:167], v[8:11]
	ds_read_b128 v[192:195], v210 offset:57344
	s_add_u32 m0, s41, 20480
	s_nop 0
	global_load_lds_dwordx4 v213, s[100:101]
	s_waitcnt lgkmcnt(8)
	v_mfma_f32_16x16x32_bf16 v[56:59], v[72:75], v[168:171], v[56:59]
	v_mfma_f32_16x16x32_bf16 v[32:35], v[216:219], v[168:171], v[32:35]
	ds_read_b128 v[196:199], v210 offset:59392
	s_add_u32 m0, s41, 24576
	s_nop 0
	global_load_lds_dwordx4 v214, s[100:101]
	s_waitcnt lgkmcnt(8)
	v_mfma_f32_16x16x32_bf16 v[12:15], v[72:75], v[172:175], v[12:15]
	v_mfma_f32_16x16x32_bf16 v[4:7], v[216:219], v[172:175], v[4:7]
	ds_read_b128 v[200:203], v210 offset:61440
	s_add_u32 m0, s41, 28672
	s_nop 0
	global_load_lds_dwordx4 v215, s[100:101]
	s_add_u32 s100, s100, 128
	s_addc_u32 s101, s101, 0
	s_waitcnt lgkmcnt(6)
	v_mfma_f32_16x16x32_bf16 v[44:47], v[64:67], v[176:179], v[44:47]
	v_mfma_f32_16x16x32_bf16 v[48:51], v[68:71], v[176:179], v[48:51]
	ds_read_b128 v[204:207], v210 offset:63488
	s_waitcnt lgkmcnt(6)
	v_mfma_f32_16x16x32_bf16 v[28:31], v[64:67], v[180:183], v[28:31]
	v_mfma_f32_16x16x32_bf16 v[16:19], v[68:71], v[180:183], v[16:19]
	ds_read_b128 v[72:75], v209 offset:32768
	ds_read_b128 v[216:219], v209 offset:34816
	ds_read_b128 v[160:163], v211 offset:49152
	s_waitcnt lgkmcnt(8)
	v_mfma_f32_16x16x32_bf16 v[60:63], v[64:67], v[184:187], v[60:63]
	v_mfma_f32_16x16x32_bf16 v[40:43], v[68:71], v[184:187], v[40:43]
	ds_read_b128 v[164:167], v211 offset:51200
	s_waitcnt lgkmcnt(8)
	v_mfma_f32_16x16x32_bf16 v[20:23], v[64:67], v[188:191], v[20:23]
	v_mfma_f32_16x16x32_bf16 v[0:3], v[68:71], v[188:191], v[0:3]
	ds_read_b128 v[168:171], v211 offset:53248
	s_waitcnt lgkmcnt(8)
	v_mfma_f32_16x16x32_bf16 v[52:55], v[64:67], v[192:195], v[52:55]
	v_mfma_f32_16x16x32_bf16 v[36:39], v[68:71], v[192:195], v[36:39]
	ds_read_b128 v[172:175], v211 offset:55296
	s_waitcnt lgkmcnt(8)
	v_mfma_f32_16x16x32_bf16 v[24:27], v[64:67], v[196:199], v[24:27]
	v_mfma_f32_16x16x32_bf16 v[8:11], v[68:71], v[196:199], v[8:11]
	ds_read_b128 v[176:179], v211 offset:57344
	s_waitcnt lgkmcnt(8)
	v_mfma_f32_16x16x32_bf16 v[56:59], v[64:67], v[200:203], v[56:59]
	v_mfma_f32_16x16x32_bf16 v[32:35], v[68:71], v[200:203], v[32:35]
	ds_read_b128 v[180:183], v211 offset:59392
	s_waitcnt lgkmcnt(8)
	v_mfma_f32_16x16x32_bf16 v[12:15], v[64:67], v[204:207], v[12:15]
	v_mfma_f32_16x16x32_bf16 v[4:7], v[68:71], v[204:207], v[4:7]
	ds_read_b128 v[184:187], v211 offset:61440
	s_waitcnt lgkmcnt(6)
	v_mfma_f32_16x16x32_bf16 v[44:47], v[72:75], v[160:163], v[44:47]
	v_mfma_f32_16x16x32_bf16 v[48:51], v[216:219], v[160:163], v[48:51]
	ds_read_b128 v[188:191], v211 offset:63488
	s_waitcnt vmcnt(0) lgkmcnt(0)
	s_barrier
	s_add_u32 m0, s41, 32768
	s_nop 0
	global_load_lds_dwordx4 v212, s[98:99]
	s_waitcnt lgkmcnt(6)
	v_mfma_f32_16x16x32_bf16 v[28:31], v[72:75], v[164:167], v[28:31]
	v_mfma_f32_16x16x32_bf16 v[16:19], v[216:219], v[164:167], v[16:19]
	ds_read_b128 v[64:67], v208 offset:0
	ds_read_b128 v[68:71], v208 offset:2048
	ds_read_b128 v[192:195], v210 offset:16384
	s_add_u32 m0, s41, 36864
	s_nop 0
	global_load_lds_dwordx4 v213, s[98:99]
	s_waitcnt lgkmcnt(8)
	v_mfma_f32_16x16x32_bf16 v[60:63], v[72:75], v[168:171], v[60:63]
	v_mfma_f32_16x16x32_bf16 v[40:43], v[216:219], v[168:171], v[40:43]
	ds_read_b128 v[196:199], v210 offset:18432
	s_add_u32 m0, s41, 40960
	s_nop 0
	global_load_lds_dwordx4 v214, s[98:99]
	s_waitcnt lgkmcnt(8)
	v_mfma_f32_16x16x32_bf16 v[20:23], v[72:75], v[172:175], v[20:23]
	v_mfma_f32_16x16x32_bf16 v[0:3], v[216:219], v[172:175], v[0:3]
	ds_read_b128 v[200:203], v210 offset:20480
	s_add_u32 m0, s41, 45056
	s_nop 0
	global_load_lds_dwordx4 v215, s[98:99]
	s_add_u32 s98, s98, 128
	s_addc_u32 s99, s99, 0
	s_waitcnt lgkmcnt(8)
	v_mfma_f32_16x16x32_bf16 v[52:55], v[72:75], v[176:179], v[52:55]
	v_mfma_f32_16x16x32_bf16 v[36:39], v[216:219], v[176:179], v[36:39]
	ds_read_b128 v[204:207], v210 offset:22528
	s_add_u32 m0, s41, 49152
	s_nop 0
	global_load_lds_dwordx4 v212, s[100:101]
	s_waitcnt lgkmcnt(8)
	v_mfma_f32_16x16x32_bf16 v[24:27], v[72:75], v[180:183], v[24:27]
	v_mfma_f32_16x16x32_bf16 v[8:11], v[216:219], v[180:183], v[8:11]
	ds_read_b128 v[160:163], v210 offset:24576
	s_add_u32 m0, s41, 53248
	s_nop 0
	global_load_lds_dwordx4 v213, s[100:101]
	s_waitcnt lgkmcnt(8)
	v_mfma_f32_16x16x32_bf16 v[56:59], v[72:75], v[184:187], v[56:59]
	v_mfma_f32_16x16x32_bf16 v[32:35], v[216:219], v[184:187], v[32:35]
	ds_read_b128 v[164:167], v210 offset:26624
	s_add_u32 m0, s41, 57344
	s_nop 0
	global_load_lds_dwordx4 v214, s[100:101]
	s_waitcnt lgkmcnt(8)
	v_mfma_f32_16x16x32_bf16 v[12:15], v[72:75], v[188:191], v[12:15]
	v_mfma_f32_16x16x32_bf16 v[4:7], v[216:219], v[188:191], v[4:7]
	ds_read_b128 v[168:171], v210 offset:28672
	s_add_u32 m0, s41, 61440
	s_nop 0
	global_load_lds_dwordx4 v215, s[100:101]
	s_add_u32 s100, s100, 128
	s_addc_u32 s101, s101, 0
	s_waitcnt lgkmcnt(6)
	v_mfma_f32_16x16x32_bf16 v[44:47], v[64:67], v[192:195], v[44:47]
	v_mfma_f32_16x16x32_bf16 v[48:51], v[68:71], v[192:195], v[48:51]
	ds_read_b128 v[172:175], v210 offset:30720
	s_waitcnt lgkmcnt(6)
	v_mfma_f32_16x16x32_bf16 v[28:31], v[64:67], v[196:199], v[28:31]
	v_mfma_f32_16x16x32_bf16 v[16:19], v[68:71], v[196:199], v[16:19]
	ds_read_b128 v[72:75], v209 offset:0
	ds_read_b128 v[216:219], v209 offset:2048
	ds_read_b128 v[176:179], v211 offset:16384
	s_waitcnt lgkmcnt(8)
	v_mfma_f32_16x16x32_bf16 v[60:63], v[64:67], v[200:203], v[60:63]
	v_mfma_f32_16x16x32_bf16 v[40:43], v[68:71], v[200:203], v[40:43]
	ds_read_b128 v[180:183], v211 offset:18432
	s_waitcnt lgkmcnt(8)
	v_mfma_f32_16x16x32_bf16 v[20:23], v[64:67], v[204:207], v[20:23]
	v_mfma_f32_16x16x32_bf16 v[0:3], v[68:71], v[204:207], v[0:3]
	ds_read_b128 v[184:187], v211 offset:20480
	s_waitcnt lgkmcnt(8)
	v_mfma_f32_16x16x32_bf16 v[52:55], v[64:67], v[160:163], v[52:55]
	v_mfma_f32_16x16x32_bf16 v[36:39], v[68:71], v[160:163], v[36:39]
	ds_read_b128 v[188:191], v211 offset:22528
	s_waitcnt lgkmcnt(8)
	v_mfma_f32_16x16x32_bf16 v[24:27], v[64:67], v[164:167], v[24:27]
	v_mfma_f32_16x16x32_bf16 v[8:11], v[68:71], v[164:167], v[8:11]
	ds_read_b128 v[192:195], v211 offset:24576
	s_waitcnt lgkmcnt(8)
	v_mfma_f32_16x16x32_bf16 v[56:59], v[64:67], v[168:171], v[56:59]
	v_mfma_f32_16x16x32_bf16 v[32:35], v[68:71], v[168:171], v[32:35]
	ds_read_b128 v[196:199], v211 offset:26624
	s_waitcnt lgkmcnt(8)
	v_mfma_f32_16x16x32_bf16 v[12:15], v[64:67], v[172:175], v[12:15]
	v_mfma_f32_16x16x32_bf16 v[4:7], v[68:71], v[172:175], v[4:7]
	ds_read_b128 v[200:203], v211 offset:28672
	s_waitcnt lgkmcnt(6)
	v_mfma_f32_16x16x32_bf16 v[44:47], v[72:75], v[176:179], v[44:47]
	v_mfma_f32_16x16x32_bf16 v[48:51], v[216:219], v[176:179], v[48:51]
	ds_read_b128 v[204:207], v211 offset:30720
	s_waitcnt vmcnt(0) lgkmcnt(0)
	s_barrier
	s_add_u32 m0, s41, 0
	s_nop 0
	global_load_lds_dwordx4 v212, s[98:99]
	s_waitcnt lgkmcnt(6)
	v_mfma_f32_16x16x32_bf16 v[28:31], v[72:75], v[180:183], v[28:31]
	v_mfma_f32_16x16x32_bf16 v[16:19], v[216:219], v[180:183], v[16:19]
	ds_read_b128 v[64:67], v208 offset:32768
	ds_read_b128 v[68:71], v208 offset:34816
	ds_read_b128 v[160:163], v210 offset:49152
	s_add_u32 m0, s41, 4096
	s_nop 0
	global_load_lds_dwordx4 v213, s[98:99]
	s_waitcnt lgkmcnt(8)
	v_mfma_f32_16x16x32_bf16 v[60:63], v[72:75], v[184:187], v[60:63]
	v_mfma_f32_16x16x32_bf16 v[40:43], v[216:219], v[184:187], v[40:43]
	ds_read_b128 v[164:167], v210 offset:51200
	s_add_u32 m0, s41, 8192
	s_nop 0
	global_load_lds_dwordx4 v214, s[98:99]
	s_waitcnt lgkmcnt(8)
	v_mfma_f32_16x16x32_bf16 v[20:23], v[72:75], v[188:191], v[20:23]
	v_mfma_f32_16x16x32_bf16 v[0:3], v[216:219], v[188:191], v[0:3]
	ds_read_b128 v[168:171], v210 offset:53248
	s_add_u32 m0, s41, 12288
	s_nop 0
	global_load_lds_dwordx4 v215, s[98:99]
	s_add_u32 s98, s98, 128
	s_addc_u32 s99, s99, 0
	s_waitcnt lgkmcnt(8)
	v_mfma_f32_16x16x32_bf16 v[52:55], v[72:75], v[192:195], v[52:55]
	v_mfma_f32_16x16x32_bf16 v[36:39], v[216:219], v[192:195], v[36:39]
	ds_read_b128 v[172:175], v210 offset:55296
	s_add_u32 m0, s41, 16384
	s_nop 0
	global_load_lds_dwordx4 v212, s[100:101]
	s_waitcnt lgkmcnt(8)
	v_mfma_f32_16x16x32_bf16 v[24:27], v[72:75], v[196:199], v[24:27]
	v_mfma_f32_16x16x32_bf16 v[8:11], v[216:219], v[196:199], v[8:11]
	ds_read_b128 v[176:179], v210 offset:57344
	s_add_u32 m0, s41, 20480
	s_nop 0
	global_load_lds_dwordx4 v213, s[100:101]
	s_waitcnt lgkmcnt(8)
	v_mfma_f32_16x16x32_bf16 v[56:59], v[72:75], v[200:203], v[56:59]
	v_mfma_f32_16x16x32_bf16 v[32:35], v[216:219], v[200:203], v[32:35]
	ds_read_b128 v[180:183], v210 offset:59392
	s_add_u32 m0, s41, 24576
	s_nop 0
	global_load_lds_dwordx4 v214, s[100:101]
	s_waitcnt lgkmcnt(8)
	v_mfma_f32_16x16x32_bf16 v[12:15], v[72:75], v[204:207], v[12:15]
	v_mfma_f32_16x16x32_bf16 v[4:7], v[216:219], v[204:207], v[4:7]
	ds_read_b128 v[184:187], v210 offset:61440
	s_add_u32 m0, s41, 28672
	s_nop 0
	global_load_lds_dwordx4 v215, s[100:101]
	s_add_u32 s100, s100, 128
	s_addc_u32 s101, s101, 0
	s_waitcnt lgkmcnt(6)
	v_mfma_f32_16x16x32_bf16 v[44:47], v[64:67], v[160:163], v[44:47]
	v_mfma_f32_16x16x32_bf16 v[48:51], v[68:71], v[160:163], v[48:51]
	ds_read_b128 v[188:191], v210 offset:63488
	s_waitcnt lgkmcnt(6)
	v_mfma_f32_16x16x32_bf16 v[28:31], v[64:67], v[164:167], v[28:31]
	v_mfma_f32_16x16x32_bf16 v[16:19], v[68:71], v[164:167], v[16:19]
	ds_read_b128 v[72:75], v209 offset:32768
	ds_read_b128 v[216:219], v209 offset:34816
	ds_read_b128 v[192:195], v211 offset:49152
	s_waitcnt lgkmcnt(8)
	v_mfma_f32_16x16x32_bf16 v[60:63], v[64:67], v[168:171], v[60:63]
	v_mfma_f32_16x16x32_bf16 v[40:43], v[68:71], v[168:171], v[40:43]
	ds_read_b128 v[196:199], v211 offset:51200
	s_waitcnt lgkmcnt(8)
	v_mfma_f32_16x16x32_bf16 v[20:23], v[64:67], v[172:175], v[20:23]
	v_mfma_f32_16x16x32_bf16 v[0:3], v[68:71], v[172:175], v[0:3]
	ds_read_b128 v[200:203], v211 offset:53248
	s_waitcnt lgkmcnt(8)
	v_mfma_f32_16x16x32_bf16 v[52:55], v[64:67], v[176:179], v[52:55]
	v_mfma_f32_16x16x32_bf16 v[36:39], v[68:71], v[176:179], v[36:39]
	ds_read_b128 v[204:207], v211 offset:55296
	s_waitcnt lgkmcnt(8)
	v_mfma_f32_16x16x32_bf16 v[24:27], v[64:67], v[180:183], v[24:27]
	v_mfma_f32_16x16x32_bf16 v[8:11], v[68:71], v[180:183], v[8:11]
	ds_read_b128 v[160:163], v211 offset:57344
	s_waitcnt lgkmcnt(8)
	v_mfma_f32_16x16x32_bf16 v[56:59], v[64:67], v[184:187], v[56:59]
	v_mfma_f32_16x16x32_bf16 v[32:35], v[68:71], v[184:187], v[32:35]
	ds_read_b128 v[164:167], v211 offset:59392
	s_waitcnt lgkmcnt(8)
	v_mfma_f32_16x16x32_bf16 v[12:15], v[64:67], v[188:191], v[12:15]
	v_mfma_f32_16x16x32_bf16 v[4:7], v[68:71], v[188:191], v[4:7]
	ds_read_b128 v[168:171], v211 offset:61440
	s_waitcnt lgkmcnt(6)
	v_mfma_f32_16x16x32_bf16 v[44:47], v[72:75], v[192:195], v[44:47]
	v_mfma_f32_16x16x32_bf16 v[48:51], v[216:219], v[192:195], v[48:51]
	ds_read_b128 v[172:175], v211 offset:63488
	s_waitcnt vmcnt(0) lgkmcnt(0)
	s_barrier
	s_add_u32 m0, s41, 32768
	s_nop 0
	global_load_lds_dwordx4 v212, s[98:99]
	s_waitcnt lgkmcnt(6)
	v_mfma_f32_16x16x32_bf16 v[28:31], v[72:75], v[196:199], v[28:31]
	v_mfma_f32_16x16x32_bf16 v[16:19], v[216:219], v[196:199], v[16:19]
	ds_read_b128 v[64:67], v208 offset:0
	ds_read_b128 v[68:71], v208 offset:2048
	ds_read_b128 v[176:179], v210 offset:16384
	s_add_u32 m0, s41, 36864
	s_nop 0
	global_load_lds_dwordx4 v213, s[98:99]
	s_waitcnt lgkmcnt(8)
	v_mfma_f32_16x16x32_bf16 v[60:63], v[72:75], v[200:203], v[60:63]
	v_mfma_f32_16x16x32_bf16 v[40:43], v[216:219], v[200:203], v[40:43]
	ds_read_b128 v[180:183], v210 offset:18432
	s_add_u32 m0, s41, 40960
	s_nop 0
	global_load_lds_dwordx4 v214, s[98:99]
	s_waitcnt lgkmcnt(8)
	v_mfma_f32_16x16x32_bf16 v[20:23], v[72:75], v[204:207], v[20:23]
	v_mfma_f32_16x16x32_bf16 v[0:3], v[216:219], v[204:207], v[0:3]
	ds_read_b128 v[184:187], v210 offset:20480
	s_add_u32 m0, s41, 45056
	s_nop 0
	global_load_lds_dwordx4 v215, s[98:99]
	s_add_u32 s98, s98, 128
	s_addc_u32 s99, s99, 0
	s_waitcnt lgkmcnt(8)
	v_mfma_f32_16x16x32_bf16 v[52:55], v[72:75], v[160:163], v[52:55]
	v_mfma_f32_16x16x32_bf16 v[36:39], v[216:219], v[160:163], v[36:39]
	ds_read_b128 v[188:191], v210 offset:22528
	s_add_u32 m0, s41, 49152
	s_nop 0
	global_load_lds_dwordx4 v212, s[100:101]
	s_waitcnt lgkmcnt(8)
	v_mfma_f32_16x16x32_bf16 v[24:27], v[72:75], v[164:167], v[24:27]
	v_mfma_f32_16x16x32_bf16 v[8:11], v[216:219], v[164:167], v[8:11]
	ds_read_b128 v[192:195], v210 offset:24576
	s_add_u32 m0, s41, 53248
	s_nop 0
	global_load_lds_dwordx4 v213, s[100:101]
	s_waitcnt lgkmcnt(8)
	v_mfma_f32_16x16x32_bf16 v[56:59], v[72:75], v[168:171], v[56:59]
	v_mfma_f32_16x16x32_bf16 v[32:35], v[216:219], v[168:171], v[32:35]
	ds_read_b128 v[196:199], v210 offset:26624
	s_add_u32 m0, s41, 57344
	s_nop 0
	global_load_lds_dwordx4 v214, s[100:101]
	s_waitcnt lgkmcnt(8)
	v_mfma_f32_16x16x32_bf16 v[12:15], v[72:75], v[172:175], v[12:15]
	v_mfma_f32_16x16x32_bf16 v[4:7], v[216:219], v[172:175], v[4:7]
	ds_read_b128 v[200:203], v210 offset:28672
	s_add_u32 m0, s41, 61440
	s_nop 0
	global_load_lds_dwordx4 v215, s[100:101]
	s_add_u32 s100, s100, 128
	s_addc_u32 s101, s101, 0
	s_waitcnt lgkmcnt(6)
	v_mfma_f32_16x16x32_bf16 v[44:47], v[64:67], v[176:179], v[44:47]
	v_mfma_f32_16x16x32_bf16 v[48:51], v[68:71], v[176:179], v[48:51]
	ds_read_b128 v[204:207], v210 offset:30720
	s_waitcnt lgkmcnt(6)
	v_mfma_f32_16x16x32_bf16 v[28:31], v[64:67], v[180:183], v[28:31]
	v_mfma_f32_16x16x32_bf16 v[16:19], v[68:71], v[180:183], v[16:19]
	ds_read_b128 v[72:75], v209 offset:0
	ds_read_b128 v[216:219], v209 offset:2048
	ds_read_b128 v[160:163], v211 offset:16384
	s_waitcnt lgkmcnt(8)
	v_mfma_f32_16x16x32_bf16 v[60:63], v[64:67], v[184:187], v[60:63]
	v_mfma_f32_16x16x32_bf16 v[40:43], v[68:71], v[184:187], v[40:43]
	ds_read_b128 v[164:167], v211 offset:18432
	s_waitcnt lgkmcnt(8)
	v_mfma_f32_16x16x32_bf16 v[20:23], v[64:67], v[188:191], v[20:23]
	v_mfma_f32_16x16x32_bf16 v[0:3], v[68:71], v[188:191], v[0:3]
	ds_read_b128 v[168:171], v211 offset:20480
	s_waitcnt lgkmcnt(8)
	v_mfma_f32_16x16x32_bf16 v[52:55], v[64:67], v[192:195], v[52:55]
	v_mfma_f32_16x16x32_bf16 v[36:39], v[68:71], v[192:195], v[36:39]
	ds_read_b128 v[172:175], v211 offset:22528
	s_waitcnt lgkmcnt(8)
	v_mfma_f32_16x16x32_bf16 v[24:27], v[64:67], v[196:199], v[24:27]
	v_mfma_f32_16x16x32_bf16 v[8:11], v[68:71], v[196:199], v[8:11]
	ds_read_b128 v[176:179], v211 offset:24576
	s_waitcnt lgkmcnt(8)
	v_mfma_f32_16x16x32_bf16 v[56:59], v[64:67], v[200:203], v[56:59]
	v_mfma_f32_16x16x32_bf16 v[32:35], v[68:71], v[200:203], v[32:35]
	ds_read_b128 v[180:183], v211 offset:26624
	s_waitcnt lgkmcnt(8)
	v_mfma_f32_16x16x32_bf16 v[12:15], v[64:67], v[204:207], v[12:15]
	v_mfma_f32_16x16x32_bf16 v[4:7], v[68:71], v[204:207], v[4:7]
	ds_read_b128 v[184:187], v211 offset:28672
	s_waitcnt lgkmcnt(6)
	v_mfma_f32_16x16x32_bf16 v[44:47], v[72:75], v[160:163], v[44:47]
	v_mfma_f32_16x16x32_bf16 v[48:51], v[216:219], v[160:163], v[48:51]
	ds_read_b128 v[188:191], v211 offset:30720
	s_waitcnt vmcnt(0) lgkmcnt(0)
	s_barrier
	s_add_u32 m0, s41, 0
	s_nop 0
	global_load_lds_dwordx4 v212, s[98:99]
	s_waitcnt lgkmcnt(6)
	v_mfma_f32_16x16x32_bf16 v[28:31], v[72:75], v[164:167], v[28:31]
	v_mfma_f32_16x16x32_bf16 v[16:19], v[216:219], v[164:167], v[16:19]
	ds_read_b128 v[64:67], v208 offset:32768
	ds_read_b128 v[68:71], v208 offset:34816
	ds_read_b128 v[192:195], v210 offset:49152
	s_add_u32 m0, s41, 4096
	s_nop 0
	global_load_lds_dwordx4 v213, s[98:99]
	s_waitcnt lgkmcnt(8)
	v_mfma_f32_16x16x32_bf16 v[60:63], v[72:75], v[168:171], v[60:63]
	v_mfma_f32_16x16x32_bf16 v[40:43], v[216:219], v[168:171], v[40:43]
	ds_read_b128 v[196:199], v210 offset:51200
	s_add_u32 m0, s41, 8192
	s_nop 0
	global_load_lds_dwordx4 v214, s[98:99]
	s_waitcnt lgkmcnt(8)
	v_mfma_f32_16x16x32_bf16 v[20:23], v[72:75], v[172:175], v[20:23]
	v_mfma_f32_16x16x32_bf16 v[0:3], v[216:219], v[172:175], v[0:3]
	ds_read_b128 v[200:203], v210 offset:53248
	s_add_u32 m0, s41, 12288
	s_nop 0
	global_load_lds_dwordx4 v215, s[98:99]
	s_add_u32 s98, s98, 128
	s_addc_u32 s99, s99, 0
	s_waitcnt lgkmcnt(8)
	v_mfma_f32_16x16x32_bf16 v[52:55], v[72:75], v[176:179], v[52:55]
	v_mfma_f32_16x16x32_bf16 v[36:39], v[216:219], v[176:179], v[36:39]
	ds_read_b128 v[204:207], v210 offset:55296
	s_add_u32 m0, s41, 16384
	s_nop 0
	global_load_lds_dwordx4 v212, s[100:101]
	s_waitcnt lgkmcnt(8)
	v_mfma_f32_16x16x32_bf16 v[24:27], v[72:75], v[180:183], v[24:27]
	v_mfma_f32_16x16x32_bf16 v[8:11], v[216:219], v[180:183], v[8:11]
	ds_read_b128 v[160:163], v210 offset:57344
	s_add_u32 m0, s41, 20480
	s_nop 0
	global_load_lds_dwordx4 v213, s[100:101]
	s_waitcnt lgkmcnt(8)
	v_mfma_f32_16x16x32_bf16 v[56:59], v[72:75], v[184:187], v[56:59]
	v_mfma_f32_16x16x32_bf16 v[32:35], v[216:219], v[184:187], v[32:35]
	ds_read_b128 v[164:167], v210 offset:59392
	s_add_u32 m0, s41, 24576
	s_nop 0
	global_load_lds_dwordx4 v214, s[100:101]
	s_waitcnt lgkmcnt(8)
	v_mfma_f32_16x16x32_bf16 v[12:15], v[72:75], v[188:191], v[12:15]
	v_mfma_f32_16x16x32_bf16 v[4:7], v[216:219], v[188:191], v[4:7]
	ds_read_b128 v[168:171], v210 offset:61440
	s_add_u32 m0, s41, 28672
	s_nop 0
	global_load_lds_dwordx4 v215, s[100:101]
	s_add_u32 s100, s100, 128
	s_addc_u32 s101, s101, 0
	s_waitcnt lgkmcnt(6)
	v_mfma_f32_16x16x32_bf16 v[44:47], v[64:67], v[192:195], v[44:47]
	v_mfma_f32_16x16x32_bf16 v[48:51], v[68:71], v[192:195], v[48:51]
	ds_read_b128 v[172:175], v210 offset:63488
	s_waitcnt lgkmcnt(6)
	v_mfma_f32_16x16x32_bf16 v[28:31], v[64:67], v[196:199], v[28:31]
	v_mfma_f32_16x16x32_bf16 v[16:19], v[68:71], v[196:199], v[16:19]
	ds_read_b128 v[72:75], v209 offset:32768
	ds_read_b128 v[216:219], v209 offset:34816
	ds_read_b128 v[176:179], v211 offset:49152
	s_waitcnt lgkmcnt(8)
	v_mfma_f32_16x16x32_bf16 v[60:63], v[64:67], v[200:203], v[60:63]
	v_mfma_f32_16x16x32_bf16 v[40:43], v[68:71], v[200:203], v[40:43]
	ds_read_b128 v[180:183], v211 offset:51200
	s_waitcnt lgkmcnt(8)
	v_mfma_f32_16x16x32_bf16 v[20:23], v[64:67], v[204:207], v[20:23]
	v_mfma_f32_16x16x32_bf16 v[0:3], v[68:71], v[204:207], v[0:3]
	ds_read_b128 v[184:187], v211 offset:53248
	s_waitcnt lgkmcnt(8)
	v_mfma_f32_16x16x32_bf16 v[52:55], v[64:67], v[160:163], v[52:55]
	v_mfma_f32_16x16x32_bf16 v[36:39], v[68:71], v[160:163], v[36:39]
	ds_read_b128 v[188:191], v211 offset:55296
	s_waitcnt lgkmcnt(8)
	v_mfma_f32_16x16x32_bf16 v[24:27], v[64:67], v[164:167], v[24:27]
	v_mfma_f32_16x16x32_bf16 v[8:11], v[68:71], v[164:167], v[8:11]
	ds_read_b128 v[192:195], v211 offset:57344
	s_waitcnt lgkmcnt(8)
	v_mfma_f32_16x16x32_bf16 v[56:59], v[64:67], v[168:171], v[56:59]
	v_mfma_f32_16x16x32_bf16 v[32:35], v[68:71], v[168:171], v[32:35]
	ds_read_b128 v[196:199], v211 offset:59392
	s_waitcnt lgkmcnt(8)
	v_mfma_f32_16x16x32_bf16 v[12:15], v[64:67], v[172:175], v[12:15]
	v_mfma_f32_16x16x32_bf16 v[4:7], v[68:71], v[172:175], v[4:7]
	ds_read_b128 v[200:203], v211 offset:61440
	s_waitcnt lgkmcnt(6)
	v_mfma_f32_16x16x32_bf16 v[44:47], v[72:75], v[176:179], v[44:47]
	v_mfma_f32_16x16x32_bf16 v[48:51], v[216:219], v[176:179], v[48:51]
	ds_read_b128 v[204:207], v211 offset:63488
	s_waitcnt vmcnt(0) lgkmcnt(0)
	s_barrier
	s_add_u32 m0, s41, 32768
	s_nop 0
	global_load_lds_dwordx4 v212, s[98:99]
	s_waitcnt lgkmcnt(6)
	v_mfma_f32_16x16x32_bf16 v[28:31], v[72:75], v[180:183], v[28:31]
	v_mfma_f32_16x16x32_bf16 v[16:19], v[216:219], v[180:183], v[16:19]
	ds_read_b128 v[64:67], v208 offset:0
	ds_read_b128 v[68:71], v208 offset:2048
	ds_read_b128 v[160:163], v210 offset:16384
	s_add_u32 m0, s41, 36864
	s_nop 0
	global_load_lds_dwordx4 v213, s[98:99]
	s_waitcnt lgkmcnt(8)
	v_mfma_f32_16x16x32_bf16 v[60:63], v[72:75], v[184:187], v[60:63]
	v_mfma_f32_16x16x32_bf16 v[40:43], v[216:219], v[184:187], v[40:43]
	ds_read_b128 v[164:167], v210 offset:18432
	s_add_u32 m0, s41, 40960
	s_nop 0
	global_load_lds_dwordx4 v214, s[98:99]
	s_waitcnt lgkmcnt(8)
	v_mfma_f32_16x16x32_bf16 v[20:23], v[72:75], v[188:191], v[20:23]
	v_mfma_f32_16x16x32_bf16 v[0:3], v[216:219], v[188:191], v[0:3]
	ds_read_b128 v[168:171], v210 offset:20480
	s_add_u32 m0, s41, 45056
	s_nop 0
	global_load_lds_dwordx4 v215, s[98:99]
	s_add_u32 s98, s98, 128
	s_addc_u32 s99, s99, 0
	s_waitcnt lgkmcnt(8)
	v_mfma_f32_16x16x32_bf16 v[52:55], v[72:75], v[192:195], v[52:55]
	v_mfma_f32_16x16x32_bf16 v[36:39], v[216:219], v[192:195], v[36:39]
	ds_read_b128 v[172:175], v210 offset:22528
	s_add_u32 m0, s41, 49152
	s_nop 0
	global_load_lds_dwordx4 v212, s[100:101]
	s_waitcnt lgkmcnt(8)
	v_mfma_f32_16x16x32_bf16 v[24:27], v[72:75], v[196:199], v[24:27]
	v_mfma_f32_16x16x32_bf16 v[8:11], v[216:219], v[196:199], v[8:11]
	ds_read_b128 v[176:179], v210 offset:24576
	s_add_u32 m0, s41, 53248
	s_nop 0
	global_load_lds_dwordx4 v213, s[100:101]
	s_waitcnt lgkmcnt(8)
	v_mfma_f32_16x16x32_bf16 v[56:59], v[72:75], v[200:203], v[56:59]
	v_mfma_f32_16x16x32_bf16 v[32:35], v[216:219], v[200:203], v[32:35]
	ds_read_b128 v[180:183], v210 offset:26624
	s_add_u32 m0, s41, 57344
	s_nop 0
	global_load_lds_dwordx4 v214, s[100:101]
	s_waitcnt lgkmcnt(8)
	v_mfma_f32_16x16x32_bf16 v[12:15], v[72:75], v[204:207], v[12:15]
	v_mfma_f32_16x16x32_bf16 v[4:7], v[216:219], v[204:207], v[4:7]
	ds_read_b128 v[184:187], v210 offset:28672
	s_add_u32 m0, s41, 61440
	s_nop 0
	global_load_lds_dwordx4 v215, s[100:101]
	s_add_u32 s100, s100, 128
	s_addc_u32 s101, s101, 0
	s_waitcnt lgkmcnt(6)
	v_mfma_f32_16x16x32_bf16 v[44:47], v[64:67], v[160:163], v[44:47]
	v_mfma_f32_16x16x32_bf16 v[48:51], v[68:71], v[160:163], v[48:51]
	ds_read_b128 v[188:191], v210 offset:30720
	s_waitcnt lgkmcnt(6)
	v_mfma_f32_16x16x32_bf16 v[28:31], v[64:67], v[164:167], v[28:31]
	v_mfma_f32_16x16x32_bf16 v[16:19], v[68:71], v[164:167], v[16:19]
	ds_read_b128 v[72:75], v209 offset:0
	ds_read_b128 v[216:219], v209 offset:2048
	ds_read_b128 v[192:195], v211 offset:16384
	s_waitcnt lgkmcnt(8)
	v_mfma_f32_16x16x32_bf16 v[60:63], v[64:67], v[168:171], v[60:63]
	v_mfma_f32_16x16x32_bf16 v[40:43], v[68:71], v[168:171], v[40:43]
	ds_read_b128 v[196:199], v211 offset:18432
	s_waitcnt lgkmcnt(8)
	v_mfma_f32_16x16x32_bf16 v[20:23], v[64:67], v[172:175], v[20:23]
	v_mfma_f32_16x16x32_bf16 v[0:3], v[68:71], v[172:175], v[0:3]
	ds_read_b128 v[200:203], v211 offset:20480
	s_waitcnt lgkmcnt(8)
	v_mfma_f32_16x16x32_bf16 v[52:55], v[64:67], v[176:179], v[52:55]
	v_mfma_f32_16x16x32_bf16 v[36:39], v[68:71], v[176:179], v[36:39]
	ds_read_b128 v[204:207], v211 offset:22528
	s_waitcnt lgkmcnt(8)
	v_mfma_f32_16x16x32_bf16 v[24:27], v[64:67], v[180:183], v[24:27]
	v_mfma_f32_16x16x32_bf16 v[8:11], v[68:71], v[180:183], v[8:11]
	ds_read_b128 v[160:163], v211 offset:24576
	s_waitcnt lgkmcnt(8)
	v_mfma_f32_16x16x32_bf16 v[56:59], v[64:67], v[184:187], v[56:59]
	v_mfma_f32_16x16x32_bf16 v[32:35], v[68:71], v[184:187], v[32:35]
	ds_read_b128 v[164:167], v211 offset:26624
	s_waitcnt lgkmcnt(8)
	v_mfma_f32_16x16x32_bf16 v[12:15], v[64:67], v[188:191], v[12:15]
	v_mfma_f32_16x16x32_bf16 v[4:7], v[68:71], v[188:191], v[4:7]
	ds_read_b128 v[168:171], v211 offset:28672
	s_waitcnt lgkmcnt(6)
	v_mfma_f32_16x16x32_bf16 v[44:47], v[72:75], v[192:195], v[44:47]
	v_mfma_f32_16x16x32_bf16 v[48:51], v[216:219], v[192:195], v[48:51]
	ds_read_b128 v[172:175], v211 offset:30720
	s_waitcnt vmcnt(0) lgkmcnt(0)
	s_barrier
	s_add_u32 m0, s41, 0
	s_nop 0
	global_load_lds_dwordx4 v212, s[98:99]
	s_waitcnt lgkmcnt(6)
	v_mfma_f32_16x16x32_bf16 v[28:31], v[72:75], v[196:199], v[28:31]
	v_mfma_f32_16x16x32_bf16 v[16:19], v[216:219], v[196:199], v[16:19]
	ds_read_b128 v[64:67], v208 offset:32768
	ds_read_b128 v[68:71], v208 offset:34816
	ds_read_b128 v[176:179], v210 offset:49152
	s_add_u32 m0, s41, 4096
	s_nop 0
	global_load_lds_dwordx4 v213, s[98:99]
	s_waitcnt lgkmcnt(8)
	v_mfma_f32_16x16x32_bf16 v[60:63], v[72:75], v[200:203], v[60:63]
	v_mfma_f32_16x16x32_bf16 v[40:43], v[216:219], v[200:203], v[40:43]
	ds_read_b128 v[180:183], v210 offset:51200
	s_add_u32 m0, s41, 8192
	s_nop 0
	global_load_lds_dwordx4 v214, s[98:99]
	s_waitcnt lgkmcnt(8)
	v_mfma_f32_16x16x32_bf16 v[20:23], v[72:75], v[204:207], v[20:23]
	v_mfma_f32_16x16x32_bf16 v[0:3], v[216:219], v[204:207], v[0:3]
	ds_read_b128 v[184:187], v210 offset:53248
	s_add_u32 m0, s41, 12288
	s_nop 0
	global_load_lds_dwordx4 v215, s[98:99]
	s_add_u32 s98, s98, 128
	s_addc_u32 s99, s99, 0
	s_waitcnt lgkmcnt(8)
	v_mfma_f32_16x16x32_bf16 v[52:55], v[72:75], v[160:163], v[52:55]
	v_mfma_f32_16x16x32_bf16 v[36:39], v[216:219], v[160:163], v[36:39]
	ds_read_b128 v[188:191], v210 offset:55296
	s_add_u32 m0, s41, 16384
	s_nop 0
	global_load_lds_dwordx4 v212, s[100:101]
	s_waitcnt lgkmcnt(8)
	v_mfma_f32_16x16x32_bf16 v[24:27], v[72:75], v[164:167], v[24:27]
	v_mfma_f32_16x16x32_bf16 v[8:11], v[216:219], v[164:167], v[8:11]
	ds_read_b128 v[192:195], v210 offset:57344
	s_add_u32 m0, s41, 20480
	s_nop 0
	global_load_lds_dwordx4 v213, s[100:101]
	s_waitcnt lgkmcnt(8)
	v_mfma_f32_16x16x32_bf16 v[56:59], v[72:75], v[168:171], v[56:59]
	v_mfma_f32_16x16x32_bf16 v[32:35], v[216:219], v[168:171], v[32:35]
	ds_read_b128 v[196:199], v210 offset:59392
	s_add_u32 m0, s41, 24576
	s_nop 0
	global_load_lds_dwordx4 v214, s[100:101]
	s_waitcnt lgkmcnt(8)
	v_mfma_f32_16x16x32_bf16 v[12:15], v[72:75], v[172:175], v[12:15]
	v_mfma_f32_16x16x32_bf16 v[4:7], v[216:219], v[172:175], v[4:7]
	ds_read_b128 v[200:203], v210 offset:61440
	s_add_u32 m0, s41, 28672
	s_nop 0
	global_load_lds_dwordx4 v215, s[100:101]
	s_add_u32 s100, s100, 128
	s_addc_u32 s101, s101, 0
	s_waitcnt lgkmcnt(6)
	v_mfma_f32_16x16x32_bf16 v[44:47], v[64:67], v[176:179], v[44:47]
	v_mfma_f32_16x16x32_bf16 v[48:51], v[68:71], v[176:179], v[48:51]
	ds_read_b128 v[204:207], v210 offset:63488
	s_waitcnt lgkmcnt(6)
	v_mfma_f32_16x16x32_bf16 v[28:31], v[64:67], v[180:183], v[28:31]
	v_mfma_f32_16x16x32_bf16 v[16:19], v[68:71], v[180:183], v[16:19]
	ds_read_b128 v[72:75], v209 offset:32768
	ds_read_b128 v[216:219], v209 offset:34816
	ds_read_b128 v[160:163], v211 offset:49152
	s_waitcnt lgkmcnt(8)
	v_mfma_f32_16x16x32_bf16 v[60:63], v[64:67], v[184:187], v[60:63]
	v_mfma_f32_16x16x32_bf16 v[40:43], v[68:71], v[184:187], v[40:43]
	ds_read_b128 v[164:167], v211 offset:51200
	s_waitcnt lgkmcnt(8)
	v_mfma_f32_16x16x32_bf16 v[20:23], v[64:67], v[188:191], v[20:23]
	v_mfma_f32_16x16x32_bf16 v[0:3], v[68:71], v[188:191], v[0:3]
	ds_read_b128 v[168:171], v211 offset:53248
	s_waitcnt lgkmcnt(8)
	v_mfma_f32_16x16x32_bf16 v[52:55], v[64:67], v[192:195], v[52:55]
	v_mfma_f32_16x16x32_bf16 v[36:39], v[68:71], v[192:195], v[36:39]
	ds_read_b128 v[172:175], v211 offset:55296
	s_waitcnt lgkmcnt(8)
	v_mfma_f32_16x16x32_bf16 v[24:27], v[64:67], v[196:199], v[24:27]
	v_mfma_f32_16x16x32_bf16 v[8:11], v[68:71], v[196:199], v[8:11]
	ds_read_b128 v[176:179], v211 offset:57344
	s_waitcnt lgkmcnt(8)
	v_mfma_f32_16x16x32_bf16 v[56:59], v[64:67], v[200:203], v[56:59]
	v_mfma_f32_16x16x32_bf16 v[32:35], v[68:71], v[200:203], v[32:35]
	ds_read_b128 v[180:183], v211 offset:59392
	s_waitcnt lgkmcnt(8)
	v_mfma_f32_16x16x32_bf16 v[12:15], v[64:67], v[204:207], v[12:15]
	v_mfma_f32_16x16x32_bf16 v[4:7], v[68:71], v[204:207], v[4:7]
	ds_read_b128 v[184:187], v211 offset:61440
	s_waitcnt lgkmcnt(6)
	v_mfma_f32_16x16x32_bf16 v[44:47], v[72:75], v[160:163], v[44:47]
	v_mfma_f32_16x16x32_bf16 v[48:51], v[216:219], v[160:163], v[48:51]
	ds_read_b128 v[188:191], v211 offset:63488
	s_waitcnt vmcnt(0) lgkmcnt(0)
	s_barrier
	s_add_u32 m0, s41, 32768
	s_nop 0
	global_load_lds_dwordx4 v212, s[98:99]
	s_waitcnt lgkmcnt(6)
	v_mfma_f32_16x16x32_bf16 v[28:31], v[72:75], v[164:167], v[28:31]
	v_mfma_f32_16x16x32_bf16 v[16:19], v[216:219], v[164:167], v[16:19]
	ds_read_b128 v[64:67], v208 offset:0
	ds_read_b128 v[68:71], v208 offset:2048
	ds_read_b128 v[192:195], v210 offset:16384
	s_add_u32 m0, s41, 36864
	s_nop 0
	global_load_lds_dwordx4 v213, s[98:99]
	s_waitcnt lgkmcnt(8)
	v_mfma_f32_16x16x32_bf16 v[60:63], v[72:75], v[168:171], v[60:63]
	v_mfma_f32_16x16x32_bf16 v[40:43], v[216:219], v[168:171], v[40:43]
	ds_read_b128 v[196:199], v210 offset:18432
	s_add_u32 m0, s41, 40960
	s_nop 0
	global_load_lds_dwordx4 v214, s[98:99]
	s_waitcnt lgkmcnt(8)
	v_mfma_f32_16x16x32_bf16 v[20:23], v[72:75], v[172:175], v[20:23]
	v_mfma_f32_16x16x32_bf16 v[0:3], v[216:219], v[172:175], v[0:3]
	ds_read_b128 v[200:203], v210 offset:20480
	s_add_u32 m0, s41, 45056
	s_nop 0
	global_load_lds_dwordx4 v215, s[98:99]
	s_add_u32 s98, s98, 128
	s_addc_u32 s99, s99, 0
	s_waitcnt lgkmcnt(8)
	v_mfma_f32_16x16x32_bf16 v[52:55], v[72:75], v[176:179], v[52:55]
	v_mfma_f32_16x16x32_bf16 v[36:39], v[216:219], v[176:179], v[36:39]
	ds_read_b128 v[204:207], v210 offset:22528
	s_add_u32 m0, s41, 49152
	s_nop 0
	global_load_lds_dwordx4 v212, s[100:101]
	s_waitcnt lgkmcnt(8)
	v_mfma_f32_16x16x32_bf16 v[24:27], v[72:75], v[180:183], v[24:27]
	v_mfma_f32_16x16x32_bf16 v[8:11], v[216:219], v[180:183], v[8:11]
	ds_read_b128 v[160:163], v210 offset:24576
	s_add_u32 m0, s41, 53248
	s_nop 0
	global_load_lds_dwordx4 v213, s[100:101]
	s_waitcnt lgkmcnt(8)
	v_mfma_f32_16x16x32_bf16 v[56:59], v[72:75], v[184:187], v[56:59]
	v_mfma_f32_16x16x32_bf16 v[32:35], v[216:219], v[184:187], v[32:35]
	ds_read_b128 v[164:167], v210 offset:26624
	s_add_u32 m0, s41, 57344
	s_nop 0
	global_load_lds_dwordx4 v214, s[100:101]
	s_waitcnt lgkmcnt(8)
	v_mfma_f32_16x16x32_bf16 v[12:15], v[72:75], v[188:191], v[12:15]
	v_mfma_f32_16x16x32_bf16 v[4:7], v[216:219], v[188:191], v[4:7]
	ds_read_b128 v[168:171], v210 offset:28672
	s_add_u32 m0, s41, 61440
	s_nop 0
	global_load_lds_dwordx4 v215, s[100:101]
	s_add_u32 s100, s100, 128
	s_addc_u32 s101, s101, 0
	s_waitcnt lgkmcnt(6)
	v_mfma_f32_16x16x32_bf16 v[44:47], v[64:67], v[192:195], v[44:47]
	v_mfma_f32_16x16x32_bf16 v[48:51], v[68:71], v[192:195], v[48:51]
	ds_read_b128 v[172:175], v210 offset:30720
	s_waitcnt lgkmcnt(6)
	v_mfma_f32_16x16x32_bf16 v[28:31], v[64:67], v[196:199], v[28:31]
	v_mfma_f32_16x16x32_bf16 v[16:19], v[68:71], v[196:199], v[16:19]
	ds_read_b128 v[72:75], v209 offset:0
	ds_read_b128 v[216:219], v209 offset:2048
	ds_read_b128 v[176:179], v211 offset:16384
	s_waitcnt lgkmcnt(8)
	v_mfma_f32_16x16x32_bf16 v[60:63], v[64:67], v[200:203], v[60:63]
	v_mfma_f32_16x16x32_bf16 v[40:43], v[68:71], v[200:203], v[40:43]
	ds_read_b128 v[180:183], v211 offset:18432
	s_waitcnt lgkmcnt(8)
	v_mfma_f32_16x16x32_bf16 v[20:23], v[64:67], v[204:207], v[20:23]
	v_mfma_f32_16x16x32_bf16 v[0:3], v[68:71], v[204:207], v[0:3]
	ds_read_b128 v[184:187], v211 offset:20480
	s_waitcnt lgkmcnt(8)
	v_mfma_f32_16x16x32_bf16 v[52:55], v[64:67], v[160:163], v[52:55]
	v_mfma_f32_16x16x32_bf16 v[36:39], v[68:71], v[160:163], v[36:39]
	ds_read_b128 v[188:191], v211 offset:22528
	s_waitcnt lgkmcnt(8)
	v_mfma_f32_16x16x32_bf16 v[24:27], v[64:67], v[164:167], v[24:27]
	v_mfma_f32_16x16x32_bf16 v[8:11], v[68:71], v[164:167], v[8:11]
	ds_read_b128 v[192:195], v211 offset:24576
	s_waitcnt lgkmcnt(8)
	v_mfma_f32_16x16x32_bf16 v[56:59], v[64:67], v[168:171], v[56:59]
	v_mfma_f32_16x16x32_bf16 v[32:35], v[68:71], v[168:171], v[32:35]
	ds_read_b128 v[196:199], v211 offset:26624
	s_waitcnt lgkmcnt(8)
	v_mfma_f32_16x16x32_bf16 v[12:15], v[64:67], v[172:175], v[12:15]
	v_mfma_f32_16x16x32_bf16 v[4:7], v[68:71], v[172:175], v[4:7]
	ds_read_b128 v[200:203], v211 offset:28672
	s_waitcnt lgkmcnt(6)
	v_mfma_f32_16x16x32_bf16 v[44:47], v[72:75], v[176:179], v[44:47]
	v_mfma_f32_16x16x32_bf16 v[48:51], v[216:219], v[176:179], v[48:51]
	ds_read_b128 v[204:207], v211 offset:30720
	s_waitcnt vmcnt(0) lgkmcnt(0)
	s_barrier
	s_add_u32 m0, s41, 0
	s_nop 0
	global_load_lds_dwordx4 v212, s[98:99]
	s_waitcnt lgkmcnt(6)
	v_mfma_f32_16x16x32_bf16 v[28:31], v[72:75], v[180:183], v[28:31]
	v_mfma_f32_16x16x32_bf16 v[16:19], v[216:219], v[180:183], v[16:19]
	ds_read_b128 v[64:67], v208 offset:32768
	ds_read_b128 v[68:71], v208 offset:34816
	ds_read_b128 v[160:163], v210 offset:49152
	s_add_u32 m0, s41, 4096
	s_nop 0
	global_load_lds_dwordx4 v213, s[98:99]
	s_waitcnt lgkmcnt(8)
	v_mfma_f32_16x16x32_bf16 v[60:63], v[72:75], v[184:187], v[60:63]
	v_mfma_f32_16x16x32_bf16 v[40:43], v[216:219], v[184:187], v[40:43]
	ds_read_b128 v[164:167], v210 offset:51200
	s_add_u32 m0, s41, 8192
	s_nop 0
	global_load_lds_dwordx4 v214, s[98:99]
	s_waitcnt lgkmcnt(8)
	v_mfma_f32_16x16x32_bf16 v[20:23], v[72:75], v[188:191], v[20:23]
	v_mfma_f32_16x16x32_bf16 v[0:3], v[216:219], v[188:191], v[0:3]
	ds_read_b128 v[168:171], v210 offset:53248
	s_add_u32 m0, s41, 12288
	s_nop 0
	global_load_lds_dwordx4 v215, s[98:99]
	s_add_u32 s98, s98, 128
	s_addc_u32 s99, s99, 0
	s_waitcnt lgkmcnt(8)
	v_mfma_f32_16x16x32_bf16 v[52:55], v[72:75], v[192:195], v[52:55]
	v_mfma_f32_16x16x32_bf16 v[36:39], v[216:219], v[192:195], v[36:39]
	ds_read_b128 v[172:175], v210 offset:55296
	s_add_u32 m0, s41, 16384
	s_nop 0
	global_load_lds_dwordx4 v212, s[100:101]
	s_waitcnt lgkmcnt(8)
	v_mfma_f32_16x16x32_bf16 v[24:27], v[72:75], v[196:199], v[24:27]
	v_mfma_f32_16x16x32_bf16 v[8:11], v[216:219], v[196:199], v[8:11]
	ds_read_b128 v[176:179], v210 offset:57344
	s_add_u32 m0, s41, 20480
	s_nop 0
	global_load_lds_dwordx4 v213, s[100:101]
	s_waitcnt lgkmcnt(8)
	v_mfma_f32_16x16x32_bf16 v[56:59], v[72:75], v[200:203], v[56:59]
	v_mfma_f32_16x16x32_bf16 v[32:35], v[216:219], v[200:203], v[32:35]
	ds_read_b128 v[180:183], v210 offset:59392
	s_add_u32 m0, s41, 24576
	s_nop 0
	global_load_lds_dwordx4 v214, s[100:101]
	s_waitcnt lgkmcnt(8)
	v_mfma_f32_16x16x32_bf16 v[12:15], v[72:75], v[204:207], v[12:15]
	v_mfma_f32_16x16x32_bf16 v[4:7], v[216:219], v[204:207], v[4:7]
	ds_read_b128 v[184:187], v210 offset:61440
	s_add_u32 m0, s41, 28672
	s_nop 0
	global_load_lds_dwordx4 v215, s[100:101]
	s_add_u32 s100, s100, 128
	s_addc_u32 s101, s101, 0
	s_waitcnt lgkmcnt(6)
	v_mfma_f32_16x16x32_bf16 v[44:47], v[64:67], v[160:163], v[44:47]
	v_mfma_f32_16x16x32_bf16 v[48:51], v[68:71], v[160:163], v[48:51]
	ds_read_b128 v[188:191], v210 offset:63488
	s_waitcnt lgkmcnt(6)
	v_mfma_f32_16x16x32_bf16 v[28:31], v[64:67], v[164:167], v[28:31]
	v_mfma_f32_16x16x32_bf16 v[16:19], v[68:71], v[164:167], v[16:19]
	ds_read_b128 v[72:75], v209 offset:32768
	ds_read_b128 v[216:219], v209 offset:34816
	ds_read_b128 v[192:195], v211 offset:49152
	s_waitcnt lgkmcnt(8)
	v_mfma_f32_16x16x32_bf16 v[60:63], v[64:67], v[168:171], v[60:63]
	v_mfma_f32_16x16x32_bf16 v[40:43], v[68:71], v[168:171], v[40:43]
	ds_read_b128 v[196:199], v211 offset:51200
	s_waitcnt lgkmcnt(8)
	v_mfma_f32_16x16x32_bf16 v[20:23], v[64:67], v[172:175], v[20:23]
	v_mfma_f32_16x16x32_bf16 v[0:3], v[68:71], v[172:175], v[0:3]
	ds_read_b128 v[200:203], v211 offset:53248
	s_waitcnt lgkmcnt(8)
	v_mfma_f32_16x16x32_bf16 v[52:55], v[64:67], v[176:179], v[52:55]
	v_mfma_f32_16x16x32_bf16 v[36:39], v[68:71], v[176:179], v[36:39]
	ds_read_b128 v[204:207], v211 offset:55296
	s_waitcnt lgkmcnt(8)
	v_mfma_f32_16x16x32_bf16 v[24:27], v[64:67], v[180:183], v[24:27]
	v_mfma_f32_16x16x32_bf16 v[8:11], v[68:71], v[180:183], v[8:11]
	ds_read_b128 v[160:163], v211 offset:57344
	s_waitcnt lgkmcnt(8)
	v_mfma_f32_16x16x32_bf16 v[56:59], v[64:67], v[184:187], v[56:59]
	v_mfma_f32_16x16x32_bf16 v[32:35], v[68:71], v[184:187], v[32:35]
	ds_read_b128 v[164:167], v211 offset:59392
	s_waitcnt lgkmcnt(8)
	v_mfma_f32_16x16x32_bf16 v[12:15], v[64:67], v[188:191], v[12:15]
	v_mfma_f32_16x16x32_bf16 v[4:7], v[68:71], v[188:191], v[4:7]
	ds_read_b128 v[168:171], v211 offset:61440
	s_waitcnt lgkmcnt(6)
	v_mfma_f32_16x16x32_bf16 v[44:47], v[72:75], v[192:195], v[44:47]
	v_mfma_f32_16x16x32_bf16 v[48:51], v[216:219], v[192:195], v[48:51]
	ds_read_b128 v[172:175], v211 offset:63488
	s_waitcnt vmcnt(0) lgkmcnt(0)
	s_barrier
	s_add_u32 m0, s41, 32768
	s_nop 0
	global_load_lds_dwordx4 v212, s[98:99]
	s_waitcnt lgkmcnt(6)
	v_mfma_f32_16x16x32_bf16 v[28:31], v[72:75], v[196:199], v[28:31]
	v_mfma_f32_16x16x32_bf16 v[16:19], v[216:219], v[196:199], v[16:19]
	ds_read_b128 v[64:67], v208 offset:0
	ds_read_b128 v[68:71], v208 offset:2048
	ds_read_b128 v[176:179], v210 offset:16384
	s_add_u32 m0, s41, 36864
	s_nop 0
	global_load_lds_dwordx4 v213, s[98:99]
	s_waitcnt lgkmcnt(8)
	v_mfma_f32_16x16x32_bf16 v[60:63], v[72:75], v[200:203], v[60:63]
	v_mfma_f32_16x16x32_bf16 v[40:43], v[216:219], v[200:203], v[40:43]
	ds_read_b128 v[180:183], v210 offset:18432
	s_add_u32 m0, s41, 40960
	s_nop 0
	global_load_lds_dwordx4 v214, s[98:99]
	s_waitcnt lgkmcnt(8)
	v_mfma_f32_16x16x32_bf16 v[20:23], v[72:75], v[204:207], v[20:23]
	v_mfma_f32_16x16x32_bf16 v[0:3], v[216:219], v[204:207], v[0:3]
	ds_read_b128 v[184:187], v210 offset:20480
	s_add_u32 m0, s41, 45056
	s_nop 0
	global_load_lds_dwordx4 v215, s[98:99]
	s_add_u32 s98, s98, 128
	s_addc_u32 s99, s99, 0
	s_waitcnt lgkmcnt(8)
	v_mfma_f32_16x16x32_bf16 v[52:55], v[72:75], v[160:163], v[52:55]
	v_mfma_f32_16x16x32_bf16 v[36:39], v[216:219], v[160:163], v[36:39]
	ds_read_b128 v[188:191], v210 offset:22528
	s_add_u32 m0, s41, 49152
	s_nop 0
	global_load_lds_dwordx4 v212, s[100:101]
	s_waitcnt lgkmcnt(8)
	v_mfma_f32_16x16x32_bf16 v[24:27], v[72:75], v[164:167], v[24:27]
	v_mfma_f32_16x16x32_bf16 v[8:11], v[216:219], v[164:167], v[8:11]
	ds_read_b128 v[192:195], v210 offset:24576
	s_add_u32 m0, s41, 53248
	s_nop 0
	global_load_lds_dwordx4 v213, s[100:101]
	s_waitcnt lgkmcnt(8)
	v_mfma_f32_16x16x32_bf16 v[56:59], v[72:75], v[168:171], v[56:59]
	v_mfma_f32_16x16x32_bf16 v[32:35], v[216:219], v[168:171], v[32:35]
	ds_read_b128 v[196:199], v210 offset:26624
	s_add_u32 m0, s41, 57344
	s_nop 0
	global_load_lds_dwordx4 v214, s[100:101]
	s_waitcnt lgkmcnt(8)
	v_mfma_f32_16x16x32_bf16 v[12:15], v[72:75], v[172:175], v[12:15]
	v_mfma_f32_16x16x32_bf16 v[4:7], v[216:219], v[172:175], v[4:7]
	ds_read_b128 v[200:203], v210 offset:28672
	s_add_u32 m0, s41, 61440
	s_nop 0
	global_load_lds_dwordx4 v215, s[100:101]
	s_add_u32 s100, s100, 128
	s_addc_u32 s101, s101, 0
	s_waitcnt lgkmcnt(6)
	v_mfma_f32_16x16x32_bf16 v[44:47], v[64:67], v[176:179], v[44:47]
	v_mfma_f32_16x16x32_bf16 v[48:51], v[68:71], v[176:179], v[48:51]
	ds_read_b128 v[204:207], v210 offset:30720
	s_waitcnt lgkmcnt(6)
	v_mfma_f32_16x16x32_bf16 v[28:31], v[64:67], v[180:183], v[28:31]
	v_mfma_f32_16x16x32_bf16 v[16:19], v[68:71], v[180:183], v[16:19]
	ds_read_b128 v[72:75], v209 offset:0
	ds_read_b128 v[216:219], v209 offset:2048
	ds_read_b128 v[160:163], v211 offset:16384
	s_waitcnt lgkmcnt(8)
	v_mfma_f32_16x16x32_bf16 v[60:63], v[64:67], v[184:187], v[60:63]
	v_mfma_f32_16x16x32_bf16 v[40:43], v[68:71], v[184:187], v[40:43]
	ds_read_b128 v[164:167], v211 offset:18432
	s_waitcnt lgkmcnt(8)
	v_mfma_f32_16x16x32_bf16 v[20:23], v[64:67], v[188:191], v[20:23]
	v_mfma_f32_16x16x32_bf16 v[0:3], v[68:71], v[188:191], v[0:3]
	ds_read_b128 v[168:171], v211 offset:20480
	s_waitcnt lgkmcnt(8)
	v_mfma_f32_16x16x32_bf16 v[52:55], v[64:67], v[192:195], v[52:55]
	v_mfma_f32_16x16x32_bf16 v[36:39], v[68:71], v[192:195], v[36:39]
	ds_read_b128 v[172:175], v211 offset:22528
	s_waitcnt lgkmcnt(8)
	v_mfma_f32_16x16x32_bf16 v[24:27], v[64:67], v[196:199], v[24:27]
	v_mfma_f32_16x16x32_bf16 v[8:11], v[68:71], v[196:199], v[8:11]
	ds_read_b128 v[176:179], v211 offset:24576
	s_waitcnt lgkmcnt(8)
	v_mfma_f32_16x16x32_bf16 v[56:59], v[64:67], v[200:203], v[56:59]
	v_mfma_f32_16x16x32_bf16 v[32:35], v[68:71], v[200:203], v[32:35]
	ds_read_b128 v[180:183], v211 offset:26624
	s_waitcnt lgkmcnt(8)
	v_mfma_f32_16x16x32_bf16 v[12:15], v[64:67], v[204:207], v[12:15]
	v_mfma_f32_16x16x32_bf16 v[4:7], v[68:71], v[204:207], v[4:7]
	ds_read_b128 v[184:187], v211 offset:28672
	s_waitcnt lgkmcnt(6)
	v_mfma_f32_16x16x32_bf16 v[44:47], v[72:75], v[160:163], v[44:47]
	v_mfma_f32_16x16x32_bf16 v[48:51], v[216:219], v[160:163], v[48:51]
	ds_read_b128 v[188:191], v211 offset:30720
	s_waitcnt vmcnt(0) lgkmcnt(0)
	s_barrier
	s_add_u32 m0, s41, 0
	s_nop 0
	global_load_lds_dwordx4 v212, s[98:99]
	s_waitcnt lgkmcnt(6)
	v_mfma_f32_16x16x32_bf16 v[28:31], v[72:75], v[164:167], v[28:31]
	v_mfma_f32_16x16x32_bf16 v[16:19], v[216:219], v[164:167], v[16:19]
	ds_read_b128 v[64:67], v208 offset:32768
	ds_read_b128 v[68:71], v208 offset:34816
	ds_read_b128 v[192:195], v210 offset:49152
	s_add_u32 m0, s41, 4096
	s_nop 0
	global_load_lds_dwordx4 v213, s[98:99]
	s_waitcnt lgkmcnt(8)
	v_mfma_f32_16x16x32_bf16 v[60:63], v[72:75], v[168:171], v[60:63]
	v_mfma_f32_16x16x32_bf16 v[40:43], v[216:219], v[168:171], v[40:43]
	ds_read_b128 v[196:199], v210 offset:51200
	s_add_u32 m0, s41, 8192
	s_nop 0
	global_load_lds_dwordx4 v214, s[98:99]
	s_waitcnt lgkmcnt(8)
	v_mfma_f32_16x16x32_bf16 v[20:23], v[72:75], v[172:175], v[20:23]
	v_mfma_f32_16x16x32_bf16 v[0:3], v[216:219], v[172:175], v[0:3]
	ds_read_b128 v[200:203], v210 offset:53248
	s_add_u32 m0, s41, 12288
	s_nop 0
	global_load_lds_dwordx4 v215, s[98:99]
	s_add_u32 s98, s98, 128
	s_addc_u32 s99, s99, 0
	s_waitcnt lgkmcnt(8)
	v_mfma_f32_16x16x32_bf16 v[52:55], v[72:75], v[176:179], v[52:55]
	v_mfma_f32_16x16x32_bf16 v[36:39], v[216:219], v[176:179], v[36:39]
	ds_read_b128 v[204:207], v210 offset:55296
	s_add_u32 m0, s41, 16384
	s_nop 0
	global_load_lds_dwordx4 v212, s[100:101]
	s_waitcnt lgkmcnt(8)
	v_mfma_f32_16x16x32_bf16 v[24:27], v[72:75], v[180:183], v[24:27]
	v_mfma_f32_16x16x32_bf16 v[8:11], v[216:219], v[180:183], v[8:11]
	ds_read_b128 v[160:163], v210 offset:57344
	s_add_u32 m0, s41, 20480
	s_nop 0
	global_load_lds_dwordx4 v213, s[100:101]
	s_waitcnt lgkmcnt(8)
	v_mfma_f32_16x16x32_bf16 v[56:59], v[72:75], v[184:187], v[56:59]
	v_mfma_f32_16x16x32_bf16 v[32:35], v[216:219], v[184:187], v[32:35]
	ds_read_b128 v[164:167], v210 offset:59392
	s_add_u32 m0, s41, 24576
	s_nop 0
	global_load_lds_dwordx4 v214, s[100:101]
	s_waitcnt lgkmcnt(8)
	v_mfma_f32_16x16x32_bf16 v[12:15], v[72:75], v[188:191], v[12:15]
	v_mfma_f32_16x16x32_bf16 v[4:7], v[216:219], v[188:191], v[4:7]
	ds_read_b128 v[168:171], v210 offset:61440
	s_add_u32 m0, s41, 28672
	s_nop 0
	global_load_lds_dwordx4 v215, s[100:101]
	s_add_u32 s100, s100, 128
	s_addc_u32 s101, s101, 0
	s_waitcnt lgkmcnt(6)
	v_mfma_f32_16x16x32_bf16 v[44:47], v[64:67], v[192:195], v[44:47]
	v_mfma_f32_16x16x32_bf16 v[48:51], v[68:71], v[192:195], v[48:51]
	ds_read_b128 v[172:175], v210 offset:63488
	s_waitcnt lgkmcnt(6)
	v_mfma_f32_16x16x32_bf16 v[28:31], v[64:67], v[196:199], v[28:31]
	v_mfma_f32_16x16x32_bf16 v[16:19], v[68:71], v[196:199], v[16:19]
	ds_read_b128 v[72:75], v209 offset:32768
	ds_read_b128 v[216:219], v209 offset:34816
	ds_read_b128 v[176:179], v211 offset:49152
	s_waitcnt lgkmcnt(8)
	v_mfma_f32_16x16x32_bf16 v[60:63], v[64:67], v[200:203], v[60:63]
	v_mfma_f32_16x16x32_bf16 v[40:43], v[68:71], v[200:203], v[40:43]
	ds_read_b128 v[180:183], v211 offset:51200
	s_waitcnt lgkmcnt(8)
	v_mfma_f32_16x16x32_bf16 v[20:23], v[64:67], v[204:207], v[20:23]
	v_mfma_f32_16x16x32_bf16 v[0:3], v[68:71], v[204:207], v[0:3]
	ds_read_b128 v[184:187], v211 offset:53248
	s_waitcnt lgkmcnt(8)
	v_mfma_f32_16x16x32_bf16 v[52:55], v[64:67], v[160:163], v[52:55]
	v_mfma_f32_16x16x32_bf16 v[36:39], v[68:71], v[160:163], v[36:39]
	ds_read_b128 v[188:191], v211 offset:55296
	s_waitcnt lgkmcnt(8)
	v_mfma_f32_16x16x32_bf16 v[24:27], v[64:67], v[164:167], v[24:27]
	v_mfma_f32_16x16x32_bf16 v[8:11], v[68:71], v[164:167], v[8:11]
	ds_read_b128 v[192:195], v211 offset:57344
	s_waitcnt lgkmcnt(8)
	v_mfma_f32_16x16x32_bf16 v[56:59], v[64:67], v[168:171], v[56:59]
	v_mfma_f32_16x16x32_bf16 v[32:35], v[68:71], v[168:171], v[32:35]
	ds_read_b128 v[196:199], v211 offset:59392
	s_waitcnt lgkmcnt(8)
	v_mfma_f32_16x16x32_bf16 v[12:15], v[64:67], v[172:175], v[12:15]
	v_mfma_f32_16x16x32_bf16 v[4:7], v[68:71], v[172:175], v[4:7]
	ds_read_b128 v[200:203], v211 offset:61440
	s_waitcnt lgkmcnt(6)
	v_mfma_f32_16x16x32_bf16 v[44:47], v[72:75], v[176:179], v[44:47]
	v_mfma_f32_16x16x32_bf16 v[48:51], v[216:219], v[176:179], v[48:51]
	ds_read_b128 v[204:207], v211 offset:63488
	s_waitcnt vmcnt(0) lgkmcnt(0)
	s_barrier
	s_add_u32 m0, s41, 32768
	s_nop 0
	global_load_lds_dwordx4 v212, s[98:99]
	s_waitcnt lgkmcnt(6)
	v_mfma_f32_16x16x32_bf16 v[28:31], v[72:75], v[180:183], v[28:31]
	v_mfma_f32_16x16x32_bf16 v[16:19], v[216:219], v[180:183], v[16:19]
	ds_read_b128 v[64:67], v208 offset:0
	ds_read_b128 v[68:71], v208 offset:2048
	ds_read_b128 v[160:163], v210 offset:16384
	s_add_u32 m0, s41, 36864
	s_nop 0
	global_load_lds_dwordx4 v213, s[98:99]
	s_waitcnt lgkmcnt(8)
	v_mfma_f32_16x16x32_bf16 v[60:63], v[72:75], v[184:187], v[60:63]
	v_mfma_f32_16x16x32_bf16 v[40:43], v[216:219], v[184:187], v[40:43]
	ds_read_b128 v[164:167], v210 offset:18432
	s_add_u32 m0, s41, 40960
	s_nop 0
	global_load_lds_dwordx4 v214, s[98:99]
	s_waitcnt lgkmcnt(8)
	v_mfma_f32_16x16x32_bf16 v[20:23], v[72:75], v[188:191], v[20:23]
	v_mfma_f32_16x16x32_bf16 v[0:3], v[216:219], v[188:191], v[0:3]
	ds_read_b128 v[168:171], v210 offset:20480
	s_add_u32 m0, s41, 45056
	s_nop 0
	global_load_lds_dwordx4 v215, s[98:99]
	s_add_u32 s98, s98, 128
	s_addc_u32 s99, s99, 0
	s_waitcnt lgkmcnt(8)
	v_mfma_f32_16x16x32_bf16 v[52:55], v[72:75], v[192:195], v[52:55]
	v_mfma_f32_16x16x32_bf16 v[36:39], v[216:219], v[192:195], v[36:39]
	ds_read_b128 v[172:175], v210 offset:22528
	s_add_u32 m0, s41, 49152
	s_nop 0
	global_load_lds_dwordx4 v212, s[100:101]
	s_waitcnt lgkmcnt(8)
	v_mfma_f32_16x16x32_bf16 v[24:27], v[72:75], v[196:199], v[24:27]
	v_mfma_f32_16x16x32_bf16 v[8:11], v[216:219], v[196:199], v[8:11]
	ds_read_b128 v[176:179], v210 offset:24576
	s_add_u32 m0, s41, 53248
	s_nop 0
	global_load_lds_dwordx4 v213, s[100:101]
	s_waitcnt lgkmcnt(8)
	v_mfma_f32_16x16x32_bf16 v[56:59], v[72:75], v[200:203], v[56:59]
	v_mfma_f32_16x16x32_bf16 v[32:35], v[216:219], v[200:203], v[32:35]
	ds_read_b128 v[180:183], v210 offset:26624
	s_add_u32 m0, s41, 57344
	s_nop 0
	global_load_lds_dwordx4 v214, s[100:101]
	s_waitcnt lgkmcnt(8)
	v_mfma_f32_16x16x32_bf16 v[12:15], v[72:75], v[204:207], v[12:15]
	v_mfma_f32_16x16x32_bf16 v[4:7], v[216:219], v[204:207], v[4:7]
	ds_read_b128 v[184:187], v210 offset:28672
	s_add_u32 m0, s41, 61440
	s_nop 0
	global_load_lds_dwordx4 v215, s[100:101]
	s_add_u32 s100, s100, 128
	s_addc_u32 s101, s101, 0
	s_waitcnt lgkmcnt(6)
	v_mfma_f32_16x16x32_bf16 v[44:47], v[64:67], v[160:163], v[44:47]
	v_mfma_f32_16x16x32_bf16 v[48:51], v[68:71], v[160:163], v[48:51]
	ds_read_b128 v[188:191], v210 offset:30720
	s_waitcnt lgkmcnt(6)
	v_mfma_f32_16x16x32_bf16 v[28:31], v[64:67], v[164:167], v[28:31]
	v_mfma_f32_16x16x32_bf16 v[16:19], v[68:71], v[164:167], v[16:19]
	ds_read_b128 v[72:75], v209 offset:0
	ds_read_b128 v[216:219], v209 offset:2048
	ds_read_b128 v[192:195], v211 offset:16384
	s_waitcnt lgkmcnt(8)
	v_mfma_f32_16x16x32_bf16 v[60:63], v[64:67], v[168:171], v[60:63]
	v_mfma_f32_16x16x32_bf16 v[40:43], v[68:71], v[168:171], v[40:43]
	ds_read_b128 v[196:199], v211 offset:18432
	s_waitcnt lgkmcnt(8)
	v_mfma_f32_16x16x32_bf16 v[20:23], v[64:67], v[172:175], v[20:23]
	v_mfma_f32_16x16x32_bf16 v[0:3], v[68:71], v[172:175], v[0:3]
	ds_read_b128 v[200:203], v211 offset:20480
	s_waitcnt lgkmcnt(8)
	v_mfma_f32_16x16x32_bf16 v[52:55], v[64:67], v[176:179], v[52:55]
	v_mfma_f32_16x16x32_bf16 v[36:39], v[68:71], v[176:179], v[36:39]
	ds_read_b128 v[204:207], v211 offset:22528
	s_waitcnt lgkmcnt(8)
	v_mfma_f32_16x16x32_bf16 v[24:27], v[64:67], v[180:183], v[24:27]
	v_mfma_f32_16x16x32_bf16 v[8:11], v[68:71], v[180:183], v[8:11]
	ds_read_b128 v[160:163], v211 offset:24576
	s_waitcnt lgkmcnt(8)
	v_mfma_f32_16x16x32_bf16 v[56:59], v[64:67], v[184:187], v[56:59]
	v_mfma_f32_16x16x32_bf16 v[32:35], v[68:71], v[184:187], v[32:35]
	ds_read_b128 v[164:167], v211 offset:26624
	s_waitcnt lgkmcnt(8)
	v_mfma_f32_16x16x32_bf16 v[12:15], v[64:67], v[188:191], v[12:15]
	v_mfma_f32_16x16x32_bf16 v[4:7], v[68:71], v[188:191], v[4:7]
	ds_read_b128 v[168:171], v211 offset:28672
	s_waitcnt lgkmcnt(6)
	v_mfma_f32_16x16x32_bf16 v[44:47], v[72:75], v[192:195], v[44:47]
	v_mfma_f32_16x16x32_bf16 v[48:51], v[216:219], v[192:195], v[48:51]
	ds_read_b128 v[172:175], v211 offset:30720
	s_waitcnt vmcnt(0) lgkmcnt(0)
	s_barrier
	s_add_u32 m0, s41, 0
	s_nop 0
	global_load_lds_dwordx4 v212, s[98:99]
	s_waitcnt lgkmcnt(6)
	v_mfma_f32_16x16x32_bf16 v[28:31], v[72:75], v[196:199], v[28:31]
	v_mfma_f32_16x16x32_bf16 v[16:19], v[216:219], v[196:199], v[16:19]
	ds_read_b128 v[64:67], v208 offset:32768
	ds_read_b128 v[68:71], v208 offset:34816
	ds_read_b128 v[176:179], v210 offset:49152
	s_add_u32 m0, s41, 4096
	s_nop 0
	global_load_lds_dwordx4 v213, s[98:99]
	s_waitcnt lgkmcnt(8)
	v_mfma_f32_16x16x32_bf16 v[60:63], v[72:75], v[200:203], v[60:63]
	v_mfma_f32_16x16x32_bf16 v[40:43], v[216:219], v[200:203], v[40:43]
	ds_read_b128 v[180:183], v210 offset:51200
	s_add_u32 m0, s41, 8192
	s_nop 0
	global_load_lds_dwordx4 v214, s[98:99]
	s_waitcnt lgkmcnt(8)
	v_mfma_f32_16x16x32_bf16 v[20:23], v[72:75], v[204:207], v[20:23]
	v_mfma_f32_16x16x32_bf16 v[0:3], v[216:219], v[204:207], v[0:3]
	ds_read_b128 v[184:187], v210 offset:53248
	s_add_u32 m0, s41, 12288
	s_nop 0
	global_load_lds_dwordx4 v215, s[98:99]
	s_add_u32 s98, s98, 128
	s_addc_u32 s99, s99, 0
	s_waitcnt lgkmcnt(8)
	v_mfma_f32_16x16x32_bf16 v[52:55], v[72:75], v[160:163], v[52:55]
	v_mfma_f32_16x16x32_bf16 v[36:39], v[216:219], v[160:163], v[36:39]
	ds_read_b128 v[188:191], v210 offset:55296
	s_add_u32 m0, s41, 16384
	s_nop 0
	global_load_lds_dwordx4 v212, s[100:101]
	s_waitcnt lgkmcnt(8)
	v_mfma_f32_16x16x32_bf16 v[24:27], v[72:75], v[164:167], v[24:27]
	v_mfma_f32_16x16x32_bf16 v[8:11], v[216:219], v[164:167], v[8:11]
	ds_read_b128 v[192:195], v210 offset:57344
	s_add_u32 m0, s41, 20480
	s_nop 0
	global_load_lds_dwordx4 v213, s[100:101]
	s_waitcnt lgkmcnt(8)
	v_mfma_f32_16x16x32_bf16 v[56:59], v[72:75], v[168:171], v[56:59]
	v_mfma_f32_16x16x32_bf16 v[32:35], v[216:219], v[168:171], v[32:35]
	ds_read_b128 v[196:199], v210 offset:59392
	s_add_u32 m0, s41, 24576
	s_nop 0
	global_load_lds_dwordx4 v214, s[100:101]
	s_waitcnt lgkmcnt(8)
	v_mfma_f32_16x16x32_bf16 v[12:15], v[72:75], v[172:175], v[12:15]
	v_mfma_f32_16x16x32_bf16 v[4:7], v[216:219], v[172:175], v[4:7]
	ds_read_b128 v[200:203], v210 offset:61440
	s_add_u32 m0, s41, 28672
	s_nop 0
	global_load_lds_dwordx4 v215, s[100:101]
	s_add_u32 s100, s100, 128
	s_addc_u32 s101, s101, 0
	s_waitcnt lgkmcnt(6)
	v_mfma_f32_16x16x32_bf16 v[44:47], v[64:67], v[176:179], v[44:47]
	v_mfma_f32_16x16x32_bf16 v[48:51], v[68:71], v[176:179], v[48:51]
	ds_read_b128 v[204:207], v210 offset:63488
	s_waitcnt lgkmcnt(6)
	v_mfma_f32_16x16x32_bf16 v[28:31], v[64:67], v[180:183], v[28:31]
	v_mfma_f32_16x16x32_bf16 v[16:19], v[68:71], v[180:183], v[16:19]
	ds_read_b128 v[72:75], v209 offset:32768
	ds_read_b128 v[216:219], v209 offset:34816
	ds_read_b128 v[160:163], v211 offset:49152
	s_waitcnt lgkmcnt(8)
	v_mfma_f32_16x16x32_bf16 v[60:63], v[64:67], v[184:187], v[60:63]
	v_mfma_f32_16x16x32_bf16 v[40:43], v[68:71], v[184:187], v[40:43]
	ds_read_b128 v[164:167], v211 offset:51200
	s_waitcnt lgkmcnt(8)
	v_mfma_f32_16x16x32_bf16 v[20:23], v[64:67], v[188:191], v[20:23]
	v_mfma_f32_16x16x32_bf16 v[0:3], v[68:71], v[188:191], v[0:3]
	ds_read_b128 v[168:171], v211 offset:53248
	s_waitcnt lgkmcnt(8)
	v_mfma_f32_16x16x32_bf16 v[52:55], v[64:67], v[192:195], v[52:55]
	v_mfma_f32_16x16x32_bf16 v[36:39], v[68:71], v[192:195], v[36:39]
	ds_read_b128 v[172:175], v211 offset:55296
	s_waitcnt lgkmcnt(8)
	v_mfma_f32_16x16x32_bf16 v[24:27], v[64:67], v[196:199], v[24:27]
	v_mfma_f32_16x16x32_bf16 v[8:11], v[68:71], v[196:199], v[8:11]
	ds_read_b128 v[176:179], v211 offset:57344
	s_waitcnt lgkmcnt(8)
	v_mfma_f32_16x16x32_bf16 v[56:59], v[64:67], v[200:203], v[56:59]
	v_mfma_f32_16x16x32_bf16 v[32:35], v[68:71], v[200:203], v[32:35]
	ds_read_b128 v[180:183], v211 offset:59392
	s_waitcnt lgkmcnt(8)
	v_mfma_f32_16x16x32_bf16 v[12:15], v[64:67], v[204:207], v[12:15]
	v_mfma_f32_16x16x32_bf16 v[4:7], v[68:71], v[204:207], v[4:7]
	ds_read_b128 v[184:187], v211 offset:61440
	s_waitcnt lgkmcnt(6)
	v_mfma_f32_16x16x32_bf16 v[44:47], v[72:75], v[160:163], v[44:47]
	v_mfma_f32_16x16x32_bf16 v[48:51], v[216:219], v[160:163], v[48:51]
	ds_read_b128 v[188:191], v211 offset:63488
	s_waitcnt vmcnt(0) lgkmcnt(0)
	s_barrier
	s_add_u32 m0, s41, 32768
	s_nop 0
	global_load_lds_dwordx4 v212, s[98:99]
	s_waitcnt lgkmcnt(6)
	v_mfma_f32_16x16x32_bf16 v[28:31], v[72:75], v[164:167], v[28:31]
	v_mfma_f32_16x16x32_bf16 v[16:19], v[216:219], v[164:167], v[16:19]
	ds_read_b128 v[64:67], v208 offset:0
	ds_read_b128 v[68:71], v208 offset:2048
	ds_read_b128 v[192:195], v210 offset:16384
	s_add_u32 m0, s41, 36864
	s_nop 0
	global_load_lds_dwordx4 v213, s[98:99]
	s_waitcnt lgkmcnt(8)
	v_mfma_f32_16x16x32_bf16 v[60:63], v[72:75], v[168:171], v[60:63]
	v_mfma_f32_16x16x32_bf16 v[40:43], v[216:219], v[168:171], v[40:43]
	ds_read_b128 v[196:199], v210 offset:18432
	s_add_u32 m0, s41, 40960
	s_nop 0
	global_load_lds_dwordx4 v214, s[98:99]
	s_waitcnt lgkmcnt(8)
	v_mfma_f32_16x16x32_bf16 v[20:23], v[72:75], v[172:175], v[20:23]
	v_mfma_f32_16x16x32_bf16 v[0:3], v[216:219], v[172:175], v[0:3]
	ds_read_b128 v[200:203], v210 offset:20480
	s_add_u32 m0, s41, 45056
	s_nop 0
	global_load_lds_dwordx4 v215, s[98:99]
	s_add_u32 s98, s98, 128
	s_addc_u32 s99, s99, 0
	s_waitcnt lgkmcnt(8)
	v_mfma_f32_16x16x32_bf16 v[52:55], v[72:75], v[176:179], v[52:55]
	v_mfma_f32_16x16x32_bf16 v[36:39], v[216:219], v[176:179], v[36:39]
	ds_read_b128 v[204:207], v210 offset:22528
	s_add_u32 m0, s41, 49152
	s_nop 0
	global_load_lds_dwordx4 v212, s[100:101]
	s_waitcnt lgkmcnt(8)
	v_mfma_f32_16x16x32_bf16 v[24:27], v[72:75], v[180:183], v[24:27]
	v_mfma_f32_16x16x32_bf16 v[8:11], v[216:219], v[180:183], v[8:11]
	ds_read_b128 v[160:163], v210 offset:24576
	s_add_u32 m0, s41, 53248
	s_nop 0
	global_load_lds_dwordx4 v213, s[100:101]
	s_waitcnt lgkmcnt(8)
	v_mfma_f32_16x16x32_bf16 v[56:59], v[72:75], v[184:187], v[56:59]
	v_mfma_f32_16x16x32_bf16 v[32:35], v[216:219], v[184:187], v[32:35]
	ds_read_b128 v[164:167], v210 offset:26624
	s_add_u32 m0, s41, 57344
	s_nop 0
	global_load_lds_dwordx4 v214, s[100:101]
	s_waitcnt lgkmcnt(8)
	v_mfma_f32_16x16x32_bf16 v[12:15], v[72:75], v[188:191], v[12:15]
	v_mfma_f32_16x16x32_bf16 v[4:7], v[216:219], v[188:191], v[4:7]
	ds_read_b128 v[168:171], v210 offset:28672
	s_add_u32 m0, s41, 61440
	s_nop 0
	global_load_lds_dwordx4 v215, s[100:101]
	s_add_u32 s100, s100, 128
	s_addc_u32 s101, s101, 0
	s_waitcnt lgkmcnt(6)
	v_mfma_f32_16x16x32_bf16 v[44:47], v[64:67], v[192:195], v[44:47]
	v_mfma_f32_16x16x32_bf16 v[48:51], v[68:71], v[192:195], v[48:51]
	ds_read_b128 v[172:175], v210 offset:30720
	s_waitcnt lgkmcnt(6)
	v_mfma_f32_16x16x32_bf16 v[28:31], v[64:67], v[196:199], v[28:31]
	v_mfma_f32_16x16x32_bf16 v[16:19], v[68:71], v[196:199], v[16:19]
	ds_read_b128 v[72:75], v209 offset:0
	ds_read_b128 v[216:219], v209 offset:2048
	ds_read_b128 v[176:179], v211 offset:16384
	s_waitcnt lgkmcnt(8)
	v_mfma_f32_16x16x32_bf16 v[60:63], v[64:67], v[200:203], v[60:63]
	v_mfma_f32_16x16x32_bf16 v[40:43], v[68:71], v[200:203], v[40:43]
	ds_read_b128 v[180:183], v211 offset:18432
	s_waitcnt lgkmcnt(8)
	v_mfma_f32_16x16x32_bf16 v[20:23], v[64:67], v[204:207], v[20:23]
	v_mfma_f32_16x16x32_bf16 v[0:3], v[68:71], v[204:207], v[0:3]
	ds_read_b128 v[184:187], v211 offset:20480
	s_waitcnt lgkmcnt(8)
	v_mfma_f32_16x16x32_bf16 v[52:55], v[64:67], v[160:163], v[52:55]
	v_mfma_f32_16x16x32_bf16 v[36:39], v[68:71], v[160:163], v[36:39]
	ds_read_b128 v[188:191], v211 offset:22528
	s_waitcnt lgkmcnt(8)
	v_mfma_f32_16x16x32_bf16 v[24:27], v[64:67], v[164:167], v[24:27]
	v_mfma_f32_16x16x32_bf16 v[8:11], v[68:71], v[164:167], v[8:11]
	ds_read_b128 v[192:195], v211 offset:24576
	s_waitcnt lgkmcnt(8)
	v_mfma_f32_16x16x32_bf16 v[56:59], v[64:67], v[168:171], v[56:59]
	v_mfma_f32_16x16x32_bf16 v[32:35], v[68:71], v[168:171], v[32:35]
	ds_read_b128 v[196:199], v211 offset:26624
	s_waitcnt lgkmcnt(8)
	v_mfma_f32_16x16x32_bf16 v[12:15], v[64:67], v[172:175], v[12:15]
	v_mfma_f32_16x16x32_bf16 v[4:7], v[68:71], v[172:175], v[4:7]
	ds_read_b128 v[200:203], v211 offset:28672
	s_waitcnt lgkmcnt(6)
	v_mfma_f32_16x16x32_bf16 v[44:47], v[72:75], v[176:179], v[44:47]
	v_mfma_f32_16x16x32_bf16 v[48:51], v[216:219], v[176:179], v[48:51]
	ds_read_b128 v[204:207], v211 offset:30720
	s_waitcnt vmcnt(0) lgkmcnt(0)
	s_barrier
	s_add_u32 m0, s41, 0
	s_nop 0
	global_load_lds_dwordx4 v212, s[98:99]
	s_waitcnt lgkmcnt(6)
	v_mfma_f32_16x16x32_bf16 v[28:31], v[72:75], v[180:183], v[28:31]
	v_mfma_f32_16x16x32_bf16 v[16:19], v[216:219], v[180:183], v[16:19]
	ds_read_b128 v[64:67], v208 offset:32768
	ds_read_b128 v[68:71], v208 offset:34816
	ds_read_b128 v[160:163], v210 offset:49152
	s_add_u32 m0, s41, 4096
	s_nop 0
	global_load_lds_dwordx4 v213, s[98:99]
	s_waitcnt lgkmcnt(8)
	v_mfma_f32_16x16x32_bf16 v[60:63], v[72:75], v[184:187], v[60:63]
	v_mfma_f32_16x16x32_bf16 v[40:43], v[216:219], v[184:187], v[40:43]
	ds_read_b128 v[164:167], v210 offset:51200
	s_add_u32 m0, s41, 8192
	s_nop 0
	global_load_lds_dwordx4 v214, s[98:99]
	s_waitcnt lgkmcnt(8)
	v_mfma_f32_16x16x32_bf16 v[20:23], v[72:75], v[188:191], v[20:23]
	v_mfma_f32_16x16x32_bf16 v[0:3], v[216:219], v[188:191], v[0:3]
	ds_read_b128 v[168:171], v210 offset:53248
	s_add_u32 m0, s41, 12288
	s_nop 0
	global_load_lds_dwordx4 v215, s[98:99]
	s_add_u32 s98, s98, 128
	s_addc_u32 s99, s99, 0
	s_waitcnt lgkmcnt(8)
	v_mfma_f32_16x16x32_bf16 v[52:55], v[72:75], v[192:195], v[52:55]
	v_mfma_f32_16x16x32_bf16 v[36:39], v[216:219], v[192:195], v[36:39]
	ds_read_b128 v[172:175], v210 offset:55296
	s_add_u32 m0, s41, 16384
	s_nop 0
	global_load_lds_dwordx4 v212, s[100:101]
	s_waitcnt lgkmcnt(8)
	v_mfma_f32_16x16x32_bf16 v[24:27], v[72:75], v[196:199], v[24:27]
	v_mfma_f32_16x16x32_bf16 v[8:11], v[216:219], v[196:199], v[8:11]
	ds_read_b128 v[176:179], v210 offset:57344
	s_add_u32 m0, s41, 20480
	s_nop 0
	global_load_lds_dwordx4 v213, s[100:101]
	s_waitcnt lgkmcnt(8)
	v_mfma_f32_16x16x32_bf16 v[56:59], v[72:75], v[200:203], v[56:59]
	v_mfma_f32_16x16x32_bf16 v[32:35], v[216:219], v[200:203], v[32:35]
	ds_read_b128 v[180:183], v210 offset:59392
	s_add_u32 m0, s41, 24576
	s_nop 0
	global_load_lds_dwordx4 v214, s[100:101]
	s_waitcnt lgkmcnt(8)
	v_mfma_f32_16x16x32_bf16 v[12:15], v[72:75], v[204:207], v[12:15]
	v_mfma_f32_16x16x32_bf16 v[4:7], v[216:219], v[204:207], v[4:7]
	ds_read_b128 v[184:187], v210 offset:61440
	s_add_u32 m0, s41, 28672
	s_nop 0
	global_load_lds_dwordx4 v215, s[100:101]
	s_add_u32 s100, s100, 128
	s_addc_u32 s101, s101, 0
	s_waitcnt lgkmcnt(6)
	v_mfma_f32_16x16x32_bf16 v[44:47], v[64:67], v[160:163], v[44:47]
	v_mfma_f32_16x16x32_bf16 v[48:51], v[68:71], v[160:163], v[48:51]
	ds_read_b128 v[188:191], v210 offset:63488
	s_waitcnt lgkmcnt(6)
	v_mfma_f32_16x16x32_bf16 v[28:31], v[64:67], v[164:167], v[28:31]
	v_mfma_f32_16x16x32_bf16 v[16:19], v[68:71], v[164:167], v[16:19]
	ds_read_b128 v[72:75], v209 offset:32768
	ds_read_b128 v[216:219], v209 offset:34816
	ds_read_b128 v[192:195], v211 offset:49152
	s_waitcnt lgkmcnt(8)
	v_mfma_f32_16x16x32_bf16 v[60:63], v[64:67], v[168:171], v[60:63]
	v_mfma_f32_16x16x32_bf16 v[40:43], v[68:71], v[168:171], v[40:43]
	ds_read_b128 v[196:199], v211 offset:51200
	s_waitcnt lgkmcnt(8)
	v_mfma_f32_16x16x32_bf16 v[20:23], v[64:67], v[172:175], v[20:23]
	v_mfma_f32_16x16x32_bf16 v[0:3], v[68:71], v[172:175], v[0:3]
	ds_read_b128 v[200:203], v211 offset:53248
	s_waitcnt lgkmcnt(8)
	v_mfma_f32_16x16x32_bf16 v[52:55], v[64:67], v[176:179], v[52:55]
	v_mfma_f32_16x16x32_bf16 v[36:39], v[68:71], v[176:179], v[36:39]
	ds_read_b128 v[204:207], v211 offset:55296
	s_waitcnt lgkmcnt(8)
	v_mfma_f32_16x16x32_bf16 v[24:27], v[64:67], v[180:183], v[24:27]
	v_mfma_f32_16x16x32_bf16 v[8:11], v[68:71], v[180:183], v[8:11]
	ds_read_b128 v[160:163], v211 offset:57344
	s_waitcnt lgkmcnt(8)
	v_mfma_f32_16x16x32_bf16 v[56:59], v[64:67], v[184:187], v[56:59]
	v_mfma_f32_16x16x32_bf16 v[32:35], v[68:71], v[184:187], v[32:35]
	ds_read_b128 v[164:167], v211 offset:59392
	s_waitcnt lgkmcnt(8)
	v_mfma_f32_16x16x32_bf16 v[12:15], v[64:67], v[188:191], v[12:15]
	v_mfma_f32_16x16x32_bf16 v[4:7], v[68:71], v[188:191], v[4:7]
	ds_read_b128 v[168:171], v211 offset:61440
	s_waitcnt lgkmcnt(6)
	v_mfma_f32_16x16x32_bf16 v[44:47], v[72:75], v[192:195], v[44:47]
	v_mfma_f32_16x16x32_bf16 v[48:51], v[216:219], v[192:195], v[48:51]
	ds_read_b128 v[172:175], v211 offset:63488
	s_waitcnt vmcnt(0) lgkmcnt(0)
	s_barrier
	s_add_u32 m0, s41, 32768
	s_nop 0
	global_load_lds_dwordx4 v212, s[98:99]
	s_waitcnt lgkmcnt(6)
	v_mfma_f32_16x16x32_bf16 v[28:31], v[72:75], v[196:199], v[28:31]
	v_mfma_f32_16x16x32_bf16 v[16:19], v[216:219], v[196:199], v[16:19]
	ds_read_b128 v[64:67], v208 offset:0
	ds_read_b128 v[68:71], v208 offset:2048
	ds_read_b128 v[176:179], v210 offset:16384
	s_add_u32 m0, s41, 36864
	s_nop 0
	global_load_lds_dwordx4 v213, s[98:99]
	s_waitcnt lgkmcnt(8)
	v_mfma_f32_16x16x32_bf16 v[60:63], v[72:75], v[200:203], v[60:63]
	v_mfma_f32_16x16x32_bf16 v[40:43], v[216:219], v[200:203], v[40:43]
	ds_read_b128 v[180:183], v210 offset:18432
	s_add_u32 m0, s41, 40960
	s_nop 0
	global_load_lds_dwordx4 v214, s[98:99]
	s_waitcnt lgkmcnt(8)
	v_mfma_f32_16x16x32_bf16 v[20:23], v[72:75], v[204:207], v[20:23]
	v_mfma_f32_16x16x32_bf16 v[0:3], v[216:219], v[204:207], v[0:3]
	ds_read_b128 v[184:187], v210 offset:20480
	s_add_u32 m0, s41, 45056
	s_nop 0
	global_load_lds_dwordx4 v215, s[98:99]
	s_add_u32 s98, s98, 128
	s_addc_u32 s99, s99, 0
	s_waitcnt lgkmcnt(8)
	v_mfma_f32_16x16x32_bf16 v[52:55], v[72:75], v[160:163], v[52:55]
	v_mfma_f32_16x16x32_bf16 v[36:39], v[216:219], v[160:163], v[36:39]
	ds_read_b128 v[188:191], v210 offset:22528
	s_add_u32 m0, s41, 49152
	s_nop 0
	global_load_lds_dwordx4 v212, s[100:101]
	s_waitcnt lgkmcnt(8)
	v_mfma_f32_16x16x32_bf16 v[24:27], v[72:75], v[164:167], v[24:27]
	v_mfma_f32_16x16x32_bf16 v[8:11], v[216:219], v[164:167], v[8:11]
	ds_read_b128 v[192:195], v210 offset:24576
	s_add_u32 m0, s41, 53248
	s_nop 0
	global_load_lds_dwordx4 v213, s[100:101]
	s_waitcnt lgkmcnt(8)
	v_mfma_f32_16x16x32_bf16 v[56:59], v[72:75], v[168:171], v[56:59]
	v_mfma_f32_16x16x32_bf16 v[32:35], v[216:219], v[168:171], v[32:35]
	ds_read_b128 v[196:199], v210 offset:26624
	s_add_u32 m0, s41, 57344
	s_nop 0
	global_load_lds_dwordx4 v214, s[100:101]
	s_waitcnt lgkmcnt(8)
	v_mfma_f32_16x16x32_bf16 v[12:15], v[72:75], v[172:175], v[12:15]
	v_mfma_f32_16x16x32_bf16 v[4:7], v[216:219], v[172:175], v[4:7]
	ds_read_b128 v[200:203], v210 offset:28672
	s_add_u32 m0, s41, 61440
	s_nop 0
	global_load_lds_dwordx4 v215, s[100:101]
	s_add_u32 s100, s100, 128
	s_addc_u32 s101, s101, 0
	s_waitcnt lgkmcnt(6)
	v_mfma_f32_16x16x32_bf16 v[44:47], v[64:67], v[176:179], v[44:47]
	v_mfma_f32_16x16x32_bf16 v[48:51], v[68:71], v[176:179], v[48:51]
	ds_read_b128 v[204:207], v210 offset:30720
	s_waitcnt lgkmcnt(6)
	v_mfma_f32_16x16x32_bf16 v[28:31], v[64:67], v[180:183], v[28:31]
	v_mfma_f32_16x16x32_bf16 v[16:19], v[68:71], v[180:183], v[16:19]
	ds_read_b128 v[72:75], v209 offset:0
	ds_read_b128 v[216:219], v209 offset:2048
	ds_read_b128 v[160:163], v211 offset:16384
	s_waitcnt lgkmcnt(8)
	v_mfma_f32_16x16x32_bf16 v[60:63], v[64:67], v[184:187], v[60:63]
	v_mfma_f32_16x16x32_bf16 v[40:43], v[68:71], v[184:187], v[40:43]
	ds_read_b128 v[164:167], v211 offset:18432
	s_waitcnt lgkmcnt(8)
	v_mfma_f32_16x16x32_bf16 v[20:23], v[64:67], v[188:191], v[20:23]
	v_mfma_f32_16x16x32_bf16 v[0:3], v[68:71], v[188:191], v[0:3]
	ds_read_b128 v[168:171], v211 offset:20480
	s_waitcnt lgkmcnt(8)
	v_mfma_f32_16x16x32_bf16 v[52:55], v[64:67], v[192:195], v[52:55]
	v_mfma_f32_16x16x32_bf16 v[36:39], v[68:71], v[192:195], v[36:39]
	ds_read_b128 v[172:175], v211 offset:22528
	s_waitcnt lgkmcnt(8)
	v_mfma_f32_16x16x32_bf16 v[24:27], v[64:67], v[196:199], v[24:27]
	v_mfma_f32_16x16x32_bf16 v[8:11], v[68:71], v[196:199], v[8:11]
	ds_read_b128 v[176:179], v211 offset:24576
	s_waitcnt lgkmcnt(8)
	v_mfma_f32_16x16x32_bf16 v[56:59], v[64:67], v[200:203], v[56:59]
	v_mfma_f32_16x16x32_bf16 v[32:35], v[68:71], v[200:203], v[32:35]
	ds_read_b128 v[180:183], v211 offset:26624
	s_waitcnt lgkmcnt(8)
	v_mfma_f32_16x16x32_bf16 v[12:15], v[64:67], v[204:207], v[12:15]
	v_mfma_f32_16x16x32_bf16 v[4:7], v[68:71], v[204:207], v[4:7]
	ds_read_b128 v[184:187], v211 offset:28672
	s_waitcnt lgkmcnt(6)
	v_mfma_f32_16x16x32_bf16 v[44:47], v[72:75], v[160:163], v[44:47]
	v_mfma_f32_16x16x32_bf16 v[48:51], v[216:219], v[160:163], v[48:51]
	ds_read_b128 v[188:191], v211 offset:30720
	s_waitcnt vmcnt(0) lgkmcnt(0)
	s_barrier
	s_add_u32 m0, s41, 0
	s_nop 0
	global_load_lds_dwordx4 v212, s[98:99]
	s_waitcnt lgkmcnt(6)
	v_mfma_f32_16x16x32_bf16 v[28:31], v[72:75], v[164:167], v[28:31]
	v_mfma_f32_16x16x32_bf16 v[16:19], v[216:219], v[164:167], v[16:19]
	ds_read_b128 v[64:67], v208 offset:32768
	ds_read_b128 v[68:71], v208 offset:34816
	ds_read_b128 v[192:195], v210 offset:49152
	s_add_u32 m0, s41, 4096
	s_nop 0
	global_load_lds_dwordx4 v213, s[98:99]
	s_waitcnt lgkmcnt(8)
	v_mfma_f32_16x16x32_bf16 v[60:63], v[72:75], v[168:171], v[60:63]
	v_mfma_f32_16x16x32_bf16 v[40:43], v[216:219], v[168:171], v[40:43]
	ds_read_b128 v[196:199], v210 offset:51200
	s_add_u32 m0, s41, 8192
	s_nop 0
	global_load_lds_dwordx4 v214, s[98:99]
	s_waitcnt lgkmcnt(8)
	v_mfma_f32_16x16x32_bf16 v[20:23], v[72:75], v[172:175], v[20:23]
	v_mfma_f32_16x16x32_bf16 v[0:3], v[216:219], v[172:175], v[0:3]
	ds_read_b128 v[200:203], v210 offset:53248
	s_add_u32 m0, s41, 12288
	s_nop 0
	global_load_lds_dwordx4 v215, s[98:99]
	s_add_u32 s98, s98, 128
	s_addc_u32 s99, s99, 0
	s_waitcnt lgkmcnt(8)
	v_mfma_f32_16x16x32_bf16 v[52:55], v[72:75], v[176:179], v[52:55]
	v_mfma_f32_16x16x32_bf16 v[36:39], v[216:219], v[176:179], v[36:39]
	ds_read_b128 v[204:207], v210 offset:55296
	s_add_u32 m0, s41, 16384
	s_nop 0
	global_load_lds_dwordx4 v212, s[100:101]
	s_waitcnt lgkmcnt(8)
	v_mfma_f32_16x16x32_bf16 v[24:27], v[72:75], v[180:183], v[24:27]
	v_mfma_f32_16x16x32_bf16 v[8:11], v[216:219], v[180:183], v[8:11]
	ds_read_b128 v[160:163], v210 offset:57344
	s_add_u32 m0, s41, 20480
	s_nop 0
	global_load_lds_dwordx4 v213, s[100:101]
	s_waitcnt lgkmcnt(8)
	v_mfma_f32_16x16x32_bf16 v[56:59], v[72:75], v[184:187], v[56:59]
	v_mfma_f32_16x16x32_bf16 v[32:35], v[216:219], v[184:187], v[32:35]
	ds_read_b128 v[164:167], v210 offset:59392
	s_add_u32 m0, s41, 24576
	s_nop 0
	global_load_lds_dwordx4 v214, s[100:101]
	s_waitcnt lgkmcnt(8)
	v_mfma_f32_16x16x32_bf16 v[12:15], v[72:75], v[188:191], v[12:15]
	v_mfma_f32_16x16x32_bf16 v[4:7], v[216:219], v[188:191], v[4:7]
	ds_read_b128 v[168:171], v210 offset:61440
	s_add_u32 m0, s41, 28672
	s_nop 0
	global_load_lds_dwordx4 v215, s[100:101]
	s_add_u32 s100, s100, 128
	s_addc_u32 s101, s101, 0
	s_waitcnt lgkmcnt(6)
	v_mfma_f32_16x16x32_bf16 v[44:47], v[64:67], v[192:195], v[44:47]
	v_mfma_f32_16x16x32_bf16 v[48:51], v[68:71], v[192:195], v[48:51]
	ds_read_b128 v[172:175], v210 offset:63488
	s_waitcnt lgkmcnt(6)
	v_mfma_f32_16x16x32_bf16 v[28:31], v[64:67], v[196:199], v[28:31]
	v_mfma_f32_16x16x32_bf16 v[16:19], v[68:71], v[196:199], v[16:19]
	ds_read_b128 v[72:75], v209 offset:32768
	ds_read_b128 v[216:219], v209 offset:34816
	ds_read_b128 v[176:179], v211 offset:49152
	s_waitcnt lgkmcnt(8)
	v_mfma_f32_16x16x32_bf16 v[60:63], v[64:67], v[200:203], v[60:63]
	v_mfma_f32_16x16x32_bf16 v[40:43], v[68:71], v[200:203], v[40:43]
	ds_read_b128 v[180:183], v211 offset:51200
	s_waitcnt lgkmcnt(8)
	v_mfma_f32_16x16x32_bf16 v[20:23], v[64:67], v[204:207], v[20:23]
	v_mfma_f32_16x16x32_bf16 v[0:3], v[68:71], v[204:207], v[0:3]
	ds_read_b128 v[184:187], v211 offset:53248
	s_waitcnt lgkmcnt(8)
	v_mfma_f32_16x16x32_bf16 v[52:55], v[64:67], v[160:163], v[52:55]
	v_mfma_f32_16x16x32_bf16 v[36:39], v[68:71], v[160:163], v[36:39]
	ds_read_b128 v[188:191], v211 offset:55296
	s_waitcnt lgkmcnt(8)
	v_mfma_f32_16x16x32_bf16 v[24:27], v[64:67], v[164:167], v[24:27]
	v_mfma_f32_16x16x32_bf16 v[8:11], v[68:71], v[164:167], v[8:11]
	ds_read_b128 v[192:195], v211 offset:57344
	s_waitcnt lgkmcnt(8)
	v_mfma_f32_16x16x32_bf16 v[56:59], v[64:67], v[168:171], v[56:59]
	v_mfma_f32_16x16x32_bf16 v[32:35], v[68:71], v[168:171], v[32:35]
	ds_read_b128 v[196:199], v211 offset:59392
	s_waitcnt lgkmcnt(8)
	v_mfma_f32_16x16x32_bf16 v[12:15], v[64:67], v[172:175], v[12:15]
	v_mfma_f32_16x16x32_bf16 v[4:7], v[68:71], v[172:175], v[4:7]
	ds_read_b128 v[200:203], v211 offset:61440
	s_waitcnt lgkmcnt(6)
	v_mfma_f32_16x16x32_bf16 v[44:47], v[72:75], v[176:179], v[44:47]
	v_mfma_f32_16x16x32_bf16 v[48:51], v[216:219], v[176:179], v[48:51]
	ds_read_b128 v[204:207], v211 offset:63488
	s_waitcnt vmcnt(0) lgkmcnt(0)
	s_barrier
	s_add_u32 m0, s41, 32768
	s_nop 0
	global_load_lds_dwordx4 v212, s[98:99]
	s_waitcnt lgkmcnt(6)
	v_mfma_f32_16x16x32_bf16 v[28:31], v[72:75], v[180:183], v[28:31]
	v_mfma_f32_16x16x32_bf16 v[16:19], v[216:219], v[180:183], v[16:19]
	ds_read_b128 v[64:67], v208 offset:0
	ds_read_b128 v[68:71], v208 offset:2048
	ds_read_b128 v[160:163], v210 offset:16384
	s_add_u32 m0, s41, 36864
	s_nop 0
	global_load_lds_dwordx4 v213, s[98:99]
	s_waitcnt lgkmcnt(8)
	v_mfma_f32_16x16x32_bf16 v[60:63], v[72:75], v[184:187], v[60:63]
	v_mfma_f32_16x16x32_bf16 v[40:43], v[216:219], v[184:187], v[40:43]
	ds_read_b128 v[164:167], v210 offset:18432
	s_add_u32 m0, s41, 40960
	s_nop 0
	global_load_lds_dwordx4 v214, s[98:99]
	s_waitcnt lgkmcnt(8)
	v_mfma_f32_16x16x32_bf16 v[20:23], v[72:75], v[188:191], v[20:23]
	v_mfma_f32_16x16x32_bf16 v[0:3], v[216:219], v[188:191], v[0:3]
	ds_read_b128 v[168:171], v210 offset:20480
	s_add_u32 m0, s41, 45056
	s_nop 0
	global_load_lds_dwordx4 v215, s[98:99]
	s_add_u32 s98, s98, 128
	s_addc_u32 s99, s99, 0
	s_waitcnt lgkmcnt(8)
	v_mfma_f32_16x16x32_bf16 v[52:55], v[72:75], v[192:195], v[52:55]
	v_mfma_f32_16x16x32_bf16 v[36:39], v[216:219], v[192:195], v[36:39]
	ds_read_b128 v[172:175], v210 offset:22528
	s_add_u32 m0, s41, 49152
	s_nop 0
	global_load_lds_dwordx4 v212, s[100:101]
	s_waitcnt lgkmcnt(8)
	v_mfma_f32_16x16x32_bf16 v[24:27], v[72:75], v[196:199], v[24:27]
	v_mfma_f32_16x16x32_bf16 v[8:11], v[216:219], v[196:199], v[8:11]
	ds_read_b128 v[176:179], v210 offset:24576
	s_add_u32 m0, s41, 53248
	s_nop 0
	global_load_lds_dwordx4 v213, s[100:101]
	s_waitcnt lgkmcnt(8)
	v_mfma_f32_16x16x32_bf16 v[56:59], v[72:75], v[200:203], v[56:59]
	v_mfma_f32_16x16x32_bf16 v[32:35], v[216:219], v[200:203], v[32:35]
	ds_read_b128 v[180:183], v210 offset:26624
	s_add_u32 m0, s41, 57344
	s_nop 0
	global_load_lds_dwordx4 v214, s[100:101]
	s_waitcnt lgkmcnt(8)
	v_mfma_f32_16x16x32_bf16 v[12:15], v[72:75], v[204:207], v[12:15]
	v_mfma_f32_16x16x32_bf16 v[4:7], v[216:219], v[204:207], v[4:7]
	ds_read_b128 v[184:187], v210 offset:28672
	s_add_u32 m0, s41, 61440
	s_nop 0
	global_load_lds_dwordx4 v215, s[100:101]
	s_add_u32 s100, s100, 128
	s_addc_u32 s101, s101, 0
	s_waitcnt lgkmcnt(6)
	v_mfma_f32_16x16x32_bf16 v[44:47], v[64:67], v[160:163], v[44:47]
	v_mfma_f32_16x16x32_bf16 v[48:51], v[68:71], v[160:163], v[48:51]
	ds_read_b128 v[188:191], v210 offset:30720
	s_waitcnt lgkmcnt(6)
	v_mfma_f32_16x16x32_bf16 v[28:31], v[64:67], v[164:167], v[28:31]
	v_mfma_f32_16x16x32_bf16 v[16:19], v[68:71], v[164:167], v[16:19]
	ds_read_b128 v[72:75], v209 offset:0
	ds_read_b128 v[216:219], v209 offset:2048
	ds_read_b128 v[192:195], v211 offset:16384
	s_waitcnt lgkmcnt(8)
	v_mfma_f32_16x16x32_bf16 v[60:63], v[64:67], v[168:171], v[60:63]
	v_mfma_f32_16x16x32_bf16 v[40:43], v[68:71], v[168:171], v[40:43]
	ds_read_b128 v[196:199], v211 offset:18432
	s_waitcnt lgkmcnt(8)
	v_mfma_f32_16x16x32_bf16 v[20:23], v[64:67], v[172:175], v[20:23]
	v_mfma_f32_16x16x32_bf16 v[0:3], v[68:71], v[172:175], v[0:3]
	ds_read_b128 v[200:203], v211 offset:20480
	s_waitcnt lgkmcnt(8)
	v_mfma_f32_16x16x32_bf16 v[52:55], v[64:67], v[176:179], v[52:55]
	v_mfma_f32_16x16x32_bf16 v[36:39], v[68:71], v[176:179], v[36:39]
	ds_read_b128 v[204:207], v211 offset:22528
	s_waitcnt lgkmcnt(8)
	v_mfma_f32_16x16x32_bf16 v[24:27], v[64:67], v[180:183], v[24:27]
	v_mfma_f32_16x16x32_bf16 v[8:11], v[68:71], v[180:183], v[8:11]
	ds_read_b128 v[160:163], v211 offset:24576
	s_waitcnt lgkmcnt(8)
	v_mfma_f32_16x16x32_bf16 v[56:59], v[64:67], v[184:187], v[56:59]
	v_mfma_f32_16x16x32_bf16 v[32:35], v[68:71], v[184:187], v[32:35]
	ds_read_b128 v[164:167], v211 offset:26624
	s_waitcnt lgkmcnt(8)
	v_mfma_f32_16x16x32_bf16 v[12:15], v[64:67], v[188:191], v[12:15]
	v_mfma_f32_16x16x32_bf16 v[4:7], v[68:71], v[188:191], v[4:7]
	ds_read_b128 v[168:171], v211 offset:28672
	s_waitcnt lgkmcnt(6)
	v_mfma_f32_16x16x32_bf16 v[44:47], v[72:75], v[192:195], v[44:47]
	v_mfma_f32_16x16x32_bf16 v[48:51], v[216:219], v[192:195], v[48:51]
	ds_read_b128 v[172:175], v211 offset:30720
	s_waitcnt vmcnt(0) lgkmcnt(0)
	s_barrier
	s_add_u32 m0, s41, 0
	s_nop 0
	global_load_lds_dwordx4 v212, s[98:99]
	s_waitcnt lgkmcnt(6)
	v_mfma_f32_16x16x32_bf16 v[28:31], v[72:75], v[196:199], v[28:31]
	v_mfma_f32_16x16x32_bf16 v[16:19], v[216:219], v[196:199], v[16:19]
	ds_read_b128 v[64:67], v208 offset:32768
	ds_read_b128 v[68:71], v208 offset:34816
	ds_read_b128 v[176:179], v210 offset:49152
	s_add_u32 m0, s41, 4096
	s_nop 0
	global_load_lds_dwordx4 v213, s[98:99]
	s_waitcnt lgkmcnt(8)
	v_mfma_f32_16x16x32_bf16 v[60:63], v[72:75], v[200:203], v[60:63]
	v_mfma_f32_16x16x32_bf16 v[40:43], v[216:219], v[200:203], v[40:43]
	ds_read_b128 v[180:183], v210 offset:51200
	s_add_u32 m0, s41, 8192
	s_nop 0
	global_load_lds_dwordx4 v214, s[98:99]
	s_waitcnt lgkmcnt(8)
	v_mfma_f32_16x16x32_bf16 v[20:23], v[72:75], v[204:207], v[20:23]
	v_mfma_f32_16x16x32_bf16 v[0:3], v[216:219], v[204:207], v[0:3]
	ds_read_b128 v[184:187], v210 offset:53248
	s_add_u32 m0, s41, 12288
	s_nop 0
	global_load_lds_dwordx4 v215, s[98:99]
	s_add_u32 s98, s98, 128
	s_addc_u32 s99, s99, 0
	s_waitcnt lgkmcnt(8)
	v_mfma_f32_16x16x32_bf16 v[52:55], v[72:75], v[160:163], v[52:55]
	v_mfma_f32_16x16x32_bf16 v[36:39], v[216:219], v[160:163], v[36:39]
	ds_read_b128 v[188:191], v210 offset:55296
	s_add_u32 m0, s41, 16384
	s_nop 0
	global_load_lds_dwordx4 v212, s[100:101]
	s_waitcnt lgkmcnt(8)
	v_mfma_f32_16x16x32_bf16 v[24:27], v[72:75], v[164:167], v[24:27]
	v_mfma_f32_16x16x32_bf16 v[8:11], v[216:219], v[164:167], v[8:11]
	ds_read_b128 v[192:195], v210 offset:57344
	s_add_u32 m0, s41, 20480
	s_nop 0
	global_load_lds_dwordx4 v213, s[100:101]
	s_waitcnt lgkmcnt(8)
	v_mfma_f32_16x16x32_bf16 v[56:59], v[72:75], v[168:171], v[56:59]
	v_mfma_f32_16x16x32_bf16 v[32:35], v[216:219], v[168:171], v[32:35]
	ds_read_b128 v[196:199], v210 offset:59392
	s_add_u32 m0, s41, 24576
	s_nop 0
	global_load_lds_dwordx4 v214, s[100:101]
	s_waitcnt lgkmcnt(8)
	v_mfma_f32_16x16x32_bf16 v[12:15], v[72:75], v[172:175], v[12:15]
	v_mfma_f32_16x16x32_bf16 v[4:7], v[216:219], v[172:175], v[4:7]
	ds_read_b128 v[200:203], v210 offset:61440
	s_add_u32 m0, s41, 28672
	s_nop 0
	global_load_lds_dwordx4 v215, s[100:101]
	s_add_u32 s100, s100, 128
	s_addc_u32 s101, s101, 0
	s_waitcnt lgkmcnt(6)
	v_mfma_f32_16x16x32_bf16 v[44:47], v[64:67], v[176:179], v[44:47]
	v_mfma_f32_16x16x32_bf16 v[48:51], v[68:71], v[176:179], v[48:51]
	ds_read_b128 v[204:207], v210 offset:63488
	s_waitcnt lgkmcnt(6)
	v_mfma_f32_16x16x32_bf16 v[28:31], v[64:67], v[180:183], v[28:31]
	v_mfma_f32_16x16x32_bf16 v[16:19], v[68:71], v[180:183], v[16:19]
	ds_read_b128 v[72:75], v209 offset:32768
	ds_read_b128 v[216:219], v209 offset:34816
	ds_read_b128 v[160:163], v211 offset:49152
	s_waitcnt lgkmcnt(8)
	v_mfma_f32_16x16x32_bf16 v[60:63], v[64:67], v[184:187], v[60:63]
	v_mfma_f32_16x16x32_bf16 v[40:43], v[68:71], v[184:187], v[40:43]
	ds_read_b128 v[164:167], v211 offset:51200
	s_waitcnt lgkmcnt(8)
	v_mfma_f32_16x16x32_bf16 v[20:23], v[64:67], v[188:191], v[20:23]
	v_mfma_f32_16x16x32_bf16 v[0:3], v[68:71], v[188:191], v[0:3]
	ds_read_b128 v[168:171], v211 offset:53248
	s_waitcnt lgkmcnt(8)
	v_mfma_f32_16x16x32_bf16 v[52:55], v[64:67], v[192:195], v[52:55]
	v_mfma_f32_16x16x32_bf16 v[36:39], v[68:71], v[192:195], v[36:39]
	ds_read_b128 v[172:175], v211 offset:55296
	s_waitcnt lgkmcnt(8)
	v_mfma_f32_16x16x32_bf16 v[24:27], v[64:67], v[196:199], v[24:27]
	v_mfma_f32_16x16x32_bf16 v[8:11], v[68:71], v[196:199], v[8:11]
	ds_read_b128 v[176:179], v211 offset:57344
	s_waitcnt lgkmcnt(8)
	v_mfma_f32_16x16x32_bf16 v[56:59], v[64:67], v[200:203], v[56:59]
	v_mfma_f32_16x16x32_bf16 v[32:35], v[68:71], v[200:203], v[32:35]
	ds_read_b128 v[180:183], v211 offset:59392
	s_waitcnt lgkmcnt(8)
	v_mfma_f32_16x16x32_bf16 v[12:15], v[64:67], v[204:207], v[12:15]
	v_mfma_f32_16x16x32_bf16 v[4:7], v[68:71], v[204:207], v[4:7]
	ds_read_b128 v[184:187], v211 offset:61440
	s_waitcnt lgkmcnt(6)
	v_mfma_f32_16x16x32_bf16 v[44:47], v[72:75], v[160:163], v[44:47]
	v_mfma_f32_16x16x32_bf16 v[48:51], v[216:219], v[160:163], v[48:51]
	ds_read_b128 v[188:191], v211 offset:63488
	s_waitcnt vmcnt(0) lgkmcnt(0)
	s_barrier
	s_add_u32 m0, s41, 32768
	s_nop 0
	global_load_lds_dwordx4 v212, s[98:99]
	s_waitcnt lgkmcnt(6)
	v_mfma_f32_16x16x32_bf16 v[28:31], v[72:75], v[164:167], v[28:31]
	v_mfma_f32_16x16x32_bf16 v[16:19], v[216:219], v[164:167], v[16:19]
	ds_read_b128 v[64:67], v208 offset:0
	ds_read_b128 v[68:71], v208 offset:2048
	ds_read_b128 v[192:195], v210 offset:16384
	s_add_u32 m0, s41, 36864
	s_nop 0
	global_load_lds_dwordx4 v213, s[98:99]
	s_waitcnt lgkmcnt(8)
	v_mfma_f32_16x16x32_bf16 v[60:63], v[72:75], v[168:171], v[60:63]
	v_mfma_f32_16x16x32_bf16 v[40:43], v[216:219], v[168:171], v[40:43]
	ds_read_b128 v[196:199], v210 offset:18432
	s_add_u32 m0, s41, 40960
	s_nop 0
	global_load_lds_dwordx4 v214, s[98:99]
	s_waitcnt lgkmcnt(8)
	v_mfma_f32_16x16x32_bf16 v[20:23], v[72:75], v[172:175], v[20:23]
	v_mfma_f32_16x16x32_bf16 v[0:3], v[216:219], v[172:175], v[0:3]
	ds_read_b128 v[200:203], v210 offset:20480
	s_add_u32 m0, s41, 45056
	s_nop 0
	global_load_lds_dwordx4 v215, s[98:99]
	s_add_u32 s98, s98, 128
	s_addc_u32 s99, s99, 0
	s_waitcnt lgkmcnt(8)
	v_mfma_f32_16x16x32_bf16 v[52:55], v[72:75], v[176:179], v[52:55]
	v_mfma_f32_16x16x32_bf16 v[36:39], v[216:219], v[176:179], v[36:39]
	ds_read_b128 v[204:207], v210 offset:22528
	s_add_u32 m0, s41, 49152
	s_nop 0
	global_load_lds_dwordx4 v212, s[100:101]
	s_waitcnt lgkmcnt(8)
	v_mfma_f32_16x16x32_bf16 v[24:27], v[72:75], v[180:183], v[24:27]
	v_mfma_f32_16x16x32_bf16 v[8:11], v[216:219], v[180:183], v[8:11]
	ds_read_b128 v[160:163], v210 offset:24576
	s_add_u32 m0, s41, 53248
	s_nop 0
	global_load_lds_dwordx4 v213, s[100:101]
	s_waitcnt lgkmcnt(8)
	v_mfma_f32_16x16x32_bf16 v[56:59], v[72:75], v[184:187], v[56:59]
	v_mfma_f32_16x16x32_bf16 v[32:35], v[216:219], v[184:187], v[32:35]
	ds_read_b128 v[164:167], v210 offset:26624
	s_add_u32 m0, s41, 57344
	s_nop 0
	global_load_lds_dwordx4 v214, s[100:101]
	s_waitcnt lgkmcnt(8)
	v_mfma_f32_16x16x32_bf16 v[12:15], v[72:75], v[188:191], v[12:15]
	v_mfma_f32_16x16x32_bf16 v[4:7], v[216:219], v[188:191], v[4:7]
	ds_read_b128 v[168:171], v210 offset:28672
	s_add_u32 m0, s41, 61440
	s_nop 0
	global_load_lds_dwordx4 v215, s[100:101]
	s_add_u32 s100, s100, 128
	s_addc_u32 s101, s101, 0
	s_waitcnt lgkmcnt(6)
	v_mfma_f32_16x16x32_bf16 v[44:47], v[64:67], v[192:195], v[44:47]
	v_mfma_f32_16x16x32_bf16 v[48:51], v[68:71], v[192:195], v[48:51]
	ds_read_b128 v[172:175], v210 offset:30720
	s_waitcnt lgkmcnt(6)
	v_mfma_f32_16x16x32_bf16 v[28:31], v[64:67], v[196:199], v[28:31]
	v_mfma_f32_16x16x32_bf16 v[16:19], v[68:71], v[196:199], v[16:19]
	ds_read_b128 v[72:75], v209 offset:0
	ds_read_b128 v[216:219], v209 offset:2048
	ds_read_b128 v[176:179], v211 offset:16384
	s_waitcnt lgkmcnt(8)
	v_mfma_f32_16x16x32_bf16 v[60:63], v[64:67], v[200:203], v[60:63]
	v_mfma_f32_16x16x32_bf16 v[40:43], v[68:71], v[200:203], v[40:43]
	ds_read_b128 v[180:183], v211 offset:18432
	s_waitcnt lgkmcnt(8)
	v_mfma_f32_16x16x32_bf16 v[20:23], v[64:67], v[204:207], v[20:23]
	v_mfma_f32_16x16x32_bf16 v[0:3], v[68:71], v[204:207], v[0:3]
	ds_read_b128 v[184:187], v211 offset:20480
	s_waitcnt lgkmcnt(8)
	v_mfma_f32_16x16x32_bf16 v[52:55], v[64:67], v[160:163], v[52:55]
	v_mfma_f32_16x16x32_bf16 v[36:39], v[68:71], v[160:163], v[36:39]
	ds_read_b128 v[188:191], v211 offset:22528
	s_waitcnt lgkmcnt(8)
	v_mfma_f32_16x16x32_bf16 v[24:27], v[64:67], v[164:167], v[24:27]
	v_mfma_f32_16x16x32_bf16 v[8:11], v[68:71], v[164:167], v[8:11]
	ds_read_b128 v[192:195], v211 offset:24576
	s_waitcnt lgkmcnt(8)
	v_mfma_f32_16x16x32_bf16 v[56:59], v[64:67], v[168:171], v[56:59]
	v_mfma_f32_16x16x32_bf16 v[32:35], v[68:71], v[168:171], v[32:35]
	ds_read_b128 v[196:199], v211 offset:26624
	s_waitcnt lgkmcnt(8)
	v_mfma_f32_16x16x32_bf16 v[12:15], v[64:67], v[172:175], v[12:15]
	v_mfma_f32_16x16x32_bf16 v[4:7], v[68:71], v[172:175], v[4:7]
	ds_read_b128 v[200:203], v211 offset:28672
	s_waitcnt lgkmcnt(6)
	v_mfma_f32_16x16x32_bf16 v[44:47], v[72:75], v[176:179], v[44:47]
	v_mfma_f32_16x16x32_bf16 v[48:51], v[216:219], v[176:179], v[48:51]
	ds_read_b128 v[204:207], v211 offset:30720
	s_waitcnt vmcnt(0) lgkmcnt(0)
	s_barrier
	s_add_u32 m0, s41, 0
	s_nop 0
	global_load_lds_dwordx4 v212, s[98:99]
	s_waitcnt lgkmcnt(6)
	v_mfma_f32_16x16x32_bf16 v[28:31], v[72:75], v[180:183], v[28:31]
	v_mfma_f32_16x16x32_bf16 v[16:19], v[216:219], v[180:183], v[16:19]
	ds_read_b128 v[64:67], v208 offset:32768
	ds_read_b128 v[68:71], v208 offset:34816
	ds_read_b128 v[160:163], v210 offset:49152
	s_add_u32 m0, s41, 4096
	s_nop 0
	global_load_lds_dwordx4 v213, s[98:99]
	s_waitcnt lgkmcnt(8)
	v_mfma_f32_16x16x32_bf16 v[60:63], v[72:75], v[184:187], v[60:63]
	v_mfma_f32_16x16x32_bf16 v[40:43], v[216:219], v[184:187], v[40:43]
	ds_read_b128 v[164:167], v210 offset:51200
	s_add_u32 m0, s41, 8192
	s_nop 0
	global_load_lds_dwordx4 v214, s[98:99]
	s_waitcnt lgkmcnt(8)
	v_mfma_f32_16x16x32_bf16 v[20:23], v[72:75], v[188:191], v[20:23]
	v_mfma_f32_16x16x32_bf16 v[0:3], v[216:219], v[188:191], v[0:3]
	ds_read_b128 v[168:171], v210 offset:53248
	s_add_u32 m0, s41, 12288
	s_nop 0
	global_load_lds_dwordx4 v215, s[98:99]
	s_add_u32 s98, s98, 128
	s_addc_u32 s99, s99, 0
	s_waitcnt lgkmcnt(8)
	v_mfma_f32_16x16x32_bf16 v[52:55], v[72:75], v[192:195], v[52:55]
	v_mfma_f32_16x16x32_bf16 v[36:39], v[216:219], v[192:195], v[36:39]
	ds_read_b128 v[172:175], v210 offset:55296
	s_add_u32 m0, s41, 16384
	s_nop 0
	global_load_lds_dwordx4 v212, s[100:101]
	s_waitcnt lgkmcnt(8)
	v_mfma_f32_16x16x32_bf16 v[24:27], v[72:75], v[196:199], v[24:27]
	v_mfma_f32_16x16x32_bf16 v[8:11], v[216:219], v[196:199], v[8:11]
	ds_read_b128 v[176:179], v210 offset:57344
	s_add_u32 m0, s41, 20480
	s_nop 0
	global_load_lds_dwordx4 v213, s[100:101]
	s_waitcnt lgkmcnt(8)
	v_mfma_f32_16x16x32_bf16 v[56:59], v[72:75], v[200:203], v[56:59]
	v_mfma_f32_16x16x32_bf16 v[32:35], v[216:219], v[200:203], v[32:35]
	ds_read_b128 v[180:183], v210 offset:59392
	s_add_u32 m0, s41, 24576
	s_nop 0
	global_load_lds_dwordx4 v214, s[100:101]
	s_waitcnt lgkmcnt(8)
	v_mfma_f32_16x16x32_bf16 v[12:15], v[72:75], v[204:207], v[12:15]
	v_mfma_f32_16x16x32_bf16 v[4:7], v[216:219], v[204:207], v[4:7]
	ds_read_b128 v[184:187], v210 offset:61440
	s_add_u32 m0, s41, 28672
	s_nop 0
	global_load_lds_dwordx4 v215, s[100:101]
	s_add_u32 s100, s100, 128
	s_addc_u32 s101, s101, 0
	s_waitcnt lgkmcnt(6)
	v_mfma_f32_16x16x32_bf16 v[44:47], v[64:67], v[160:163], v[44:47]
	v_mfma_f32_16x16x32_bf16 v[48:51], v[68:71], v[160:163], v[48:51]
	ds_read_b128 v[188:191], v210 offset:63488
	s_waitcnt lgkmcnt(6)
	v_mfma_f32_16x16x32_bf16 v[28:31], v[64:67], v[164:167], v[28:31]
	v_mfma_f32_16x16x32_bf16 v[16:19], v[68:71], v[164:167], v[16:19]
	ds_read_b128 v[72:75], v209 offset:32768
	ds_read_b128 v[216:219], v209 offset:34816
	ds_read_b128 v[192:195], v211 offset:49152
	s_waitcnt lgkmcnt(8)
	v_mfma_f32_16x16x32_bf16 v[60:63], v[64:67], v[168:171], v[60:63]
	v_mfma_f32_16x16x32_bf16 v[40:43], v[68:71], v[168:171], v[40:43]
	ds_read_b128 v[196:199], v211 offset:51200
	s_waitcnt lgkmcnt(8)
	v_mfma_f32_16x16x32_bf16 v[20:23], v[64:67], v[172:175], v[20:23]
	v_mfma_f32_16x16x32_bf16 v[0:3], v[68:71], v[172:175], v[0:3]
	ds_read_b128 v[200:203], v211 offset:53248
	s_waitcnt lgkmcnt(8)
	v_mfma_f32_16x16x32_bf16 v[52:55], v[64:67], v[176:179], v[52:55]
	v_mfma_f32_16x16x32_bf16 v[36:39], v[68:71], v[176:179], v[36:39]
	ds_read_b128 v[204:207], v211 offset:55296
	s_waitcnt lgkmcnt(8)
	v_mfma_f32_16x16x32_bf16 v[24:27], v[64:67], v[180:183], v[24:27]
	v_mfma_f32_16x16x32_bf16 v[8:11], v[68:71], v[180:183], v[8:11]
	ds_read_b128 v[160:163], v211 offset:57344
	s_waitcnt lgkmcnt(8)
	v_mfma_f32_16x16x32_bf16 v[56:59], v[64:67], v[184:187], v[56:59]
	v_mfma_f32_16x16x32_bf16 v[32:35], v[68:71], v[184:187], v[32:35]
	ds_read_b128 v[164:167], v211 offset:59392
	s_waitcnt lgkmcnt(8)
	v_mfma_f32_16x16x32_bf16 v[12:15], v[64:67], v[188:191], v[12:15]
	v_mfma_f32_16x16x32_bf16 v[4:7], v[68:71], v[188:191], v[4:7]
	ds_read_b128 v[168:171], v211 offset:61440
	s_waitcnt lgkmcnt(6)
	v_mfma_f32_16x16x32_bf16 v[44:47], v[72:75], v[192:195], v[44:47]
	v_mfma_f32_16x16x32_bf16 v[48:51], v[216:219], v[192:195], v[48:51]
	ds_read_b128 v[172:175], v211 offset:63488
	s_waitcnt vmcnt(0) lgkmcnt(0)
	s_barrier
	s_add_u32 m0, s41, 32768
	s_nop 0
	global_load_lds_dwordx4 v212, s[98:99]
	s_waitcnt lgkmcnt(6)
	v_mfma_f32_16x16x32_bf16 v[28:31], v[72:75], v[196:199], v[28:31]
	v_mfma_f32_16x16x32_bf16 v[16:19], v[216:219], v[196:199], v[16:19]
	ds_read_b128 v[64:67], v208 offset:0
	ds_read_b128 v[68:71], v208 offset:2048
	ds_read_b128 v[176:179], v210 offset:16384
	s_add_u32 m0, s41, 36864
	s_nop 0
	global_load_lds_dwordx4 v213, s[98:99]
	s_waitcnt lgkmcnt(8)
	v_mfma_f32_16x16x32_bf16 v[60:63], v[72:75], v[200:203], v[60:63]
	v_mfma_f32_16x16x32_bf16 v[40:43], v[216:219], v[200:203], v[40:43]
	ds_read_b128 v[180:183], v210 offset:18432
	s_add_u32 m0, s41, 40960
	s_nop 0
	global_load_lds_dwordx4 v214, s[98:99]
	s_waitcnt lgkmcnt(8)
	v_mfma_f32_16x16x32_bf16 v[20:23], v[72:75], v[204:207], v[20:23]
	v_mfma_f32_16x16x32_bf16 v[0:3], v[216:219], v[204:207], v[0:3]
	ds_read_b128 v[184:187], v210 offset:20480
	s_add_u32 m0, s41, 45056
	s_nop 0
	global_load_lds_dwordx4 v215, s[98:99]
	s_add_u32 s98, s98, 128
	s_addc_u32 s99, s99, 0
	s_waitcnt lgkmcnt(8)
	v_mfma_f32_16x16x32_bf16 v[52:55], v[72:75], v[160:163], v[52:55]
	v_mfma_f32_16x16x32_bf16 v[36:39], v[216:219], v[160:163], v[36:39]
	ds_read_b128 v[188:191], v210 offset:22528
	s_add_u32 m0, s41, 49152
	s_nop 0
	global_load_lds_dwordx4 v212, s[100:101]
	s_waitcnt lgkmcnt(8)
	v_mfma_f32_16x16x32_bf16 v[24:27], v[72:75], v[164:167], v[24:27]
	v_mfma_f32_16x16x32_bf16 v[8:11], v[216:219], v[164:167], v[8:11]
	ds_read_b128 v[192:195], v210 offset:24576
	s_add_u32 m0, s41, 53248
	s_nop 0
	global_load_lds_dwordx4 v213, s[100:101]
	s_waitcnt lgkmcnt(8)
	v_mfma_f32_16x16x32_bf16 v[56:59], v[72:75], v[168:171], v[56:59]
	v_mfma_f32_16x16x32_bf16 v[32:35], v[216:219], v[168:171], v[32:35]
	ds_read_b128 v[196:199], v210 offset:26624
	s_add_u32 m0, s41, 57344
	s_nop 0
	global_load_lds_dwordx4 v214, s[100:101]
	s_waitcnt lgkmcnt(8)
	v_mfma_f32_16x16x32_bf16 v[12:15], v[72:75], v[172:175], v[12:15]
	v_mfma_f32_16x16x32_bf16 v[4:7], v[216:219], v[172:175], v[4:7]
	ds_read_b128 v[200:203], v210 offset:28672
	s_add_u32 m0, s41, 61440
	s_nop 0
	global_load_lds_dwordx4 v215, s[100:101]
	s_add_u32 s100, s100, 128
	s_addc_u32 s101, s101, 0
	s_waitcnt lgkmcnt(6)
	v_mfma_f32_16x16x32_bf16 v[44:47], v[64:67], v[176:179], v[44:47]
	v_mfma_f32_16x16x32_bf16 v[48:51], v[68:71], v[176:179], v[48:51]
	ds_read_b128 v[204:207], v210 offset:30720
	s_waitcnt lgkmcnt(6)
	v_mfma_f32_16x16x32_bf16 v[28:31], v[64:67], v[180:183], v[28:31]
	v_mfma_f32_16x16x32_bf16 v[16:19], v[68:71], v[180:183], v[16:19]
	ds_read_b128 v[72:75], v209 offset:0
	ds_read_b128 v[216:219], v209 offset:2048
	ds_read_b128 v[160:163], v211 offset:16384
	s_waitcnt lgkmcnt(8)
	v_mfma_f32_16x16x32_bf16 v[60:63], v[64:67], v[184:187], v[60:63]
	v_mfma_f32_16x16x32_bf16 v[40:43], v[68:71], v[184:187], v[40:43]
	ds_read_b128 v[164:167], v211 offset:18432
	s_waitcnt lgkmcnt(8)
	v_mfma_f32_16x16x32_bf16 v[20:23], v[64:67], v[188:191], v[20:23]
	v_mfma_f32_16x16x32_bf16 v[0:3], v[68:71], v[188:191], v[0:3]
	ds_read_b128 v[168:171], v211 offset:20480
	s_waitcnt lgkmcnt(8)
	v_mfma_f32_16x16x32_bf16 v[52:55], v[64:67], v[192:195], v[52:55]
	v_mfma_f32_16x16x32_bf16 v[36:39], v[68:71], v[192:195], v[36:39]
	ds_read_b128 v[172:175], v211 offset:22528
	s_waitcnt lgkmcnt(8)
	v_mfma_f32_16x16x32_bf16 v[24:27], v[64:67], v[196:199], v[24:27]
	v_mfma_f32_16x16x32_bf16 v[8:11], v[68:71], v[196:199], v[8:11]
	ds_read_b128 v[176:179], v211 offset:24576
	s_waitcnt lgkmcnt(8)
	v_mfma_f32_16x16x32_bf16 v[56:59], v[64:67], v[200:203], v[56:59]
	v_mfma_f32_16x16x32_bf16 v[32:35], v[68:71], v[200:203], v[32:35]
	ds_read_b128 v[180:183], v211 offset:26624
	s_waitcnt lgkmcnt(8)
	v_mfma_f32_16x16x32_bf16 v[12:15], v[64:67], v[204:207], v[12:15]
	v_mfma_f32_16x16x32_bf16 v[4:7], v[68:71], v[204:207], v[4:7]
	ds_read_b128 v[184:187], v211 offset:28672
	s_waitcnt lgkmcnt(6)
	v_mfma_f32_16x16x32_bf16 v[44:47], v[72:75], v[160:163], v[44:47]
	v_mfma_f32_16x16x32_bf16 v[48:51], v[216:219], v[160:163], v[48:51]
	ds_read_b128 v[188:191], v211 offset:30720
	s_waitcnt vmcnt(0) lgkmcnt(0)
	s_barrier
	s_add_u32 m0, s41, 0
	s_nop 0
	global_load_lds_dwordx4 v212, s[98:99]
	s_waitcnt lgkmcnt(6)
	v_mfma_f32_16x16x32_bf16 v[28:31], v[72:75], v[164:167], v[28:31]
	v_mfma_f32_16x16x32_bf16 v[16:19], v[216:219], v[164:167], v[16:19]
	ds_read_b128 v[64:67], v208 offset:32768
	ds_read_b128 v[68:71], v208 offset:34816
	ds_read_b128 v[192:195], v210 offset:49152
	s_add_u32 m0, s41, 4096
	s_nop 0
	global_load_lds_dwordx4 v213, s[98:99]
	s_waitcnt lgkmcnt(8)
	v_mfma_f32_16x16x32_bf16 v[60:63], v[72:75], v[168:171], v[60:63]
	v_mfma_f32_16x16x32_bf16 v[40:43], v[216:219], v[168:171], v[40:43]
	ds_read_b128 v[196:199], v210 offset:51200
	s_add_u32 m0, s41, 8192
	s_nop 0
	global_load_lds_dwordx4 v214, s[98:99]
	s_waitcnt lgkmcnt(8)
	v_mfma_f32_16x16x32_bf16 v[20:23], v[72:75], v[172:175], v[20:23]
	v_mfma_f32_16x16x32_bf16 v[0:3], v[216:219], v[172:175], v[0:3]
	ds_read_b128 v[200:203], v210 offset:53248
	s_add_u32 m0, s41, 12288
	s_nop 0
	global_load_lds_dwordx4 v215, s[98:99]
	s_add_u32 s98, s98, 128
	s_addc_u32 s99, s99, 0
	s_waitcnt lgkmcnt(8)
	v_mfma_f32_16x16x32_bf16 v[52:55], v[72:75], v[176:179], v[52:55]
	v_mfma_f32_16x16x32_bf16 v[36:39], v[216:219], v[176:179], v[36:39]
	ds_read_b128 v[204:207], v210 offset:55296
	s_add_u32 m0, s41, 16384
	s_nop 0
	global_load_lds_dwordx4 v212, s[100:101]
	s_waitcnt lgkmcnt(8)
	v_mfma_f32_16x16x32_bf16 v[24:27], v[72:75], v[180:183], v[24:27]
	v_mfma_f32_16x16x32_bf16 v[8:11], v[216:219], v[180:183], v[8:11]
	ds_read_b128 v[160:163], v210 offset:57344
	s_add_u32 m0, s41, 20480
	s_nop 0
	global_load_lds_dwordx4 v213, s[100:101]
	s_waitcnt lgkmcnt(8)
	v_mfma_f32_16x16x32_bf16 v[56:59], v[72:75], v[184:187], v[56:59]
	v_mfma_f32_16x16x32_bf16 v[32:35], v[216:219], v[184:187], v[32:35]
	ds_read_b128 v[164:167], v210 offset:59392
	s_add_u32 m0, s41, 24576
	s_nop 0
	global_load_lds_dwordx4 v214, s[100:101]
	s_waitcnt lgkmcnt(8)
	v_mfma_f32_16x16x32_bf16 v[12:15], v[72:75], v[188:191], v[12:15]
	v_mfma_f32_16x16x32_bf16 v[4:7], v[216:219], v[188:191], v[4:7]
	ds_read_b128 v[168:171], v210 offset:61440
	s_add_u32 m0, s41, 28672
	s_nop 0
	global_load_lds_dwordx4 v215, s[100:101]
	s_add_u32 s100, s100, 128
	s_addc_u32 s101, s101, 0
	s_waitcnt lgkmcnt(6)
	v_mfma_f32_16x16x32_bf16 v[44:47], v[64:67], v[192:195], v[44:47]
	v_mfma_f32_16x16x32_bf16 v[48:51], v[68:71], v[192:195], v[48:51]
	ds_read_b128 v[172:175], v210 offset:63488
	s_waitcnt lgkmcnt(6)
	v_mfma_f32_16x16x32_bf16 v[28:31], v[64:67], v[196:199], v[28:31]
	v_mfma_f32_16x16x32_bf16 v[16:19], v[68:71], v[196:199], v[16:19]
	ds_read_b128 v[72:75], v209 offset:32768
	ds_read_b128 v[216:219], v209 offset:34816
	ds_read_b128 v[176:179], v211 offset:49152
	s_waitcnt lgkmcnt(8)
	v_mfma_f32_16x16x32_bf16 v[60:63], v[64:67], v[200:203], v[60:63]
	v_mfma_f32_16x16x32_bf16 v[40:43], v[68:71], v[200:203], v[40:43]
	ds_read_b128 v[180:183], v211 offset:51200
	s_waitcnt lgkmcnt(8)
	v_mfma_f32_16x16x32_bf16 v[20:23], v[64:67], v[204:207], v[20:23]
	v_mfma_f32_16x16x32_bf16 v[0:3], v[68:71], v[204:207], v[0:3]
	ds_read_b128 v[184:187], v211 offset:53248
	s_waitcnt lgkmcnt(8)
	v_mfma_f32_16x16x32_bf16 v[52:55], v[64:67], v[160:163], v[52:55]
	v_mfma_f32_16x16x32_bf16 v[36:39], v[68:71], v[160:163], v[36:39]
	ds_read_b128 v[188:191], v211 offset:55296
	s_waitcnt lgkmcnt(8)
	v_mfma_f32_16x16x32_bf16 v[24:27], v[64:67], v[164:167], v[24:27]
	v_mfma_f32_16x16x32_bf16 v[8:11], v[68:71], v[164:167], v[8:11]
	ds_read_b128 v[192:195], v211 offset:57344
	s_waitcnt lgkmcnt(8)
	v_mfma_f32_16x16x32_bf16 v[56:59], v[64:67], v[168:171], v[56:59]
	v_mfma_f32_16x16x32_bf16 v[32:35], v[68:71], v[168:171], v[32:35]
	ds_read_b128 v[196:199], v211 offset:59392
	s_waitcnt lgkmcnt(8)
	v_mfma_f32_16x16x32_bf16 v[12:15], v[64:67], v[172:175], v[12:15]
	v_mfma_f32_16x16x32_bf16 v[4:7], v[68:71], v[172:175], v[4:7]
	ds_read_b128 v[200:203], v211 offset:61440
	s_waitcnt lgkmcnt(6)
	v_mfma_f32_16x16x32_bf16 v[44:47], v[72:75], v[176:179], v[44:47]
	v_mfma_f32_16x16x32_bf16 v[48:51], v[216:219], v[176:179], v[48:51]
	ds_read_b128 v[204:207], v211 offset:63488
	s_waitcnt vmcnt(0) lgkmcnt(0)
	s_barrier
	s_add_u32 m0, s41, 32768
	s_nop 0
	global_load_lds_dwordx4 v212, s[98:99]
	s_waitcnt lgkmcnt(6)
	v_mfma_f32_16x16x32_bf16 v[28:31], v[72:75], v[180:183], v[28:31]
	v_mfma_f32_16x16x32_bf16 v[16:19], v[216:219], v[180:183], v[16:19]
	ds_read_b128 v[64:67], v208 offset:0
	ds_read_b128 v[68:71], v208 offset:2048
	ds_read_b128 v[160:163], v210 offset:16384
	s_add_u32 m0, s41, 36864
	s_nop 0
	global_load_lds_dwordx4 v213, s[98:99]
	s_waitcnt lgkmcnt(8)
	v_mfma_f32_16x16x32_bf16 v[60:63], v[72:75], v[184:187], v[60:63]
	v_mfma_f32_16x16x32_bf16 v[40:43], v[216:219], v[184:187], v[40:43]
	ds_read_b128 v[164:167], v210 offset:18432
	s_add_u32 m0, s41, 40960
	s_nop 0
	global_load_lds_dwordx4 v214, s[98:99]
	s_waitcnt lgkmcnt(8)
	v_mfma_f32_16x16x32_bf16 v[20:23], v[72:75], v[188:191], v[20:23]
	v_mfma_f32_16x16x32_bf16 v[0:3], v[216:219], v[188:191], v[0:3]
	ds_read_b128 v[168:171], v210 offset:20480
	s_add_u32 m0, s41, 45056
	s_nop 0
	global_load_lds_dwordx4 v215, s[98:99]
	s_add_u32 s98, s98, 128
	s_addc_u32 s99, s99, 0
	s_waitcnt lgkmcnt(8)
	v_mfma_f32_16x16x32_bf16 v[52:55], v[72:75], v[192:195], v[52:55]
	v_mfma_f32_16x16x32_bf16 v[36:39], v[216:219], v[192:195], v[36:39]
	ds_read_b128 v[172:175], v210 offset:22528
	s_add_u32 m0, s41, 49152
	s_nop 0
	global_load_lds_dwordx4 v212, s[100:101]
	s_waitcnt lgkmcnt(8)
	v_mfma_f32_16x16x32_bf16 v[24:27], v[72:75], v[196:199], v[24:27]
	v_mfma_f32_16x16x32_bf16 v[8:11], v[216:219], v[196:199], v[8:11]
	ds_read_b128 v[176:179], v210 offset:24576
	s_add_u32 m0, s41, 53248
	s_nop 0
	global_load_lds_dwordx4 v213, s[100:101]
	s_waitcnt lgkmcnt(8)
	v_mfma_f32_16x16x32_bf16 v[56:59], v[72:75], v[200:203], v[56:59]
	v_mfma_f32_16x16x32_bf16 v[32:35], v[216:219], v[200:203], v[32:35]
	ds_read_b128 v[180:183], v210 offset:26624
	s_add_u32 m0, s41, 57344
	s_nop 0
	global_load_lds_dwordx4 v214, s[100:101]
	s_waitcnt lgkmcnt(8)
	v_mfma_f32_16x16x32_bf16 v[12:15], v[72:75], v[204:207], v[12:15]
	v_mfma_f32_16x16x32_bf16 v[4:7], v[216:219], v[204:207], v[4:7]
	ds_read_b128 v[184:187], v210 offset:28672
	s_add_u32 m0, s41, 61440
	s_nop 0
	global_load_lds_dwordx4 v215, s[100:101]
	s_add_u32 s100, s100, 128
	s_addc_u32 s101, s101, 0
	s_waitcnt lgkmcnt(6)
	v_mfma_f32_16x16x32_bf16 v[44:47], v[64:67], v[160:163], v[44:47]
	v_mfma_f32_16x16x32_bf16 v[48:51], v[68:71], v[160:163], v[48:51]
	ds_read_b128 v[188:191], v210 offset:30720
	s_waitcnt lgkmcnt(6)
	v_mfma_f32_16x16x32_bf16 v[28:31], v[64:67], v[164:167], v[28:31]
	v_mfma_f32_16x16x32_bf16 v[16:19], v[68:71], v[164:167], v[16:19]
	ds_read_b128 v[72:75], v209 offset:0
	ds_read_b128 v[216:219], v209 offset:2048
	ds_read_b128 v[192:195], v211 offset:16384
	s_waitcnt lgkmcnt(8)
	v_mfma_f32_16x16x32_bf16 v[60:63], v[64:67], v[168:171], v[60:63]
	v_mfma_f32_16x16x32_bf16 v[40:43], v[68:71], v[168:171], v[40:43]
	ds_read_b128 v[196:199], v211 offset:18432
	s_waitcnt lgkmcnt(8)
	v_mfma_f32_16x16x32_bf16 v[20:23], v[64:67], v[172:175], v[20:23]
	v_mfma_f32_16x16x32_bf16 v[0:3], v[68:71], v[172:175], v[0:3]
	ds_read_b128 v[200:203], v211 offset:20480
	s_waitcnt lgkmcnt(8)
	v_mfma_f32_16x16x32_bf16 v[52:55], v[64:67], v[176:179], v[52:55]
	v_mfma_f32_16x16x32_bf16 v[36:39], v[68:71], v[176:179], v[36:39]
	ds_read_b128 v[204:207], v211 offset:22528
	s_waitcnt lgkmcnt(8)
	v_mfma_f32_16x16x32_bf16 v[24:27], v[64:67], v[180:183], v[24:27]
	v_mfma_f32_16x16x32_bf16 v[8:11], v[68:71], v[180:183], v[8:11]
	ds_read_b128 v[160:163], v211 offset:24576
	s_waitcnt lgkmcnt(8)
	v_mfma_f32_16x16x32_bf16 v[56:59], v[64:67], v[184:187], v[56:59]
	v_mfma_f32_16x16x32_bf16 v[32:35], v[68:71], v[184:187], v[32:35]
	ds_read_b128 v[164:167], v211 offset:26624
	s_waitcnt lgkmcnt(8)
	v_mfma_f32_16x16x32_bf16 v[12:15], v[64:67], v[188:191], v[12:15]
	v_mfma_f32_16x16x32_bf16 v[4:7], v[68:71], v[188:191], v[4:7]
	ds_read_b128 v[168:171], v211 offset:28672
	s_waitcnt lgkmcnt(6)
	v_mfma_f32_16x16x32_bf16 v[44:47], v[72:75], v[192:195], v[44:47]
	v_mfma_f32_16x16x32_bf16 v[48:51], v[216:219], v[192:195], v[48:51]
	ds_read_b128 v[172:175], v211 offset:30720
	s_waitcnt vmcnt(0) lgkmcnt(0)
	s_barrier
	s_add_u32 m0, s41, 0
	s_nop 0
	global_load_lds_dwordx4 v212, s[98:99]
	s_waitcnt lgkmcnt(6)
	v_mfma_f32_16x16x32_bf16 v[28:31], v[72:75], v[196:199], v[28:31]
	v_mfma_f32_16x16x32_bf16 v[16:19], v[216:219], v[196:199], v[16:19]
	ds_read_b128 v[64:67], v208 offset:32768
	ds_read_b128 v[68:71], v208 offset:34816
	ds_read_b128 v[176:179], v210 offset:49152
	s_add_u32 m0, s41, 4096
	s_nop 0
	global_load_lds_dwordx4 v213, s[98:99]
	s_waitcnt lgkmcnt(8)
	v_mfma_f32_16x16x32_bf16 v[60:63], v[72:75], v[200:203], v[60:63]
	v_mfma_f32_16x16x32_bf16 v[40:43], v[216:219], v[200:203], v[40:43]
	ds_read_b128 v[180:183], v210 offset:51200
	s_add_u32 m0, s41, 8192
	s_nop 0
	global_load_lds_dwordx4 v214, s[98:99]
	s_waitcnt lgkmcnt(8)
	v_mfma_f32_16x16x32_bf16 v[20:23], v[72:75], v[204:207], v[20:23]
	v_mfma_f32_16x16x32_bf16 v[0:3], v[216:219], v[204:207], v[0:3]
	ds_read_b128 v[184:187], v210 offset:53248
	s_add_u32 m0, s41, 12288
	s_nop 0
	global_load_lds_dwordx4 v215, s[98:99]
	s_add_u32 s98, s98, 128
	s_addc_u32 s99, s99, 0
	s_waitcnt lgkmcnt(8)
	v_mfma_f32_16x16x32_bf16 v[52:55], v[72:75], v[160:163], v[52:55]
	v_mfma_f32_16x16x32_bf16 v[36:39], v[216:219], v[160:163], v[36:39]
	ds_read_b128 v[188:191], v210 offset:55296
	s_add_u32 m0, s41, 16384
	s_nop 0
	global_load_lds_dwordx4 v212, s[100:101]
	s_waitcnt lgkmcnt(8)
	v_mfma_f32_16x16x32_bf16 v[24:27], v[72:75], v[164:167], v[24:27]
	v_mfma_f32_16x16x32_bf16 v[8:11], v[216:219], v[164:167], v[8:11]
	ds_read_b128 v[192:195], v210 offset:57344
	s_add_u32 m0, s41, 20480
	s_nop 0
	global_load_lds_dwordx4 v213, s[100:101]
	s_waitcnt lgkmcnt(8)
	v_mfma_f32_16x16x32_bf16 v[56:59], v[72:75], v[168:171], v[56:59]
	v_mfma_f32_16x16x32_bf16 v[32:35], v[216:219], v[168:171], v[32:35]
	ds_read_b128 v[196:199], v210 offset:59392
	s_add_u32 m0, s41, 24576
	s_nop 0
	global_load_lds_dwordx4 v214, s[100:101]
	s_waitcnt lgkmcnt(8)
	v_mfma_f32_16x16x32_bf16 v[12:15], v[72:75], v[172:175], v[12:15]
	v_mfma_f32_16x16x32_bf16 v[4:7], v[216:219], v[172:175], v[4:7]
	ds_read_b128 v[200:203], v210 offset:61440
	s_add_u32 m0, s41, 28672
	s_nop 0
	global_load_lds_dwordx4 v215, s[100:101]
	s_add_u32 s100, s100, 128
	s_addc_u32 s101, s101, 0
	s_waitcnt lgkmcnt(6)
	v_mfma_f32_16x16x32_bf16 v[44:47], v[64:67], v[176:179], v[44:47]
	v_mfma_f32_16x16x32_bf16 v[48:51], v[68:71], v[176:179], v[48:51]
	ds_read_b128 v[204:207], v210 offset:63488
	s_waitcnt lgkmcnt(6)
	v_mfma_f32_16x16x32_bf16 v[28:31], v[64:67], v[180:183], v[28:31]
	v_mfma_f32_16x16x32_bf16 v[16:19], v[68:71], v[180:183], v[16:19]
	ds_read_b128 v[72:75], v209 offset:32768
	ds_read_b128 v[216:219], v209 offset:34816
	ds_read_b128 v[160:163], v211 offset:49152
	s_waitcnt lgkmcnt(8)
	v_mfma_f32_16x16x32_bf16 v[60:63], v[64:67], v[184:187], v[60:63]
	v_mfma_f32_16x16x32_bf16 v[40:43], v[68:71], v[184:187], v[40:43]
	ds_read_b128 v[164:167], v211 offset:51200
	s_waitcnt lgkmcnt(8)
	v_mfma_f32_16x16x32_bf16 v[20:23], v[64:67], v[188:191], v[20:23]
	v_mfma_f32_16x16x32_bf16 v[0:3], v[68:71], v[188:191], v[0:3]
	ds_read_b128 v[168:171], v211 offset:53248
	s_waitcnt lgkmcnt(8)
	v_mfma_f32_16x16x32_bf16 v[52:55], v[64:67], v[192:195], v[52:55]
	v_mfma_f32_16x16x32_bf16 v[36:39], v[68:71], v[192:195], v[36:39]
	ds_read_b128 v[172:175], v211 offset:55296
	s_waitcnt lgkmcnt(8)
	v_mfma_f32_16x16x32_bf16 v[24:27], v[64:67], v[196:199], v[24:27]
	v_mfma_f32_16x16x32_bf16 v[8:11], v[68:71], v[196:199], v[8:11]
	ds_read_b128 v[176:179], v211 offset:57344
	s_waitcnt lgkmcnt(8)
	v_mfma_f32_16x16x32_bf16 v[56:59], v[64:67], v[200:203], v[56:59]
	v_mfma_f32_16x16x32_bf16 v[32:35], v[68:71], v[200:203], v[32:35]
	ds_read_b128 v[180:183], v211 offset:59392
	s_waitcnt lgkmcnt(8)
	v_mfma_f32_16x16x32_bf16 v[12:15], v[64:67], v[204:207], v[12:15]
	v_mfma_f32_16x16x32_bf16 v[4:7], v[68:71], v[204:207], v[4:7]
	ds_read_b128 v[184:187], v211 offset:61440
	s_waitcnt lgkmcnt(6)
	v_mfma_f32_16x16x32_bf16 v[44:47], v[72:75], v[160:163], v[44:47]
	v_mfma_f32_16x16x32_bf16 v[48:51], v[216:219], v[160:163], v[48:51]
	ds_read_b128 v[188:191], v211 offset:63488
	s_waitcnt vmcnt(0) lgkmcnt(0)
	s_barrier
	s_add_u32 m0, s41, 32768
	s_nop 0
	global_load_lds_dwordx4 v212, s[98:99]
	s_waitcnt lgkmcnt(6)
	v_mfma_f32_16x16x32_bf16 v[28:31], v[72:75], v[164:167], v[28:31]
	v_mfma_f32_16x16x32_bf16 v[16:19], v[216:219], v[164:167], v[16:19]
	ds_read_b128 v[64:67], v208 offset:0
	ds_read_b128 v[68:71], v208 offset:2048
	ds_read_b128 v[192:195], v210 offset:16384
	s_add_u32 m0, s41, 36864
	s_nop 0
	global_load_lds_dwordx4 v213, s[98:99]
	s_waitcnt lgkmcnt(8)
	v_mfma_f32_16x16x32_bf16 v[60:63], v[72:75], v[168:171], v[60:63]
	v_mfma_f32_16x16x32_bf16 v[40:43], v[216:219], v[168:171], v[40:43]
	ds_read_b128 v[196:199], v210 offset:18432
	s_add_u32 m0, s41, 40960
	s_nop 0
	global_load_lds_dwordx4 v214, s[98:99]
	s_waitcnt lgkmcnt(8)
	v_mfma_f32_16x16x32_bf16 v[20:23], v[72:75], v[172:175], v[20:23]
	v_mfma_f32_16x16x32_bf16 v[0:3], v[216:219], v[172:175], v[0:3]
	ds_read_b128 v[200:203], v210 offset:20480
	s_add_u32 m0, s41, 45056
	s_nop 0
	global_load_lds_dwordx4 v215, s[98:99]
	s_add_u32 s98, s98, 128
	s_addc_u32 s99, s99, 0
	s_waitcnt lgkmcnt(8)
	v_mfma_f32_16x16x32_bf16 v[52:55], v[72:75], v[176:179], v[52:55]
	v_mfma_f32_16x16x32_bf16 v[36:39], v[216:219], v[176:179], v[36:39]
	ds_read_b128 v[204:207], v210 offset:22528
	s_add_u32 m0, s41, 49152
	s_nop 0
	global_load_lds_dwordx4 v212, s[100:101]
	s_waitcnt lgkmcnt(8)
	v_mfma_f32_16x16x32_bf16 v[24:27], v[72:75], v[180:183], v[24:27]
	v_mfma_f32_16x16x32_bf16 v[8:11], v[216:219], v[180:183], v[8:11]
	ds_read_b128 v[160:163], v210 offset:24576
	s_add_u32 m0, s41, 53248
	s_nop 0
	global_load_lds_dwordx4 v213, s[100:101]
	s_waitcnt lgkmcnt(8)
	v_mfma_f32_16x16x32_bf16 v[56:59], v[72:75], v[184:187], v[56:59]
	v_mfma_f32_16x16x32_bf16 v[32:35], v[216:219], v[184:187], v[32:35]
	ds_read_b128 v[164:167], v210 offset:26624
	s_add_u32 m0, s41, 57344
	s_nop 0
	global_load_lds_dwordx4 v214, s[100:101]
	s_waitcnt lgkmcnt(8)
	v_mfma_f32_16x16x32_bf16 v[12:15], v[72:75], v[188:191], v[12:15]
	v_mfma_f32_16x16x32_bf16 v[4:7], v[216:219], v[188:191], v[4:7]
	ds_read_b128 v[168:171], v210 offset:28672
	s_add_u32 m0, s41, 61440
	s_nop 0
	global_load_lds_dwordx4 v215, s[100:101]
	s_add_u32 s100, s100, 128
	s_addc_u32 s101, s101, 0
	s_waitcnt lgkmcnt(6)
	v_mfma_f32_16x16x32_bf16 v[44:47], v[64:67], v[192:195], v[44:47]
	v_mfma_f32_16x16x32_bf16 v[48:51], v[68:71], v[192:195], v[48:51]
	ds_read_b128 v[172:175], v210 offset:30720
	s_waitcnt lgkmcnt(6)
	v_mfma_f32_16x16x32_bf16 v[28:31], v[64:67], v[196:199], v[28:31]
	v_mfma_f32_16x16x32_bf16 v[16:19], v[68:71], v[196:199], v[16:19]
	ds_read_b128 v[72:75], v209 offset:0
	ds_read_b128 v[216:219], v209 offset:2048
	ds_read_b128 v[176:179], v211 offset:16384
	s_waitcnt lgkmcnt(8)
	v_mfma_f32_16x16x32_bf16 v[60:63], v[64:67], v[200:203], v[60:63]
	v_mfma_f32_16x16x32_bf16 v[40:43], v[68:71], v[200:203], v[40:43]
	ds_read_b128 v[180:183], v211 offset:18432
	s_waitcnt lgkmcnt(8)
	v_mfma_f32_16x16x32_bf16 v[20:23], v[64:67], v[204:207], v[20:23]
	v_mfma_f32_16x16x32_bf16 v[0:3], v[68:71], v[204:207], v[0:3]
	ds_read_b128 v[184:187], v211 offset:20480
	s_waitcnt lgkmcnt(8)
	v_mfma_f32_16x16x32_bf16 v[52:55], v[64:67], v[160:163], v[52:55]
	v_mfma_f32_16x16x32_bf16 v[36:39], v[68:71], v[160:163], v[36:39]
	ds_read_b128 v[188:191], v211 offset:22528
	s_waitcnt lgkmcnt(8)
	v_mfma_f32_16x16x32_bf16 v[24:27], v[64:67], v[164:167], v[24:27]
	v_mfma_f32_16x16x32_bf16 v[8:11], v[68:71], v[164:167], v[8:11]
	ds_read_b128 v[192:195], v211 offset:24576
	s_waitcnt lgkmcnt(8)
	v_mfma_f32_16x16x32_bf16 v[56:59], v[64:67], v[168:171], v[56:59]
	v_mfma_f32_16x16x32_bf16 v[32:35], v[68:71], v[168:171], v[32:35]
	ds_read_b128 v[196:199], v211 offset:26624
	s_waitcnt lgkmcnt(8)
	v_mfma_f32_16x16x32_bf16 v[12:15], v[64:67], v[172:175], v[12:15]
	v_mfma_f32_16x16x32_bf16 v[4:7], v[68:71], v[172:175], v[4:7]
	ds_read_b128 v[200:203], v211 offset:28672
	s_waitcnt lgkmcnt(6)
	v_mfma_f32_16x16x32_bf16 v[44:47], v[72:75], v[176:179], v[44:47]
	v_mfma_f32_16x16x32_bf16 v[48:51], v[216:219], v[176:179], v[48:51]
	ds_read_b128 v[204:207], v211 offset:30720
	s_waitcnt vmcnt(0) lgkmcnt(0)
	s_barrier
	s_add_u32 m0, s41, 0
	s_nop 0
	global_load_lds_dwordx4 v212, s[98:99]
	s_waitcnt lgkmcnt(6)
	v_mfma_f32_16x16x32_bf16 v[28:31], v[72:75], v[180:183], v[28:31]
	v_mfma_f32_16x16x32_bf16 v[16:19], v[216:219], v[180:183], v[16:19]
	ds_read_b128 v[64:67], v208 offset:32768
	ds_read_b128 v[68:71], v208 offset:34816
	ds_read_b128 v[160:163], v210 offset:49152
	s_add_u32 m0, s41, 4096
	s_nop 0
	global_load_lds_dwordx4 v213, s[98:99]
	s_waitcnt lgkmcnt(8)
	v_mfma_f32_16x16x32_bf16 v[60:63], v[72:75], v[184:187], v[60:63]
	v_mfma_f32_16x16x32_bf16 v[40:43], v[216:219], v[184:187], v[40:43]
	ds_read_b128 v[164:167], v210 offset:51200
	s_add_u32 m0, s41, 8192
	s_nop 0
	global_load_lds_dwordx4 v214, s[98:99]
	s_waitcnt lgkmcnt(8)
	v_mfma_f32_16x16x32_bf16 v[20:23], v[72:75], v[188:191], v[20:23]
	v_mfma_f32_16x16x32_bf16 v[0:3], v[216:219], v[188:191], v[0:3]
	ds_read_b128 v[168:171], v210 offset:53248
	s_add_u32 m0, s41, 12288
	s_nop 0
	global_load_lds_dwordx4 v215, s[98:99]
	s_add_u32 s98, s98, 128
	s_addc_u32 s99, s99, 0
	s_waitcnt lgkmcnt(8)
	v_mfma_f32_16x16x32_bf16 v[52:55], v[72:75], v[192:195], v[52:55]
	v_mfma_f32_16x16x32_bf16 v[36:39], v[216:219], v[192:195], v[36:39]
	ds_read_b128 v[172:175], v210 offset:55296
	s_add_u32 m0, s41, 16384
	s_nop 0
	global_load_lds_dwordx4 v212, s[100:101]
	s_waitcnt lgkmcnt(8)
	v_mfma_f32_16x16x32_bf16 v[24:27], v[72:75], v[196:199], v[24:27]
	v_mfma_f32_16x16x32_bf16 v[8:11], v[216:219], v[196:199], v[8:11]
	ds_read_b128 v[176:179], v210 offset:57344
	s_add_u32 m0, s41, 20480
	s_nop 0
	global_load_lds_dwordx4 v213, s[100:101]
	s_waitcnt lgkmcnt(8)
	v_mfma_f32_16x16x32_bf16 v[56:59], v[72:75], v[200:203], v[56:59]
	v_mfma_f32_16x16x32_bf16 v[32:35], v[216:219], v[200:203], v[32:35]
	ds_read_b128 v[180:183], v210 offset:59392
	s_add_u32 m0, s41, 24576
	s_nop 0
	global_load_lds_dwordx4 v214, s[100:101]
	s_waitcnt lgkmcnt(8)
	v_mfma_f32_16x16x32_bf16 v[12:15], v[72:75], v[204:207], v[12:15]
	v_mfma_f32_16x16x32_bf16 v[4:7], v[216:219], v[204:207], v[4:7]
	ds_read_b128 v[184:187], v210 offset:61440
	s_add_u32 m0, s41, 28672
	s_nop 0
	global_load_lds_dwordx4 v215, s[100:101]
	s_add_u32 s100, s100, 128
	s_addc_u32 s101, s101, 0
	s_waitcnt lgkmcnt(6)
	v_mfma_f32_16x16x32_bf16 v[44:47], v[64:67], v[160:163], v[44:47]
	v_mfma_f32_16x16x32_bf16 v[48:51], v[68:71], v[160:163], v[48:51]
	ds_read_b128 v[188:191], v210 offset:63488
	s_waitcnt lgkmcnt(6)
	v_mfma_f32_16x16x32_bf16 v[28:31], v[64:67], v[164:167], v[28:31]
	v_mfma_f32_16x16x32_bf16 v[16:19], v[68:71], v[164:167], v[16:19]
	ds_read_b128 v[72:75], v209 offset:32768
	ds_read_b128 v[216:219], v209 offset:34816
	ds_read_b128 v[192:195], v211 offset:49152
	s_waitcnt lgkmcnt(8)
	v_mfma_f32_16x16x32_bf16 v[60:63], v[64:67], v[168:171], v[60:63]
	v_mfma_f32_16x16x32_bf16 v[40:43], v[68:71], v[168:171], v[40:43]
	ds_read_b128 v[196:199], v211 offset:51200
	s_waitcnt lgkmcnt(8)
	v_mfma_f32_16x16x32_bf16 v[20:23], v[64:67], v[172:175], v[20:23]
	v_mfma_f32_16x16x32_bf16 v[0:3], v[68:71], v[172:175], v[0:3]
	ds_read_b128 v[200:203], v211 offset:53248
	s_waitcnt lgkmcnt(8)
	v_mfma_f32_16x16x32_bf16 v[52:55], v[64:67], v[176:179], v[52:55]
	v_mfma_f32_16x16x32_bf16 v[36:39], v[68:71], v[176:179], v[36:39]
	ds_read_b128 v[204:207], v211 offset:55296
	s_waitcnt lgkmcnt(8)
	v_mfma_f32_16x16x32_bf16 v[24:27], v[64:67], v[180:183], v[24:27]
	v_mfma_f32_16x16x32_bf16 v[8:11], v[68:71], v[180:183], v[8:11]
	ds_read_b128 v[160:163], v211 offset:57344
	s_waitcnt lgkmcnt(8)
	v_mfma_f32_16x16x32_bf16 v[56:59], v[64:67], v[184:187], v[56:59]
	v_mfma_f32_16x16x32_bf16 v[32:35], v[68:71], v[184:187], v[32:35]
	ds_read_b128 v[164:167], v211 offset:59392
	s_waitcnt lgkmcnt(8)
	v_mfma_f32_16x16x32_bf16 v[12:15], v[64:67], v[188:191], v[12:15]
	v_mfma_f32_16x16x32_bf16 v[4:7], v[68:71], v[188:191], v[4:7]
	ds_read_b128 v[168:171], v211 offset:61440
	s_waitcnt lgkmcnt(6)
	v_mfma_f32_16x16x32_bf16 v[44:47], v[72:75], v[192:195], v[44:47]
	v_mfma_f32_16x16x32_bf16 v[48:51], v[216:219], v[192:195], v[48:51]
	ds_read_b128 v[172:175], v211 offset:63488
	s_waitcnt vmcnt(0) lgkmcnt(0)
	s_barrier
	s_add_u32 m0, s41, 32768
	s_nop 0
	global_load_lds_dwordx4 v212, s[98:99]
	s_waitcnt lgkmcnt(6)
	v_mfma_f32_16x16x32_bf16 v[28:31], v[72:75], v[196:199], v[28:31]
	v_mfma_f32_16x16x32_bf16 v[16:19], v[216:219], v[196:199], v[16:19]
	ds_read_b128 v[64:67], v208 offset:0
	ds_read_b128 v[68:71], v208 offset:2048
	ds_read_b128 v[176:179], v210 offset:16384
	s_add_u32 m0, s41, 36864
	s_nop 0
	global_load_lds_dwordx4 v213, s[98:99]
	s_waitcnt lgkmcnt(8)
	v_mfma_f32_16x16x32_bf16 v[60:63], v[72:75], v[200:203], v[60:63]
	v_mfma_f32_16x16x32_bf16 v[40:43], v[216:219], v[200:203], v[40:43]
	ds_read_b128 v[180:183], v210 offset:18432
	s_add_u32 m0, s41, 40960
	s_nop 0
	global_load_lds_dwordx4 v214, s[98:99]
	s_waitcnt lgkmcnt(8)
	v_mfma_f32_16x16x32_bf16 v[20:23], v[72:75], v[204:207], v[20:23]
	v_mfma_f32_16x16x32_bf16 v[0:3], v[216:219], v[204:207], v[0:3]
	ds_read_b128 v[184:187], v210 offset:20480
	s_add_u32 m0, s41, 45056
	s_nop 0
	global_load_lds_dwordx4 v215, s[98:99]
	s_add_u32 s98, s98, 128
	s_addc_u32 s99, s99, 0
	s_waitcnt lgkmcnt(8)
	v_mfma_f32_16x16x32_bf16 v[52:55], v[72:75], v[160:163], v[52:55]
	v_mfma_f32_16x16x32_bf16 v[36:39], v[216:219], v[160:163], v[36:39]
	ds_read_b128 v[188:191], v210 offset:22528
	s_add_u32 m0, s41, 49152
	s_nop 0
	global_load_lds_dwordx4 v212, s[100:101]
	s_waitcnt lgkmcnt(8)
	v_mfma_f32_16x16x32_bf16 v[24:27], v[72:75], v[164:167], v[24:27]
	v_mfma_f32_16x16x32_bf16 v[8:11], v[216:219], v[164:167], v[8:11]
	ds_read_b128 v[192:195], v210 offset:24576
	s_add_u32 m0, s41, 53248
	s_nop 0
	global_load_lds_dwordx4 v213, s[100:101]
	s_waitcnt lgkmcnt(8)
	v_mfma_f32_16x16x32_bf16 v[56:59], v[72:75], v[168:171], v[56:59]
	v_mfma_f32_16x16x32_bf16 v[32:35], v[216:219], v[168:171], v[32:35]
	ds_read_b128 v[196:199], v210 offset:26624
	s_add_u32 m0, s41, 57344
	s_nop 0
	global_load_lds_dwordx4 v214, s[100:101]
	s_waitcnt lgkmcnt(8)
	v_mfma_f32_16x16x32_bf16 v[12:15], v[72:75], v[172:175], v[12:15]
	v_mfma_f32_16x16x32_bf16 v[4:7], v[216:219], v[172:175], v[4:7]
	ds_read_b128 v[200:203], v210 offset:28672
	s_add_u32 m0, s41, 61440
	s_nop 0
	global_load_lds_dwordx4 v215, s[100:101]
	s_add_u32 s100, s100, 128
	s_addc_u32 s101, s101, 0
	s_waitcnt lgkmcnt(6)
	v_mfma_f32_16x16x32_bf16 v[44:47], v[64:67], v[176:179], v[44:47]
	v_mfma_f32_16x16x32_bf16 v[48:51], v[68:71], v[176:179], v[48:51]
	ds_read_b128 v[204:207], v210 offset:30720
	s_waitcnt lgkmcnt(6)
	v_mfma_f32_16x16x32_bf16 v[28:31], v[64:67], v[180:183], v[28:31]
	v_mfma_f32_16x16x32_bf16 v[16:19], v[68:71], v[180:183], v[16:19]
	ds_read_b128 v[72:75], v209 offset:0
	ds_read_b128 v[216:219], v209 offset:2048
	ds_read_b128 v[160:163], v211 offset:16384
	s_waitcnt lgkmcnt(8)
	v_mfma_f32_16x16x32_bf16 v[60:63], v[64:67], v[184:187], v[60:63]
	v_mfma_f32_16x16x32_bf16 v[40:43], v[68:71], v[184:187], v[40:43]
	ds_read_b128 v[164:167], v211 offset:18432
	s_waitcnt lgkmcnt(8)
	v_mfma_f32_16x16x32_bf16 v[20:23], v[64:67], v[188:191], v[20:23]
	v_mfma_f32_16x16x32_bf16 v[0:3], v[68:71], v[188:191], v[0:3]
	ds_read_b128 v[168:171], v211 offset:20480
	s_waitcnt lgkmcnt(8)
	v_mfma_f32_16x16x32_bf16 v[52:55], v[64:67], v[192:195], v[52:55]
	v_mfma_f32_16x16x32_bf16 v[36:39], v[68:71], v[192:195], v[36:39]
	ds_read_b128 v[172:175], v211 offset:22528
	s_waitcnt lgkmcnt(8)
	v_mfma_f32_16x16x32_bf16 v[24:27], v[64:67], v[196:199], v[24:27]
	v_mfma_f32_16x16x32_bf16 v[8:11], v[68:71], v[196:199], v[8:11]
	ds_read_b128 v[176:179], v211 offset:24576
	s_waitcnt lgkmcnt(8)
	v_mfma_f32_16x16x32_bf16 v[56:59], v[64:67], v[200:203], v[56:59]
	v_mfma_f32_16x16x32_bf16 v[32:35], v[68:71], v[200:203], v[32:35]
	ds_read_b128 v[180:183], v211 offset:26624
	s_waitcnt lgkmcnt(8)
	v_mfma_f32_16x16x32_bf16 v[12:15], v[64:67], v[204:207], v[12:15]
	v_mfma_f32_16x16x32_bf16 v[4:7], v[68:71], v[204:207], v[4:7]
	ds_read_b128 v[184:187], v211 offset:28672
	s_waitcnt lgkmcnt(6)
	v_mfma_f32_16x16x32_bf16 v[44:47], v[72:75], v[160:163], v[44:47]
	v_mfma_f32_16x16x32_bf16 v[48:51], v[216:219], v[160:163], v[48:51]
	ds_read_b128 v[188:191], v211 offset:30720
	s_waitcnt vmcnt(0) lgkmcnt(0)
	s_barrier
	s_add_u32 m0, s41, 0
	s_nop 0
	global_load_lds_dwordx4 v212, s[98:99]
	s_waitcnt lgkmcnt(6)
	v_mfma_f32_16x16x32_bf16 v[28:31], v[72:75], v[164:167], v[28:31]
	v_mfma_f32_16x16x32_bf16 v[16:19], v[216:219], v[164:167], v[16:19]
	ds_read_b128 v[64:67], v208 offset:32768
	ds_read_b128 v[68:71], v208 offset:34816
	ds_read_b128 v[192:195], v210 offset:49152
	s_add_u32 m0, s41, 4096
	s_nop 0
	global_load_lds_dwordx4 v213, s[98:99]
	s_waitcnt lgkmcnt(8)
	v_mfma_f32_16x16x32_bf16 v[60:63], v[72:75], v[168:171], v[60:63]
	v_mfma_f32_16x16x32_bf16 v[40:43], v[216:219], v[168:171], v[40:43]
	ds_read_b128 v[196:199], v210 offset:51200
	s_add_u32 m0, s41, 8192
	s_nop 0
	global_load_lds_dwordx4 v214, s[98:99]
	s_waitcnt lgkmcnt(8)
	v_mfma_f32_16x16x32_bf16 v[20:23], v[72:75], v[172:175], v[20:23]
	v_mfma_f32_16x16x32_bf16 v[0:3], v[216:219], v[172:175], v[0:3]
	ds_read_b128 v[200:203], v210 offset:53248
	s_add_u32 m0, s41, 12288
	s_nop 0
	global_load_lds_dwordx4 v215, s[98:99]
	s_add_u32 s98, s98, 128
	s_addc_u32 s99, s99, 0
	s_waitcnt lgkmcnt(8)
	v_mfma_f32_16x16x32_bf16 v[52:55], v[72:75], v[176:179], v[52:55]
	v_mfma_f32_16x16x32_bf16 v[36:39], v[216:219], v[176:179], v[36:39]
	ds_read_b128 v[204:207], v210 offset:55296
	s_add_u32 m0, s41, 16384
	s_nop 0
	global_load_lds_dwordx4 v212, s[100:101]
	s_waitcnt lgkmcnt(8)
	v_mfma_f32_16x16x32_bf16 v[24:27], v[72:75], v[180:183], v[24:27]
	v_mfma_f32_16x16x32_bf16 v[8:11], v[216:219], v[180:183], v[8:11]
	ds_read_b128 v[160:163], v210 offset:57344
	s_add_u32 m0, s41, 20480
	s_nop 0
	global_load_lds_dwordx4 v213, s[100:101]
	s_waitcnt lgkmcnt(8)
	v_mfma_f32_16x16x32_bf16 v[56:59], v[72:75], v[184:187], v[56:59]
	v_mfma_f32_16x16x32_bf16 v[32:35], v[216:219], v[184:187], v[32:35]
	ds_read_b128 v[164:167], v210 offset:59392
	s_add_u32 m0, s41, 24576
	s_nop 0
	global_load_lds_dwordx4 v214, s[100:101]
	s_waitcnt lgkmcnt(8)
	v_mfma_f32_16x16x32_bf16 v[12:15], v[72:75], v[188:191], v[12:15]
	v_mfma_f32_16x16x32_bf16 v[4:7], v[216:219], v[188:191], v[4:7]
	ds_read_b128 v[168:171], v210 offset:61440
	s_add_u32 m0, s41, 28672
	s_nop 0
	global_load_lds_dwordx4 v215, s[100:101]
	s_add_u32 s100, s100, 128
	s_addc_u32 s101, s101, 0
	s_waitcnt lgkmcnt(6)
	v_mfma_f32_16x16x32_bf16 v[44:47], v[64:67], v[192:195], v[44:47]
	v_mfma_f32_16x16x32_bf16 v[48:51], v[68:71], v[192:195], v[48:51]
	ds_read_b128 v[172:175], v210 offset:63488
	s_waitcnt lgkmcnt(6)
	v_mfma_f32_16x16x32_bf16 v[28:31], v[64:67], v[196:199], v[28:31]
	v_mfma_f32_16x16x32_bf16 v[16:19], v[68:71], v[196:199], v[16:19]
	ds_read_b128 v[72:75], v209 offset:32768
	ds_read_b128 v[216:219], v209 offset:34816
	ds_read_b128 v[176:179], v211 offset:49152
	s_waitcnt lgkmcnt(8)
	v_mfma_f32_16x16x32_bf16 v[60:63], v[64:67], v[200:203], v[60:63]
	v_mfma_f32_16x16x32_bf16 v[40:43], v[68:71], v[200:203], v[40:43]
	ds_read_b128 v[180:183], v211 offset:51200
	s_waitcnt lgkmcnt(8)
	v_mfma_f32_16x16x32_bf16 v[20:23], v[64:67], v[204:207], v[20:23]
	v_mfma_f32_16x16x32_bf16 v[0:3], v[68:71], v[204:207], v[0:3]
	ds_read_b128 v[184:187], v211 offset:53248
	s_waitcnt lgkmcnt(8)
	v_mfma_f32_16x16x32_bf16 v[52:55], v[64:67], v[160:163], v[52:55]
	v_mfma_f32_16x16x32_bf16 v[36:39], v[68:71], v[160:163], v[36:39]
	ds_read_b128 v[188:191], v211 offset:55296
	s_waitcnt lgkmcnt(8)
	v_mfma_f32_16x16x32_bf16 v[24:27], v[64:67], v[164:167], v[24:27]
	v_mfma_f32_16x16x32_bf16 v[8:11], v[68:71], v[164:167], v[8:11]
	ds_read_b128 v[192:195], v211 offset:57344
	s_waitcnt lgkmcnt(8)
	v_mfma_f32_16x16x32_bf16 v[56:59], v[64:67], v[168:171], v[56:59]
	v_mfma_f32_16x16x32_bf16 v[32:35], v[68:71], v[168:171], v[32:35]
	ds_read_b128 v[196:199], v211 offset:59392
	s_waitcnt lgkmcnt(8)
	v_mfma_f32_16x16x32_bf16 v[12:15], v[64:67], v[172:175], v[12:15]
	v_mfma_f32_16x16x32_bf16 v[4:7], v[68:71], v[172:175], v[4:7]
	ds_read_b128 v[200:203], v211 offset:61440
	s_waitcnt lgkmcnt(6)
	v_mfma_f32_16x16x32_bf16 v[44:47], v[72:75], v[176:179], v[44:47]
	v_mfma_f32_16x16x32_bf16 v[48:51], v[216:219], v[176:179], v[48:51]
	ds_read_b128 v[204:207], v211 offset:63488
	s_waitcnt vmcnt(0) lgkmcnt(0)
	s_barrier
	s_add_u32 m0, s41, 32768
	s_nop 0
	global_load_lds_dwordx4 v212, s[98:99]
	s_waitcnt lgkmcnt(6)
	v_mfma_f32_16x16x32_bf16 v[28:31], v[72:75], v[180:183], v[28:31]
	v_mfma_f32_16x16x32_bf16 v[16:19], v[216:219], v[180:183], v[16:19]
	ds_read_b128 v[64:67], v208 offset:0
	ds_read_b128 v[68:71], v208 offset:2048
	ds_read_b128 v[160:163], v210 offset:16384
	s_add_u32 m0, s41, 36864
	s_nop 0
	global_load_lds_dwordx4 v213, s[98:99]
	s_waitcnt lgkmcnt(8)
	v_mfma_f32_16x16x32_bf16 v[60:63], v[72:75], v[184:187], v[60:63]
	v_mfma_f32_16x16x32_bf16 v[40:43], v[216:219], v[184:187], v[40:43]
	ds_read_b128 v[164:167], v210 offset:18432
	s_add_u32 m0, s41, 40960
	s_nop 0
	global_load_lds_dwordx4 v214, s[98:99]
	s_waitcnt lgkmcnt(8)
	v_mfma_f32_16x16x32_bf16 v[20:23], v[72:75], v[188:191], v[20:23]
	v_mfma_f32_16x16x32_bf16 v[0:3], v[216:219], v[188:191], v[0:3]
	ds_read_b128 v[168:171], v210 offset:20480
	s_add_u32 m0, s41, 45056
	s_nop 0
	global_load_lds_dwordx4 v215, s[98:99]
	s_add_u32 s98, s98, 128
	s_addc_u32 s99, s99, 0
	s_waitcnt lgkmcnt(8)
	v_mfma_f32_16x16x32_bf16 v[52:55], v[72:75], v[192:195], v[52:55]
	v_mfma_f32_16x16x32_bf16 v[36:39], v[216:219], v[192:195], v[36:39]
	ds_read_b128 v[172:175], v210 offset:22528
	s_add_u32 m0, s41, 49152
	s_nop 0
	global_load_lds_dwordx4 v212, s[100:101]
	s_waitcnt lgkmcnt(8)
	v_mfma_f32_16x16x32_bf16 v[24:27], v[72:75], v[196:199], v[24:27]
	v_mfma_f32_16x16x32_bf16 v[8:11], v[216:219], v[196:199], v[8:11]
	ds_read_b128 v[176:179], v210 offset:24576
	s_add_u32 m0, s41, 53248
	s_nop 0
	global_load_lds_dwordx4 v213, s[100:101]
	s_waitcnt lgkmcnt(8)
	v_mfma_f32_16x16x32_bf16 v[56:59], v[72:75], v[200:203], v[56:59]
	v_mfma_f32_16x16x32_bf16 v[32:35], v[216:219], v[200:203], v[32:35]
	ds_read_b128 v[180:183], v210 offset:26624
	s_add_u32 m0, s41, 57344
	s_nop 0
	global_load_lds_dwordx4 v214, s[100:101]
	s_waitcnt lgkmcnt(8)
	v_mfma_f32_16x16x32_bf16 v[12:15], v[72:75], v[204:207], v[12:15]
	v_mfma_f32_16x16x32_bf16 v[4:7], v[216:219], v[204:207], v[4:7]
	ds_read_b128 v[184:187], v210 offset:28672
	s_add_u32 m0, s41, 61440
	s_nop 0
	global_load_lds_dwordx4 v215, s[100:101]
	s_add_u32 s100, s100, 128
	s_addc_u32 s101, s101, 0
	s_waitcnt lgkmcnt(6)
	v_mfma_f32_16x16x32_bf16 v[44:47], v[64:67], v[160:163], v[44:47]
	v_mfma_f32_16x16x32_bf16 v[48:51], v[68:71], v[160:163], v[48:51]
	ds_read_b128 v[188:191], v210 offset:30720
	s_waitcnt lgkmcnt(6)
	v_mfma_f32_16x16x32_bf16 v[28:31], v[64:67], v[164:167], v[28:31]
	v_mfma_f32_16x16x32_bf16 v[16:19], v[68:71], v[164:167], v[16:19]
	ds_read_b128 v[72:75], v209 offset:0
	ds_read_b128 v[216:219], v209 offset:2048
	ds_read_b128 v[192:195], v211 offset:16384
	s_waitcnt lgkmcnt(8)
	v_mfma_f32_16x16x32_bf16 v[60:63], v[64:67], v[168:171], v[60:63]
	v_mfma_f32_16x16x32_bf16 v[40:43], v[68:71], v[168:171], v[40:43]
	ds_read_b128 v[196:199], v211 offset:18432
	s_waitcnt lgkmcnt(8)
	v_mfma_f32_16x16x32_bf16 v[20:23], v[64:67], v[172:175], v[20:23]
	v_mfma_f32_16x16x32_bf16 v[0:3], v[68:71], v[172:175], v[0:3]
	ds_read_b128 v[200:203], v211 offset:20480
	s_waitcnt lgkmcnt(8)
	v_mfma_f32_16x16x32_bf16 v[52:55], v[64:67], v[176:179], v[52:55]
	v_mfma_f32_16x16x32_bf16 v[36:39], v[68:71], v[176:179], v[36:39]
	ds_read_b128 v[204:207], v211 offset:22528
	s_waitcnt lgkmcnt(8)
	v_mfma_f32_16x16x32_bf16 v[24:27], v[64:67], v[180:183], v[24:27]
	v_mfma_f32_16x16x32_bf16 v[8:11], v[68:71], v[180:183], v[8:11]
	ds_read_b128 v[160:163], v211 offset:24576
	s_waitcnt lgkmcnt(8)
	v_mfma_f32_16x16x32_bf16 v[56:59], v[64:67], v[184:187], v[56:59]
	v_mfma_f32_16x16x32_bf16 v[32:35], v[68:71], v[184:187], v[32:35]
	ds_read_b128 v[164:167], v211 offset:26624
	s_waitcnt lgkmcnt(8)
	v_mfma_f32_16x16x32_bf16 v[12:15], v[64:67], v[188:191], v[12:15]
	v_mfma_f32_16x16x32_bf16 v[4:7], v[68:71], v[188:191], v[4:7]
	ds_read_b128 v[168:171], v211 offset:28672
	s_waitcnt lgkmcnt(6)
	v_mfma_f32_16x16x32_bf16 v[44:47], v[72:75], v[192:195], v[44:47]
	v_mfma_f32_16x16x32_bf16 v[48:51], v[216:219], v[192:195], v[48:51]
	ds_read_b128 v[172:175], v211 offset:30720
	s_waitcnt lgkmcnt(6)
	v_mfma_f32_16x16x32_bf16 v[28:31], v[72:75], v[196:199], v[28:31]
	v_mfma_f32_16x16x32_bf16 v[16:19], v[216:219], v[196:199], v[16:19]
	s_waitcnt lgkmcnt(5)
	v_mfma_f32_16x16x32_bf16 v[60:63], v[72:75], v[200:203], v[60:63]
	v_mfma_f32_16x16x32_bf16 v[40:43], v[216:219], v[200:203], v[40:43]
	s_waitcnt lgkmcnt(4)
	v_mfma_f32_16x16x32_bf16 v[20:23], v[72:75], v[204:207], v[20:23]
	v_mfma_f32_16x16x32_bf16 v[0:3], v[216:219], v[204:207], v[0:3]
	s_waitcnt lgkmcnt(3)
	v_mfma_f32_16x16x32_bf16 v[52:55], v[72:75], v[160:163], v[52:55]
	v_mfma_f32_16x16x32_bf16 v[36:39], v[216:219], v[160:163], v[36:39]
	s_waitcnt lgkmcnt(2)
	v_mfma_f32_16x16x32_bf16 v[24:27], v[72:75], v[164:167], v[24:27]
	v_mfma_f32_16x16x32_bf16 v[8:11], v[216:219], v[164:167], v[8:11]
	s_waitcnt lgkmcnt(1)
	v_mfma_f32_16x16x32_bf16 v[56:59], v[72:75], v[168:171], v[56:59]
	v_mfma_f32_16x16x32_bf16 v[32:35], v[216:219], v[168:171], v[32:35]
	s_waitcnt lgkmcnt(0)
	v_mfma_f32_16x16x32_bf16 v[12:15], v[72:75], v[172:175], v[12:15]
	v_mfma_f32_16x16x32_bf16 v[4:7], v[216:219], v[172:175], v[4:7]
	s_mov_b32 s40, 0x8000
	v_add_u32_e32 v68, s40, v101
	v_add_u32_e32 v69, v68, v102
	s_waitcnt vmcnt(0)
	s_barrier
	ds_read_b128 v[64:67], v69
	v_add_u32_e32 v126, v68, v100
	ds_read_b128 v[72:75], v126 offset:16384
	ds_read_b128 v[118:121], v126 offset:20480
	ds_read_b128 v[122:125], v126 offset:24576
	s_ashr_i32 s39, s39, 5
	s_mul_hi_i32 s4, s39, 0x3000
	s_waitcnt lgkmcnt(0)
	v_mfma_f32_16x16x32_bf16 v[130:133], v[64:67], v[72:75], v[44:47]
	v_add_u32_e32 v128, 0x400, v105
	s_nop 1
	ds_read_b128 v[44:47], v69 offset:2048
	v_mfma_f32_16x16x32_bf16 v[134:137], v[64:67], v[118:121], v[60:63]
	ds_read_b128 v[68:71], v126 offset:18432
	v_mfma_f32_16x16x32_bf16 v[138:141], v[64:67], v[122:125], v[52:55]
	s_nop 2
	ds_read_b128 v[52:55], v126 offset:22528
	s_waitcnt lgkmcnt(0)
	v_mfma_f32_16x16x32_bf16 v[48:51], v[44:47], v[72:75], v[48:51]
	ds_read_b128 v[72:75], v126 offset:26624
	v_mfma_f32_16x16x32_bf16 v[118:121], v[44:47], v[118:121], v[40:43]
	ds_read_b128 v[142:145], v126 offset:28672
	s_waitcnt lgkmcnt(0)
	v_mfma_f32_16x16x32_bf16 v[56:59], v[64:67], v[142:145], v[56:59]
	ds_read_b128 v[40:43], v126 offset:30720
	v_mfma_f32_16x16x32_bf16 v[122:125], v[44:47], v[122:125], v[36:39]
	s_nop 2
	v_add_u32_e32 v36, s40, v103
	v_add_u32_e32 v37, v36, v102
	ds_read_b128 v[60:63], v37
	v_mfma_f32_16x16x32_bf16 v[142:145], v[44:47], v[142:145], v[32:35]
	v_add_u32_e32 v126, v36, v100
	s_mul_i32 s40, s39, 0x3000
	s_add_u32 s30, s33, s40
	ds_read_b128 v[32:35], v37 offset:2048
	v_mfma_f32_16x16x32_bf16 v[146:149], v[64:67], v[68:71], v[28:31]
	s_addc_u32 s31, s34, s4
	s_lshl_b32 s4, s38, 9
	s_add_u32 s30, s30, s4
	ds_read_b128 v[28:31], v126 offset:16384
	s_waitcnt lgkmcnt(0)
	v_mfma_f32_16x16x32_bf16 v[130:133], v[60:63], v[28:31], v[130:133]
	ds_read_b128 v[150:153], v126 offset:18432
	s_addc_u32 s31, s31, 0
	v_mfma_f32_16x16x32_bf16 v[28:31], v[32:35], v[28:31], v[48:51]
	ds_read_b128 v[36:39], v126 offset:20480
	s_waitcnt lgkmcnt(0)
	v_mfma_f32_16x16x32_bf16 v[134:137], v[60:63], v[36:39], v[134:137]
	ds_read_b128 v[154:157], v126 offset:22528
	v_mfma_f32_16x16x32_bf16 v[36:39], v[32:35], v[36:39], v[118:121]
	ds_read_b128 v[48:51], v126 offset:24576
	s_waitcnt lgkmcnt(0)
	v_mfma_f32_16x16x32_bf16 v[118:121], v[60:63], v[48:51], v[138:141]
	s_nop 2
	ds_read_b128 v[138:141], v126 offset:26624
	v_mfma_f32_16x16x32_bf16 v[48:51], v[32:35], v[48:51], v[122:125]
	s_nop 2
	ds_read_b128 v[122:125], v126 offset:28672
	s_waitcnt lgkmcnt(0)
	v_mfma_f32_16x16x32_bf16 v[158:161], v[60:63], v[122:125], v[56:59]
	ds_read_b128 v[162:165], v126 offset:30720
	s_barrier
	v_mfma_f32_16x16x32_bf16 v[56:59], v[32:35], v[122:125], v[142:145]
	v_mfma_f32_16x16x32_bf16 v[24:27], v[64:67], v[72:75], v[24:27]
	v_mfma_f32_16x16x32_bf16 v[16:19], v[44:47], v[68:71], v[16:19]
	v_mfma_f32_16x16x32_bf16 v[8:11], v[44:47], v[72:75], v[8:11]
	v_mfma_f32_16x16x32_bf16 v[68:71], v[60:63], v[150:153], v[146:149]
	v_mfma_f32_16x16x32_bf16 v[24:27], v[60:63], v[138:141], v[24:27]
	v_mfma_f32_16x16x32_bf16 v[16:19], v[32:35], v[150:153], v[16:19]
	v_mfma_f32_16x16x32_bf16 v[8:11], v[32:35], v[138:141], v[8:11]
	v_mfma_f32_16x16x32_bf16 v[20:23], v[64:67], v[52:55], v[20:23]
	v_mfma_f32_16x16x32_bf16 v[12:15], v[64:67], v[40:43], v[12:15]
	v_lshl_add_u64 v[64:65], s[30:31], 0, v[76:77]
	s_add_i32 s30, s39, 4
	s_add_i32 s31, s40, 0xc000
	s_mul_hi_i32 s30, s30, 0x3000
	s_add_u32 s31, s33, s31
	s_addc_u32 s38, s34, s30
	v_lshl_add_u64 v[66:67], v[64:65], 0, s[26:27]
	v_add_co_u32_e32 v64, vcc, s37, v64
	s_add_u32 s30, s31, s4
	s_nop 0
	v_addc_co_u32_e32 v65, vcc, 0, v65, vcc
	s_addc_u32 s31, s38, 0
	v_mfma_f32_16x16x32_bf16 v[20:23], v[60:63], v[154:157], v[20:23]
	s_waitcnt lgkmcnt(0)
	v_mfma_f32_16x16x32_bf16 v[12:15], v[60:63], v[162:165], v[12:15]
	ds_write2_b32 v105, v130, v68 offset1:16
	global_load_dwordx4 v[60:63], v[64:65], off
	ds_write2_b32 v105, v131, v69 offset0:128 offset1:144
	v_lshl_add_u64 v[68:69], s[30:31], 0, v[76:77]
	s_add_i32 s30, s39, 8
	s_add_i32 s31, s40, 0x18000
	s_mul_hi_i32 s30, s30, 0x3000
	s_add_u32 s31, s33, s31
	s_addc_u32 s38, s34, s30
	v_lshl_add_u64 v[122:123], v[68:69], 0, s[26:27]
	v_add_co_u32_e32 v68, vcc, s37, v68
	s_add_u32 s30, s31, s4
	s_nop 0
	v_addc_co_u32_e32 v69, vcc, 0, v69, vcc
	s_addc_u32 s31, s38, 0
	global_load_dwordx4 v[64:67], v[66:67], off offset:16
	ds_write2_b32 v128, v132, v70 offset1:16
	global_load_dwordx4 v[72:75], v[68:69], off
	ds_write2_b32 v128, v133, v71 offset0:128 offset1:144
	global_load_dwordx4 v[68:71], v[122:123], off offset:16
	v_lshl_add_u64 v[122:123], s[30:31], 0, v[76:77]
	s_add_i32 s30, s39, 12
	s_add_i32 s31, s40, 0x24000
	s_mul_hi_i32 s30, s30, 0x3000
	s_add_u32 s31, s33, s31
	s_addc_u32 s38, s34, s30
	v_lshl_add_u64 v[126:127], v[122:123], 0, s[26:27]
	v_add_co_u32_e32 v122, vcc, s37, v122
	s_add_u32 s30, s31, s4
	s_nop 0
	v_addc_co_u32_e32 v123, vcc, 0, v123, vcc
	s_addc_u32 s31, s38, 0
	ds_write2_b32 v105, v134, v20 offset0:32 offset1:48
	global_load_dwordx4 v[122:125], v[122:123], off
	ds_write2_b32 v105, v135, v21 offset0:160 offset1:176
	v_lshl_add_u64 v[20:21], s[30:31], 0, v[76:77]
	s_add_i32 s30, s39, 16
	s_add_i32 s31, s40, 0x30000
	s_mul_hi_i32 s30, s30, 0x3000
	s_add_u32 s31, s33, s31
	s_addc_u32 s38, s34, s30
	global_load_dwordx4 v[130:133], v[126:127], off offset:16
	v_lshl_add_u64 v[126:127], v[20:21], 0, s[26:27]
	v_add_co_u32_e32 v20, vcc, s37, v20
	s_add_u32 s30, s31, s4
	s_nop 0
	v_addc_co_u32_e32 v21, vcc, 0, v21, vcc
	s_addc_u32 s31, s38, 0
	ds_write2_b32 v128, v136, v22 offset0:32 offset1:48
	global_load_dwordx4 v[138:141], v[20:21], off
	ds_write2_b32 v128, v137, v23 offset0:160 offset1:176
	global_load_dwordx4 v[20:23], v[126:127], off offset:16
	v_lshl_add_u64 v[126:127], s[30:31], 0, v[76:77]
	s_add_i32 s30, s39, 20
	s_add_i32 s31, s40, 0x3c000
	s_mul_hi_i32 s30, s30, 0x3000
	s_add_u32 s31, s33, s31
	s_addc_u32 s38, s34, s30
	v_lshl_add_u64 v[142:143], v[126:127], 0, s[26:27]
	v_add_co_u32_e32 v126, vcc, s37, v126
	s_add_u32 s30, s31, s4
	s_nop 0
	v_addc_co_u32_e32 v127, vcc, 0, v127, vcc
	s_addc_u32 s31, s38, 0
	ds_write2_b32 v105, v118, v24 offset0:64 offset1:80
	global_load_dwordx4 v[134:137], v[126:127], off
	ds_write2_b32 v105, v119, v25 offset0:192 offset1:208
	v_lshl_add_u64 v[24:25], s[30:31], 0, v[76:77]
	s_add_i32 s30, s39, 24
	s_add_i32 s31, s40, 0x48000
	s_mul_hi_i32 s30, s30, 0x3000
	s_add_u32 s31, s33, s31
	s_addc_u32 s38, s34, s30
	v_lshl_add_u64 v[118:119], v[24:25], 0, s[26:27]
	v_add_co_u32_e32 v24, vcc, s37, v24
	s_add_u32 s30, s31, s4
	s_nop 0
	v_addc_co_u32_e32 v25, vcc, 0, v25, vcc
	s_addc_u32 s31, s38, 0
	s_add_i32 s39, s39, 28
	s_add_i32 s40, s40, 0x54000
	global_load_dwordx4 v[142:145], v[142:143], off offset:16
	ds_write2_b32 v128, v120, v26 offset0:64 offset1:80
	global_load_dwordx4 v[146:149], v[24:25], off
	ds_write2_b32 v128, v121, v27 offset0:192 offset1:208
	global_load_dwordx4 v[24:27], v[118:119], off offset:16
	v_lshl_add_u64 v[118:119], s[30:31], 0, v[76:77]
	s_mul_hi_i32 s30, s39, 0x3000
	s_add_u32 s31, s33, s40
	s_addc_u32 s38, s34, s30
	v_lshl_add_u64 v[126:127], v[118:119], 0, s[26:27]
	v_add_co_u32_e32 v118, vcc, s37, v118
	s_add_u32 s30, s31, s4
	s_nop 0
	v_addc_co_u32_e32 v119, vcc, 0, v119, vcc
	s_addc_u32 s31, s38, 0
	ds_write2st64_b32 v106, v158, v159 offset1:2
	global_load_dwordx4 v[118:121], v[118:119], off
	ds_write2st64_b32 v106, v160, v161 offset0:4 offset1:6
	global_load_dwordx4 v[150:153], v[126:127], off offset:16
	v_lshl_add_u64 v[126:127], s[30:31], 0, v[76:77]
	v_lshl_add_u64 v[166:167], v[126:127], 0, s[26:27]
	v_add_co_u32_e32 v126, vcc, s37, v126
	ds_write2st64_b32 v107, v12, v13 offset1:2
	s_nop 0
	v_addc_co_u32_e32 v127, vcc, 0, v127, vcc
	global_load_dwordx4 v[158:161], v[126:127], off
	ds_write2st64_b32 v107, v14, v15 offset0:4 offset1:6
	global_load_dwordx4 v[12:15], v[166:167], off offset:16
	v_mfma_f32_16x16x32_bf16 v[0:3], v[44:47], v[52:55], v[0:3]
	v_lshl_add_u64 v[126:127], v[82:83], 0, s[28:29]
	v_lshl_add_u64 v[126:127], v[126:127], 0, s[4:5]
	v_mfma_f32_16x16x32_bf16 v[4:7], v[44:47], v[40:43], v[4:7]
	s_waitcnt vmcnt(0)
	v_pk_add_f32 v[62:63], v[62:63], 0 op_sel_hi:[1,0]
	v_pk_add_f32 v[60:61], v[60:61], 0 op_sel_hi:[1,0]
	v_pk_add_f32 v[66:67], v[66:67], 0 op_sel_hi:[1,0]
	v_mfma_f32_16x16x32_bf16 v[0:3], v[32:35], v[154:157], v[0:3]
	v_add_f32_e64 v64, v64, 0
	v_add_f32_e64 v65, v65, 0
	v_pk_add_f32 v[62:63], v[62:63], v[74:75]
	v_pk_add_f32 v[60:61], v[60:61], v[72:73]
	v_mfma_f32_16x16x32_bf16 v[4:7], v[32:35], v[162:165], v[4:7]
	ds_read_b128 v[32:35], v104
	ds_read_b128 v[154:157], v104 offset:16
	ds_read_b128 v[174:177], v108
	ds_read_b128 v[166:169], v110 offset:16
	ds_read_b128 v[170:173], v110
	ds_read_b128 v[52:55], v109 offset:16
	ds_read_b128 v[40:43], v109
	ds_read_b128 v[44:47], v108 offset:16
	global_load_dwordx4 v[162:165], v[126:127], off offset:16 nt
	global_load_dwordx4 v[178:181], v[126:127], off nt
	v_pk_add_f32 v[66:67], v[66:67], v[70:71]
	v_pk_add_f32 v[64:65], v[64:65], v[68:69]
	v_pk_add_f32 v[62:63], v[62:63], v[124:125]
	v_pk_add_f32 v[60:61], v[60:61], v[122:123]
	v_pk_add_f32 v[66:67], v[66:67], v[132:133]
	v_pk_add_f32 v[64:65], v[64:65], v[130:131]
	v_pk_add_f32 v[62:63], v[62:63], v[140:141]
	v_pk_add_f32 v[60:61], v[60:61], v[138:139]
	v_pk_add_f32 v[22:23], v[66:67], v[22:23]
	v_pk_add_f32 v[20:21], v[64:65], v[20:21]
	v_pk_add_f32 v[62:63], v[62:63], v[136:137]
	v_pk_add_f32 v[60:61], v[60:61], v[134:135]
	s_add_i32 s2, s2, s3
	s_add_i32 s35, s35, s36
	s_cmpk_gt_i32 s2, 0x3ff
	v_pk_add_f32 v[22:23], v[22:23], v[144:145]
	v_pk_add_f32 v[20:21], v[20:21], v[142:143]
	v_pk_add_f32 v[62:63], v[62:63], v[148:149]
	v_pk_add_f32 v[60:61], v[60:61], v[146:147]
	v_pk_add_f32 v[22:23], v[22:23], v[26:27]
	v_pk_add_f32 v[20:21], v[20:21], v[24:25]
	v_pk_add_f32 v[24:25], v[62:63], v[120:121]
	v_pk_add_f32 v[26:27], v[60:61], v[118:119]
	v_pk_add_f32 v[22:23], v[22:23], v[152:153]
	v_pk_add_f32 v[20:21], v[20:21], v[150:151]
	v_pk_add_f32 v[60:61], v[24:25], v[160:161]
	v_pk_add_f32 v[62:63], v[26:27], v[158:159]
	v_pk_add_f32 v[64:65], v[22:23], v[14:15]
	v_pk_add_f32 v[66:67], v[20:21], v[12:13]
	v_lshl_add_u64 v[26:27], v[88:89], 0, s[28:29]
	v_lshl_add_u64 v[26:27], v[26:27], 0, s[4:5]
	s_waitcnt vmcnt(1) lgkmcnt(6)
	v_pk_fma_f32 v[22:23], v[64:65], v[156:157], v[164:165]
	s_waitcnt vmcnt(0)
	v_pk_fma_f32 v[14:15], v[60:61], v[34:35], v[180:181]
	v_pk_fma_f32 v[12:13], v[62:63], v[32:33], v[178:179]
	v_pk_fma_f32 v[20:21], v[66:67], v[154:155], v[162:163]
	global_store_dwordx4 v[126:127], v[12:15], off
	global_store_dwordx4 v[126:127], v[20:23], off offset:16
	s_nop 0
	v_lshl_add_u64 v[12:13], v[84:85], 0, s[28:29]
	v_lshl_add_u64 v[24:25], v[12:13], 0, s[4:5]
	global_load_dwordx4 v[12:15], v[24:25], off offset:16 nt
	global_load_dwordx4 v[20:23], v[24:25], off nt
	s_waitcnt vmcnt(1) lgkmcnt(0)
	v_pk_fma_f32 v[14:15], v[64:65], v[46:47], v[14:15]
	v_pk_fma_f32 v[12:13], v[66:67], v[44:45], v[12:13]
	s_waitcnt vmcnt(0)
	v_pk_fma_f32 v[22:23], v[60:61], v[176:177], v[22:23]
	v_pk_fma_f32 v[20:21], v[62:63], v[174:175], v[20:21]
	global_store_dwordx4 v[24:25], v[12:15], off offset:16
	global_store_dwordx4 v[24:25], v[20:23], off
	s_nop 0
	v_lshl_add_u64 v[12:13], v[86:87], 0, s[28:29]
	v_lshl_add_u64 v[24:25], v[12:13], 0, s[4:5]
	global_load_dwordx4 v[12:15], v[24:25], off offset:16 nt
	global_load_dwordx4 v[20:23], v[24:25], off nt
	s_waitcnt vmcnt(1)
	v_pk_fma_f32 v[14:15], v[64:65], v[54:55], v[14:15]
	s_waitcnt vmcnt(0)
	v_pk_fma_f32 v[22:23], v[60:61], v[42:43], v[22:23]
	v_pk_fma_f32 v[20:21], v[62:63], v[40:41], v[20:21]
	v_pk_fma_f32 v[12:13], v[66:67], v[52:53], v[12:13]
	global_store_dwordx4 v[24:25], v[20:23], off
	global_store_dwordx4 v[24:25], v[12:15], off offset:16
	global_load_dwordx4 v[12:15], v[26:27], off offset:16 nt
	v_lshl_add_u64 v[24:25], v[90:91], 0, s[28:29]
	global_load_dwordx4 v[20:23], v[26:27], off nt
	v_lshl_add_u64 v[40:41], v[24:25], 0, s[4:5]
	v_lshl_add_u64 v[42:43], v[92:93], 0, s[28:29]
	v_lshl_add_u64 v[42:43], v[42:43], 0, s[4:5]
	s_waitcnt vmcnt(1)
	v_pk_fma_f32 v[14:15], v[64:65], v[168:169], v[14:15]
	v_pk_fma_f32 v[12:13], v[66:67], v[166:167], v[12:13]
	s_waitcnt vmcnt(0)
	v_pk_fma_f32 v[22:23], v[60:61], v[172:173], v[22:23]
	v_pk_fma_f32 v[20:21], v[62:63], v[170:171], v[20:21]
	global_store_dwordx4 v[26:27], v[20:23], off
	global_store_dwordx4 v[26:27], v[12:15], off offset:16
	ds_write2_b32 v105, v28, v16 offset1:16
	ds_write2_b32 v105, v29, v17 offset0:128 offset1:144
	ds_write2_b32 v128, v30, v18 offset1:16
	ds_write2_b32 v128, v31, v19 offset0:128 offset1:144
	ds_write2_b32 v105, v36, v0 offset0:32 offset1:48
	ds_write2_b32 v105, v37, v1 offset0:160 offset1:176
	ds_write2_b32 v128, v38, v2 offset0:32 offset1:48
	ds_write2_b32 v128, v39, v3 offset0:160 offset1:176
	ds_write2_b32 v105, v48, v8 offset0:64 offset1:80
	ds_write2_b32 v105, v49, v9 offset0:192 offset1:208
	ds_write2_b32 v128, v50, v10 offset0:64 offset1:80
	ds_write2_b32 v128, v51, v11 offset0:192 offset1:208
	ds_write2st64_b32 v106, v56, v57 offset1:2
	ds_write2st64_b32 v106, v58, v59 offset0:4 offset1:6
	ds_write2st64_b32 v107, v4, v5 offset1:2
	ds_write2st64_b32 v107, v6, v7 offset0:4 offset1:6
	ds_read_b128 v[28:31], v104
	ds_read_b128 v[24:27], v104 offset:16
	ds_read_b128 v[20:23], v108
	ds_read_b128 v[16:19], v108 offset:16
	ds_read_b128 v[12:15], v109
	ds_read_b128 v[8:11], v109 offset:16
	ds_read_b128 v[4:7], v110
	ds_read_b128 v[0:3], v110 offset:16
	global_load_dwordx4 v[32:35], v[40:41], off offset:16 nt
	global_load_dwordx4 v[36:39], v[40:41], off nt
	s_waitcnt vmcnt(1) lgkmcnt(6)
	v_pk_fma_f32 v[26:27], v[64:65], v[26:27], v[34:35]
	s_waitcnt vmcnt(0)
	v_pk_fma_f32 v[30:31], v[60:61], v[30:31], v[38:39]
	v_pk_fma_f32 v[28:29], v[62:63], v[28:29], v[36:37]
	v_pk_fma_f32 v[24:25], v[66:67], v[24:25], v[32:33]
	global_store_dwordx4 v[40:41], v[28:31], off
	global_store_dwordx4 v[40:41], v[24:27], off offset:16
	global_load_dwordx4 v[24:27], v[42:43], off offset:16 nt
	v_lshl_add_u64 v[32:33], v[94:95], 0, s[28:29]
	global_load_dwordx4 v[28:31], v[42:43], off nt
	v_lshl_add_u64 v[32:33], v[32:33], 0, s[4:5]
	s_waitcnt vmcnt(1) lgkmcnt(4)
	v_pk_fma_f32 v[18:19], v[64:65], v[18:19], v[26:27]
	v_pk_fma_f32 v[16:17], v[66:67], v[16:17], v[24:25]
	s_waitcnt vmcnt(0)
	v_pk_fma_f32 v[22:23], v[60:61], v[22:23], v[30:31]
	v_pk_fma_f32 v[20:21], v[62:63], v[20:21], v[28:29]
	global_store_dwordx4 v[42:43], v[20:23], off
	global_store_dwordx4 v[42:43], v[16:19], off offset:16
	global_load_dwordx4 v[16:19], v[32:33], off offset:16 nt
	v_lshl_add_u64 v[24:25], v[96:97], 0, s[28:29]
	global_load_dwordx4 v[20:23], v[32:33], off nt
	v_lshl_add_u64 v[24:25], v[24:25], 0, s[4:5]
	s_waitcnt vmcnt(1) lgkmcnt(2)
	v_pk_fma_f32 v[10:11], v[64:65], v[10:11], v[18:19]
	v_pk_fma_f32 v[8:9], v[66:67], v[8:9], v[16:17]
	s_waitcnt vmcnt(0)
	v_pk_fma_f32 v[14:15], v[60:61], v[14:15], v[22:23]
	v_pk_fma_f32 v[12:13], v[62:63], v[12:13], v[20:21]
	global_store_dwordx4 v[32:33], v[12:15], off
	global_store_dwordx4 v[32:33], v[8:11], off offset:16
	global_load_dwordx4 v[8:11], v[24:25], off offset:16 nt
	s_waitcnt vmcnt(0) lgkmcnt(0)
	v_pk_fma_f32 v[2:3], v[64:65], v[2:3], v[10:11]
	global_load_dwordx4 v[12:15], v[24:25], off nt
	v_pk_fma_f32 v[0:1], v[66:67], v[0:1], v[8:9]
	global_store_dwordx4 v[24:25], v[0:3], off offset:16
	s_waitcnt vmcnt(1)
	v_pk_fma_f32 v[6:7], v[60:61], v[6:7], v[14:15]
	v_pk_fma_f32 v[4:5], v[62:63], v[4:5], v[12:13]
	global_store_dwordx4 v[24:25], v[4:7], off
	s_cbranch_scc0 .LBB0_686
